# norm output stores written through (sc0 sc1) so the grid barrier has less dirty L2 data to flush
# baseline (speedup 1.0000x reference)
; __device__ __forceinline__ unsigned pk2(float lo, float hi) { const g_f32x2 f = {lo, hi}; return __builtin_bit_cast(unsigned, __builtin_convertvector(f, g_bf16x2)); }
; __device__ __forceinline__ int obid() { int b = blockIdx.x; asm volatile("" : "+s"(b)); return b; }
; __device__ __forceinline__ void p_norm(const float* hlat, const float* hctx, const float* g, const float* modl, int sh_off, int sc_off, bf16_t* A, int M,
;                                        const float* part, const float* cgate, float* hcout) {
;     const int tid = otid(), lane = tid & 63, wave = tid >> 6;
;     const int stride = gridDim.x * 8;
;     int row = obid() * 8 + wave;
;     float4 v[4], nv[4];
;     ...
;     if (row < M) PN_LOAD(v, row);
;     while (row < M) {
;         const int nrow = row + stride;
;         if (nrow < M) PN_LOAD(nv, nrow);
;         const int r = row < NLAT ? (row >> 11) : 16;
;         float ss = 0.f;
; #pragma unroll
;         for (int i = 0; i < 4; ++i) {
;             if (part != nullptr && row >= NLAT) {
;                 const size_t po = (size_t)(row - NLAT) * 1024 + i * 256 + lane * 4;
;                 const float4 p0 = *(const float4*)(part + po), p1 = *(const float4*)(part + (size_t)4096 * 1024 + po), cg = *(const float4*)(cgate + i * 256 + lane * 4);
;                 v[i].x += cg.x * (p0.x + p1.x); v[i].y += cg.y * (p0.y + p1.y); v[i].z += cg.z * (p0.z + p1.z); v[i].w += cg.w * (p0.w + p1.w);
;                 *(float4*)(hcout + po) = v[i];
;             }
;             ss += v[i].x * v[i].x + v[i].y * v[i].y + v[i].z * v[i].z + v[i].w * v[i].w; }
;         ss = wave_sum(ss);
;         const float rstd = rsqrtf(ss * (1.0f / 1024.0f) + EPS);
;         const float* mr = modl + (size_t)r * 6144;
; #pragma unroll
;         for (int i = 0; i < 4; ++i) {
;             const int k = i * 256 + lane * 4;
;             const float4 gg = *(const float4*)(g + k), scv = *(const float4*)(mr + sc_off + k), shv = *(const float4*)(mr + sh_off + k);
;             const float o0 = v[i].x * rstd * gg.x * (1.0f + scv.x) + shv.x, o1 = v[i].y * rstd * gg.y * (1.0f + scv.y) + shv.y;
;             const float o2 = v[i].z * rstd * gg.z * (1.0f + scv.z) + shv.z, o3 = v[i].w * rstd * gg.w * (1.0f + scv.w) + shv.w;
;             uint2 w; w.x = pk2(o0, o1); w.y = pk2(o2, o3);
;             *(uint2*)(A + (size_t)row * 1024 + k) = w;
.LBB0_406:
	s_load_dwordx2 s[6:7], s[16:17], 0x0
	s_mul_hi_u32 s5, s8, 0x66000
	s_mov_b32 s9, s55
	v_mov_b32_e32 v14, v253
	s_waitcnt lgkmcnt(0)
	v_writelane_b32 v255, s6, 41
	v_ashrrev_i32_e32 v1, 6, v14
	s_nop 0
	v_writelane_b32 v255, s7, 42
	s_mul_i32 s6, s8, 0x66000
	s_add_u32 s6, s56, s6
	s_addc_u32 s7, s57, s5
	v_writelane_b32 v255, s6, 43
	s_mov_b32 s5, s63
	s_lshl_b32 s5, s5, 3
	v_writelane_b32 v255, s7, 44
	v_writelane_b32 v255, s8, 45
	s_lshl_b32 s6, s8, 10
	s_mov_b32 s7, s55
	v_writelane_b32 v255, s9, 46
	v_writelane_b32 v255, s6, 47
	v_add_u32_e32 v50, s5, v1
	s_waitcnt vmcnt(0) lgkmcnt(0)
	v_readlane_b32 s100, v255, 45
	s_load_dwordx2 s[48:49], s[0:1], 0x30
	s_cmp_eq_u32 s100, 0
	s_cselect_b32 s101, 0, 0xe8
	s_load_dwordx2 s[46:47], s[0:1], s101
	s_load_dwordx2 s[16:17], s[0:1], 0x10
	s_mul_i32 s101, s100, 0x66000
	s_add_u32 s50, s56, s101
	s_addc_u32 s51, s57, 0
	s_sub_u32 s20, s101, 0x66000
	s_cmp_eq_u32 s100, 0
	s_cselect_b32 s20, 0, s20
	s_add_u32 s20, s20, 0x65000
	s_add_u32 s20, s56, s20
	s_addc_u32 s21, s57, 0
	s_add_u32 s98, s50, 0x1000
	s_addc_u32 s99, s51, 0
	s_lshl_b32 s101, s100, 12
	v_and_b32_e32 v240, 63, v253
	v_lshlrev_b32_e32 v241, 4, v240
	v_lshrrev_b32_e32 v148, 7, v50
	v_lshlrev_b32_e32 v146, 4, v50
	v_lshl_add_u32 v144, v146, 12, v241
	v_lshlrev_b32_e32 v146, 11, v146
	v_lshl_add_u32 v146, v240, 3, v146
	v_mul_u32_u24_e32 v148, 0x6000, v148
	v_add_u32_e32 v148, v148, v241
	s_waitcnt lgkmcnt(0)
	s_add_u32 s48, s48, s101
	s_addc_u32 s49, s49, 0
	s_cmp_eq_u32 s100, 0
	s_cselect_b32 s16, s16, s64
	s_cselect_b32 s17, s17, s65
	s_cmp_eq_u32 s100, 0
	s_cbranch_scc1 .Lnorm_P1_alt
	global_load_dwordx4 v[80:83], v144, s[46:47] nt
	global_load_dwordx4 v[84:87], v144, s[46:47] offset:1024 nt
	global_load_dwordx4 v[88:91], v144, s[46:47] offset:2048 nt
	global_load_dwordx4 v[92:95], v144, s[46:47] offset:3072 nt
	v_add_u32_e32 v144, 0x1000, v144
	global_load_dwordx4 v[34:37], v148, s[98:99]
	global_load_dwordx4 v[38:41], v148, s[98:99] offset:1024
	global_load_dwordx4 v[42:45], v148, s[98:99] offset:2048
	global_load_dwordx4 v[46:49], v148, s[98:99] offset:3072
	global_load_dwordx4 v[224:227], v148, s[50:51]
	global_load_dwordx4 v[228:231], v148, s[50:51] offset:1024
	global_load_dwordx4 v[232:235], v148, s[50:51] offset:2048
	global_load_dwordx4 v[236:239], v148, s[50:51] offset:3072
	global_load_dwordx4 v[188:191], v241, s[48:49]
	global_load_dwordx4 v[192:195], v241, s[48:49] offset:1024
	global_load_dwordx4 v[196:199], v241, s[48:49] offset:2048
	global_load_dwordx4 v[200:203], v241, s[48:49] offset:3072
	global_load_dwordx4 v[96:99], v144, s[46:47] nt
	global_load_dwordx4 v[100:103], v144, s[46:47] offset:1024 nt
	global_load_dwordx4 v[104:107], v144, s[46:47] offset:2048 nt
	global_load_dwordx4 v[108:111], v144, s[46:47] offset:3072 nt
	v_add_u32_e32 v144, 0x1000, v144
	global_load_dwordx4 v[112:115], v144, s[46:47] nt
	global_load_dwordx4 v[116:119], v144, s[46:47] offset:1024 nt
	global_load_dwordx4 v[120:123], v144, s[46:47] offset:2048 nt
	global_load_dwordx4 v[124:127], v144, s[46:47] offset:3072 nt
	v_add_u32_e32 v144, 0x1000, v144
	global_load_dwordx4 v[128:131], v144, s[46:47] nt
	global_load_dwordx4 v[132:135], v144, s[46:47] offset:1024 nt
	global_load_dwordx4 v[136:139], v144, s[46:47] offset:2048 nt
	global_load_dwordx4 v[140:143], v144, s[46:47] offset:3072 nt
	v_add_u32_e32 v144, 0x1000, v144
	global_load_dwordx4 v[156:159], v144, s[46:47] nt
	global_load_dwordx4 v[160:163], v144, s[46:47] offset:1024 nt
	global_load_dwordx4 v[164:167], v144, s[46:47] offset:2048 nt
	global_load_dwordx4 v[168:171], v144, s[46:47] offset:3072 nt
	v_add_u32_e32 v144, 0x1000, v144
	global_load_dwordx4 v[172:175], v144, s[46:47] nt
	global_load_dwordx4 v[176:179], v144, s[46:47] offset:1024 nt
	global_load_dwordx4 v[180:183], v144, s[46:47] offset:2048 nt
	global_load_dwordx4 v[184:187], v144, s[46:47] offset:3072 nt
	v_add_u32_e32 v144, 0x1000, v144
	s_waitcnt vmcnt(32)
	v_pk_mul_f32 v[242:243], v[80:81], v[80:81]
	v_pk_mul_f32 v[244:245], v[84:85], v[84:85]
	v_pk_mul_f32 v[246:247], v[82:83], v[82:83]
	v_pk_mul_f32 v[248:249], v[86:87], v[86:87]
	v_add_f32_e32 v204, v245, v244
	v_add_f32_e32 v205, v243, v242
	v_add_f32_e32 v204, v248, v204
	v_add_f32_e32 v205, v246, v205
	v_add_f32_e32 v204, v249, v204
	v_add_f32_e32 v205, v247, v205
	v_pk_mul_f32 v[242:243], v[88:89], v[88:89]
	v_pk_mul_f32 v[244:245], v[92:93], v[92:93]
	v_pk_mul_f32 v[246:247], v[90:91], v[90:91]
	v_pk_mul_f32 v[248:249], v[94:95], v[94:95]
	v_add_f32_e32 v206, v243, v242
	v_add_f32_e32 v207, v245, v244
	v_add_f32_e32 v206, v246, v206
	v_add_f32_e32 v207, v248, v207
	v_add_f32_e32 v206, v247, v206
	v_add_f32_e32 v207, v249, v207
	v_add_f32_e32 v204, v205, v204
	v_add_f32_e32 v204, v204, v206
	v_add_f32_e32 v204, v204, v207
	ds_swizzle_b32 v205, v204 offset:swizzle(SWAP,1)
	s_waitcnt lgkmcnt(0)
	v_add_f32_e32 v204, v204, v205
	ds_swizzle_b32 v205, v204 offset:swizzle(SWAP,2)
	s_waitcnt lgkmcnt(0)
	v_add_f32_e32 v204, v204, v205
	ds_swizzle_b32 v205, v204 offset:swizzle(SWAP,4)
	s_waitcnt lgkmcnt(0)
	v_add_f32_e32 v204, v204, v205
	ds_swizzle_b32 v205, v204 offset:swizzle(SWAP,8)
	s_waitcnt lgkmcnt(0)
	v_add_f32_e32 v204, v204, v205
	ds_swizzle_b32 v205, v204 offset:swizzle(SWAP,16)
	s_waitcnt lgkmcnt(0)
	v_add_f32_e32 v204, v204, v205
	v_mov_b32_e32 v205, v204
	s_nop 1
	v_permlane32_swap_b32_e32 v204, v205
	v_add_f32_e32 v204, v204, v205
	v_mov_b32_e32 v205, 0x358637bd
	v_fmamk_f32 v204, v204, 0x3a800000, v205
	v_rsq_f32_e32 v204, v204
	s_nop 0
	s_waitcnt vmcnt(20)
; __device__ __forceinline__ unsigned pk2(float lo, float hi) { const g_f32x2 f = {lo, hi}; return __builtin_bit_cast(unsigned, __builtin_convertvector(f, g_bf16x2)); }
; __device__ __forceinline__ void p_norm(const float* hlat, const float* hctx, const float* g, const float* modl, int sh_off, int sc_off, bf16_t* A, int M,
;                                        const float* part, const float* cgate, float* hcout) {
;     ...
;             ss += v[i].x * v[i].x + v[i].y * v[i].y + v[i].z * v[i].z + v[i].w * v[i].w; }
;         ss = wave_sum(ss);
;         const float rstd = rsqrtf(ss * (1.0f / 1024.0f) + EPS);
;         const float* mr = modl + (size_t)r * 6144;
; #pragma unroll
;         for (int i = 0; i < 4; ++i) {
;             const int k = i * 256 + lane * 4;
;             const float4 gg = *(const float4*)(g + k), scv = *(const float4*)(mr + sc_off + k), shv = *(const float4*)(mr + sh_off + k);
;             const float o0 = v[i].x * rstd * gg.x * (1.0f + scv.x) + shv.x, o1 = v[i].y * rstd * gg.y * (1.0f + scv.y) + shv.y;
;             const float o2 = v[i].z * rstd * gg.z * (1.0f + scv.z) + shv.z, o3 = v[i].w * rstd * gg.w * (1.0f + scv.w) + shv.w;
;             uint2 w; w.x = pk2(o0, o1); w.y = pk2(o2, o3);
;             *(uint2*)(A + (size_t)row * 1024 + k) = w;
	v_pk_add_f32 v[34:35], v[34:35], 1.0 op_sel_hi:[1,0]
	v_pk_add_f32 v[36:37], v[36:37], 1.0 op_sel_hi:[1,0]
	v_pk_add_f32 v[38:39], v[38:39], 1.0 op_sel_hi:[1,0]
	v_pk_add_f32 v[40:41], v[40:41], 1.0 op_sel_hi:[1,0]
	v_pk_add_f32 v[42:43], v[42:43], 1.0 op_sel_hi:[1,0]
	v_pk_add_f32 v[44:45], v[44:45], 1.0 op_sel_hi:[1,0]
	v_pk_add_f32 v[46:47], v[46:47], 1.0 op_sel_hi:[1,0]
	v_pk_add_f32 v[48:49], v[48:49], 1.0 op_sel_hi:[1,0]
	v_pk_mul_f32 v[80:81], v[80:81], v[204:205] op_sel_hi:[1,0]
	v_pk_mul_f32 v[82:83], v[82:83], v[204:205] op_sel_hi:[1,0]
	v_pk_mul_f32 v[80:81], v[188:189], v[80:81]
	v_pk_mul_f32 v[82:83], v[190:191], v[82:83]
	v_pk_fma_f32 v[80:81], v[34:35], v[80:81], v[224:225]
	v_pk_fma_f32 v[82:83], v[36:37], v[82:83], v[226:227]
	v_cvt_pk_bf16_f32 v80, v80, v81
	v_cvt_pk_bf16_f32 v81, v82, v83
	global_store_dwordx2 v146, v[80:81], s[66:67] sc0 sc1
	v_pk_mul_f32 v[84:85], v[84:85], v[204:205] op_sel_hi:[1,0]
	v_pk_mul_f32 v[86:87], v[86:87], v[204:205] op_sel_hi:[1,0]
	v_pk_mul_f32 v[84:85], v[192:193], v[84:85]
	v_pk_mul_f32 v[86:87], v[194:195], v[86:87]
	v_pk_fma_f32 v[84:85], v[38:39], v[84:85], v[228:229]
	v_pk_fma_f32 v[86:87], v[40:41], v[86:87], v[230:231]
	v_cvt_pk_bf16_f32 v84, v84, v85
	v_cvt_pk_bf16_f32 v85, v86, v87
	global_store_dwordx2 v146, v[84:85], s[66:67] offset:512 sc0 sc1
	v_pk_mul_f32 v[88:89], v[88:89], v[204:205] op_sel_hi:[1,0]
	v_pk_mul_f32 v[90:91], v[90:91], v[204:205] op_sel_hi:[1,0]
	v_pk_mul_f32 v[88:89], v[196:197], v[88:89]
	v_pk_mul_f32 v[90:91], v[198:199], v[90:91]
	v_pk_fma_f32 v[88:89], v[42:43], v[88:89], v[232:233]
	v_pk_fma_f32 v[90:91], v[44:45], v[90:91], v[234:235]
	v_cvt_pk_bf16_f32 v88, v88, v89
	v_cvt_pk_bf16_f32 v89, v90, v91
	global_store_dwordx2 v146, v[88:89], s[66:67] offset:1024 sc0 sc1
	v_pk_mul_f32 v[92:93], v[92:93], v[204:205] op_sel_hi:[1,0]
	v_pk_mul_f32 v[94:95], v[94:95], v[204:205] op_sel_hi:[1,0]
	v_pk_mul_f32 v[92:93], v[200:201], v[92:93]
	v_pk_mul_f32 v[94:95], v[202:203], v[94:95]
	v_pk_fma_f32 v[92:93], v[46:47], v[92:93], v[236:237]
	v_pk_fma_f32 v[94:95], v[48:49], v[94:95], v[238:239]
	v_cvt_pk_bf16_f32 v92, v92, v93
	v_cvt_pk_bf16_f32 v93, v94, v95
	global_store_dwordx2 v146, v[92:93], s[66:67] offset:1536 sc0 sc1
	v_add_u32_e32 v146, 0x800, v146
	global_load_dwordx4 v[80:83], v144, s[46:47] nt
	global_load_dwordx4 v[84:87], v144, s[46:47] offset:1024 nt
	global_load_dwordx4 v[88:91], v144, s[46:47] offset:2048 nt
	global_load_dwordx4 v[92:95], v144, s[46:47] offset:3072 nt
	v_add_u32_e32 v144, 0x1000, v144
	s_waitcnt vmcnt(24)
	v_pk_mul_f32 v[242:243], v[96:97], v[96:97]
	v_pk_mul_f32 v[244:245], v[100:101], v[100:101]
	v_pk_mul_f32 v[246:247], v[98:99], v[98:99]
	v_pk_mul_f32 v[248:249], v[102:103], v[102:103]
	v_add_f32_e32 v204, v245, v244
	v_add_f32_e32 v205, v243, v242
	v_add_f32_e32 v204, v248, v204
	v_add_f32_e32 v205, v246, v205
	v_add_f32_e32 v204, v249, v204
	v_add_f32_e32 v205, v247, v205
	v_pk_mul_f32 v[242:243], v[104:105], v[104:105]
	v_pk_mul_f32 v[244:245], v[108:109], v[108:109]
	v_pk_mul_f32 v[246:247], v[106:107], v[106:107]
	v_pk_mul_f32 v[248:249], v[110:111], v[110:111]
	v_add_f32_e32 v206, v243, v242
	v_add_f32_e32 v207, v245, v244
	v_add_f32_e32 v206, v246, v206
	v_add_f32_e32 v207, v248, v207
	v_add_f32_e32 v206, v247, v206
	v_add_f32_e32 v207, v249, v207
	v_add_f32_e32 v204, v205, v204
	v_add_f32_e32 v204, v204, v206
	v_add_f32_e32 v204, v204, v207
	ds_swizzle_b32 v205, v204 offset:swizzle(SWAP,1)
	s_waitcnt lgkmcnt(0)
	v_add_f32_e32 v204, v204, v205
	ds_swizzle_b32 v205, v204 offset:swizzle(SWAP,2)
	s_waitcnt lgkmcnt(0)
	v_add_f32_e32 v204, v204, v205
	ds_swizzle_b32 v205, v204 offset:swizzle(SWAP,4)
	s_waitcnt lgkmcnt(0)
	v_add_f32_e32 v204, v204, v205
	ds_swizzle_b32 v205, v204 offset:swizzle(SWAP,8)
	s_waitcnt lgkmcnt(0)
	v_add_f32_e32 v204, v204, v205
	ds_swizzle_b32 v205, v204 offset:swizzle(SWAP,16)
	s_waitcnt lgkmcnt(0)
	v_add_f32_e32 v204, v204, v205
	v_mov_b32_e32 v205, v204
	s_nop 1
	v_permlane32_swap_b32_e32 v204, v205
	v_add_f32_e32 v204, v204, v205
	v_mov_b32_e32 v205, 0x358637bd
	v_fmamk_f32 v204, v204, 0x3a800000, v205
	v_rsq_f32_e32 v204, v204
	s_nop 0
	v_pk_mul_f32 v[96:97], v[96:97], v[204:205] op_sel_hi:[1,0]
	v_pk_mul_f32 v[98:99], v[98:99], v[204:205] op_sel_hi:[1,0]
	v_pk_mul_f32 v[96:97], v[188:189], v[96:97]
	v_pk_mul_f32 v[98:99], v[190:191], v[98:99]
	v_pk_fma_f32 v[96:97], v[34:35], v[96:97], v[224:225]
	v_pk_fma_f32 v[98:99], v[36:37], v[98:99], v[226:227]
	v_cvt_pk_bf16_f32 v96, v96, v97
	v_cvt_pk_bf16_f32 v97, v98, v99
	global_store_dwordx2 v146, v[96:97], s[66:67] sc0 sc1
	v_pk_mul_f32 v[100:101], v[100:101], v[204:205] op_sel_hi:[1,0]
	v_pk_mul_f32 v[102:103], v[102:103], v[204:205] op_sel_hi:[1,0]
	v_pk_mul_f32 v[100:101], v[192:193], v[100:101]
	v_pk_mul_f32 v[102:103], v[194:195], v[102:103]
	v_pk_fma_f32 v[100:101], v[38:39], v[100:101], v[228:229]
	v_pk_fma_f32 v[102:103], v[40:41], v[102:103], v[230:231]
	v_cvt_pk_bf16_f32 v100, v100, v101
	v_cvt_pk_bf16_f32 v101, v102, v103
	global_store_dwordx2 v146, v[100:101], s[66:67] offset:512 sc0 sc1
	v_pk_mul_f32 v[104:105], v[104:105], v[204:205] op_sel_hi:[1,0]
	v_pk_mul_f32 v[106:107], v[106:107], v[204:205] op_sel_hi:[1,0]
	v_pk_mul_f32 v[104:105], v[196:197], v[104:105]
	v_pk_mul_f32 v[106:107], v[198:199], v[106:107]
	v_pk_fma_f32 v[104:105], v[42:43], v[104:105], v[232:233]
	v_pk_fma_f32 v[106:107], v[44:45], v[106:107], v[234:235]
	v_cvt_pk_bf16_f32 v104, v104, v105
	v_cvt_pk_bf16_f32 v105, v106, v107
	global_store_dwordx2 v146, v[104:105], s[66:67] offset:1024 sc0 sc1
	v_pk_mul_f32 v[108:109], v[108:109], v[204:205] op_sel_hi:[1,0]
	v_pk_mul_f32 v[110:111], v[110:111], v[204:205] op_sel_hi:[1,0]
	v_pk_mul_f32 v[108:109], v[200:201], v[108:109]
	v_pk_mul_f32 v[110:111], v[202:203], v[110:111]
	v_pk_fma_f32 v[108:109], v[46:47], v[108:109], v[236:237]
	v_pk_fma_f32 v[110:111], v[48:49], v[110:111], v[238:239]
	v_cvt_pk_bf16_f32 v108, v108, v109
	v_cvt_pk_bf16_f32 v109, v110, v111
	global_store_dwordx2 v146, v[108:109], s[66:67] offset:1536 sc0 sc1
	v_add_u32_e32 v146, 0x800, v146
	global_load_dwordx4 v[96:99], v144, s[46:47] nt
	global_load_dwordx4 v[100:103], v144, s[46:47] offset:1024 nt
	global_load_dwordx4 v[104:107], v144, s[46:47] offset:2048 nt
	global_load_dwordx4 v[108:111], v144, s[46:47] offset:3072 nt
	v_add_u32_e32 v144, 0x1000, v144
	s_waitcnt vmcnt(28)
; __device__ __forceinline__ unsigned pk2(float lo, float hi) { const g_f32x2 f = {lo, hi}; return __builtin_bit_cast(unsigned, __builtin_convertvector(f, g_bf16x2)); }
; __device__ __forceinline__ void p_norm(const float* hlat, const float* hctx, const float* g, const float* modl, int sh_off, int sc_off, bf16_t* A, int M,
;                                        const float* part, const float* cgate, float* hcout) {
;     ...
;             ss += v[i].x * v[i].x + v[i].y * v[i].y + v[i].z * v[i].z + v[i].w * v[i].w; }
;         ss = wave_sum(ss);
;         const float rstd = rsqrtf(ss * (1.0f / 1024.0f) + EPS);
;         const float* mr = modl + (size_t)r * 6144;
; #pragma unroll
;         for (int i = 0; i < 4; ++i) {
;             const int k = i * 256 + lane * 4;
;             const float4 gg = *(const float4*)(g + k), scv = *(const float4*)(mr + sc_off + k), shv = *(const float4*)(mr + sh_off + k);
;             const float o0 = v[i].x * rstd * gg.x * (1.0f + scv.x) + shv.x, o1 = v[i].y * rstd * gg.y * (1.0f + scv.y) + shv.y;
;             const float o2 = v[i].z * rstd * gg.z * (1.0f + scv.z) + shv.z, o3 = v[i].w * rstd * gg.w * (1.0f + scv.w) + shv.w;
;             uint2 w; w.x = pk2(o0, o1); w.y = pk2(o2, o3);
;             *(uint2*)(A + (size_t)row * 1024 + k) = w;
	v_pk_mul_f32 v[242:243], v[112:113], v[112:113]
	v_pk_mul_f32 v[244:245], v[116:117], v[116:117]
	v_pk_mul_f32 v[246:247], v[114:115], v[114:115]
	v_pk_mul_f32 v[248:249], v[118:119], v[118:119]
	v_add_f32_e32 v204, v245, v244
	v_add_f32_e32 v205, v243, v242
	v_add_f32_e32 v204, v248, v204
	v_add_f32_e32 v205, v246, v205
	v_add_f32_e32 v204, v249, v204
	v_add_f32_e32 v205, v247, v205
	v_pk_mul_f32 v[242:243], v[120:121], v[120:121]
	v_pk_mul_f32 v[244:245], v[124:125], v[124:125]
	v_pk_mul_f32 v[246:247], v[122:123], v[122:123]
	v_pk_mul_f32 v[248:249], v[126:127], v[126:127]
	v_add_f32_e32 v206, v243, v242
	v_add_f32_e32 v207, v245, v244
	v_add_f32_e32 v206, v246, v206
	v_add_f32_e32 v207, v248, v207
	v_add_f32_e32 v206, v247, v206
	v_add_f32_e32 v207, v249, v207
	v_add_f32_e32 v204, v205, v204
	v_add_f32_e32 v204, v204, v206
	v_add_f32_e32 v204, v204, v207
	ds_swizzle_b32 v205, v204 offset:swizzle(SWAP,1)
	s_waitcnt lgkmcnt(0)
	v_add_f32_e32 v204, v204, v205
	ds_swizzle_b32 v205, v204 offset:swizzle(SWAP,2)
	s_waitcnt lgkmcnt(0)
	v_add_f32_e32 v204, v204, v205
	ds_swizzle_b32 v205, v204 offset:swizzle(SWAP,4)
	s_waitcnt lgkmcnt(0)
	v_add_f32_e32 v204, v204, v205
	ds_swizzle_b32 v205, v204 offset:swizzle(SWAP,8)
	s_waitcnt lgkmcnt(0)
	v_add_f32_e32 v204, v204, v205
	ds_swizzle_b32 v205, v204 offset:swizzle(SWAP,16)
	s_waitcnt lgkmcnt(0)
	v_add_f32_e32 v204, v204, v205
	v_mov_b32_e32 v205, v204
	s_nop 1
	v_permlane32_swap_b32_e32 v204, v205
	v_add_f32_e32 v204, v204, v205
	v_mov_b32_e32 v205, 0x358637bd
	v_fmamk_f32 v204, v204, 0x3a800000, v205
	v_rsq_f32_e32 v204, v204
	s_nop 0
	v_pk_mul_f32 v[112:113], v[112:113], v[204:205] op_sel_hi:[1,0]
	v_pk_mul_f32 v[114:115], v[114:115], v[204:205] op_sel_hi:[1,0]
	v_pk_mul_f32 v[112:113], v[188:189], v[112:113]
	v_pk_mul_f32 v[114:115], v[190:191], v[114:115]
	v_pk_fma_f32 v[112:113], v[34:35], v[112:113], v[224:225]
	v_pk_fma_f32 v[114:115], v[36:37], v[114:115], v[226:227]
	v_cvt_pk_bf16_f32 v112, v112, v113
	v_cvt_pk_bf16_f32 v113, v114, v115
	global_store_dwordx2 v146, v[112:113], s[66:67] sc0 sc1
	v_pk_mul_f32 v[116:117], v[116:117], v[204:205] op_sel_hi:[1,0]
	v_pk_mul_f32 v[118:119], v[118:119], v[204:205] op_sel_hi:[1,0]
	v_pk_mul_f32 v[116:117], v[192:193], v[116:117]
	v_pk_mul_f32 v[118:119], v[194:195], v[118:119]
	v_pk_fma_f32 v[116:117], v[38:39], v[116:117], v[228:229]
	v_pk_fma_f32 v[118:119], v[40:41], v[118:119], v[230:231]
	v_cvt_pk_bf16_f32 v116, v116, v117
	v_cvt_pk_bf16_f32 v117, v118, v119
	global_store_dwordx2 v146, v[116:117], s[66:67] offset:512 sc0 sc1
	v_pk_mul_f32 v[120:121], v[120:121], v[204:205] op_sel_hi:[1,0]
	v_pk_mul_f32 v[122:123], v[122:123], v[204:205] op_sel_hi:[1,0]
	v_pk_mul_f32 v[120:121], v[196:197], v[120:121]
	v_pk_mul_f32 v[122:123], v[198:199], v[122:123]
	v_pk_fma_f32 v[120:121], v[42:43], v[120:121], v[232:233]
	v_pk_fma_f32 v[122:123], v[44:45], v[122:123], v[234:235]
	v_cvt_pk_bf16_f32 v120, v120, v121
	v_cvt_pk_bf16_f32 v121, v122, v123
	global_store_dwordx2 v146, v[120:121], s[66:67] offset:1024 sc0 sc1
	v_pk_mul_f32 v[124:125], v[124:125], v[204:205] op_sel_hi:[1,0]
	v_pk_mul_f32 v[126:127], v[126:127], v[204:205] op_sel_hi:[1,0]
	v_pk_mul_f32 v[124:125], v[200:201], v[124:125]
	v_pk_mul_f32 v[126:127], v[202:203], v[126:127]
	v_pk_fma_f32 v[124:125], v[46:47], v[124:125], v[236:237]
	v_pk_fma_f32 v[126:127], v[48:49], v[126:127], v[238:239]
	v_cvt_pk_bf16_f32 v124, v124, v125
	v_cvt_pk_bf16_f32 v125, v126, v127
	global_store_dwordx2 v146, v[124:125], s[66:67] offset:1536 sc0 sc1
	v_add_u32_e32 v146, 0x800, v146
	global_load_dwordx4 v[112:115], v144, s[46:47] nt
	global_load_dwordx4 v[116:119], v144, s[46:47] offset:1024 nt
	global_load_dwordx4 v[120:123], v144, s[46:47] offset:2048 nt
	global_load_dwordx4 v[124:127], v144, s[46:47] offset:3072 nt
	v_add_u32_e32 v144, 0x1000, v144
	s_waitcnt vmcnt(32)
	v_pk_mul_f32 v[242:243], v[128:129], v[128:129]
	v_pk_mul_f32 v[244:245], v[132:133], v[132:133]
	v_pk_mul_f32 v[246:247], v[130:131], v[130:131]
	v_pk_mul_f32 v[248:249], v[134:135], v[134:135]
	v_add_f32_e32 v204, v245, v244
	v_add_f32_e32 v205, v243, v242
	v_add_f32_e32 v204, v248, v204
	v_add_f32_e32 v205, v246, v205
	v_add_f32_e32 v204, v249, v204
	v_add_f32_e32 v205, v247, v205
	v_pk_mul_f32 v[242:243], v[136:137], v[136:137]
	v_pk_mul_f32 v[244:245], v[140:141], v[140:141]
	v_pk_mul_f32 v[246:247], v[138:139], v[138:139]
	v_pk_mul_f32 v[248:249], v[142:143], v[142:143]
	v_add_f32_e32 v206, v243, v242
	v_add_f32_e32 v207, v245, v244
	v_add_f32_e32 v206, v246, v206
	v_add_f32_e32 v207, v248, v207
	v_add_f32_e32 v206, v247, v206
	v_add_f32_e32 v207, v249, v207
	v_add_f32_e32 v204, v205, v204
	v_add_f32_e32 v204, v204, v206
	v_add_f32_e32 v204, v204, v207
	ds_swizzle_b32 v205, v204 offset:swizzle(SWAP,1)
	s_waitcnt lgkmcnt(0)
	v_add_f32_e32 v204, v204, v205
	ds_swizzle_b32 v205, v204 offset:swizzle(SWAP,2)
	s_waitcnt lgkmcnt(0)
	v_add_f32_e32 v204, v204, v205
	ds_swizzle_b32 v205, v204 offset:swizzle(SWAP,4)
	s_waitcnt lgkmcnt(0)
	v_add_f32_e32 v204, v204, v205
	ds_swizzle_b32 v205, v204 offset:swizzle(SWAP,8)
	s_waitcnt lgkmcnt(0)
	v_add_f32_e32 v204, v204, v205
	ds_swizzle_b32 v205, v204 offset:swizzle(SWAP,16)
	s_waitcnt lgkmcnt(0)
; __device__ __forceinline__ unsigned pk2(float lo, float hi) { const g_f32x2 f = {lo, hi}; return __builtin_bit_cast(unsigned, __builtin_convertvector(f, g_bf16x2)); }
; __device__ __forceinline__ void p_norm(const float* hlat, const float* hctx, const float* g, const float* modl, int sh_off, int sc_off, bf16_t* A, int M,
;                                        const float* part, const float* cgate, float* hcout) {
;     ...
;             ss += v[i].x * v[i].x + v[i].y * v[i].y + v[i].z * v[i].z + v[i].w * v[i].w; }
;         ss = wave_sum(ss);
;         const float rstd = rsqrtf(ss * (1.0f / 1024.0f) + EPS);
;         const float* mr = modl + (size_t)r * 6144;
; #pragma unroll
;         for (int i = 0; i < 4; ++i) {
;             const int k = i * 256 + lane * 4;
;             const float4 gg = *(const float4*)(g + k), scv = *(const float4*)(mr + sc_off + k), shv = *(const float4*)(mr + sh_off + k);
;             const float o0 = v[i].x * rstd * gg.x * (1.0f + scv.x) + shv.x, o1 = v[i].y * rstd * gg.y * (1.0f + scv.y) + shv.y;
;             const float o2 = v[i].z * rstd * gg.z * (1.0f + scv.z) + shv.z, o3 = v[i].w * rstd * gg.w * (1.0f + scv.w) + shv.w;
;             uint2 w; w.x = pk2(o0, o1); w.y = pk2(o2, o3);
;             *(uint2*)(A + (size_t)row * 1024 + k) = w;
	v_add_f32_e32 v204, v204, v205
	v_mov_b32_e32 v205, v204
	s_nop 1
	v_permlane32_swap_b32_e32 v204, v205
	v_add_f32_e32 v204, v204, v205
	v_mov_b32_e32 v205, 0x358637bd
	v_fmamk_f32 v204, v204, 0x3a800000, v205
	v_rsq_f32_e32 v204, v204
	s_nop 0
	v_pk_mul_f32 v[128:129], v[128:129], v[204:205] op_sel_hi:[1,0]
	v_pk_mul_f32 v[130:131], v[130:131], v[204:205] op_sel_hi:[1,0]
	v_pk_mul_f32 v[128:129], v[188:189], v[128:129]
	v_pk_mul_f32 v[130:131], v[190:191], v[130:131]
	v_pk_fma_f32 v[128:129], v[34:35], v[128:129], v[224:225]
	v_pk_fma_f32 v[130:131], v[36:37], v[130:131], v[226:227]
	v_cvt_pk_bf16_f32 v128, v128, v129
	v_cvt_pk_bf16_f32 v129, v130, v131
	global_store_dwordx2 v146, v[128:129], s[66:67] sc0 sc1
	v_pk_mul_f32 v[132:133], v[132:133], v[204:205] op_sel_hi:[1,0]
	v_pk_mul_f32 v[134:135], v[134:135], v[204:205] op_sel_hi:[1,0]
	v_pk_mul_f32 v[132:133], v[192:193], v[132:133]
	v_pk_mul_f32 v[134:135], v[194:195], v[134:135]
	v_pk_fma_f32 v[132:133], v[38:39], v[132:133], v[228:229]
	v_pk_fma_f32 v[134:135], v[40:41], v[134:135], v[230:231]
	v_cvt_pk_bf16_f32 v132, v132, v133
	v_cvt_pk_bf16_f32 v133, v134, v135
	global_store_dwordx2 v146, v[132:133], s[66:67] offset:512 sc0 sc1
	v_pk_mul_f32 v[136:137], v[136:137], v[204:205] op_sel_hi:[1,0]
	v_pk_mul_f32 v[138:139], v[138:139], v[204:205] op_sel_hi:[1,0]
	v_pk_mul_f32 v[136:137], v[196:197], v[136:137]
	v_pk_mul_f32 v[138:139], v[198:199], v[138:139]
	v_pk_fma_f32 v[136:137], v[42:43], v[136:137], v[232:233]
	v_pk_fma_f32 v[138:139], v[44:45], v[138:139], v[234:235]
	v_cvt_pk_bf16_f32 v136, v136, v137
	v_cvt_pk_bf16_f32 v137, v138, v139
	global_store_dwordx2 v146, v[136:137], s[66:67] offset:1024 sc0 sc1
	v_pk_mul_f32 v[140:141], v[140:141], v[204:205] op_sel_hi:[1,0]
	v_pk_mul_f32 v[142:143], v[142:143], v[204:205] op_sel_hi:[1,0]
	v_pk_mul_f32 v[140:141], v[200:201], v[140:141]
	v_pk_mul_f32 v[142:143], v[202:203], v[142:143]
	v_pk_fma_f32 v[140:141], v[46:47], v[140:141], v[236:237]
	v_pk_fma_f32 v[142:143], v[48:49], v[142:143], v[238:239]
	v_cvt_pk_bf16_f32 v140, v140, v141
	v_cvt_pk_bf16_f32 v141, v142, v143
	global_store_dwordx2 v146, v[140:141], s[66:67] offset:1536 sc0 sc1
	v_add_u32_e32 v146, 0x800, v146
	global_load_dwordx4 v[128:131], v144, s[46:47] nt
	global_load_dwordx4 v[132:135], v144, s[46:47] offset:1024 nt
	global_load_dwordx4 v[136:139], v144, s[46:47] offset:2048 nt
	global_load_dwordx4 v[140:143], v144, s[46:47] offset:3072 nt
	v_add_u32_e32 v144, 0x1000, v144
	s_waitcnt vmcnt(36)
	v_pk_mul_f32 v[242:243], v[156:157], v[156:157]
	v_pk_mul_f32 v[244:245], v[160:161], v[160:161]
	v_pk_mul_f32 v[246:247], v[158:159], v[158:159]
	v_pk_mul_f32 v[248:249], v[162:163], v[162:163]
	v_add_f32_e32 v204, v245, v244
	v_add_f32_e32 v205, v243, v242
	v_add_f32_e32 v204, v248, v204
	v_add_f32_e32 v205, v246, v205
	v_add_f32_e32 v204, v249, v204
	v_add_f32_e32 v205, v247, v205
	v_pk_mul_f32 v[242:243], v[164:165], v[164:165]
	v_pk_mul_f32 v[244:245], v[168:169], v[168:169]
	v_pk_mul_f32 v[246:247], v[166:167], v[166:167]
	v_pk_mul_f32 v[248:249], v[170:171], v[170:171]
	v_add_f32_e32 v206, v243, v242
	v_add_f32_e32 v207, v245, v244
	v_add_f32_e32 v206, v246, v206
	v_add_f32_e32 v207, v248, v207
	v_add_f32_e32 v206, v247, v206
	v_add_f32_e32 v207, v249, v207
	v_add_f32_e32 v204, v205, v204
	v_add_f32_e32 v204, v204, v206
	v_add_f32_e32 v204, v204, v207
	ds_swizzle_b32 v205, v204 offset:swizzle(SWAP,1)
	s_waitcnt lgkmcnt(0)
	v_add_f32_e32 v204, v204, v205
	ds_swizzle_b32 v205, v204 offset:swizzle(SWAP,2)
	s_waitcnt lgkmcnt(0)
	v_add_f32_e32 v204, v204, v205
	ds_swizzle_b32 v205, v204 offset:swizzle(SWAP,4)
	s_waitcnt lgkmcnt(0)
	v_add_f32_e32 v204, v204, v205
	ds_swizzle_b32 v205, v204 offset:swizzle(SWAP,8)
	s_waitcnt lgkmcnt(0)
	v_add_f32_e32 v204, v204, v205
	ds_swizzle_b32 v205, v204 offset:swizzle(SWAP,16)
	s_waitcnt lgkmcnt(0)
	v_add_f32_e32 v204, v204, v205
	v_mov_b32_e32 v205, v204
	s_nop 1
	v_permlane32_swap_b32_e32 v204, v205
	v_add_f32_e32 v204, v204, v205
	v_mov_b32_e32 v205, 0x358637bd
	v_fmamk_f32 v204, v204, 0x3a800000, v205
	v_rsq_f32_e32 v204, v204
	s_nop 0
	v_pk_mul_f32 v[156:157], v[156:157], v[204:205] op_sel_hi:[1,0]
	v_pk_mul_f32 v[158:159], v[158:159], v[204:205] op_sel_hi:[1,0]
	v_pk_mul_f32 v[156:157], v[188:189], v[156:157]
	v_pk_mul_f32 v[158:159], v[190:191], v[158:159]
	v_pk_fma_f32 v[156:157], v[34:35], v[156:157], v[224:225]
	v_pk_fma_f32 v[158:159], v[36:37], v[158:159], v[226:227]
	v_cvt_pk_bf16_f32 v156, v156, v157
	v_cvt_pk_bf16_f32 v157, v158, v159
	global_store_dwordx2 v146, v[156:157], s[66:67] sc0 sc1
	v_pk_mul_f32 v[160:161], v[160:161], v[204:205] op_sel_hi:[1,0]
	v_pk_mul_f32 v[162:163], v[162:163], v[204:205] op_sel_hi:[1,0]
	v_pk_mul_f32 v[160:161], v[192:193], v[160:161]
	v_pk_mul_f32 v[162:163], v[194:195], v[162:163]
	v_pk_fma_f32 v[160:161], v[38:39], v[160:161], v[228:229]
	v_pk_fma_f32 v[162:163], v[40:41], v[162:163], v[230:231]
	v_cvt_pk_bf16_f32 v160, v160, v161
	v_cvt_pk_bf16_f32 v161, v162, v163
	global_store_dwordx2 v146, v[160:161], s[66:67] offset:512 sc0 sc1
	v_pk_mul_f32 v[164:165], v[164:165], v[204:205] op_sel_hi:[1,0]
	v_pk_mul_f32 v[166:167], v[166:167], v[204:205] op_sel_hi:[1,0]
	v_pk_mul_f32 v[164:165], v[196:197], v[164:165]
	v_pk_mul_f32 v[166:167], v[198:199], v[166:167]
	v_pk_fma_f32 v[164:165], v[42:43], v[164:165], v[232:233]
	v_pk_fma_f32 v[166:167], v[44:45], v[166:167], v[234:235]
	v_cvt_pk_bf16_f32 v164, v164, v165
	v_cvt_pk_bf16_f32 v165, v166, v167
	global_store_dwordx2 v146, v[164:165], s[66:67] offset:1024 sc0 sc1
	v_pk_mul_f32 v[168:169], v[168:169], v[204:205] op_sel_hi:[1,0]
	v_pk_mul_f32 v[170:171], v[170:171], v[204:205] op_sel_hi:[1,0]
	v_pk_mul_f32 v[168:169], v[200:201], v[168:169]
	v_pk_mul_f32 v[170:171], v[202:203], v[170:171]
	v_pk_fma_f32 v[168:169], v[46:47], v[168:169], v[236:237]
	v_pk_fma_f32 v[170:171], v[48:49], v[170:171], v[238:239]
	v_cvt_pk_bf16_f32 v168, v168, v169
	v_cvt_pk_bf16_f32 v169, v170, v171
	global_store_dwordx2 v146, v[168:169], s[66:67] offset:1536 sc0 sc1
	v_add_u32_e32 v146, 0x800, v146
	global_load_dwordx4 v[156:159], v144, s[46:47] nt
	global_load_dwordx4 v[160:163], v144, s[46:47] offset:1024 nt
	global_load_dwordx4 v[164:167], v144, s[46:47] offset:2048 nt
	global_load_dwordx4 v[168:171], v144, s[46:47] offset:3072 nt
	v_add_u32_e32 v144, 0x1000, v144
	s_waitcnt vmcnt(40)
; __device__ __forceinline__ unsigned pk2(float lo, float hi) { const g_f32x2 f = {lo, hi}; return __builtin_bit_cast(unsigned, __builtin_convertvector(f, g_bf16x2)); }
; __device__ __forceinline__ void p_norm(const float* hlat, const float* hctx, const float* g, const float* modl, int sh_off, int sc_off, bf16_t* A, int M,
;                                        const float* part, const float* cgate, float* hcout) {
;     ...
;             ss += v[i].x * v[i].x + v[i].y * v[i].y + v[i].z * v[i].z + v[i].w * v[i].w; }
;         ss = wave_sum(ss);
;         const float rstd = rsqrtf(ss * (1.0f / 1024.0f) + EPS);
;         const float* mr = modl + (size_t)r * 6144;
; #pragma unroll
;         for (int i = 0; i < 4; ++i) {
;             const int k = i * 256 + lane * 4;
;             const float4 gg = *(const float4*)(g + k), scv = *(const float4*)(mr + sc_off + k), shv = *(const float4*)(mr + sh_off + k);
;             const float o0 = v[i].x * rstd * gg.x * (1.0f + scv.x) + shv.x, o1 = v[i].y * rstd * gg.y * (1.0f + scv.y) + shv.y;
;             const float o2 = v[i].z * rstd * gg.z * (1.0f + scv.z) + shv.z, o3 = v[i].w * rstd * gg.w * (1.0f + scv.w) + shv.w;
;             uint2 w; w.x = pk2(o0, o1); w.y = pk2(o2, o3);
;             *(uint2*)(A + (size_t)row * 1024 + k) = w;
	v_pk_mul_f32 v[242:243], v[172:173], v[172:173]
	v_pk_mul_f32 v[244:245], v[176:177], v[176:177]
	v_pk_mul_f32 v[246:247], v[174:175], v[174:175]
	v_pk_mul_f32 v[248:249], v[178:179], v[178:179]
	v_add_f32_e32 v204, v245, v244
	v_add_f32_e32 v205, v243, v242
	v_add_f32_e32 v204, v248, v204
	v_add_f32_e32 v205, v246, v205
	v_add_f32_e32 v204, v249, v204
	v_add_f32_e32 v205, v247, v205
	v_pk_mul_f32 v[242:243], v[180:181], v[180:181]
	v_pk_mul_f32 v[244:245], v[184:185], v[184:185]
	v_pk_mul_f32 v[246:247], v[182:183], v[182:183]
	v_pk_mul_f32 v[248:249], v[186:187], v[186:187]
	v_add_f32_e32 v206, v243, v242
	v_add_f32_e32 v207, v245, v244
	v_add_f32_e32 v206, v246, v206
	v_add_f32_e32 v207, v248, v207
	v_add_f32_e32 v206, v247, v206
	v_add_f32_e32 v207, v249, v207
	v_add_f32_e32 v204, v205, v204
	v_add_f32_e32 v204, v204, v206
	v_add_f32_e32 v204, v204, v207
	ds_swizzle_b32 v205, v204 offset:swizzle(SWAP,1)
	s_waitcnt lgkmcnt(0)
	v_add_f32_e32 v204, v204, v205
	ds_swizzle_b32 v205, v204 offset:swizzle(SWAP,2)
	s_waitcnt lgkmcnt(0)
	v_add_f32_e32 v204, v204, v205
	ds_swizzle_b32 v205, v204 offset:swizzle(SWAP,4)
	s_waitcnt lgkmcnt(0)
	v_add_f32_e32 v204, v204, v205
	ds_swizzle_b32 v205, v204 offset:swizzle(SWAP,8)
	s_waitcnt lgkmcnt(0)
	v_add_f32_e32 v204, v204, v205
	ds_swizzle_b32 v205, v204 offset:swizzle(SWAP,16)
	s_waitcnt lgkmcnt(0)
	v_add_f32_e32 v204, v204, v205
	v_mov_b32_e32 v205, v204
	s_nop 1
	v_permlane32_swap_b32_e32 v204, v205
	v_add_f32_e32 v204, v204, v205
	v_mov_b32_e32 v205, 0x358637bd
	v_fmamk_f32 v204, v204, 0x3a800000, v205
	v_rsq_f32_e32 v204, v204
	s_nop 0
	v_pk_mul_f32 v[172:173], v[172:173], v[204:205] op_sel_hi:[1,0]
	v_pk_mul_f32 v[174:175], v[174:175], v[204:205] op_sel_hi:[1,0]
	v_pk_mul_f32 v[172:173], v[188:189], v[172:173]
	v_pk_mul_f32 v[174:175], v[190:191], v[174:175]
	v_pk_fma_f32 v[172:173], v[34:35], v[172:173], v[224:225]
	v_pk_fma_f32 v[174:175], v[36:37], v[174:175], v[226:227]
	v_cvt_pk_bf16_f32 v172, v172, v173
	v_cvt_pk_bf16_f32 v173, v174, v175
	global_store_dwordx2 v146, v[172:173], s[66:67] sc0 sc1
	v_pk_mul_f32 v[176:177], v[176:177], v[204:205] op_sel_hi:[1,0]
	v_pk_mul_f32 v[178:179], v[178:179], v[204:205] op_sel_hi:[1,0]
	v_pk_mul_f32 v[176:177], v[192:193], v[176:177]
	v_pk_mul_f32 v[178:179], v[194:195], v[178:179]
	v_pk_fma_f32 v[176:177], v[38:39], v[176:177], v[228:229]
	v_pk_fma_f32 v[178:179], v[40:41], v[178:179], v[230:231]
	v_cvt_pk_bf16_f32 v176, v176, v177
	v_cvt_pk_bf16_f32 v177, v178, v179
	global_store_dwordx2 v146, v[176:177], s[66:67] offset:512 sc0 sc1
	v_pk_mul_f32 v[180:181], v[180:181], v[204:205] op_sel_hi:[1,0]
	v_pk_mul_f32 v[182:183], v[182:183], v[204:205] op_sel_hi:[1,0]
	v_pk_mul_f32 v[180:181], v[196:197], v[180:181]
	v_pk_mul_f32 v[182:183], v[198:199], v[182:183]
	v_pk_fma_f32 v[180:181], v[42:43], v[180:181], v[232:233]
	v_pk_fma_f32 v[182:183], v[44:45], v[182:183], v[234:235]
	v_cvt_pk_bf16_f32 v180, v180, v181
	v_cvt_pk_bf16_f32 v181, v182, v183
	global_store_dwordx2 v146, v[180:181], s[66:67] offset:1024 sc0 sc1
	v_pk_mul_f32 v[184:185], v[184:185], v[204:205] op_sel_hi:[1,0]
	v_pk_mul_f32 v[186:187], v[186:187], v[204:205] op_sel_hi:[1,0]
	v_pk_mul_f32 v[184:185], v[200:201], v[184:185]
	v_pk_mul_f32 v[186:187], v[202:203], v[186:187]
	v_pk_fma_f32 v[184:185], v[46:47], v[184:185], v[236:237]
	v_pk_fma_f32 v[186:187], v[48:49], v[186:187], v[238:239]
	v_cvt_pk_bf16_f32 v184, v184, v185
	v_cvt_pk_bf16_f32 v185, v186, v187
	global_store_dwordx2 v146, v[184:185], s[66:67] offset:1536 sc0 sc1
	v_add_u32_e32 v146, 0x800, v146
	global_load_dwordx4 v[172:175], v144, s[46:47] nt
	global_load_dwordx4 v[176:179], v144, s[46:47] offset:1024 nt
	global_load_dwordx4 v[180:183], v144, s[46:47] offset:2048 nt
	global_load_dwordx4 v[184:187], v144, s[46:47] offset:3072 nt
	v_add_u32_e32 v144, 0x1000, v144
	s_waitcnt vmcnt(40)
	v_pk_mul_f32 v[242:243], v[80:81], v[80:81]
	v_pk_mul_f32 v[244:245], v[84:85], v[84:85]
	v_pk_mul_f32 v[246:247], v[82:83], v[82:83]
	v_pk_mul_f32 v[248:249], v[86:87], v[86:87]
	v_add_f32_e32 v204, v245, v244
	v_add_f32_e32 v205, v243, v242
	v_add_f32_e32 v204, v248, v204
	v_add_f32_e32 v205, v246, v205
	v_add_f32_e32 v204, v249, v204
	v_add_f32_e32 v205, v247, v205
	v_pk_mul_f32 v[242:243], v[88:89], v[88:89]
	v_pk_mul_f32 v[244:245], v[92:93], v[92:93]
	v_pk_mul_f32 v[246:247], v[90:91], v[90:91]
	v_pk_mul_f32 v[248:249], v[94:95], v[94:95]
	v_add_f32_e32 v206, v243, v242
	v_add_f32_e32 v207, v245, v244
	v_add_f32_e32 v206, v246, v206
	v_add_f32_e32 v207, v248, v207
	v_add_f32_e32 v206, v247, v206
	v_add_f32_e32 v207, v249, v207
	v_add_f32_e32 v204, v205, v204
	v_add_f32_e32 v204, v204, v206
	v_add_f32_e32 v204, v204, v207
	ds_swizzle_b32 v205, v204 offset:swizzle(SWAP,1)
	s_waitcnt lgkmcnt(0)
	v_add_f32_e32 v204, v204, v205
	ds_swizzle_b32 v205, v204 offset:swizzle(SWAP,2)
	s_waitcnt lgkmcnt(0)
	v_add_f32_e32 v204, v204, v205
	ds_swizzle_b32 v205, v204 offset:swizzle(SWAP,4)
	s_waitcnt lgkmcnt(0)
	v_add_f32_e32 v204, v204, v205
	ds_swizzle_b32 v205, v204 offset:swizzle(SWAP,8)
	s_waitcnt lgkmcnt(0)
	v_add_f32_e32 v204, v204, v205
	ds_swizzle_b32 v205, v204 offset:swizzle(SWAP,16)
	s_waitcnt lgkmcnt(0)
; __device__ __forceinline__ unsigned pk2(float lo, float hi) { const g_f32x2 f = {lo, hi}; return __builtin_bit_cast(unsigned, __builtin_convertvector(f, g_bf16x2)); }
; __device__ __forceinline__ void p_norm(const float* hlat, const float* hctx, const float* g, const float* modl, int sh_off, int sc_off, bf16_t* A, int M,
;                                        const float* part, const float* cgate, float* hcout) {
;     ...
;             ss += v[i].x * v[i].x + v[i].y * v[i].y + v[i].z * v[i].z + v[i].w * v[i].w; }
;         ss = wave_sum(ss);
;         const float rstd = rsqrtf(ss * (1.0f / 1024.0f) + EPS);
;         const float* mr = modl + (size_t)r * 6144;
; #pragma unroll
;         for (int i = 0; i < 4; ++i) {
;             const int k = i * 256 + lane * 4;
;             const float4 gg = *(const float4*)(g + k), scv = *(const float4*)(mr + sc_off + k), shv = *(const float4*)(mr + sh_off + k);
;             const float o0 = v[i].x * rstd * gg.x * (1.0f + scv.x) + shv.x, o1 = v[i].y * rstd * gg.y * (1.0f + scv.y) + shv.y;
;             const float o2 = v[i].z * rstd * gg.z * (1.0f + scv.z) + shv.z, o3 = v[i].w * rstd * gg.w * (1.0f + scv.w) + shv.w;
;             uint2 w; w.x = pk2(o0, o1); w.y = pk2(o2, o3);
;             *(uint2*)(A + (size_t)row * 1024 + k) = w;
	v_add_f32_e32 v204, v204, v205
	v_mov_b32_e32 v205, v204
	s_nop 1
	v_permlane32_swap_b32_e32 v204, v205
	v_add_f32_e32 v204, v204, v205
	v_mov_b32_e32 v205, 0x358637bd
	v_fmamk_f32 v204, v204, 0x3a800000, v205
	v_rsq_f32_e32 v204, v204
	s_nop 0
	v_pk_mul_f32 v[80:81], v[80:81], v[204:205] op_sel_hi:[1,0]
	v_pk_mul_f32 v[82:83], v[82:83], v[204:205] op_sel_hi:[1,0]
	v_pk_mul_f32 v[80:81], v[188:189], v[80:81]
	v_pk_mul_f32 v[82:83], v[190:191], v[82:83]
	v_pk_fma_f32 v[80:81], v[34:35], v[80:81], v[224:225]
	v_pk_fma_f32 v[82:83], v[36:37], v[82:83], v[226:227]
	v_cvt_pk_bf16_f32 v80, v80, v81
	v_cvt_pk_bf16_f32 v81, v82, v83
	global_store_dwordx2 v146, v[80:81], s[66:67] sc0 sc1
	v_pk_mul_f32 v[84:85], v[84:85], v[204:205] op_sel_hi:[1,0]
	v_pk_mul_f32 v[86:87], v[86:87], v[204:205] op_sel_hi:[1,0]
	v_pk_mul_f32 v[84:85], v[192:193], v[84:85]
	v_pk_mul_f32 v[86:87], v[194:195], v[86:87]
	v_pk_fma_f32 v[84:85], v[38:39], v[84:85], v[228:229]
	v_pk_fma_f32 v[86:87], v[40:41], v[86:87], v[230:231]
	v_cvt_pk_bf16_f32 v84, v84, v85
	v_cvt_pk_bf16_f32 v85, v86, v87
	global_store_dwordx2 v146, v[84:85], s[66:67] offset:512 sc0 sc1
	v_pk_mul_f32 v[88:89], v[88:89], v[204:205] op_sel_hi:[1,0]
	v_pk_mul_f32 v[90:91], v[90:91], v[204:205] op_sel_hi:[1,0]
	v_pk_mul_f32 v[88:89], v[196:197], v[88:89]
	v_pk_mul_f32 v[90:91], v[198:199], v[90:91]
	v_pk_fma_f32 v[88:89], v[42:43], v[88:89], v[232:233]
	v_pk_fma_f32 v[90:91], v[44:45], v[90:91], v[234:235]
	v_cvt_pk_bf16_f32 v88, v88, v89
	v_cvt_pk_bf16_f32 v89, v90, v91
	global_store_dwordx2 v146, v[88:89], s[66:67] offset:1024 sc0 sc1
	v_pk_mul_f32 v[92:93], v[92:93], v[204:205] op_sel_hi:[1,0]
	v_pk_mul_f32 v[94:95], v[94:95], v[204:205] op_sel_hi:[1,0]
	v_pk_mul_f32 v[92:93], v[200:201], v[92:93]
	v_pk_mul_f32 v[94:95], v[202:203], v[94:95]
	v_pk_fma_f32 v[92:93], v[46:47], v[92:93], v[236:237]
	v_pk_fma_f32 v[94:95], v[48:49], v[94:95], v[238:239]
	v_cvt_pk_bf16_f32 v92, v92, v93
	v_cvt_pk_bf16_f32 v93, v94, v95
	global_store_dwordx2 v146, v[92:93], s[66:67] offset:1536 sc0 sc1
	v_add_u32_e32 v146, 0x800, v146
	global_load_dwordx4 v[80:83], v144, s[46:47] nt
	global_load_dwordx4 v[84:87], v144, s[46:47] offset:1024 nt
	global_load_dwordx4 v[88:91], v144, s[46:47] offset:2048 nt
	global_load_dwordx4 v[92:95], v144, s[46:47] offset:3072 nt
	v_add_u32_e32 v144, 0x1000, v144
	s_waitcnt vmcnt(40)
	v_pk_mul_f32 v[242:243], v[96:97], v[96:97]
	v_pk_mul_f32 v[244:245], v[100:101], v[100:101]
	v_pk_mul_f32 v[246:247], v[98:99], v[98:99]
	v_pk_mul_f32 v[248:249], v[102:103], v[102:103]
	v_add_f32_e32 v204, v245, v244
	v_add_f32_e32 v205, v243, v242
	v_add_f32_e32 v204, v248, v204
	v_add_f32_e32 v205, v246, v205
	v_add_f32_e32 v204, v249, v204
	v_add_f32_e32 v205, v247, v205
	v_pk_mul_f32 v[242:243], v[104:105], v[104:105]
	v_pk_mul_f32 v[244:245], v[108:109], v[108:109]
	v_pk_mul_f32 v[246:247], v[106:107], v[106:107]
	v_pk_mul_f32 v[248:249], v[110:111], v[110:111]
	v_add_f32_e32 v206, v243, v242
	v_add_f32_e32 v207, v245, v244
	v_add_f32_e32 v206, v246, v206
	v_add_f32_e32 v207, v248, v207
	v_add_f32_e32 v206, v247, v206
	v_add_f32_e32 v207, v249, v207
	v_add_f32_e32 v204, v205, v204
	v_add_f32_e32 v204, v204, v206
	v_add_f32_e32 v204, v204, v207
	ds_swizzle_b32 v205, v204 offset:swizzle(SWAP,1)
	s_waitcnt lgkmcnt(0)
	v_add_f32_e32 v204, v204, v205
	ds_swizzle_b32 v205, v204 offset:swizzle(SWAP,2)
	s_waitcnt lgkmcnt(0)
	v_add_f32_e32 v204, v204, v205
	ds_swizzle_b32 v205, v204 offset:swizzle(SWAP,4)
	s_waitcnt lgkmcnt(0)
	v_add_f32_e32 v204, v204, v205
	ds_swizzle_b32 v205, v204 offset:swizzle(SWAP,8)
	s_waitcnt lgkmcnt(0)
	v_add_f32_e32 v204, v204, v205
	ds_swizzle_b32 v205, v204 offset:swizzle(SWAP,16)
	s_waitcnt lgkmcnt(0)
	v_add_f32_e32 v204, v204, v205
	v_mov_b32_e32 v205, v204
	s_nop 1
	v_permlane32_swap_b32_e32 v204, v205
	v_add_f32_e32 v204, v204, v205
	v_mov_b32_e32 v205, 0x358637bd
	v_fmamk_f32 v204, v204, 0x3a800000, v205
	v_rsq_f32_e32 v204, v204
	s_nop 0
	v_pk_mul_f32 v[96:97], v[96:97], v[204:205] op_sel_hi:[1,0]
	v_pk_mul_f32 v[98:99], v[98:99], v[204:205] op_sel_hi:[1,0]
	v_pk_mul_f32 v[96:97], v[188:189], v[96:97]
	v_pk_mul_f32 v[98:99], v[190:191], v[98:99]
	v_pk_fma_f32 v[96:97], v[34:35], v[96:97], v[224:225]
	v_pk_fma_f32 v[98:99], v[36:37], v[98:99], v[226:227]
	v_cvt_pk_bf16_f32 v96, v96, v97
	v_cvt_pk_bf16_f32 v97, v98, v99
	global_store_dwordx2 v146, v[96:97], s[66:67] sc0 sc1
	v_pk_mul_f32 v[100:101], v[100:101], v[204:205] op_sel_hi:[1,0]
	v_pk_mul_f32 v[102:103], v[102:103], v[204:205] op_sel_hi:[1,0]
	v_pk_mul_f32 v[100:101], v[192:193], v[100:101]
	v_pk_mul_f32 v[102:103], v[194:195], v[102:103]
	v_pk_fma_f32 v[100:101], v[38:39], v[100:101], v[228:229]
	v_pk_fma_f32 v[102:103], v[40:41], v[102:103], v[230:231]
	v_cvt_pk_bf16_f32 v100, v100, v101
	v_cvt_pk_bf16_f32 v101, v102, v103
	global_store_dwordx2 v146, v[100:101], s[66:67] offset:512 sc0 sc1
	v_pk_mul_f32 v[104:105], v[104:105], v[204:205] op_sel_hi:[1,0]
	v_pk_mul_f32 v[106:107], v[106:107], v[204:205] op_sel_hi:[1,0]
	v_pk_mul_f32 v[104:105], v[196:197], v[104:105]
	v_pk_mul_f32 v[106:107], v[198:199], v[106:107]
	v_pk_fma_f32 v[104:105], v[42:43], v[104:105], v[232:233]
	v_pk_fma_f32 v[106:107], v[44:45], v[106:107], v[234:235]
	v_cvt_pk_bf16_f32 v104, v104, v105
	v_cvt_pk_bf16_f32 v105, v106, v107
	global_store_dwordx2 v146, v[104:105], s[66:67] offset:1024 sc0 sc1
	v_pk_mul_f32 v[108:109], v[108:109], v[204:205] op_sel_hi:[1,0]
	v_pk_mul_f32 v[110:111], v[110:111], v[204:205] op_sel_hi:[1,0]
	v_pk_mul_f32 v[108:109], v[200:201], v[108:109]
	v_pk_mul_f32 v[110:111], v[202:203], v[110:111]
	v_pk_fma_f32 v[108:109], v[46:47], v[108:109], v[236:237]
	v_pk_fma_f32 v[110:111], v[48:49], v[110:111], v[238:239]
	v_cvt_pk_bf16_f32 v108, v108, v109
	v_cvt_pk_bf16_f32 v109, v110, v111
	global_store_dwordx2 v146, v[108:109], s[66:67] offset:1536 sc0 sc1
	v_add_u32_e32 v146, 0x800, v146
	global_load_dwordx4 v[96:99], v144, s[46:47] nt
	global_load_dwordx4 v[100:103], v144, s[46:47] offset:1024 nt
	global_load_dwordx4 v[104:107], v144, s[46:47] offset:2048 nt
	global_load_dwordx4 v[108:111], v144, s[46:47] offset:3072 nt
	v_add_u32_e32 v144, 0x1000, v144
	s_waitcnt vmcnt(40)
; __device__ __forceinline__ unsigned pk2(float lo, float hi) { const g_f32x2 f = {lo, hi}; return __builtin_bit_cast(unsigned, __builtin_convertvector(f, g_bf16x2)); }
; __device__ __forceinline__ void p_norm(const float* hlat, const float* hctx, const float* g, const float* modl, int sh_off, int sc_off, bf16_t* A, int M,
;                                        const float* part, const float* cgate, float* hcout) {
;     ...
;             ss += v[i].x * v[i].x + v[i].y * v[i].y + v[i].z * v[i].z + v[i].w * v[i].w; }
;         ss = wave_sum(ss);
;         const float rstd = rsqrtf(ss * (1.0f / 1024.0f) + EPS);
;         const float* mr = modl + (size_t)r * 6144;
; #pragma unroll
;         for (int i = 0; i < 4; ++i) {
;             const int k = i * 256 + lane * 4;
;             const float4 gg = *(const float4*)(g + k), scv = *(const float4*)(mr + sc_off + k), shv = *(const float4*)(mr + sh_off + k);
;             const float o0 = v[i].x * rstd * gg.x * (1.0f + scv.x) + shv.x, o1 = v[i].y * rstd * gg.y * (1.0f + scv.y) + shv.y;
;             const float o2 = v[i].z * rstd * gg.z * (1.0f + scv.z) + shv.z, o3 = v[i].w * rstd * gg.w * (1.0f + scv.w) + shv.w;
;             uint2 w; w.x = pk2(o0, o1); w.y = pk2(o2, o3);
;             *(uint2*)(A + (size_t)row * 1024 + k) = w;
	v_pk_mul_f32 v[242:243], v[112:113], v[112:113]
	v_pk_mul_f32 v[244:245], v[116:117], v[116:117]
	v_pk_mul_f32 v[246:247], v[114:115], v[114:115]
	v_pk_mul_f32 v[248:249], v[118:119], v[118:119]
	v_add_f32_e32 v204, v245, v244
	v_add_f32_e32 v205, v243, v242
	v_add_f32_e32 v204, v248, v204
	v_add_f32_e32 v205, v246, v205
	v_add_f32_e32 v204, v249, v204
	v_add_f32_e32 v205, v247, v205
	v_pk_mul_f32 v[242:243], v[120:121], v[120:121]
	v_pk_mul_f32 v[244:245], v[124:125], v[124:125]
	v_pk_mul_f32 v[246:247], v[122:123], v[122:123]
	v_pk_mul_f32 v[248:249], v[126:127], v[126:127]
	v_add_f32_e32 v206, v243, v242
	v_add_f32_e32 v207, v245, v244
	v_add_f32_e32 v206, v246, v206
	v_add_f32_e32 v207, v248, v207
	v_add_f32_e32 v206, v247, v206
	v_add_f32_e32 v207, v249, v207
	v_add_f32_e32 v204, v205, v204
	v_add_f32_e32 v204, v204, v206
	v_add_f32_e32 v204, v204, v207
	ds_swizzle_b32 v205, v204 offset:swizzle(SWAP,1)
	s_waitcnt lgkmcnt(0)
	v_add_f32_e32 v204, v204, v205
	ds_swizzle_b32 v205, v204 offset:swizzle(SWAP,2)
	s_waitcnt lgkmcnt(0)
	v_add_f32_e32 v204, v204, v205
	ds_swizzle_b32 v205, v204 offset:swizzle(SWAP,4)
	s_waitcnt lgkmcnt(0)
	v_add_f32_e32 v204, v204, v205
	ds_swizzle_b32 v205, v204 offset:swizzle(SWAP,8)
	s_waitcnt lgkmcnt(0)
	v_add_f32_e32 v204, v204, v205
	ds_swizzle_b32 v205, v204 offset:swizzle(SWAP,16)
	s_waitcnt lgkmcnt(0)
	v_add_f32_e32 v204, v204, v205
	v_mov_b32_e32 v205, v204
	s_nop 1
	v_permlane32_swap_b32_e32 v204, v205
	v_add_f32_e32 v204, v204, v205
	v_mov_b32_e32 v205, 0x358637bd
	v_fmamk_f32 v204, v204, 0x3a800000, v205
	v_rsq_f32_e32 v204, v204
	s_nop 0
	v_pk_mul_f32 v[112:113], v[112:113], v[204:205] op_sel_hi:[1,0]
	v_pk_mul_f32 v[114:115], v[114:115], v[204:205] op_sel_hi:[1,0]
	v_pk_mul_f32 v[112:113], v[188:189], v[112:113]
	v_pk_mul_f32 v[114:115], v[190:191], v[114:115]
	v_pk_fma_f32 v[112:113], v[34:35], v[112:113], v[224:225]
	v_pk_fma_f32 v[114:115], v[36:37], v[114:115], v[226:227]
	v_cvt_pk_bf16_f32 v112, v112, v113
	v_cvt_pk_bf16_f32 v113, v114, v115
	global_store_dwordx2 v146, v[112:113], s[66:67] sc0 sc1
	v_pk_mul_f32 v[116:117], v[116:117], v[204:205] op_sel_hi:[1,0]
	v_pk_mul_f32 v[118:119], v[118:119], v[204:205] op_sel_hi:[1,0]
	v_pk_mul_f32 v[116:117], v[192:193], v[116:117]
	v_pk_mul_f32 v[118:119], v[194:195], v[118:119]
	v_pk_fma_f32 v[116:117], v[38:39], v[116:117], v[228:229]
	v_pk_fma_f32 v[118:119], v[40:41], v[118:119], v[230:231]
	v_cvt_pk_bf16_f32 v116, v116, v117
	v_cvt_pk_bf16_f32 v117, v118, v119
	global_store_dwordx2 v146, v[116:117], s[66:67] offset:512 sc0 sc1
	v_pk_mul_f32 v[120:121], v[120:121], v[204:205] op_sel_hi:[1,0]
	v_pk_mul_f32 v[122:123], v[122:123], v[204:205] op_sel_hi:[1,0]
	v_pk_mul_f32 v[120:121], v[196:197], v[120:121]
	v_pk_mul_f32 v[122:123], v[198:199], v[122:123]
	v_pk_fma_f32 v[120:121], v[42:43], v[120:121], v[232:233]
	v_pk_fma_f32 v[122:123], v[44:45], v[122:123], v[234:235]
	v_cvt_pk_bf16_f32 v120, v120, v121
	v_cvt_pk_bf16_f32 v121, v122, v123
	global_store_dwordx2 v146, v[120:121], s[66:67] offset:1024 sc0 sc1
	v_pk_mul_f32 v[124:125], v[124:125], v[204:205] op_sel_hi:[1,0]
	v_pk_mul_f32 v[126:127], v[126:127], v[204:205] op_sel_hi:[1,0]
	v_pk_mul_f32 v[124:125], v[200:201], v[124:125]
	v_pk_mul_f32 v[126:127], v[202:203], v[126:127]
	v_pk_fma_f32 v[124:125], v[46:47], v[124:125], v[236:237]
	v_pk_fma_f32 v[126:127], v[48:49], v[126:127], v[238:239]
	v_cvt_pk_bf16_f32 v124, v124, v125
	v_cvt_pk_bf16_f32 v125, v126, v127
	global_store_dwordx2 v146, v[124:125], s[66:67] offset:1536 sc0 sc1
	v_add_u32_e32 v146, 0x800, v146
	global_load_dwordx4 v[112:115], v144, s[46:47] nt
	global_load_dwordx4 v[116:119], v144, s[46:47] offset:1024 nt
	global_load_dwordx4 v[120:123], v144, s[46:47] offset:2048 nt
	global_load_dwordx4 v[124:127], v144, s[46:47] offset:3072 nt
	v_add_u32_e32 v144, 0x1000, v144
	s_waitcnt vmcnt(40)
	v_pk_mul_f32 v[242:243], v[128:129], v[128:129]
	v_pk_mul_f32 v[244:245], v[132:133], v[132:133]
	v_pk_mul_f32 v[246:247], v[130:131], v[130:131]
	v_pk_mul_f32 v[248:249], v[134:135], v[134:135]
	v_add_f32_e32 v204, v245, v244
	v_add_f32_e32 v205, v243, v242
	v_add_f32_e32 v204, v248, v204
	v_add_f32_e32 v205, v246, v205
	v_add_f32_e32 v204, v249, v204
	v_add_f32_e32 v205, v247, v205
	v_pk_mul_f32 v[242:243], v[136:137], v[136:137]
	v_pk_mul_f32 v[244:245], v[140:141], v[140:141]
	v_pk_mul_f32 v[246:247], v[138:139], v[138:139]
	v_pk_mul_f32 v[248:249], v[142:143], v[142:143]
	v_add_f32_e32 v206, v243, v242
	v_add_f32_e32 v207, v245, v244
	v_add_f32_e32 v206, v246, v206
	v_add_f32_e32 v207, v248, v207
	v_add_f32_e32 v206, v247, v206
	v_add_f32_e32 v207, v249, v207
	v_add_f32_e32 v204, v205, v204
	v_add_f32_e32 v204, v204, v206
	v_add_f32_e32 v204, v204, v207
	ds_swizzle_b32 v205, v204 offset:swizzle(SWAP,1)
	s_waitcnt lgkmcnt(0)
	v_add_f32_e32 v204, v204, v205
	ds_swizzle_b32 v205, v204 offset:swizzle(SWAP,2)
	s_waitcnt lgkmcnt(0)
	v_add_f32_e32 v204, v204, v205
	ds_swizzle_b32 v205, v204 offset:swizzle(SWAP,4)
	s_waitcnt lgkmcnt(0)
	v_add_f32_e32 v204, v204, v205
	ds_swizzle_b32 v205, v204 offset:swizzle(SWAP,8)
	s_waitcnt lgkmcnt(0)
	v_add_f32_e32 v204, v204, v205
	ds_swizzle_b32 v205, v204 offset:swizzle(SWAP,16)
	s_waitcnt lgkmcnt(0)
; __device__ __forceinline__ unsigned pk2(float lo, float hi) { const g_f32x2 f = {lo, hi}; return __builtin_bit_cast(unsigned, __builtin_convertvector(f, g_bf16x2)); }
; __device__ __forceinline__ void p_norm(const float* hlat, const float* hctx, const float* g, const float* modl, int sh_off, int sc_off, bf16_t* A, int M,
;                                        const float* part, const float* cgate, float* hcout) {
;     ...
;         float ss = 0.f;
; #pragma unroll
;         for (int i = 0; i < 4; ++i) {
;             if (part != nullptr && row >= NLAT) {
;                 const size_t po = (size_t)(row - NLAT) * 1024 + i * 256 + lane * 4;
;                 const float4 p0 = *(const float4*)(part + po), p1 = *(const float4*)(part + (size_t)4096 * 1024 + po), cg = *(const float4*)(cgate + i * 256 + lane * 4);
;                 v[i].x += cg.x * (p0.x + p1.x); v[i].y += cg.y * (p0.y + p1.y); v[i].z += cg.z * (p0.z + p1.z); v[i].w += cg.w * (p0.w + p1.w);
;                 *(float4*)(hcout + po) = v[i];
;             }
;             ss += v[i].x * v[i].x + v[i].y * v[i].y + v[i].z * v[i].z + v[i].w * v[i].w; }
;         ss = wave_sum(ss);
;         const float rstd = rsqrtf(ss * (1.0f / 1024.0f) + EPS);
;         const float* mr = modl + (size_t)r * 6144;
; #pragma unroll
;         for (int i = 0; i < 4; ++i) {
;             const int k = i * 256 + lane * 4;
;             const float4 gg = *(const float4*)(g + k), scv = *(const float4*)(mr + sc_off + k), shv = *(const float4*)(mr + sh_off + k);
;             const float o0 = v[i].x * rstd * gg.x * (1.0f + scv.x) + shv.x, o1 = v[i].y * rstd * gg.y * (1.0f + scv.y) + shv.y;
;             const float o2 = v[i].z * rstd * gg.z * (1.0f + scv.z) + shv.z, o3 = v[i].w * rstd * gg.w * (1.0f + scv.w) + shv.w;
;             uint2 w; w.x = pk2(o0, o1); w.y = pk2(o2, o3);
;             *(uint2*)(A + (size_t)row * 1024 + k) = w;
;         }
	v_add_f32_e32 v204, v204, v205
	v_mov_b32_e32 v205, v204
	s_nop 1
	v_permlane32_swap_b32_e32 v204, v205
	v_add_f32_e32 v204, v204, v205
	v_mov_b32_e32 v205, 0x358637bd
	v_fmamk_f32 v204, v204, 0x3a800000, v205
	v_rsq_f32_e32 v204, v204
	s_nop 0
	v_pk_mul_f32 v[128:129], v[128:129], v[204:205] op_sel_hi:[1,0]
	v_pk_mul_f32 v[130:131], v[130:131], v[204:205] op_sel_hi:[1,0]
	v_pk_mul_f32 v[128:129], v[188:189], v[128:129]
	v_pk_mul_f32 v[130:131], v[190:191], v[130:131]
	v_pk_fma_f32 v[128:129], v[34:35], v[128:129], v[224:225]
	v_pk_fma_f32 v[130:131], v[36:37], v[130:131], v[226:227]
	v_cvt_pk_bf16_f32 v128, v128, v129
	v_cvt_pk_bf16_f32 v129, v130, v131
	global_store_dwordx2 v146, v[128:129], s[66:67] sc0 sc1
	v_pk_mul_f32 v[132:133], v[132:133], v[204:205] op_sel_hi:[1,0]
	v_pk_mul_f32 v[134:135], v[134:135], v[204:205] op_sel_hi:[1,0]
	v_pk_mul_f32 v[132:133], v[192:193], v[132:133]
	v_pk_mul_f32 v[134:135], v[194:195], v[134:135]
	v_pk_fma_f32 v[132:133], v[38:39], v[132:133], v[228:229]
	v_pk_fma_f32 v[134:135], v[40:41], v[134:135], v[230:231]
	v_cvt_pk_bf16_f32 v132, v132, v133
	v_cvt_pk_bf16_f32 v133, v134, v135
	global_store_dwordx2 v146, v[132:133], s[66:67] offset:512 sc0 sc1
	v_pk_mul_f32 v[136:137], v[136:137], v[204:205] op_sel_hi:[1,0]
	v_pk_mul_f32 v[138:139], v[138:139], v[204:205] op_sel_hi:[1,0]
	v_pk_mul_f32 v[136:137], v[196:197], v[136:137]
	v_pk_mul_f32 v[138:139], v[198:199], v[138:139]
	v_pk_fma_f32 v[136:137], v[42:43], v[136:137], v[232:233]
	v_pk_fma_f32 v[138:139], v[44:45], v[138:139], v[234:235]
	v_cvt_pk_bf16_f32 v136, v136, v137
	v_cvt_pk_bf16_f32 v137, v138, v139
	global_store_dwordx2 v146, v[136:137], s[66:67] offset:1024 sc0 sc1
	v_pk_mul_f32 v[140:141], v[140:141], v[204:205] op_sel_hi:[1,0]
	v_pk_mul_f32 v[142:143], v[142:143], v[204:205] op_sel_hi:[1,0]
	v_pk_mul_f32 v[140:141], v[200:201], v[140:141]
	v_pk_mul_f32 v[142:143], v[202:203], v[142:143]
	v_pk_fma_f32 v[140:141], v[46:47], v[140:141], v[236:237]
	v_pk_fma_f32 v[142:143], v[48:49], v[142:143], v[238:239]
	v_cvt_pk_bf16_f32 v140, v140, v141
	v_cvt_pk_bf16_f32 v141, v142, v143
	global_store_dwordx2 v146, v[140:141], s[66:67] offset:1536 sc0 sc1
	v_add_u32_e32 v146, 0x800, v146
	global_load_dwordx4 v[128:131], v144, s[46:47] nt
	global_load_dwordx4 v[132:135], v144, s[46:47] offset:1024 nt
	global_load_dwordx4 v[136:139], v144, s[46:47] offset:2048 nt
	global_load_dwordx4 v[140:143], v144, s[46:47] offset:3072 nt
	v_add_u32_e32 v144, 0x1000, v144
	s_waitcnt vmcnt(40)
	v_pk_mul_f32 v[242:243], v[156:157], v[156:157]
	v_pk_mul_f32 v[244:245], v[160:161], v[160:161]
	v_pk_mul_f32 v[246:247], v[158:159], v[158:159]
	v_pk_mul_f32 v[248:249], v[162:163], v[162:163]
	v_add_f32_e32 v204, v245, v244
	v_add_f32_e32 v205, v243, v242
	v_add_f32_e32 v204, v248, v204
	v_add_f32_e32 v205, v246, v205
	v_add_f32_e32 v204, v249, v204
	v_add_f32_e32 v205, v247, v205
	v_pk_mul_f32 v[242:243], v[164:165], v[164:165]
	v_pk_mul_f32 v[244:245], v[168:169], v[168:169]
	v_pk_mul_f32 v[246:247], v[166:167], v[166:167]
	v_pk_mul_f32 v[248:249], v[170:171], v[170:171]
	v_add_f32_e32 v206, v243, v242
	v_add_f32_e32 v207, v245, v244
	v_add_f32_e32 v206, v246, v206
	v_add_f32_e32 v207, v248, v207
	v_add_f32_e32 v206, v247, v206
	v_add_f32_e32 v207, v249, v207
	v_add_f32_e32 v204, v205, v204
	v_add_f32_e32 v204, v204, v206
	v_add_f32_e32 v204, v204, v207
	ds_swizzle_b32 v205, v204 offset:swizzle(SWAP,1)
	s_waitcnt lgkmcnt(0)
	v_add_f32_e32 v204, v204, v205
	ds_swizzle_b32 v205, v204 offset:swizzle(SWAP,2)
	s_waitcnt lgkmcnt(0)
	v_add_f32_e32 v204, v204, v205
	ds_swizzle_b32 v205, v204 offset:swizzle(SWAP,4)
	s_waitcnt lgkmcnt(0)
	v_add_f32_e32 v204, v204, v205
	ds_swizzle_b32 v205, v204 offset:swizzle(SWAP,8)
	s_waitcnt lgkmcnt(0)
	v_add_f32_e32 v204, v204, v205
	ds_swizzle_b32 v205, v204 offset:swizzle(SWAP,16)
	s_waitcnt lgkmcnt(0)
	v_add_f32_e32 v204, v204, v205
	v_mov_b32_e32 v205, v204
	s_nop 1
	v_permlane32_swap_b32_e32 v204, v205
	v_add_f32_e32 v204, v204, v205
	v_mov_b32_e32 v205, 0x358637bd
	v_fmamk_f32 v204, v204, 0x3a800000, v205
	v_rsq_f32_e32 v204, v204
	s_nop 0
	v_pk_mul_f32 v[156:157], v[156:157], v[204:205] op_sel_hi:[1,0]
	v_pk_mul_f32 v[158:159], v[158:159], v[204:205] op_sel_hi:[1,0]
	v_pk_mul_f32 v[156:157], v[188:189], v[156:157]
	v_pk_mul_f32 v[158:159], v[190:191], v[158:159]
	v_pk_fma_f32 v[156:157], v[34:35], v[156:157], v[224:225]
	v_pk_fma_f32 v[158:159], v[36:37], v[158:159], v[226:227]
	v_cvt_pk_bf16_f32 v156, v156, v157
	v_cvt_pk_bf16_f32 v157, v158, v159
	global_store_dwordx2 v146, v[156:157], s[66:67] sc0 sc1
	v_pk_mul_f32 v[160:161], v[160:161], v[204:205] op_sel_hi:[1,0]
	v_pk_mul_f32 v[162:163], v[162:163], v[204:205] op_sel_hi:[1,0]
	v_pk_mul_f32 v[160:161], v[192:193], v[160:161]
	v_pk_mul_f32 v[162:163], v[194:195], v[162:163]
	v_pk_fma_f32 v[160:161], v[38:39], v[160:161], v[228:229]
	v_pk_fma_f32 v[162:163], v[40:41], v[162:163], v[230:231]
	v_cvt_pk_bf16_f32 v160, v160, v161
	v_cvt_pk_bf16_f32 v161, v162, v163
	global_store_dwordx2 v146, v[160:161], s[66:67] offset:512 sc0 sc1
	v_pk_mul_f32 v[164:165], v[164:165], v[204:205] op_sel_hi:[1,0]
	v_pk_mul_f32 v[166:167], v[166:167], v[204:205] op_sel_hi:[1,0]
	v_pk_mul_f32 v[164:165], v[196:197], v[164:165]
	v_pk_mul_f32 v[166:167], v[198:199], v[166:167]
	v_pk_fma_f32 v[164:165], v[42:43], v[164:165], v[232:233]
	v_pk_fma_f32 v[166:167], v[44:45], v[166:167], v[234:235]
	v_cvt_pk_bf16_f32 v164, v164, v165
	v_cvt_pk_bf16_f32 v165, v166, v167
	global_store_dwordx2 v146, v[164:165], s[66:67] offset:1024 sc0 sc1
	v_pk_mul_f32 v[168:169], v[168:169], v[204:205] op_sel_hi:[1,0]
	v_pk_mul_f32 v[170:171], v[170:171], v[204:205] op_sel_hi:[1,0]
	v_pk_mul_f32 v[168:169], v[200:201], v[168:169]
	v_pk_mul_f32 v[170:171], v[202:203], v[170:171]
	v_pk_fma_f32 v[168:169], v[46:47], v[168:169], v[236:237]
	v_pk_fma_f32 v[170:171], v[48:49], v[170:171], v[238:239]
	v_cvt_pk_bf16_f32 v168, v168, v169
	v_cvt_pk_bf16_f32 v169, v170, v171
	global_store_dwordx2 v146, v[168:169], s[66:67] offset:1536 sc0 sc1
	v_add_u32_e32 v146, 0x800, v146
	v_lshl_add_u32 v144, v50, 13, v241
	v_mov_b32_e32 v152, v144
	v_add_u32_e32 v150, 0x1000000, v144
	global_load_dwordx4 v[156:159], v144, s[16:17]
	global_load_dwordx4 v[160:163], v144, s[16:17] offset:1024
	global_load_dwordx4 v[164:167], v144, s[16:17] offset:2048
	global_load_dwordx4 v[168:171], v144, s[16:17] offset:3072
	v_add_u32_e32 v144, 0x1000, v144
	s_waitcnt vmcnt(40)
; __device__ __forceinline__ unsigned pk2(float lo, float hi) { const g_f32x2 f = {lo, hi}; return __builtin_bit_cast(unsigned, __builtin_convertvector(f, g_bf16x2)); }
; __device__ __forceinline__ void p_norm(const float* hlat, const float* hctx, const float* g, const float* modl, int sh_off, int sc_off, bf16_t* A, int M,
;                                        const float* part, const float* cgate, float* hcout) {
;     ...
;         float ss = 0.f;
; #pragma unroll
;         for (int i = 0; i < 4; ++i) {
;             if (part != nullptr && row >= NLAT) {
;                 const size_t po = (size_t)(row - NLAT) * 1024 + i * 256 + lane * 4;
;                 const float4 p0 = *(const float4*)(part + po), p1 = *(const float4*)(part + (size_t)4096 * 1024 + po), cg = *(const float4*)(cgate + i * 256 + lane * 4);
;                 v[i].x += cg.x * (p0.x + p1.x); v[i].y += cg.y * (p0.y + p1.y); v[i].z += cg.z * (p0.z + p1.z); v[i].w += cg.w * (p0.w + p1.w);
;                 *(float4*)(hcout + po) = v[i];
;             }
;             ss += v[i].x * v[i].x + v[i].y * v[i].y + v[i].z * v[i].z + v[i].w * v[i].w; }
;         ss = wave_sum(ss);
;         const float rstd = rsqrtf(ss * (1.0f / 1024.0f) + EPS);
;         const float* mr = modl + (size_t)r * 6144;
; #pragma unroll
;         for (int i = 0; i < 4; ++i) {
;             const int k = i * 256 + lane * 4;
;             const float4 gg = *(const float4*)(g + k), scv = *(const float4*)(mr + sc_off + k), shv = *(const float4*)(mr + sh_off + k);
;             const float o0 = v[i].x * rstd * gg.x * (1.0f + scv.x) + shv.x, o1 = v[i].y * rstd * gg.y * (1.0f + scv.y) + shv.y;
;             const float o2 = v[i].z * rstd * gg.z * (1.0f + scv.z) + shv.z, o3 = v[i].w * rstd * gg.w * (1.0f + scv.w) + shv.w;
;             uint2 w; w.x = pk2(o0, o1); w.y = pk2(o2, o3);
;             *(uint2*)(A + (size_t)row * 1024 + k) = w;
;         }
	v_pk_mul_f32 v[242:243], v[172:173], v[172:173]
	v_pk_mul_f32 v[244:245], v[176:177], v[176:177]
	v_pk_mul_f32 v[246:247], v[174:175], v[174:175]
	v_pk_mul_f32 v[248:249], v[178:179], v[178:179]
	v_add_f32_e32 v204, v245, v244
	v_add_f32_e32 v205, v243, v242
	v_add_f32_e32 v204, v248, v204
	v_add_f32_e32 v205, v246, v205
	v_add_f32_e32 v204, v249, v204
	v_add_f32_e32 v205, v247, v205
	v_pk_mul_f32 v[242:243], v[180:181], v[180:181]
	v_pk_mul_f32 v[244:245], v[184:185], v[184:185]
	v_pk_mul_f32 v[246:247], v[182:183], v[182:183]
	v_pk_mul_f32 v[248:249], v[186:187], v[186:187]
	v_add_f32_e32 v206, v243, v242
	v_add_f32_e32 v207, v245, v244
	v_add_f32_e32 v206, v246, v206
	v_add_f32_e32 v207, v248, v207
	v_add_f32_e32 v206, v247, v206
	v_add_f32_e32 v207, v249, v207
	v_add_f32_e32 v204, v205, v204
	v_add_f32_e32 v204, v204, v206
	v_add_f32_e32 v204, v204, v207
	ds_swizzle_b32 v205, v204 offset:swizzle(SWAP,1)
	s_waitcnt lgkmcnt(0)
	v_add_f32_e32 v204, v204, v205
	ds_swizzle_b32 v205, v204 offset:swizzle(SWAP,2)
	s_waitcnt lgkmcnt(0)
	v_add_f32_e32 v204, v204, v205
	ds_swizzle_b32 v205, v204 offset:swizzle(SWAP,4)
	s_waitcnt lgkmcnt(0)
	v_add_f32_e32 v204, v204, v205
	ds_swizzle_b32 v205, v204 offset:swizzle(SWAP,8)
	s_waitcnt lgkmcnt(0)
	v_add_f32_e32 v204, v204, v205
	ds_swizzle_b32 v205, v204 offset:swizzle(SWAP,16)
	s_waitcnt lgkmcnt(0)
	v_add_f32_e32 v204, v204, v205
	v_mov_b32_e32 v205, v204
	s_nop 1
	v_permlane32_swap_b32_e32 v204, v205
	v_add_f32_e32 v204, v204, v205
	v_mov_b32_e32 v205, 0x358637bd
	v_fmamk_f32 v204, v204, 0x3a800000, v205
	v_rsq_f32_e32 v204, v204
	s_nop 0
	v_pk_mul_f32 v[172:173], v[172:173], v[204:205] op_sel_hi:[1,0]
	v_pk_mul_f32 v[174:175], v[174:175], v[204:205] op_sel_hi:[1,0]
	v_pk_mul_f32 v[172:173], v[188:189], v[172:173]
	v_pk_mul_f32 v[174:175], v[190:191], v[174:175]
	v_pk_fma_f32 v[172:173], v[34:35], v[172:173], v[224:225]
	v_pk_fma_f32 v[174:175], v[36:37], v[174:175], v[226:227]
	v_cvt_pk_bf16_f32 v172, v172, v173
	v_cvt_pk_bf16_f32 v173, v174, v175
	global_store_dwordx2 v146, v[172:173], s[66:67] sc0 sc1
	v_pk_mul_f32 v[176:177], v[176:177], v[204:205] op_sel_hi:[1,0]
	v_pk_mul_f32 v[178:179], v[178:179], v[204:205] op_sel_hi:[1,0]
	v_pk_mul_f32 v[176:177], v[192:193], v[176:177]
	v_pk_mul_f32 v[178:179], v[194:195], v[178:179]
	v_pk_fma_f32 v[176:177], v[38:39], v[176:177], v[228:229]
	v_pk_fma_f32 v[178:179], v[40:41], v[178:179], v[230:231]
	v_cvt_pk_bf16_f32 v176, v176, v177
	v_cvt_pk_bf16_f32 v177, v178, v179
	global_store_dwordx2 v146, v[176:177], s[66:67] offset:512 sc0 sc1
	v_pk_mul_f32 v[180:181], v[180:181], v[204:205] op_sel_hi:[1,0]
	v_pk_mul_f32 v[182:183], v[182:183], v[204:205] op_sel_hi:[1,0]
	v_pk_mul_f32 v[180:181], v[196:197], v[180:181]
	v_pk_mul_f32 v[182:183], v[198:199], v[182:183]
	v_pk_fma_f32 v[180:181], v[42:43], v[180:181], v[232:233]
	v_pk_fma_f32 v[182:183], v[44:45], v[182:183], v[234:235]
	v_cvt_pk_bf16_f32 v180, v180, v181
	v_cvt_pk_bf16_f32 v181, v182, v183
	global_store_dwordx2 v146, v[180:181], s[66:67] offset:1024 sc0 sc1
	v_pk_mul_f32 v[184:185], v[184:185], v[204:205] op_sel_hi:[1,0]
	v_pk_mul_f32 v[186:187], v[186:187], v[204:205] op_sel_hi:[1,0]
	v_pk_mul_f32 v[184:185], v[200:201], v[184:185]
	v_pk_mul_f32 v[186:187], v[202:203], v[186:187]
	v_pk_fma_f32 v[184:185], v[46:47], v[184:185], v[236:237]
	v_pk_fma_f32 v[186:187], v[48:49], v[186:187], v[238:239]
	v_cvt_pk_bf16_f32 v184, v184, v185
	v_cvt_pk_bf16_f32 v185, v186, v187
	global_store_dwordx2 v146, v[184:185], s[66:67] offset:1536 sc0 sc1
	v_add_u32_e32 v146, 0x800, v146
	global_load_dwordx4 v[172:175], v144, s[16:17]
	global_load_dwordx4 v[176:179], v144, s[16:17] offset:1024
	global_load_dwordx4 v[180:183], v144, s[16:17] offset:2048
	global_load_dwordx4 v[184:187], v144, s[16:17] offset:3072
	v_add_u32_e32 v144, 0x1000, v144
	s_waitcnt vmcnt(40)
	v_pk_mul_f32 v[242:243], v[80:81], v[80:81]
	v_pk_mul_f32 v[244:245], v[84:85], v[84:85]
	v_pk_mul_f32 v[246:247], v[82:83], v[82:83]
	v_pk_mul_f32 v[248:249], v[86:87], v[86:87]
	v_add_f32_e32 v204, v245, v244
	v_add_f32_e32 v205, v243, v242
	v_add_f32_e32 v204, v248, v204
	v_add_f32_e32 v205, v246, v205
	v_add_f32_e32 v204, v249, v204
	v_add_f32_e32 v205, v247, v205
	v_pk_mul_f32 v[242:243], v[88:89], v[88:89]
	v_pk_mul_f32 v[244:245], v[92:93], v[92:93]
	v_pk_mul_f32 v[246:247], v[90:91], v[90:91]
	v_pk_mul_f32 v[248:249], v[94:95], v[94:95]
	v_add_f32_e32 v206, v243, v242
	v_add_f32_e32 v207, v245, v244
	v_add_f32_e32 v206, v246, v206
	v_add_f32_e32 v207, v248, v207
	v_add_f32_e32 v206, v247, v206
	v_add_f32_e32 v207, v249, v207
	v_add_f32_e32 v204, v205, v204
	v_add_f32_e32 v204, v204, v206
	v_add_f32_e32 v204, v204, v207
	ds_swizzle_b32 v205, v204 offset:swizzle(SWAP,1)
	s_waitcnt lgkmcnt(0)
	v_add_f32_e32 v204, v204, v205
	ds_swizzle_b32 v205, v204 offset:swizzle(SWAP,2)
	s_waitcnt lgkmcnt(0)
	v_add_f32_e32 v204, v204, v205
	ds_swizzle_b32 v205, v204 offset:swizzle(SWAP,4)
	s_waitcnt lgkmcnt(0)
	v_add_f32_e32 v204, v204, v205
	ds_swizzle_b32 v205, v204 offset:swizzle(SWAP,8)
	s_waitcnt lgkmcnt(0)
	v_add_f32_e32 v204, v204, v205
	ds_swizzle_b32 v205, v204 offset:swizzle(SWAP,16)
	s_waitcnt lgkmcnt(0)
; __device__ __forceinline__ unsigned pk2(float lo, float hi) { const g_f32x2 f = {lo, hi}; return __builtin_bit_cast(unsigned, __builtin_convertvector(f, g_bf16x2)); }
; __device__ __forceinline__ void p_norm(const float* hlat, const float* hctx, const float* g, const float* modl, int sh_off, int sc_off, bf16_t* A, int M,
;                                        const float* part, const float* cgate, float* hcout) {
;     ...
;         float ss = 0.f;
; #pragma unroll
;         for (int i = 0; i < 4; ++i) {
;             if (part != nullptr && row >= NLAT) {
;                 const size_t po = (size_t)(row - NLAT) * 1024 + i * 256 + lane * 4;
;                 const float4 p0 = *(const float4*)(part + po), p1 = *(const float4*)(part + (size_t)4096 * 1024 + po), cg = *(const float4*)(cgate + i * 256 + lane * 4);
;                 v[i].x += cg.x * (p0.x + p1.x); v[i].y += cg.y * (p0.y + p1.y); v[i].z += cg.z * (p0.z + p1.z); v[i].w += cg.w * (p0.w + p1.w);
;                 *(float4*)(hcout + po) = v[i];
;             }
;             ss += v[i].x * v[i].x + v[i].y * v[i].y + v[i].z * v[i].z + v[i].w * v[i].w; }
;         ss = wave_sum(ss);
;         const float rstd = rsqrtf(ss * (1.0f / 1024.0f) + EPS);
;         const float* mr = modl + (size_t)r * 6144;
; #pragma unroll
;         for (int i = 0; i < 4; ++i) {
;             const int k = i * 256 + lane * 4;
;             const float4 gg = *(const float4*)(g + k), scv = *(const float4*)(mr + sc_off + k), shv = *(const float4*)(mr + sh_off + k);
;             const float o0 = v[i].x * rstd * gg.x * (1.0f + scv.x) + shv.x, o1 = v[i].y * rstd * gg.y * (1.0f + scv.y) + shv.y;
;             const float o2 = v[i].z * rstd * gg.z * (1.0f + scv.z) + shv.z, o3 = v[i].w * rstd * gg.w * (1.0f + scv.w) + shv.w;
;             uint2 w; w.x = pk2(o0, o1); w.y = pk2(o2, o3);
;             *(uint2*)(A + (size_t)row * 1024 + k) = w;
;         }
	v_add_f32_e32 v204, v204, v205
	v_mov_b32_e32 v205, v204
	s_nop 1
	v_permlane32_swap_b32_e32 v204, v205
	v_add_f32_e32 v204, v204, v205
	v_mov_b32_e32 v205, 0x358637bd
	v_fmamk_f32 v204, v204, 0x3a800000, v205
	v_rsq_f32_e32 v204, v204
	s_nop 0
	v_pk_mul_f32 v[80:81], v[80:81], v[204:205] op_sel_hi:[1,0]
	v_pk_mul_f32 v[82:83], v[82:83], v[204:205] op_sel_hi:[1,0]
	v_pk_mul_f32 v[80:81], v[188:189], v[80:81]
	v_pk_mul_f32 v[82:83], v[190:191], v[82:83]
	v_pk_fma_f32 v[80:81], v[34:35], v[80:81], v[224:225]
	v_pk_fma_f32 v[82:83], v[36:37], v[82:83], v[226:227]
	v_cvt_pk_bf16_f32 v80, v80, v81
	v_cvt_pk_bf16_f32 v81, v82, v83
	global_store_dwordx2 v146, v[80:81], s[66:67] sc0 sc1
	v_pk_mul_f32 v[84:85], v[84:85], v[204:205] op_sel_hi:[1,0]
	v_pk_mul_f32 v[86:87], v[86:87], v[204:205] op_sel_hi:[1,0]
	v_pk_mul_f32 v[84:85], v[192:193], v[84:85]
	v_pk_mul_f32 v[86:87], v[194:195], v[86:87]
	v_pk_fma_f32 v[84:85], v[38:39], v[84:85], v[228:229]
	v_pk_fma_f32 v[86:87], v[40:41], v[86:87], v[230:231]
	v_cvt_pk_bf16_f32 v84, v84, v85
	v_cvt_pk_bf16_f32 v85, v86, v87
	global_store_dwordx2 v146, v[84:85], s[66:67] offset:512 sc0 sc1
	v_pk_mul_f32 v[88:89], v[88:89], v[204:205] op_sel_hi:[1,0]
	v_pk_mul_f32 v[90:91], v[90:91], v[204:205] op_sel_hi:[1,0]
	v_pk_mul_f32 v[88:89], v[196:197], v[88:89]
	v_pk_mul_f32 v[90:91], v[198:199], v[90:91]
	v_pk_fma_f32 v[88:89], v[42:43], v[88:89], v[232:233]
	v_pk_fma_f32 v[90:91], v[44:45], v[90:91], v[234:235]
	v_cvt_pk_bf16_f32 v88, v88, v89
	v_cvt_pk_bf16_f32 v89, v90, v91
	global_store_dwordx2 v146, v[88:89], s[66:67] offset:1024 sc0 sc1
	v_pk_mul_f32 v[92:93], v[92:93], v[204:205] op_sel_hi:[1,0]
	v_pk_mul_f32 v[94:95], v[94:95], v[204:205] op_sel_hi:[1,0]
	v_pk_mul_f32 v[92:93], v[200:201], v[92:93]
	v_pk_mul_f32 v[94:95], v[202:203], v[94:95]
	v_pk_fma_f32 v[92:93], v[46:47], v[92:93], v[236:237]
	v_pk_fma_f32 v[94:95], v[48:49], v[94:95], v[238:239]
	v_cvt_pk_bf16_f32 v92, v92, v93
	v_cvt_pk_bf16_f32 v93, v94, v95
	global_store_dwordx2 v146, v[92:93], s[66:67] offset:1536 sc0 sc1
	v_add_u32_e32 v146, 0x800, v146
	global_load_dwordx4 v[8:11], v241, s[20:21]
	global_load_dwordx4 v[52:55], v241, s[20:21] offset:1024
	global_load_dwordx4 v[60:63], v241, s[20:21] offset:2048
	global_load_dwordx4 v[64:67], v241, s[20:21] offset:3072
	s_waitcnt vmcnt(40)
	v_pk_mul_f32 v[242:243], v[96:97], v[96:97]
	v_pk_mul_f32 v[244:245], v[100:101], v[100:101]
	v_pk_mul_f32 v[246:247], v[98:99], v[98:99]
	v_pk_mul_f32 v[248:249], v[102:103], v[102:103]
	v_add_f32_e32 v204, v245, v244
	v_add_f32_e32 v205, v243, v242
	v_add_f32_e32 v204, v248, v204
	v_add_f32_e32 v205, v246, v205
	v_add_f32_e32 v204, v249, v204
	v_add_f32_e32 v205, v247, v205
	v_pk_mul_f32 v[242:243], v[104:105], v[104:105]
	v_pk_mul_f32 v[244:245], v[108:109], v[108:109]
	v_pk_mul_f32 v[246:247], v[106:107], v[106:107]
	v_pk_mul_f32 v[248:249], v[110:111], v[110:111]
	v_add_f32_e32 v206, v243, v242
	v_add_f32_e32 v207, v245, v244
	v_add_f32_e32 v206, v246, v206
	v_add_f32_e32 v207, v248, v207
	v_add_f32_e32 v206, v247, v206
	v_add_f32_e32 v207, v249, v207
	v_add_f32_e32 v204, v205, v204
	v_add_f32_e32 v204, v204, v206
	v_add_f32_e32 v204, v204, v207
	ds_swizzle_b32 v205, v204 offset:swizzle(SWAP,1)
	s_waitcnt lgkmcnt(0)
	v_add_f32_e32 v204, v204, v205
	ds_swizzle_b32 v205, v204 offset:swizzle(SWAP,2)
	s_waitcnt lgkmcnt(0)
	v_add_f32_e32 v204, v204, v205
	ds_swizzle_b32 v205, v204 offset:swizzle(SWAP,4)
	s_waitcnt lgkmcnt(0)
	v_add_f32_e32 v204, v204, v205
	ds_swizzle_b32 v205, v204 offset:swizzle(SWAP,8)
	s_waitcnt lgkmcnt(0)
	v_add_f32_e32 v204, v204, v205
	ds_swizzle_b32 v205, v204 offset:swizzle(SWAP,16)
	s_waitcnt lgkmcnt(0)
	v_add_f32_e32 v204, v204, v205
	v_mov_b32_e32 v205, v204
	s_nop 1
	v_permlane32_swap_b32_e32 v204, v205
	v_add_f32_e32 v204, v204, v205
	v_mov_b32_e32 v205, 0x358637bd
	v_fmamk_f32 v204, v204, 0x3a800000, v205
	v_rsq_f32_e32 v204, v204
	s_nop 0
	v_pk_mul_f32 v[96:97], v[96:97], v[204:205] op_sel_hi:[1,0]
	v_pk_mul_f32 v[98:99], v[98:99], v[204:205] op_sel_hi:[1,0]
	v_pk_mul_f32 v[96:97], v[188:189], v[96:97]
	v_pk_mul_f32 v[98:99], v[190:191], v[98:99]
	v_pk_fma_f32 v[96:97], v[34:35], v[96:97], v[224:225]
	v_pk_fma_f32 v[98:99], v[36:37], v[98:99], v[226:227]
	v_cvt_pk_bf16_f32 v96, v96, v97
	v_cvt_pk_bf16_f32 v97, v98, v99
	global_store_dwordx2 v146, v[96:97], s[66:67] sc0 sc1
	v_pk_mul_f32 v[100:101], v[100:101], v[204:205] op_sel_hi:[1,0]
	v_pk_mul_f32 v[102:103], v[102:103], v[204:205] op_sel_hi:[1,0]
	v_pk_mul_f32 v[100:101], v[192:193], v[100:101]
	v_pk_mul_f32 v[102:103], v[194:195], v[102:103]
	v_pk_fma_f32 v[100:101], v[38:39], v[100:101], v[228:229]
	v_pk_fma_f32 v[102:103], v[40:41], v[102:103], v[230:231]
	v_cvt_pk_bf16_f32 v100, v100, v101
	v_cvt_pk_bf16_f32 v101, v102, v103
	global_store_dwordx2 v146, v[100:101], s[66:67] offset:512 sc0 sc1
	v_pk_mul_f32 v[104:105], v[104:105], v[204:205] op_sel_hi:[1,0]
	v_pk_mul_f32 v[106:107], v[106:107], v[204:205] op_sel_hi:[1,0]
	v_pk_mul_f32 v[104:105], v[196:197], v[104:105]
	v_pk_mul_f32 v[106:107], v[198:199], v[106:107]
	v_pk_fma_f32 v[104:105], v[42:43], v[104:105], v[232:233]
	v_pk_fma_f32 v[106:107], v[44:45], v[106:107], v[234:235]
	v_cvt_pk_bf16_f32 v104, v104, v105
	v_cvt_pk_bf16_f32 v105, v106, v107
	global_store_dwordx2 v146, v[104:105], s[66:67] offset:1024 sc0 sc1
	v_pk_mul_f32 v[108:109], v[108:109], v[204:205] op_sel_hi:[1,0]
	v_pk_mul_f32 v[110:111], v[110:111], v[204:205] op_sel_hi:[1,0]
	v_pk_mul_f32 v[108:109], v[200:201], v[108:109]
	v_pk_mul_f32 v[110:111], v[202:203], v[110:111]
	v_pk_fma_f32 v[108:109], v[46:47], v[108:109], v[236:237]
	v_pk_fma_f32 v[110:111], v[48:49], v[110:111], v[238:239]
	v_cvt_pk_bf16_f32 v108, v108, v109
	v_cvt_pk_bf16_f32 v109, v110, v111
	global_store_dwordx2 v146, v[108:109], s[66:67] offset:1536 sc0 sc1
	v_add_u32_e32 v146, 0x800, v146
	global_load_dwordx4 v[80:83], v152, s[70:71]
	global_load_dwordx4 v[84:87], v152, s[70:71] offset:1024
	global_load_dwordx4 v[88:91], v152, s[70:71] offset:2048
	global_load_dwordx4 v[92:95], v152, s[70:71] offset:3072
	global_load_dwordx4 v[96:99], v150, s[70:71]
	global_load_dwordx4 v[100:103], v150, s[70:71] offset:1024
	global_load_dwordx4 v[104:107], v150, s[70:71] offset:2048
	global_load_dwordx4 v[108:111], v150, s[70:71] offset:3072
	s_waitcnt vmcnt(44)
; __device__ __forceinline__ unsigned pk2(float lo, float hi) { const g_f32x2 f = {lo, hi}; return __builtin_bit_cast(unsigned, __builtin_convertvector(f, g_bf16x2)); }
; __device__ __forceinline__ void p_norm(const float* hlat, const float* hctx, const float* g, const float* modl, int sh_off, int sc_off, bf16_t* A, int M,
;                                        const float* part, const float* cgate, float* hcout) {
;     ...
;         float ss = 0.f;
; #pragma unroll
;         for (int i = 0; i < 4; ++i) {
;             if (part != nullptr && row >= NLAT) {
;                 const size_t po = (size_t)(row - NLAT) * 1024 + i * 256 + lane * 4;
;                 const float4 p0 = *(const float4*)(part + po), p1 = *(const float4*)(part + (size_t)4096 * 1024 + po), cg = *(const float4*)(cgate + i * 256 + lane * 4);
;                 v[i].x += cg.x * (p0.x + p1.x); v[i].y += cg.y * (p0.y + p1.y); v[i].z += cg.z * (p0.z + p1.z); v[i].w += cg.w * (p0.w + p1.w);
;                 *(float4*)(hcout + po) = v[i];
;             }
;             ss += v[i].x * v[i].x + v[i].y * v[i].y + v[i].z * v[i].z + v[i].w * v[i].w; }
;         ss = wave_sum(ss);
;         const float rstd = rsqrtf(ss * (1.0f / 1024.0f) + EPS);
;         const float* mr = modl + (size_t)r * 6144;
; #pragma unroll
;         for (int i = 0; i < 4; ++i) {
;             const int k = i * 256 + lane * 4;
;             const float4 gg = *(const float4*)(g + k), scv = *(const float4*)(mr + sc_off + k), shv = *(const float4*)(mr + sh_off + k);
;             const float o0 = v[i].x * rstd * gg.x * (1.0f + scv.x) + shv.x, o1 = v[i].y * rstd * gg.y * (1.0f + scv.y) + shv.y;
;             const float o2 = v[i].z * rstd * gg.z * (1.0f + scv.z) + shv.z, o3 = v[i].w * rstd * gg.w * (1.0f + scv.w) + shv.w;
;             uint2 w; w.x = pk2(o0, o1); w.y = pk2(o2, o3);
;             *(uint2*)(A + (size_t)row * 1024 + k) = w;
;         }
	v_pk_mul_f32 v[242:243], v[112:113], v[112:113]
	v_pk_mul_f32 v[244:245], v[116:117], v[116:117]
	v_pk_mul_f32 v[246:247], v[114:115], v[114:115]
	v_pk_mul_f32 v[248:249], v[118:119], v[118:119]
	v_add_f32_e32 v204, v245, v244
	v_add_f32_e32 v205, v243, v242
	v_add_f32_e32 v204, v248, v204
	v_add_f32_e32 v205, v246, v205
	v_add_f32_e32 v204, v249, v204
	v_add_f32_e32 v205, v247, v205
	v_pk_mul_f32 v[242:243], v[120:121], v[120:121]
	v_pk_mul_f32 v[244:245], v[124:125], v[124:125]
	v_pk_mul_f32 v[246:247], v[122:123], v[122:123]
	v_pk_mul_f32 v[248:249], v[126:127], v[126:127]
	v_add_f32_e32 v206, v243, v242
	v_add_f32_e32 v207, v245, v244
	v_add_f32_e32 v206, v246, v206
	v_add_f32_e32 v207, v248, v207
	v_add_f32_e32 v206, v247, v206
	v_add_f32_e32 v207, v249, v207
	v_add_f32_e32 v204, v205, v204
	v_add_f32_e32 v204, v204, v206
	v_add_f32_e32 v204, v204, v207
	ds_swizzle_b32 v205, v204 offset:swizzle(SWAP,1)
	s_waitcnt lgkmcnt(0)
	v_add_f32_e32 v204, v204, v205
	ds_swizzle_b32 v205, v204 offset:swizzle(SWAP,2)
	s_waitcnt lgkmcnt(0)
	v_add_f32_e32 v204, v204, v205
	ds_swizzle_b32 v205, v204 offset:swizzle(SWAP,4)
	s_waitcnt lgkmcnt(0)
	v_add_f32_e32 v204, v204, v205
	ds_swizzle_b32 v205, v204 offset:swizzle(SWAP,8)
	s_waitcnt lgkmcnt(0)
	v_add_f32_e32 v204, v204, v205
	ds_swizzle_b32 v205, v204 offset:swizzle(SWAP,16)
	s_waitcnt lgkmcnt(0)
	v_add_f32_e32 v204, v204, v205
	v_mov_b32_e32 v205, v204
	s_nop 1
	v_permlane32_swap_b32_e32 v204, v205
	v_add_f32_e32 v204, v204, v205
	v_mov_b32_e32 v205, 0x358637bd
	v_fmamk_f32 v204, v204, 0x3a800000, v205
	v_rsq_f32_e32 v204, v204
	s_nop 0
	v_pk_mul_f32 v[112:113], v[112:113], v[204:205] op_sel_hi:[1,0]
	v_pk_mul_f32 v[114:115], v[114:115], v[204:205] op_sel_hi:[1,0]
	v_pk_mul_f32 v[112:113], v[188:189], v[112:113]
	v_pk_mul_f32 v[114:115], v[190:191], v[114:115]
	v_pk_fma_f32 v[112:113], v[34:35], v[112:113], v[224:225]
	v_pk_fma_f32 v[114:115], v[36:37], v[114:115], v[226:227]
	v_cvt_pk_bf16_f32 v112, v112, v113
	v_cvt_pk_bf16_f32 v113, v114, v115
	global_store_dwordx2 v146, v[112:113], s[66:67] sc0 sc1
	v_pk_mul_f32 v[116:117], v[116:117], v[204:205] op_sel_hi:[1,0]
	v_pk_mul_f32 v[118:119], v[118:119], v[204:205] op_sel_hi:[1,0]
	v_pk_mul_f32 v[116:117], v[192:193], v[116:117]
	v_pk_mul_f32 v[118:119], v[194:195], v[118:119]
	v_pk_fma_f32 v[116:117], v[38:39], v[116:117], v[228:229]
	v_pk_fma_f32 v[118:119], v[40:41], v[118:119], v[230:231]
	v_cvt_pk_bf16_f32 v116, v116, v117
	v_cvt_pk_bf16_f32 v117, v118, v119
	global_store_dwordx2 v146, v[116:117], s[66:67] offset:512 sc0 sc1
	v_pk_mul_f32 v[120:121], v[120:121], v[204:205] op_sel_hi:[1,0]
	v_pk_mul_f32 v[122:123], v[122:123], v[204:205] op_sel_hi:[1,0]
	v_pk_mul_f32 v[120:121], v[196:197], v[120:121]
	v_pk_mul_f32 v[122:123], v[198:199], v[122:123]
	v_pk_fma_f32 v[120:121], v[42:43], v[120:121], v[232:233]
	v_pk_fma_f32 v[122:123], v[44:45], v[122:123], v[234:235]
	v_cvt_pk_bf16_f32 v120, v120, v121
	v_cvt_pk_bf16_f32 v121, v122, v123
	global_store_dwordx2 v146, v[120:121], s[66:67] offset:1024 sc0 sc1
	v_pk_mul_f32 v[124:125], v[124:125], v[204:205] op_sel_hi:[1,0]
	v_pk_mul_f32 v[126:127], v[126:127], v[204:205] op_sel_hi:[1,0]
	v_pk_mul_f32 v[124:125], v[200:201], v[124:125]
	v_pk_mul_f32 v[126:127], v[202:203], v[126:127]
	v_pk_fma_f32 v[124:125], v[46:47], v[124:125], v[236:237]
	v_pk_fma_f32 v[126:127], v[48:49], v[126:127], v[238:239]
	v_cvt_pk_bf16_f32 v124, v124, v125
	v_cvt_pk_bf16_f32 v125, v126, v127
	global_store_dwordx2 v146, v[124:125], s[66:67] offset:1536 sc0 sc1
	v_add_u32_e32 v146, 0x800, v146
	v_add_u32_e32 v207, 0x1000, v152
	global_load_dwordx4 v[112:115], v207, s[70:71]
	global_load_dwordx4 v[116:119], v207, s[70:71] offset:1024
	global_load_dwordx4 v[120:123], v207, s[70:71] offset:2048
	global_load_dwordx4 v[124:127], v207, s[70:71] offset:3072
	s_waitcnt vmcnt(44)
	v_pk_mul_f32 v[242:243], v[128:129], v[128:129]
	v_pk_mul_f32 v[244:245], v[132:133], v[132:133]
	v_pk_mul_f32 v[246:247], v[130:131], v[130:131]
	v_pk_mul_f32 v[248:249], v[134:135], v[134:135]
	v_add_f32_e32 v204, v245, v244
	v_add_f32_e32 v205, v243, v242
	v_add_f32_e32 v204, v248, v204
	v_add_f32_e32 v205, v246, v205
	v_add_f32_e32 v204, v249, v204
	v_add_f32_e32 v205, v247, v205
	v_pk_mul_f32 v[242:243], v[136:137], v[136:137]
	v_pk_mul_f32 v[244:245], v[140:141], v[140:141]
	v_pk_mul_f32 v[246:247], v[138:139], v[138:139]
	v_pk_mul_f32 v[248:249], v[142:143], v[142:143]
	v_add_f32_e32 v206, v243, v242
	v_add_f32_e32 v207, v245, v244
	v_add_f32_e32 v206, v246, v206
	v_add_f32_e32 v207, v248, v207
	v_add_f32_e32 v206, v247, v206
	v_add_f32_e32 v207, v249, v207
	v_add_f32_e32 v204, v205, v204
	v_add_f32_e32 v204, v204, v206
	v_add_f32_e32 v204, v204, v207
	ds_swizzle_b32 v205, v204 offset:swizzle(SWAP,1)
	s_waitcnt lgkmcnt(0)
	v_add_f32_e32 v204, v204, v205
	ds_swizzle_b32 v205, v204 offset:swizzle(SWAP,2)
	s_waitcnt lgkmcnt(0)
	v_add_f32_e32 v204, v204, v205
	ds_swizzle_b32 v205, v204 offset:swizzle(SWAP,4)
	s_waitcnt lgkmcnt(0)
	v_add_f32_e32 v204, v204, v205
	ds_swizzle_b32 v205, v204 offset:swizzle(SWAP,8)
	s_waitcnt lgkmcnt(0)
	v_add_f32_e32 v204, v204, v205
	ds_swizzle_b32 v205, v204 offset:swizzle(SWAP,16)
	s_waitcnt lgkmcnt(0)
; __device__ __forceinline__ unsigned pk2(float lo, float hi) { const g_f32x2 f = {lo, hi}; return __builtin_bit_cast(unsigned, __builtin_convertvector(f, g_bf16x2)); }
; __device__ __forceinline__ void p_norm(const float* hlat, const float* hctx, const float* g, const float* modl, int sh_off, int sc_off, bf16_t* A, int M,
;                                        const float* part, const float* cgate, float* hcout) {
;     ...
;             if (part != nullptr && row >= NLAT) {
;                 const size_t po = (size_t)(row - NLAT) * 1024 + i * 256 + lane * 4;
;                 const float4 p0 = *(const float4*)(part + po), p1 = *(const float4*)(part + (size_t)4096 * 1024 + po), cg = *(const float4*)(cgate + i * 256 + lane * 4);
;                 v[i].x += cg.x * (p0.x + p1.x); v[i].y += cg.y * (p0.y + p1.y); v[i].z += cg.z * (p0.z + p1.z); v[i].w += cg.w * (p0.w + p1.w);
;                 *(float4*)(hcout + po) = v[i];
;             }
;             ss += v[i].x * v[i].x + v[i].y * v[i].y + v[i].z * v[i].z + v[i].w * v[i].w; }
;         ss = wave_sum(ss);
;         const float rstd = rsqrtf(ss * (1.0f / 1024.0f) + EPS);
;         const float* mr = modl + (size_t)r * 6144;
; #pragma unroll
;         for (int i = 0; i < 4; ++i) {
;             const int k = i * 256 + lane * 4;
;             const float4 gg = *(const float4*)(g + k), scv = *(const float4*)(mr + sc_off + k), shv = *(const float4*)(mr + sh_off + k);
;             const float o0 = v[i].x * rstd * gg.x * (1.0f + scv.x) + shv.x, o1 = v[i].y * rstd * gg.y * (1.0f + scv.y) + shv.y;
;             const float o2 = v[i].z * rstd * gg.z * (1.0f + scv.z) + shv.z, o3 = v[i].w * rstd * gg.w * (1.0f + scv.w) + shv.w;
;             uint2 w; w.x = pk2(o0, o1); w.y = pk2(o2, o3);
;             *(uint2*)(A + (size_t)row * 1024 + k) = w;
;         }
	v_add_f32_e32 v204, v204, v205
	v_mov_b32_e32 v205, v204
	s_nop 1
	v_permlane32_swap_b32_e32 v204, v205
	v_add_f32_e32 v204, v204, v205
	v_mov_b32_e32 v205, 0x358637bd
	v_fmamk_f32 v204, v204, 0x3a800000, v205
	v_rsq_f32_e32 v204, v204
	s_nop 0
	v_pk_mul_f32 v[128:129], v[128:129], v[204:205] op_sel_hi:[1,0]
	v_pk_mul_f32 v[130:131], v[130:131], v[204:205] op_sel_hi:[1,0]
	v_pk_mul_f32 v[128:129], v[188:189], v[128:129]
	v_pk_mul_f32 v[130:131], v[190:191], v[130:131]
	v_pk_fma_f32 v[128:129], v[34:35], v[128:129], v[224:225]
	v_pk_fma_f32 v[130:131], v[36:37], v[130:131], v[226:227]
	v_cvt_pk_bf16_f32 v128, v128, v129
	v_cvt_pk_bf16_f32 v129, v130, v131
	global_store_dwordx2 v146, v[128:129], s[66:67] sc0 sc1
	v_pk_mul_f32 v[132:133], v[132:133], v[204:205] op_sel_hi:[1,0]
	v_pk_mul_f32 v[134:135], v[134:135], v[204:205] op_sel_hi:[1,0]
	v_pk_mul_f32 v[132:133], v[192:193], v[132:133]
	v_pk_mul_f32 v[134:135], v[194:195], v[134:135]
	v_pk_fma_f32 v[132:133], v[38:39], v[132:133], v[228:229]
	v_pk_fma_f32 v[134:135], v[40:41], v[134:135], v[230:231]
	v_cvt_pk_bf16_f32 v132, v132, v133
	v_cvt_pk_bf16_f32 v133, v134, v135
	global_store_dwordx2 v146, v[132:133], s[66:67] offset:512 sc0 sc1
	v_pk_mul_f32 v[136:137], v[136:137], v[204:205] op_sel_hi:[1,0]
	v_pk_mul_f32 v[138:139], v[138:139], v[204:205] op_sel_hi:[1,0]
	v_pk_mul_f32 v[136:137], v[196:197], v[136:137]
	v_pk_mul_f32 v[138:139], v[198:199], v[138:139]
	v_pk_fma_f32 v[136:137], v[42:43], v[136:137], v[232:233]
	v_pk_fma_f32 v[138:139], v[44:45], v[138:139], v[234:235]
	v_cvt_pk_bf16_f32 v136, v136, v137
	v_cvt_pk_bf16_f32 v137, v138, v139
	global_store_dwordx2 v146, v[136:137], s[66:67] offset:1024 sc0 sc1
	v_pk_mul_f32 v[140:141], v[140:141], v[204:205] op_sel_hi:[1,0]
	v_pk_mul_f32 v[142:143], v[142:143], v[204:205] op_sel_hi:[1,0]
	v_pk_mul_f32 v[140:141], v[200:201], v[140:141]
	v_pk_mul_f32 v[142:143], v[202:203], v[142:143]
	v_pk_fma_f32 v[140:141], v[46:47], v[140:141], v[236:237]
	v_pk_fma_f32 v[142:143], v[48:49], v[142:143], v[238:239]
	v_cvt_pk_bf16_f32 v140, v140, v141
	v_cvt_pk_bf16_f32 v141, v142, v143
	global_store_dwordx2 v146, v[140:141], s[66:67] offset:1536 sc0 sc1
	v_add_u32_e32 v146, 0x800, v146
	v_add_u32_e32 v151, 0x60000, v241
	global_load_dwordx4 v[34:37], v151, s[98:99]
	global_load_dwordx4 v[38:41], v151, s[98:99] offset:1024
	global_load_dwordx4 v[42:45], v151, s[98:99] offset:2048
	global_load_dwordx4 v[46:49], v151, s[98:99] offset:3072
	global_load_dwordx4 v[224:227], v151, s[50:51]
	global_load_dwordx4 v[228:231], v151, s[50:51] offset:1024
	global_load_dwordx4 v[232:235], v151, s[50:51] offset:2048
	global_load_dwordx4 v[236:239], v151, s[50:51] offset:3072
	v_add_u32_e32 v207, 0x1000, v150
	global_load_dwordx4 v[128:131], v207, s[70:71]
	global_load_dwordx4 v[132:135], v207, s[70:71] offset:1024
	global_load_dwordx4 v[136:139], v207, s[70:71] offset:2048
	global_load_dwordx4 v[140:143], v207, s[70:71] offset:3072
	s_waitcnt vmcnt(24)
	v_pk_add_f32 v[80:81], v[80:81], v[96:97]
	v_pk_add_f32 v[82:83], v[82:83], v[98:99]
	v_pk_fma_f32 v[156:157], v[80:81], v[8:9], v[156:157]
	v_pk_fma_f32 v[158:159], v[82:83], v[10:11], v[158:159]
	global_store_dwordx4 v152, v[156:159], s[64:65]
	v_pk_add_f32 v[84:85], v[84:85], v[100:101]
	v_pk_add_f32 v[86:87], v[86:87], v[102:103]
	v_pk_fma_f32 v[160:161], v[84:85], v[52:53], v[160:161]
	v_pk_fma_f32 v[162:163], v[86:87], v[54:55], v[162:163]
	global_store_dwordx4 v152, v[160:163], s[64:65] offset:1024
	v_pk_add_f32 v[88:89], v[88:89], v[104:105]
	v_pk_add_f32 v[90:91], v[90:91], v[106:107]
	v_pk_fma_f32 v[164:165], v[88:89], v[60:61], v[164:165]
	v_pk_fma_f32 v[166:167], v[90:91], v[62:63], v[166:167]
	global_store_dwordx4 v152, v[164:167], s[64:65] offset:2048
	v_pk_add_f32 v[92:93], v[92:93], v[108:109]
	v_pk_add_f32 v[94:95], v[94:95], v[110:111]
	v_pk_fma_f32 v[168:169], v[92:93], v[64:65], v[168:169]
	v_pk_fma_f32 v[170:171], v[94:95], v[66:67], v[170:171]
	global_store_dwordx4 v152, v[168:171], s[64:65] offset:3072
	v_add_u32_e32 v152, 0x1000, v152
	v_pk_mul_f32 v[242:243], v[156:157], v[156:157]
	v_pk_mul_f32 v[244:245], v[160:161], v[160:161]
	v_pk_mul_f32 v[246:247], v[158:159], v[158:159]
	v_pk_mul_f32 v[248:249], v[162:163], v[162:163]
	v_add_f32_e32 v204, v245, v244
	v_add_f32_e32 v205, v243, v242
	v_add_f32_e32 v204, v248, v204
	v_add_f32_e32 v205, v246, v205
	v_add_f32_e32 v204, v249, v204
	v_add_f32_e32 v205, v247, v205
	v_pk_mul_f32 v[242:243], v[164:165], v[164:165]
	v_pk_mul_f32 v[244:245], v[168:169], v[168:169]
	v_pk_mul_f32 v[246:247], v[166:167], v[166:167]
	v_pk_mul_f32 v[248:249], v[170:171], v[170:171]
	v_add_f32_e32 v206, v243, v242
	v_add_f32_e32 v207, v245, v244
	v_add_f32_e32 v206, v246, v206
	v_add_f32_e32 v207, v248, v207
	v_add_f32_e32 v206, v247, v206
	v_add_f32_e32 v207, v249, v207
	v_add_f32_e32 v204, v205, v204
	v_add_f32_e32 v204, v204, v206
	v_add_f32_e32 v204, v204, v207
	ds_swizzle_b32 v205, v204 offset:swizzle(SWAP,1)
	s_waitcnt lgkmcnt(0)
	v_add_f32_e32 v204, v204, v205
	ds_swizzle_b32 v205, v204 offset:swizzle(SWAP,2)
	s_waitcnt lgkmcnt(0)
	v_add_f32_e32 v204, v204, v205
	ds_swizzle_b32 v205, v204 offset:swizzle(SWAP,4)
	s_waitcnt lgkmcnt(0)
	v_add_f32_e32 v204, v204, v205
	ds_swizzle_b32 v205, v204 offset:swizzle(SWAP,8)
	s_waitcnt lgkmcnt(0)
	v_add_f32_e32 v204, v204, v205
	ds_swizzle_b32 v205, v204 offset:swizzle(SWAP,16)
	s_waitcnt lgkmcnt(0)
	v_add_f32_e32 v204, v204, v205
	v_mov_b32_e32 v205, v204
	s_nop 1
	v_permlane32_swap_b32_e32 v204, v205
	v_add_f32_e32 v204, v204, v205
	v_mov_b32_e32 v205, 0x358637bd
	v_fmamk_f32 v204, v204, 0x3a800000, v205
	v_rsq_f32_e32 v204, v204
	s_nop 0
	s_waitcnt vmcnt(8)
; __device__ __forceinline__ unsigned pk2(float lo, float hi) { const g_f32x2 f = {lo, hi}; return __builtin_bit_cast(unsigned, __builtin_convertvector(f, g_bf16x2)); }
; __device__ __forceinline__ void p_norm(const float* hlat, const float* hctx, const float* g, const float* modl, int sh_off, int sc_off, bf16_t* A, int M,
;                                        const float* part, const float* cgate, float* hcout) {
;     ...
;             if (part != nullptr && row >= NLAT) {
;                 const size_t po = (size_t)(row - NLAT) * 1024 + i * 256 + lane * 4;
;                 const float4 p0 = *(const float4*)(part + po), p1 = *(const float4*)(part + (size_t)4096 * 1024 + po), cg = *(const float4*)(cgate + i * 256 + lane * 4);
;                 v[i].x += cg.x * (p0.x + p1.x); v[i].y += cg.y * (p0.y + p1.y); v[i].z += cg.z * (p0.z + p1.z); v[i].w += cg.w * (p0.w + p1.w);
;                 *(float4*)(hcout + po) = v[i];
;             }
;             ss += v[i].x * v[i].x + v[i].y * v[i].y + v[i].z * v[i].z + v[i].w * v[i].w; }
;         ss = wave_sum(ss);
;         const float rstd = rsqrtf(ss * (1.0f / 1024.0f) + EPS);
;         const float* mr = modl + (size_t)r * 6144;
; #pragma unroll
;         for (int i = 0; i < 4; ++i) {
;             const int k = i * 256 + lane * 4;
;             const float4 gg = *(const float4*)(g + k), scv = *(const float4*)(mr + sc_off + k), shv = *(const float4*)(mr + sh_off + k);
;             const float o0 = v[i].x * rstd * gg.x * (1.0f + scv.x) + shv.x, o1 = v[i].y * rstd * gg.y * (1.0f + scv.y) + shv.y;
;             const float o2 = v[i].z * rstd * gg.z * (1.0f + scv.z) + shv.z, o3 = v[i].w * rstd * gg.w * (1.0f + scv.w) + shv.w;
;             uint2 w; w.x = pk2(o0, o1); w.y = pk2(o2, o3);
;             *(uint2*)(A + (size_t)row * 1024 + k) = w;
;         }
	v_pk_add_f32 v[34:35], v[34:35], 1.0 op_sel_hi:[1,0]
	v_pk_add_f32 v[36:37], v[36:37], 1.0 op_sel_hi:[1,0]
	v_pk_add_f32 v[38:39], v[38:39], 1.0 op_sel_hi:[1,0]
	v_pk_add_f32 v[40:41], v[40:41], 1.0 op_sel_hi:[1,0]
	v_pk_add_f32 v[42:43], v[42:43], 1.0 op_sel_hi:[1,0]
	v_pk_add_f32 v[44:45], v[44:45], 1.0 op_sel_hi:[1,0]
	v_pk_add_f32 v[46:47], v[46:47], 1.0 op_sel_hi:[1,0]
	v_pk_add_f32 v[48:49], v[48:49], 1.0 op_sel_hi:[1,0]
	v_lshlrev_b32_e32 v146, 12, v50
	v_lshl_add_u32 v146, v240, 3, v146
	v_add_u32_e32 v146, 0x4000000, v146
	v_pk_mul_f32 v[156:157], v[156:157], v[204:205] op_sel_hi:[1,0]
	v_pk_mul_f32 v[158:159], v[158:159], v[204:205] op_sel_hi:[1,0]
	v_pk_mul_f32 v[156:157], v[188:189], v[156:157]
	v_pk_mul_f32 v[158:159], v[190:191], v[158:159]
	v_pk_fma_f32 v[156:157], v[34:35], v[156:157], v[224:225]
	v_pk_fma_f32 v[158:159], v[36:37], v[158:159], v[226:227]
	v_cvt_pk_bf16_f32 v156, v156, v157
	v_cvt_pk_bf16_f32 v157, v158, v159
	global_store_dwordx2 v146, v[156:157], s[66:67] sc0 sc1
	v_pk_mul_f32 v[160:161], v[160:161], v[204:205] op_sel_hi:[1,0]
	v_pk_mul_f32 v[162:163], v[162:163], v[204:205] op_sel_hi:[1,0]
	v_pk_mul_f32 v[160:161], v[192:193], v[160:161]
	v_pk_mul_f32 v[162:163], v[194:195], v[162:163]
	v_pk_fma_f32 v[160:161], v[38:39], v[160:161], v[228:229]
	v_pk_fma_f32 v[162:163], v[40:41], v[162:163], v[230:231]
	v_cvt_pk_bf16_f32 v160, v160, v161
	v_cvt_pk_bf16_f32 v161, v162, v163
	global_store_dwordx2 v146, v[160:161], s[66:67] offset:512 sc0 sc1
	v_pk_mul_f32 v[164:165], v[164:165], v[204:205] op_sel_hi:[1,0]
	v_pk_mul_f32 v[166:167], v[166:167], v[204:205] op_sel_hi:[1,0]
	v_pk_mul_f32 v[164:165], v[196:197], v[164:165]
	v_pk_mul_f32 v[166:167], v[198:199], v[166:167]
	v_pk_fma_f32 v[164:165], v[42:43], v[164:165], v[232:233]
	v_pk_fma_f32 v[166:167], v[44:45], v[166:167], v[234:235]
	v_cvt_pk_bf16_f32 v164, v164, v165
	v_cvt_pk_bf16_f32 v165, v166, v167
	global_store_dwordx2 v146, v[164:165], s[66:67] offset:1024 sc0 sc1
	v_pk_mul_f32 v[168:169], v[168:169], v[204:205] op_sel_hi:[1,0]
	v_pk_mul_f32 v[170:171], v[170:171], v[204:205] op_sel_hi:[1,0]
	v_pk_mul_f32 v[168:169], v[200:201], v[168:169]
	v_pk_mul_f32 v[170:171], v[202:203], v[170:171]
	v_pk_fma_f32 v[168:169], v[46:47], v[168:169], v[236:237]
	v_pk_fma_f32 v[170:171], v[48:49], v[170:171], v[238:239]
	v_cvt_pk_bf16_f32 v168, v168, v169
	v_cvt_pk_bf16_f32 v169, v170, v171
	global_store_dwordx2 v146, v[168:169], s[66:67] offset:1536 sc0 sc1
	v_add_u32_e32 v146, 0x800, v146
	s_waitcnt vmcnt(8)
	v_pk_add_f32 v[112:113], v[112:113], v[128:129]
	v_pk_add_f32 v[114:115], v[114:115], v[130:131]
	v_pk_fma_f32 v[172:173], v[112:113], v[8:9], v[172:173]
	v_pk_fma_f32 v[174:175], v[114:115], v[10:11], v[174:175]
	global_store_dwordx4 v152, v[172:175], s[64:65]
	v_pk_add_f32 v[116:117], v[116:117], v[132:133]
	v_pk_add_f32 v[118:119], v[118:119], v[134:135]
	v_pk_fma_f32 v[176:177], v[116:117], v[52:53], v[176:177]
	v_pk_fma_f32 v[178:179], v[118:119], v[54:55], v[178:179]
	global_store_dwordx4 v152, v[176:179], s[64:65] offset:1024
	v_pk_add_f32 v[120:121], v[120:121], v[136:137]
	v_pk_add_f32 v[122:123], v[122:123], v[138:139]
	v_pk_fma_f32 v[180:181], v[120:121], v[60:61], v[180:181]
	v_pk_fma_f32 v[182:183], v[122:123], v[62:63], v[182:183]
	global_store_dwordx4 v152, v[180:183], s[64:65] offset:2048
	v_pk_add_f32 v[124:125], v[124:125], v[140:141]
	v_pk_add_f32 v[126:127], v[126:127], v[142:143]
	v_pk_fma_f32 v[184:185], v[124:125], v[64:65], v[184:185]
	v_pk_fma_f32 v[186:187], v[126:127], v[66:67], v[186:187]
	global_store_dwordx4 v152, v[184:187], s[64:65] offset:3072
	v_add_u32_e32 v152, 0x1000, v152
	v_pk_mul_f32 v[242:243], v[172:173], v[172:173]
	v_pk_mul_f32 v[244:245], v[176:177], v[176:177]
	v_pk_mul_f32 v[246:247], v[174:175], v[174:175]
	v_pk_mul_f32 v[248:249], v[178:179], v[178:179]
	v_add_f32_e32 v204, v245, v244
	v_add_f32_e32 v205, v243, v242
	v_add_f32_e32 v204, v248, v204
	v_add_f32_e32 v205, v246, v205
	v_add_f32_e32 v204, v249, v204
	v_add_f32_e32 v205, v247, v205
	v_pk_mul_f32 v[242:243], v[180:181], v[180:181]
	v_pk_mul_f32 v[244:245], v[184:185], v[184:185]
	v_pk_mul_f32 v[246:247], v[182:183], v[182:183]
	v_pk_mul_f32 v[248:249], v[186:187], v[186:187]
	v_add_f32_e32 v206, v243, v242
	v_add_f32_e32 v207, v245, v244
	v_add_f32_e32 v206, v246, v206
	v_add_f32_e32 v207, v248, v207
	v_add_f32_e32 v206, v247, v206
	v_add_f32_e32 v207, v249, v207
	v_add_f32_e32 v204, v205, v204
	v_add_f32_e32 v204, v204, v206
	v_add_f32_e32 v204, v204, v207
	ds_swizzle_b32 v205, v204 offset:swizzle(SWAP,1)
	s_waitcnt lgkmcnt(0)
	v_add_f32_e32 v204, v204, v205
	ds_swizzle_b32 v205, v204 offset:swizzle(SWAP,2)
	s_waitcnt lgkmcnt(0)
	v_add_f32_e32 v204, v204, v205
	ds_swizzle_b32 v205, v204 offset:swizzle(SWAP,4)
	s_waitcnt lgkmcnt(0)
	v_add_f32_e32 v204, v204, v205
	ds_swizzle_b32 v205, v204 offset:swizzle(SWAP,8)
	s_waitcnt lgkmcnt(0)
	v_add_f32_e32 v204, v204, v205
	ds_swizzle_b32 v205, v204 offset:swizzle(SWAP,16)
	s_waitcnt lgkmcnt(0)
; __device__ __forceinline__ unsigned pk2(float lo, float hi) { const g_f32x2 f = {lo, hi}; return __builtin_bit_cast(unsigned, __builtin_convertvector(f, g_bf16x2)); }
; #define PN_LOAD(dst, rw) do { const float* s_ = (rw) < NLAT ? hlat + (size_t)(rw) * 1024 : hctx + (size_t)((rw) - NLAT) * 1024; \
;         _Pragma("unroll") for (int i = 0; i < 4; ++i) dst[i] = *(const float4*)(s_ + i * 256 + lane * 4); } while (0)
; __device__ __forceinline__ void p_norm(const float* hlat, const float* hctx, const float* g, const float* modl, int sh_off, int sc_off, bf16_t* A, int M,
;                                        const float* part, const float* cgate, float* hcout) {
;     ...
;     if (row < M) PN_LOAD(v, row);
;     while (row < M) {
;         const int nrow = row + stride;
;         if (nrow < M) PN_LOAD(nv, nrow);
;     ...
;         float ss = 0.f;
; #pragma unroll
;         for (int i = 0; i < 4; ++i) {
;             if (part != nullptr && row >= NLAT) {
;                 const size_t po = (size_t)(row - NLAT) * 1024 + i * 256 + lane * 4;
;                 const float4 p0 = *(const float4*)(part + po), p1 = *(const float4*)(part + (size_t)4096 * 1024 + po), cg = *(const float4*)(cgate + i * 256 + lane * 4);
;                 v[i].x += cg.x * (p0.x + p1.x); v[i].y += cg.y * (p0.y + p1.y); v[i].z += cg.z * (p0.z + p1.z); v[i].w += cg.w * (p0.w + p1.w);
;                 *(float4*)(hcout + po) = v[i];
;             }
;             ss += v[i].x * v[i].x + v[i].y * v[i].y + v[i].z * v[i].z + v[i].w * v[i].w; }
;         ss = wave_sum(ss);
;         const float rstd = rsqrtf(ss * (1.0f / 1024.0f) + EPS);
;         const float* mr = modl + (size_t)r * 6144;
; #pragma unroll
;         for (int i = 0; i < 4; ++i) {
;             const int k = i * 256 + lane * 4;
;             const float4 gg = *(const float4*)(g + k), scv = *(const float4*)(mr + sc_off + k), shv = *(const float4*)(mr + sh_off + k);
;             const float o0 = v[i].x * rstd * gg.x * (1.0f + scv.x) + shv.x, o1 = v[i].y * rstd * gg.y * (1.0f + scv.y) + shv.y;
;             const float o2 = v[i].z * rstd * gg.z * (1.0f + scv.z) + shv.z, o3 = v[i].w * rstd * gg.w * (1.0f + scv.w) + shv.w;
;             uint2 w; w.x = pk2(o0, o1); w.y = pk2(o2, o3);
;             *(uint2*)(A + (size_t)row * 1024 + k) = w;
;         }
	v_add_f32_e32 v204, v204, v205
	v_mov_b32_e32 v205, v204
	s_nop 1
	v_permlane32_swap_b32_e32 v204, v205
	v_add_f32_e32 v204, v204, v205
	v_mov_b32_e32 v205, 0x358637bd
	v_fmamk_f32 v204, v204, 0x3a800000, v205
	v_rsq_f32_e32 v204, v204
	s_nop 0
	v_pk_mul_f32 v[172:173], v[172:173], v[204:205] op_sel_hi:[1,0]
	v_pk_mul_f32 v[174:175], v[174:175], v[204:205] op_sel_hi:[1,0]
	v_pk_mul_f32 v[172:173], v[188:189], v[172:173]
	v_pk_mul_f32 v[174:175], v[190:191], v[174:175]
	v_pk_fma_f32 v[172:173], v[34:35], v[172:173], v[224:225]
	v_pk_fma_f32 v[174:175], v[36:37], v[174:175], v[226:227]
	v_cvt_pk_bf16_f32 v172, v172, v173
	v_cvt_pk_bf16_f32 v173, v174, v175
	global_store_dwordx2 v146, v[172:173], s[66:67] sc0 sc1
	v_pk_mul_f32 v[176:177], v[176:177], v[204:205] op_sel_hi:[1,0]
	v_pk_mul_f32 v[178:179], v[178:179], v[204:205] op_sel_hi:[1,0]
	v_pk_mul_f32 v[176:177], v[192:193], v[176:177]
	v_pk_mul_f32 v[178:179], v[194:195], v[178:179]
	v_pk_fma_f32 v[176:177], v[38:39], v[176:177], v[228:229]
	v_pk_fma_f32 v[178:179], v[40:41], v[178:179], v[230:231]
	v_cvt_pk_bf16_f32 v176, v176, v177
	v_cvt_pk_bf16_f32 v177, v178, v179
	global_store_dwordx2 v146, v[176:177], s[66:67] offset:512 sc0 sc1
	v_pk_mul_f32 v[180:181], v[180:181], v[204:205] op_sel_hi:[1,0]
	v_pk_mul_f32 v[182:183], v[182:183], v[204:205] op_sel_hi:[1,0]
	v_pk_mul_f32 v[180:181], v[196:197], v[180:181]
	v_pk_mul_f32 v[182:183], v[198:199], v[182:183]
	v_pk_fma_f32 v[180:181], v[42:43], v[180:181], v[232:233]
	v_pk_fma_f32 v[182:183], v[44:45], v[182:183], v[234:235]
	v_cvt_pk_bf16_f32 v180, v180, v181
	v_cvt_pk_bf16_f32 v181, v182, v183
	global_store_dwordx2 v146, v[180:181], s[66:67] offset:1024 sc0 sc1
	v_pk_mul_f32 v[184:185], v[184:185], v[204:205] op_sel_hi:[1,0]
	v_pk_mul_f32 v[186:187], v[186:187], v[204:205] op_sel_hi:[1,0]
	v_pk_mul_f32 v[184:185], v[200:201], v[184:185]
	v_pk_mul_f32 v[186:187], v[202:203], v[186:187]
	v_pk_fma_f32 v[184:185], v[46:47], v[184:185], v[236:237]
	v_pk_fma_f32 v[186:187], v[48:49], v[186:187], v[238:239]
	v_cvt_pk_bf16_f32 v184, v184, v185
	v_cvt_pk_bf16_f32 v185, v186, v187
	global_store_dwordx2 v146, v[184:185], s[66:67] offset:1536 sc0 sc1
	v_add_u32_e32 v146, 0x800, v146
	s_branch .Lnorm_P1_end
.Lnorm_P1_alt:
	global_load_dwordx4 v[80:83], v144, s[46:47] nt
	global_load_dwordx4 v[84:87], v144, s[46:47] offset:1024 nt
	global_load_dwordx4 v[88:91], v144, s[46:47] offset:2048 nt
	global_load_dwordx4 v[92:95], v144, s[46:47] offset:3072 nt
	v_add_u32_e32 v144, 0x1000, v144
	global_load_dwordx4 v[34:37], v148, s[98:99]
	global_load_dwordx4 v[38:41], v148, s[98:99] offset:1024
	global_load_dwordx4 v[42:45], v148, s[98:99] offset:2048
	global_load_dwordx4 v[46:49], v148, s[98:99] offset:3072
	global_load_dwordx4 v[224:227], v148, s[50:51]
	global_load_dwordx4 v[228:231], v148, s[50:51] offset:1024
	global_load_dwordx4 v[232:235], v148, s[50:51] offset:2048
	global_load_dwordx4 v[236:239], v148, s[50:51] offset:3072
	global_load_dwordx4 v[188:191], v241, s[48:49]
	global_load_dwordx4 v[192:195], v241, s[48:49] offset:1024
	global_load_dwordx4 v[196:199], v241, s[48:49] offset:2048
	global_load_dwordx4 v[200:203], v241, s[48:49] offset:3072
	global_load_dwordx4 v[96:99], v144, s[46:47] nt
	global_load_dwordx4 v[100:103], v144, s[46:47] offset:1024 nt
	global_load_dwordx4 v[104:107], v144, s[46:47] offset:2048 nt
	global_load_dwordx4 v[108:111], v144, s[46:47] offset:3072 nt
	v_add_u32_e32 v144, 0x1000, v144
	global_load_dwordx4 v[112:115], v144, s[46:47] nt
	global_load_dwordx4 v[116:119], v144, s[46:47] offset:1024 nt
	global_load_dwordx4 v[120:123], v144, s[46:47] offset:2048 nt
	global_load_dwordx4 v[124:127], v144, s[46:47] offset:3072 nt
	v_add_u32_e32 v144, 0x1000, v144
	global_load_dwordx4 v[128:131], v144, s[46:47] nt
	global_load_dwordx4 v[132:135], v144, s[46:47] offset:1024 nt
	global_load_dwordx4 v[136:139], v144, s[46:47] offset:2048 nt
	global_load_dwordx4 v[140:143], v144, s[46:47] offset:3072 nt
	v_add_u32_e32 v144, 0x1000, v144
	global_load_dwordx4 v[156:159], v144, s[46:47] nt
	global_load_dwordx4 v[160:163], v144, s[46:47] offset:1024 nt
	global_load_dwordx4 v[164:167], v144, s[46:47] offset:2048 nt
	global_load_dwordx4 v[168:171], v144, s[46:47] offset:3072 nt
	v_add_u32_e32 v144, 0x1000, v144
	global_load_dwordx4 v[172:175], v144, s[46:47] nt
	global_load_dwordx4 v[176:179], v144, s[46:47] offset:1024 nt
	global_load_dwordx4 v[180:183], v144, s[46:47] offset:2048 nt
	global_load_dwordx4 v[184:187], v144, s[46:47] offset:3072 nt
	v_add_u32_e32 v144, 0x1000, v144
	s_waitcnt vmcnt(32)
	v_pk_mul_f32 v[242:243], v[80:81], v[80:81]
	v_pk_mul_f32 v[244:245], v[84:85], v[84:85]
	v_pk_mul_f32 v[246:247], v[82:83], v[82:83]
	v_pk_mul_f32 v[248:249], v[86:87], v[86:87]
	v_add_f32_e32 v204, v245, v244
	v_add_f32_e32 v205, v243, v242
	v_add_f32_e32 v204, v248, v204
	v_add_f32_e32 v205, v246, v205
	v_add_f32_e32 v204, v249, v204
	v_add_f32_e32 v205, v247, v205
	v_pk_mul_f32 v[242:243], v[88:89], v[88:89]
	v_pk_mul_f32 v[244:245], v[92:93], v[92:93]
	v_pk_mul_f32 v[246:247], v[90:91], v[90:91]
	v_pk_mul_f32 v[248:249], v[94:95], v[94:95]
	v_add_f32_e32 v206, v243, v242
	v_add_f32_e32 v207, v245, v244
	v_add_f32_e32 v206, v246, v206
	v_add_f32_e32 v207, v248, v207
	v_add_f32_e32 v206, v247, v206
	v_add_f32_e32 v207, v249, v207
	v_add_f32_e32 v204, v205, v204
	v_add_f32_e32 v204, v204, v206
	v_add_f32_e32 v204, v204, v207
	ds_swizzle_b32 v205, v204 offset:swizzle(SWAP,1)
	s_waitcnt lgkmcnt(0)
	v_add_f32_e32 v204, v204, v205
	ds_swizzle_b32 v205, v204 offset:swizzle(SWAP,2)
	s_waitcnt lgkmcnt(0)
; __device__ __forceinline__ unsigned pk2(float lo, float hi) { const g_f32x2 f = {lo, hi}; return __builtin_bit_cast(unsigned, __builtin_convertvector(f, g_bf16x2)); }
; __device__ __forceinline__ void p_norm(const float* hlat, const float* hctx, const float* g, const float* modl, int sh_off, int sc_off, bf16_t* A, int M,
;                                        const float* part, const float* cgate, float* hcout) {
;     ...
;         float ss = 0.f;
; #pragma unroll
;         for (int i = 0; i < 4; ++i) {
;             if (part != nullptr && row >= NLAT) {
;                 const size_t po = (size_t)(row - NLAT) * 1024 + i * 256 + lane * 4;
;                 const float4 p0 = *(const float4*)(part + po), p1 = *(const float4*)(part + (size_t)4096 * 1024 + po), cg = *(const float4*)(cgate + i * 256 + lane * 4);
;                 v[i].x += cg.x * (p0.x + p1.x); v[i].y += cg.y * (p0.y + p1.y); v[i].z += cg.z * (p0.z + p1.z); v[i].w += cg.w * (p0.w + p1.w);
;                 *(float4*)(hcout + po) = v[i];
;             }
;             ss += v[i].x * v[i].x + v[i].y * v[i].y + v[i].z * v[i].z + v[i].w * v[i].w; }
;         ss = wave_sum(ss);
;         const float rstd = rsqrtf(ss * (1.0f / 1024.0f) + EPS);
;         const float* mr = modl + (size_t)r * 6144;
; #pragma unroll
;         for (int i = 0; i < 4; ++i) {
;             const int k = i * 256 + lane * 4;
;             const float4 gg = *(const float4*)(g + k), scv = *(const float4*)(mr + sc_off + k), shv = *(const float4*)(mr + sh_off + k);
;             const float o0 = v[i].x * rstd * gg.x * (1.0f + scv.x) + shv.x, o1 = v[i].y * rstd * gg.y * (1.0f + scv.y) + shv.y;
;             const float o2 = v[i].z * rstd * gg.z * (1.0f + scv.z) + shv.z, o3 = v[i].w * rstd * gg.w * (1.0f + scv.w) + shv.w;
;             uint2 w; w.x = pk2(o0, o1); w.y = pk2(o2, o3);
;             *(uint2*)(A + (size_t)row * 1024 + k) = w;
;         }
	v_add_f32_e32 v204, v204, v205
	ds_swizzle_b32 v205, v204 offset:swizzle(SWAP,4)
	s_waitcnt lgkmcnt(0)
	v_add_f32_e32 v204, v204, v205
	ds_swizzle_b32 v205, v204 offset:swizzle(SWAP,8)
	s_waitcnt lgkmcnt(0)
	v_add_f32_e32 v204, v204, v205
	ds_swizzle_b32 v205, v204 offset:swizzle(SWAP,16)
	s_waitcnt lgkmcnt(0)
	v_add_f32_e32 v204, v204, v205
	v_mov_b32_e32 v205, v204
	s_nop 1
	v_permlane32_swap_b32_e32 v204, v205
	v_add_f32_e32 v204, v204, v205
	v_mov_b32_e32 v205, 0x358637bd
	v_fmamk_f32 v204, v204, 0x3a800000, v205
	v_rsq_f32_e32 v204, v204
	s_nop 0
	s_waitcnt vmcnt(20)
	v_pk_add_f32 v[34:35], v[34:35], 1.0 op_sel_hi:[1,0]
	v_pk_add_f32 v[36:37], v[36:37], 1.0 op_sel_hi:[1,0]
	v_pk_add_f32 v[38:39], v[38:39], 1.0 op_sel_hi:[1,0]
	v_pk_add_f32 v[40:41], v[40:41], 1.0 op_sel_hi:[1,0]
	v_pk_add_f32 v[42:43], v[42:43], 1.0 op_sel_hi:[1,0]
	v_pk_add_f32 v[44:45], v[44:45], 1.0 op_sel_hi:[1,0]
	v_pk_add_f32 v[46:47], v[46:47], 1.0 op_sel_hi:[1,0]
	v_pk_add_f32 v[48:49], v[48:49], 1.0 op_sel_hi:[1,0]
	v_pk_mul_f32 v[80:81], v[80:81], v[204:205] op_sel_hi:[1,0]
	v_pk_mul_f32 v[82:83], v[82:83], v[204:205] op_sel_hi:[1,0]
	v_pk_mul_f32 v[80:81], v[188:189], v[80:81]
	v_pk_mul_f32 v[82:83], v[190:191], v[82:83]
	v_pk_fma_f32 v[80:81], v[34:35], v[80:81], v[224:225]
	v_pk_fma_f32 v[82:83], v[36:37], v[82:83], v[226:227]
	v_cvt_pk_bf16_f32 v80, v80, v81
	v_cvt_pk_bf16_f32 v81, v82, v83
	global_store_dwordx2 v146, v[80:81], s[66:67] sc0 sc1
	v_pk_mul_f32 v[84:85], v[84:85], v[204:205] op_sel_hi:[1,0]
	v_pk_mul_f32 v[86:87], v[86:87], v[204:205] op_sel_hi:[1,0]
	v_pk_mul_f32 v[84:85], v[192:193], v[84:85]
	v_pk_mul_f32 v[86:87], v[194:195], v[86:87]
	v_pk_fma_f32 v[84:85], v[38:39], v[84:85], v[228:229]
	v_pk_fma_f32 v[86:87], v[40:41], v[86:87], v[230:231]
	v_cvt_pk_bf16_f32 v84, v84, v85
	v_cvt_pk_bf16_f32 v85, v86, v87
	global_store_dwordx2 v146, v[84:85], s[66:67] offset:512 sc0 sc1
	v_pk_mul_f32 v[88:89], v[88:89], v[204:205] op_sel_hi:[1,0]
	v_pk_mul_f32 v[90:91], v[90:91], v[204:205] op_sel_hi:[1,0]
	v_pk_mul_f32 v[88:89], v[196:197], v[88:89]
	v_pk_mul_f32 v[90:91], v[198:199], v[90:91]
	v_pk_fma_f32 v[88:89], v[42:43], v[88:89], v[232:233]
	v_pk_fma_f32 v[90:91], v[44:45], v[90:91], v[234:235]
	v_cvt_pk_bf16_f32 v88, v88, v89
	v_cvt_pk_bf16_f32 v89, v90, v91
	global_store_dwordx2 v146, v[88:89], s[66:67] offset:1024 sc0 sc1
	v_pk_mul_f32 v[92:93], v[92:93], v[204:205] op_sel_hi:[1,0]
	v_pk_mul_f32 v[94:95], v[94:95], v[204:205] op_sel_hi:[1,0]
	v_pk_mul_f32 v[92:93], v[200:201], v[92:93]
	v_pk_mul_f32 v[94:95], v[202:203], v[94:95]
	v_pk_fma_f32 v[92:93], v[46:47], v[92:93], v[236:237]
	v_pk_fma_f32 v[94:95], v[48:49], v[94:95], v[238:239]
	v_cvt_pk_bf16_f32 v92, v92, v93
	v_cvt_pk_bf16_f32 v93, v94, v95
	global_store_dwordx2 v146, v[92:93], s[66:67] offset:1536 sc0 sc1
	v_add_u32_e32 v146, 0x800, v146
	global_load_dwordx4 v[80:83], v144, s[46:47] nt
	global_load_dwordx4 v[84:87], v144, s[46:47] offset:1024 nt
	global_load_dwordx4 v[88:91], v144, s[46:47] offset:2048 nt
	global_load_dwordx4 v[92:95], v144, s[46:47] offset:3072 nt
	v_add_u32_e32 v144, 0x1000, v144
	s_waitcnt vmcnt(24)
	v_pk_mul_f32 v[242:243], v[96:97], v[96:97]
	v_pk_mul_f32 v[244:245], v[100:101], v[100:101]
	v_pk_mul_f32 v[246:247], v[98:99], v[98:99]
	v_pk_mul_f32 v[248:249], v[102:103], v[102:103]
	v_add_f32_e32 v204, v245, v244
	v_add_f32_e32 v205, v243, v242
	v_add_f32_e32 v204, v248, v204
	v_add_f32_e32 v205, v246, v205
	v_add_f32_e32 v204, v249, v204
	v_add_f32_e32 v205, v247, v205
	v_pk_mul_f32 v[242:243], v[104:105], v[104:105]
	v_pk_mul_f32 v[244:245], v[108:109], v[108:109]
	v_pk_mul_f32 v[246:247], v[106:107], v[106:107]
	v_pk_mul_f32 v[248:249], v[110:111], v[110:111]
	v_add_f32_e32 v206, v243, v242
	v_add_f32_e32 v207, v245, v244
	v_add_f32_e32 v206, v246, v206
	v_add_f32_e32 v207, v248, v207
	v_add_f32_e32 v206, v247, v206
	v_add_f32_e32 v207, v249, v207
	v_add_f32_e32 v204, v205, v204
	v_add_f32_e32 v204, v204, v206
	v_add_f32_e32 v204, v204, v207
	ds_swizzle_b32 v205, v204 offset:swizzle(SWAP,1)
	s_waitcnt lgkmcnt(0)
	v_add_f32_e32 v204, v204, v205
	ds_swizzle_b32 v205, v204 offset:swizzle(SWAP,2)
	s_waitcnt lgkmcnt(0)
	v_add_f32_e32 v204, v204, v205
	ds_swizzle_b32 v205, v204 offset:swizzle(SWAP,4)
	s_waitcnt lgkmcnt(0)
	v_add_f32_e32 v204, v204, v205
	ds_swizzle_b32 v205, v204 offset:swizzle(SWAP,8)
	s_waitcnt lgkmcnt(0)
	v_add_f32_e32 v204, v204, v205
	ds_swizzle_b32 v205, v204 offset:swizzle(SWAP,16)
	s_waitcnt lgkmcnt(0)
; __device__ __forceinline__ unsigned pk2(float lo, float hi) { const g_f32x2 f = {lo, hi}; return __builtin_bit_cast(unsigned, __builtin_convertvector(f, g_bf16x2)); }
; __device__ __forceinline__ void p_norm(const float* hlat, const float* hctx, const float* g, const float* modl, int sh_off, int sc_off, bf16_t* A, int M,
;                                        const float* part, const float* cgate, float* hcout) {
;     ...
;         float ss = 0.f;
; #pragma unroll
;         for (int i = 0; i < 4; ++i) {
;             if (part != nullptr && row >= NLAT) {
;                 const size_t po = (size_t)(row - NLAT) * 1024 + i * 256 + lane * 4;
;                 const float4 p0 = *(const float4*)(part + po), p1 = *(const float4*)(part + (size_t)4096 * 1024 + po), cg = *(const float4*)(cgate + i * 256 + lane * 4);
;                 v[i].x += cg.x * (p0.x + p1.x); v[i].y += cg.y * (p0.y + p1.y); v[i].z += cg.z * (p0.z + p1.z); v[i].w += cg.w * (p0.w + p1.w);
;                 *(float4*)(hcout + po) = v[i];
;             }
;             ss += v[i].x * v[i].x + v[i].y * v[i].y + v[i].z * v[i].z + v[i].w * v[i].w; }
;         ss = wave_sum(ss);
;         const float rstd = rsqrtf(ss * (1.0f / 1024.0f) + EPS);
;         const float* mr = modl + (size_t)r * 6144;
; #pragma unroll
;         for (int i = 0; i < 4; ++i) {
;             const int k = i * 256 + lane * 4;
;             const float4 gg = *(const float4*)(g + k), scv = *(const float4*)(mr + sc_off + k), shv = *(const float4*)(mr + sh_off + k);
;             const float o0 = v[i].x * rstd * gg.x * (1.0f + scv.x) + shv.x, o1 = v[i].y * rstd * gg.y * (1.0f + scv.y) + shv.y;
;             const float o2 = v[i].z * rstd * gg.z * (1.0f + scv.z) + shv.z, o3 = v[i].w * rstd * gg.w * (1.0f + scv.w) + shv.w;
;             uint2 w; w.x = pk2(o0, o1); w.y = pk2(o2, o3);
;             *(uint2*)(A + (size_t)row * 1024 + k) = w;
;         }
	v_add_f32_e32 v204, v204, v205
	v_mov_b32_e32 v205, v204
	s_nop 1
	v_permlane32_swap_b32_e32 v204, v205
	v_add_f32_e32 v204, v204, v205
	v_mov_b32_e32 v205, 0x358637bd
	v_fmamk_f32 v204, v204, 0x3a800000, v205
	v_rsq_f32_e32 v204, v204
	s_nop 0
	v_pk_mul_f32 v[96:97], v[96:97], v[204:205] op_sel_hi:[1,0]
	v_pk_mul_f32 v[98:99], v[98:99], v[204:205] op_sel_hi:[1,0]
	v_pk_mul_f32 v[96:97], v[188:189], v[96:97]
	v_pk_mul_f32 v[98:99], v[190:191], v[98:99]
	v_pk_fma_f32 v[96:97], v[34:35], v[96:97], v[224:225]
	v_pk_fma_f32 v[98:99], v[36:37], v[98:99], v[226:227]
	v_cvt_pk_bf16_f32 v96, v96, v97
	v_cvt_pk_bf16_f32 v97, v98, v99
	global_store_dwordx2 v146, v[96:97], s[66:67] sc0 sc1
	v_pk_mul_f32 v[100:101], v[100:101], v[204:205] op_sel_hi:[1,0]
	v_pk_mul_f32 v[102:103], v[102:103], v[204:205] op_sel_hi:[1,0]
	v_pk_mul_f32 v[100:101], v[192:193], v[100:101]
	v_pk_mul_f32 v[102:103], v[194:195], v[102:103]
	v_pk_fma_f32 v[100:101], v[38:39], v[100:101], v[228:229]
	v_pk_fma_f32 v[102:103], v[40:41], v[102:103], v[230:231]
	v_cvt_pk_bf16_f32 v100, v100, v101
	v_cvt_pk_bf16_f32 v101, v102, v103
	global_store_dwordx2 v146, v[100:101], s[66:67] offset:512 sc0 sc1
	v_pk_mul_f32 v[104:105], v[104:105], v[204:205] op_sel_hi:[1,0]
	v_pk_mul_f32 v[106:107], v[106:107], v[204:205] op_sel_hi:[1,0]
	v_pk_mul_f32 v[104:105], v[196:197], v[104:105]
	v_pk_mul_f32 v[106:107], v[198:199], v[106:107]
	v_pk_fma_f32 v[104:105], v[42:43], v[104:105], v[232:233]
	v_pk_fma_f32 v[106:107], v[44:45], v[106:107], v[234:235]
	v_cvt_pk_bf16_f32 v104, v104, v105
	v_cvt_pk_bf16_f32 v105, v106, v107
	global_store_dwordx2 v146, v[104:105], s[66:67] offset:1024 sc0 sc1
	v_pk_mul_f32 v[108:109], v[108:109], v[204:205] op_sel_hi:[1,0]
	v_pk_mul_f32 v[110:111], v[110:111], v[204:205] op_sel_hi:[1,0]
	v_pk_mul_f32 v[108:109], v[200:201], v[108:109]
	v_pk_mul_f32 v[110:111], v[202:203], v[110:111]
	v_pk_fma_f32 v[108:109], v[46:47], v[108:109], v[236:237]
	v_pk_fma_f32 v[110:111], v[48:49], v[110:111], v[238:239]
	v_cvt_pk_bf16_f32 v108, v108, v109
	v_cvt_pk_bf16_f32 v109, v110, v111
	global_store_dwordx2 v146, v[108:109], s[66:67] offset:1536 sc0 sc1
	v_add_u32_e32 v146, 0x800, v146
	global_load_dwordx4 v[96:99], v144, s[46:47] nt
	global_load_dwordx4 v[100:103], v144, s[46:47] offset:1024 nt
	global_load_dwordx4 v[104:107], v144, s[46:47] offset:2048 nt
	global_load_dwordx4 v[108:111], v144, s[46:47] offset:3072 nt
	v_add_u32_e32 v144, 0x1000, v144
	s_waitcnt vmcnt(28)
	v_pk_mul_f32 v[242:243], v[112:113], v[112:113]
	v_pk_mul_f32 v[244:245], v[116:117], v[116:117]
	v_pk_mul_f32 v[246:247], v[114:115], v[114:115]
	v_pk_mul_f32 v[248:249], v[118:119], v[118:119]
	v_add_f32_e32 v204, v245, v244
	v_add_f32_e32 v205, v243, v242
	v_add_f32_e32 v204, v248, v204
	v_add_f32_e32 v205, v246, v205
	v_add_f32_e32 v204, v249, v204
	v_add_f32_e32 v205, v247, v205
	v_pk_mul_f32 v[242:243], v[120:121], v[120:121]
	v_pk_mul_f32 v[244:245], v[124:125], v[124:125]
	v_pk_mul_f32 v[246:247], v[122:123], v[122:123]
	v_pk_mul_f32 v[248:249], v[126:127], v[126:127]
	v_add_f32_e32 v206, v243, v242
	v_add_f32_e32 v207, v245, v244
	v_add_f32_e32 v206, v246, v206
	v_add_f32_e32 v207, v248, v207
	v_add_f32_e32 v206, v247, v206
	v_add_f32_e32 v207, v249, v207
	v_add_f32_e32 v204, v205, v204
	v_add_f32_e32 v204, v204, v206
	v_add_f32_e32 v204, v204, v207
	ds_swizzle_b32 v205, v204 offset:swizzle(SWAP,1)
	s_waitcnt lgkmcnt(0)
	v_add_f32_e32 v204, v204, v205
	ds_swizzle_b32 v205, v204 offset:swizzle(SWAP,2)
	s_waitcnt lgkmcnt(0)
	v_add_f32_e32 v204, v204, v205
	ds_swizzle_b32 v205, v204 offset:swizzle(SWAP,4)
	s_waitcnt lgkmcnt(0)
	v_add_f32_e32 v204, v204, v205
	ds_swizzle_b32 v205, v204 offset:swizzle(SWAP,8)
	s_waitcnt lgkmcnt(0)
	v_add_f32_e32 v204, v204, v205
	ds_swizzle_b32 v205, v204 offset:swizzle(SWAP,16)
	s_waitcnt lgkmcnt(0)
	v_add_f32_e32 v204, v204, v205
	v_mov_b32_e32 v205, v204
	s_nop 1
	v_permlane32_swap_b32_e32 v204, v205
	v_add_f32_e32 v204, v204, v205
	v_mov_b32_e32 v205, 0x358637bd
	v_fmamk_f32 v204, v204, 0x3a800000, v205
	v_rsq_f32_e32 v204, v204
	s_nop 0
	v_pk_mul_f32 v[112:113], v[112:113], v[204:205] op_sel_hi:[1,0]
	v_pk_mul_f32 v[114:115], v[114:115], v[204:205] op_sel_hi:[1,0]
	v_pk_mul_f32 v[112:113], v[188:189], v[112:113]
	v_pk_mul_f32 v[114:115], v[190:191], v[114:115]
	v_pk_fma_f32 v[112:113], v[34:35], v[112:113], v[224:225]
	v_pk_fma_f32 v[114:115], v[36:37], v[114:115], v[226:227]
	v_cvt_pk_bf16_f32 v112, v112, v113
	v_cvt_pk_bf16_f32 v113, v114, v115
	global_store_dwordx2 v146, v[112:113], s[66:67] sc0 sc1
	v_pk_mul_f32 v[116:117], v[116:117], v[204:205] op_sel_hi:[1,0]
	v_pk_mul_f32 v[118:119], v[118:119], v[204:205] op_sel_hi:[1,0]
	v_pk_mul_f32 v[116:117], v[192:193], v[116:117]
	v_pk_mul_f32 v[118:119], v[194:195], v[118:119]
	v_pk_fma_f32 v[116:117], v[38:39], v[116:117], v[228:229]
	v_pk_fma_f32 v[118:119], v[40:41], v[118:119], v[230:231]
	v_cvt_pk_bf16_f32 v116, v116, v117
	v_cvt_pk_bf16_f32 v117, v118, v119
	global_store_dwordx2 v146, v[116:117], s[66:67] offset:512 sc0 sc1
	v_pk_mul_f32 v[120:121], v[120:121], v[204:205] op_sel_hi:[1,0]
	v_pk_mul_f32 v[122:123], v[122:123], v[204:205] op_sel_hi:[1,0]
	v_pk_mul_f32 v[120:121], v[196:197], v[120:121]
	v_pk_mul_f32 v[122:123], v[198:199], v[122:123]
	v_pk_fma_f32 v[120:121], v[42:43], v[120:121], v[232:233]
	v_pk_fma_f32 v[122:123], v[44:45], v[122:123], v[234:235]
	v_cvt_pk_bf16_f32 v120, v120, v121
	v_cvt_pk_bf16_f32 v121, v122, v123
	global_store_dwordx2 v146, v[120:121], s[66:67] offset:1024 sc0 sc1
	v_pk_mul_f32 v[124:125], v[124:125], v[204:205] op_sel_hi:[1,0]
	v_pk_mul_f32 v[126:127], v[126:127], v[204:205] op_sel_hi:[1,0]
	v_pk_mul_f32 v[124:125], v[200:201], v[124:125]
	v_pk_mul_f32 v[126:127], v[202:203], v[126:127]
	v_pk_fma_f32 v[124:125], v[46:47], v[124:125], v[236:237]
	v_pk_fma_f32 v[126:127], v[48:49], v[126:127], v[238:239]
	v_cvt_pk_bf16_f32 v124, v124, v125
	v_cvt_pk_bf16_f32 v125, v126, v127
	global_store_dwordx2 v146, v[124:125], s[66:67] offset:1536 sc0 sc1
	v_add_u32_e32 v146, 0x800, v146
	global_load_dwordx4 v[112:115], v144, s[46:47] nt
	global_load_dwordx4 v[116:119], v144, s[46:47] offset:1024 nt
	global_load_dwordx4 v[120:123], v144, s[46:47] offset:2048 nt
	global_load_dwordx4 v[124:127], v144, s[46:47] offset:3072 nt
	v_add_u32_e32 v144, 0x1000, v144
	s_waitcnt vmcnt(32)
; __device__ __forceinline__ unsigned pk2(float lo, float hi) { const g_f32x2 f = {lo, hi}; return __builtin_bit_cast(unsigned, __builtin_convertvector(f, g_bf16x2)); }
; __device__ __forceinline__ void p_norm(const float* hlat, const float* hctx, const float* g, const float* modl, int sh_off, int sc_off, bf16_t* A, int M,
;                                        const float* part, const float* cgate, float* hcout) {
;     ...
;         float ss = 0.f;
; #pragma unroll
;         for (int i = 0; i < 4; ++i) {
;             if (part != nullptr && row >= NLAT) {
;                 const size_t po = (size_t)(row - NLAT) * 1024 + i * 256 + lane * 4;
;                 const float4 p0 = *(const float4*)(part + po), p1 = *(const float4*)(part + (size_t)4096 * 1024 + po), cg = *(const float4*)(cgate + i * 256 + lane * 4);
;                 v[i].x += cg.x * (p0.x + p1.x); v[i].y += cg.y * (p0.y + p1.y); v[i].z += cg.z * (p0.z + p1.z); v[i].w += cg.w * (p0.w + p1.w);
;                 *(float4*)(hcout + po) = v[i];
;             }
;             ss += v[i].x * v[i].x + v[i].y * v[i].y + v[i].z * v[i].z + v[i].w * v[i].w; }
;         ss = wave_sum(ss);
;         const float rstd = rsqrtf(ss * (1.0f / 1024.0f) + EPS);
;         const float* mr = modl + (size_t)r * 6144;
; #pragma unroll
;         for (int i = 0; i < 4; ++i) {
;             const int k = i * 256 + lane * 4;
;             const float4 gg = *(const float4*)(g + k), scv = *(const float4*)(mr + sc_off + k), shv = *(const float4*)(mr + sh_off + k);
;             const float o0 = v[i].x * rstd * gg.x * (1.0f + scv.x) + shv.x, o1 = v[i].y * rstd * gg.y * (1.0f + scv.y) + shv.y;
;             const float o2 = v[i].z * rstd * gg.z * (1.0f + scv.z) + shv.z, o3 = v[i].w * rstd * gg.w * (1.0f + scv.w) + shv.w;
;             uint2 w; w.x = pk2(o0, o1); w.y = pk2(o2, o3);
;             *(uint2*)(A + (size_t)row * 1024 + k) = w;
;         }
	v_pk_mul_f32 v[242:243], v[128:129], v[128:129]
	v_pk_mul_f32 v[244:245], v[132:133], v[132:133]
	v_pk_mul_f32 v[246:247], v[130:131], v[130:131]
	v_pk_mul_f32 v[248:249], v[134:135], v[134:135]
	v_add_f32_e32 v204, v245, v244
	v_add_f32_e32 v205, v243, v242
	v_add_f32_e32 v204, v248, v204
	v_add_f32_e32 v205, v246, v205
	v_add_f32_e32 v204, v249, v204
	v_add_f32_e32 v205, v247, v205
	v_pk_mul_f32 v[242:243], v[136:137], v[136:137]
	v_pk_mul_f32 v[244:245], v[140:141], v[140:141]
	v_pk_mul_f32 v[246:247], v[138:139], v[138:139]
	v_pk_mul_f32 v[248:249], v[142:143], v[142:143]
	v_add_f32_e32 v206, v243, v242
	v_add_f32_e32 v207, v245, v244
	v_add_f32_e32 v206, v246, v206
	v_add_f32_e32 v207, v248, v207
	v_add_f32_e32 v206, v247, v206
	v_add_f32_e32 v207, v249, v207
	v_add_f32_e32 v204, v205, v204
	v_add_f32_e32 v204, v204, v206
	v_add_f32_e32 v204, v204, v207
	ds_swizzle_b32 v205, v204 offset:swizzle(SWAP,1)
	s_waitcnt lgkmcnt(0)
	v_add_f32_e32 v204, v204, v205
	ds_swizzle_b32 v205, v204 offset:swizzle(SWAP,2)
	s_waitcnt lgkmcnt(0)
	v_add_f32_e32 v204, v204, v205
	ds_swizzle_b32 v205, v204 offset:swizzle(SWAP,4)
	s_waitcnt lgkmcnt(0)
	v_add_f32_e32 v204, v204, v205
	ds_swizzle_b32 v205, v204 offset:swizzle(SWAP,8)
	s_waitcnt lgkmcnt(0)
	v_add_f32_e32 v204, v204, v205
	ds_swizzle_b32 v205, v204 offset:swizzle(SWAP,16)
	s_waitcnt lgkmcnt(0)
	v_add_f32_e32 v204, v204, v205
	v_mov_b32_e32 v205, v204
	s_nop 1
	v_permlane32_swap_b32_e32 v204, v205
	v_add_f32_e32 v204, v204, v205
	v_mov_b32_e32 v205, 0x358637bd
	v_fmamk_f32 v204, v204, 0x3a800000, v205
	v_rsq_f32_e32 v204, v204
	s_nop 0
	v_pk_mul_f32 v[128:129], v[128:129], v[204:205] op_sel_hi:[1,0]
	v_pk_mul_f32 v[130:131], v[130:131], v[204:205] op_sel_hi:[1,0]
	v_pk_mul_f32 v[128:129], v[188:189], v[128:129]
	v_pk_mul_f32 v[130:131], v[190:191], v[130:131]
	v_pk_fma_f32 v[128:129], v[34:35], v[128:129], v[224:225]
	v_pk_fma_f32 v[130:131], v[36:37], v[130:131], v[226:227]
	v_cvt_pk_bf16_f32 v128, v128, v129
	v_cvt_pk_bf16_f32 v129, v130, v131
	global_store_dwordx2 v146, v[128:129], s[66:67] sc0 sc1
	v_pk_mul_f32 v[132:133], v[132:133], v[204:205] op_sel_hi:[1,0]
	v_pk_mul_f32 v[134:135], v[134:135], v[204:205] op_sel_hi:[1,0]
	v_pk_mul_f32 v[132:133], v[192:193], v[132:133]
	v_pk_mul_f32 v[134:135], v[194:195], v[134:135]
	v_pk_fma_f32 v[132:133], v[38:39], v[132:133], v[228:229]
	v_pk_fma_f32 v[134:135], v[40:41], v[134:135], v[230:231]
	v_cvt_pk_bf16_f32 v132, v132, v133
	v_cvt_pk_bf16_f32 v133, v134, v135
	global_store_dwordx2 v146, v[132:133], s[66:67] offset:512 sc0 sc1
	v_pk_mul_f32 v[136:137], v[136:137], v[204:205] op_sel_hi:[1,0]
	v_pk_mul_f32 v[138:139], v[138:139], v[204:205] op_sel_hi:[1,0]
	v_pk_mul_f32 v[136:137], v[196:197], v[136:137]
	v_pk_mul_f32 v[138:139], v[198:199], v[138:139]
	v_pk_fma_f32 v[136:137], v[42:43], v[136:137], v[232:233]
	v_pk_fma_f32 v[138:139], v[44:45], v[138:139], v[234:235]
	v_cvt_pk_bf16_f32 v136, v136, v137
	v_cvt_pk_bf16_f32 v137, v138, v139
	global_store_dwordx2 v146, v[136:137], s[66:67] offset:1024 sc0 sc1
	v_pk_mul_f32 v[140:141], v[140:141], v[204:205] op_sel_hi:[1,0]
	v_pk_mul_f32 v[142:143], v[142:143], v[204:205] op_sel_hi:[1,0]
	v_pk_mul_f32 v[140:141], v[200:201], v[140:141]
	v_pk_mul_f32 v[142:143], v[202:203], v[142:143]
	v_pk_fma_f32 v[140:141], v[46:47], v[140:141], v[236:237]
	v_pk_fma_f32 v[142:143], v[48:49], v[142:143], v[238:239]
	v_cvt_pk_bf16_f32 v140, v140, v141
	v_cvt_pk_bf16_f32 v141, v142, v143
	global_store_dwordx2 v146, v[140:141], s[66:67] offset:1536 sc0 sc1
	v_add_u32_e32 v146, 0x800, v146
	global_load_dwordx4 v[128:131], v144, s[46:47] nt
	global_load_dwordx4 v[132:135], v144, s[46:47] offset:1024 nt
	global_load_dwordx4 v[136:139], v144, s[46:47] offset:2048 nt
	global_load_dwordx4 v[140:143], v144, s[46:47] offset:3072 nt
	v_add_u32_e32 v144, 0x1000, v144
	s_waitcnt vmcnt(36)
	v_pk_mul_f32 v[242:243], v[156:157], v[156:157]
	v_pk_mul_f32 v[244:245], v[160:161], v[160:161]
	v_pk_mul_f32 v[246:247], v[158:159], v[158:159]
	v_pk_mul_f32 v[248:249], v[162:163], v[162:163]
	v_add_f32_e32 v204, v245, v244
	v_add_f32_e32 v205, v243, v242
	v_add_f32_e32 v204, v248, v204
	v_add_f32_e32 v205, v246, v205
	v_add_f32_e32 v204, v249, v204
	v_add_f32_e32 v205, v247, v205
	v_pk_mul_f32 v[242:243], v[164:165], v[164:165]
	v_pk_mul_f32 v[244:245], v[168:169], v[168:169]
	v_pk_mul_f32 v[246:247], v[166:167], v[166:167]
	v_pk_mul_f32 v[248:249], v[170:171], v[170:171]
	v_add_f32_e32 v206, v243, v242
	v_add_f32_e32 v207, v245, v244
	v_add_f32_e32 v206, v246, v206
	v_add_f32_e32 v207, v248, v207
	v_add_f32_e32 v206, v247, v206
	v_add_f32_e32 v207, v249, v207
	v_add_f32_e32 v204, v205, v204
	v_add_f32_e32 v204, v204, v206
	v_add_f32_e32 v204, v204, v207
	ds_swizzle_b32 v205, v204 offset:swizzle(SWAP,1)
	s_waitcnt lgkmcnt(0)
	v_add_f32_e32 v204, v204, v205
	ds_swizzle_b32 v205, v204 offset:swizzle(SWAP,2)
	s_waitcnt lgkmcnt(0)
	v_add_f32_e32 v204, v204, v205
	ds_swizzle_b32 v205, v204 offset:swizzle(SWAP,4)
	s_waitcnt lgkmcnt(0)
	v_add_f32_e32 v204, v204, v205
	ds_swizzle_b32 v205, v204 offset:swizzle(SWAP,8)
	s_waitcnt lgkmcnt(0)
	v_add_f32_e32 v204, v204, v205
	ds_swizzle_b32 v205, v204 offset:swizzle(SWAP,16)
	s_waitcnt lgkmcnt(0)
; __device__ __forceinline__ unsigned pk2(float lo, float hi) { const g_f32x2 f = {lo, hi}; return __builtin_bit_cast(unsigned, __builtin_convertvector(f, g_bf16x2)); }
; __device__ __forceinline__ void p_norm(const float* hlat, const float* hctx, const float* g, const float* modl, int sh_off, int sc_off, bf16_t* A, int M,
;                                        const float* part, const float* cgate, float* hcout) {
;     ...
;         float ss = 0.f;
; #pragma unroll
;         for (int i = 0; i < 4; ++i) {
;             if (part != nullptr && row >= NLAT) {
;                 const size_t po = (size_t)(row - NLAT) * 1024 + i * 256 + lane * 4;
;                 const float4 p0 = *(const float4*)(part + po), p1 = *(const float4*)(part + (size_t)4096 * 1024 + po), cg = *(const float4*)(cgate + i * 256 + lane * 4);
;                 v[i].x += cg.x * (p0.x + p1.x); v[i].y += cg.y * (p0.y + p1.y); v[i].z += cg.z * (p0.z + p1.z); v[i].w += cg.w * (p0.w + p1.w);
;                 *(float4*)(hcout + po) = v[i];
;             }
;             ss += v[i].x * v[i].x + v[i].y * v[i].y + v[i].z * v[i].z + v[i].w * v[i].w; }
;         ss = wave_sum(ss);
;         const float rstd = rsqrtf(ss * (1.0f / 1024.0f) + EPS);
;         const float* mr = modl + (size_t)r * 6144;
; #pragma unroll
;         for (int i = 0; i < 4; ++i) {
;             const int k = i * 256 + lane * 4;
;             const float4 gg = *(const float4*)(g + k), scv = *(const float4*)(mr + sc_off + k), shv = *(const float4*)(mr + sh_off + k);
;             const float o0 = v[i].x * rstd * gg.x * (1.0f + scv.x) + shv.x, o1 = v[i].y * rstd * gg.y * (1.0f + scv.y) + shv.y;
;             const float o2 = v[i].z * rstd * gg.z * (1.0f + scv.z) + shv.z, o3 = v[i].w * rstd * gg.w * (1.0f + scv.w) + shv.w;
;             uint2 w; w.x = pk2(o0, o1); w.y = pk2(o2, o3);
;             *(uint2*)(A + (size_t)row * 1024 + k) = w;
;         }
	v_add_f32_e32 v204, v204, v205
	v_mov_b32_e32 v205, v204
	s_nop 1
	v_permlane32_swap_b32_e32 v204, v205
	v_add_f32_e32 v204, v204, v205
	v_mov_b32_e32 v205, 0x358637bd
	v_fmamk_f32 v204, v204, 0x3a800000, v205
	v_rsq_f32_e32 v204, v204
	s_nop 0
	v_pk_mul_f32 v[156:157], v[156:157], v[204:205] op_sel_hi:[1,0]
	v_pk_mul_f32 v[158:159], v[158:159], v[204:205] op_sel_hi:[1,0]
	v_pk_mul_f32 v[156:157], v[188:189], v[156:157]
	v_pk_mul_f32 v[158:159], v[190:191], v[158:159]
	v_pk_fma_f32 v[156:157], v[34:35], v[156:157], v[224:225]
	v_pk_fma_f32 v[158:159], v[36:37], v[158:159], v[226:227]
	v_cvt_pk_bf16_f32 v156, v156, v157
	v_cvt_pk_bf16_f32 v157, v158, v159
	global_store_dwordx2 v146, v[156:157], s[66:67] sc0 sc1
	v_pk_mul_f32 v[160:161], v[160:161], v[204:205] op_sel_hi:[1,0]
	v_pk_mul_f32 v[162:163], v[162:163], v[204:205] op_sel_hi:[1,0]
	v_pk_mul_f32 v[160:161], v[192:193], v[160:161]
	v_pk_mul_f32 v[162:163], v[194:195], v[162:163]
	v_pk_fma_f32 v[160:161], v[38:39], v[160:161], v[228:229]
	v_pk_fma_f32 v[162:163], v[40:41], v[162:163], v[230:231]
	v_cvt_pk_bf16_f32 v160, v160, v161
	v_cvt_pk_bf16_f32 v161, v162, v163
	global_store_dwordx2 v146, v[160:161], s[66:67] offset:512 sc0 sc1
	v_pk_mul_f32 v[164:165], v[164:165], v[204:205] op_sel_hi:[1,0]
	v_pk_mul_f32 v[166:167], v[166:167], v[204:205] op_sel_hi:[1,0]
	v_pk_mul_f32 v[164:165], v[196:197], v[164:165]
	v_pk_mul_f32 v[166:167], v[198:199], v[166:167]
	v_pk_fma_f32 v[164:165], v[42:43], v[164:165], v[232:233]
	v_pk_fma_f32 v[166:167], v[44:45], v[166:167], v[234:235]
	v_cvt_pk_bf16_f32 v164, v164, v165
	v_cvt_pk_bf16_f32 v165, v166, v167
	global_store_dwordx2 v146, v[164:165], s[66:67] offset:1024 sc0 sc1
	v_pk_mul_f32 v[168:169], v[168:169], v[204:205] op_sel_hi:[1,0]
	v_pk_mul_f32 v[170:171], v[170:171], v[204:205] op_sel_hi:[1,0]
	v_pk_mul_f32 v[168:169], v[200:201], v[168:169]
	v_pk_mul_f32 v[170:171], v[202:203], v[170:171]
	v_pk_fma_f32 v[168:169], v[46:47], v[168:169], v[236:237]
	v_pk_fma_f32 v[170:171], v[48:49], v[170:171], v[238:239]
	v_cvt_pk_bf16_f32 v168, v168, v169
	v_cvt_pk_bf16_f32 v169, v170, v171
	global_store_dwordx2 v146, v[168:169], s[66:67] offset:1536 sc0 sc1
	v_add_u32_e32 v146, 0x800, v146
	global_load_dwordx4 v[156:159], v144, s[46:47] nt
	global_load_dwordx4 v[160:163], v144, s[46:47] offset:1024 nt
	global_load_dwordx4 v[164:167], v144, s[46:47] offset:2048 nt
	global_load_dwordx4 v[168:171], v144, s[46:47] offset:3072 nt
	v_add_u32_e32 v144, 0x1000, v144
	s_waitcnt vmcnt(40)
	v_pk_mul_f32 v[242:243], v[172:173], v[172:173]
	v_pk_mul_f32 v[244:245], v[176:177], v[176:177]
	v_pk_mul_f32 v[246:247], v[174:175], v[174:175]
	v_pk_mul_f32 v[248:249], v[178:179], v[178:179]
	v_add_f32_e32 v204, v245, v244
	v_add_f32_e32 v205, v243, v242
	v_add_f32_e32 v204, v248, v204
	v_add_f32_e32 v205, v246, v205
	v_add_f32_e32 v204, v249, v204
	v_add_f32_e32 v205, v247, v205
	v_pk_mul_f32 v[242:243], v[180:181], v[180:181]
	v_pk_mul_f32 v[244:245], v[184:185], v[184:185]
	v_pk_mul_f32 v[246:247], v[182:183], v[182:183]
	v_pk_mul_f32 v[248:249], v[186:187], v[186:187]
	v_add_f32_e32 v206, v243, v242
	v_add_f32_e32 v207, v245, v244
	v_add_f32_e32 v206, v246, v206
	v_add_f32_e32 v207, v248, v207
	v_add_f32_e32 v206, v247, v206
	v_add_f32_e32 v207, v249, v207
	v_add_f32_e32 v204, v205, v204
	v_add_f32_e32 v204, v204, v206
	v_add_f32_e32 v204, v204, v207
	ds_swizzle_b32 v205, v204 offset:swizzle(SWAP,1)
	s_waitcnt lgkmcnt(0)
	v_add_f32_e32 v204, v204, v205
	ds_swizzle_b32 v205, v204 offset:swizzle(SWAP,2)
	s_waitcnt lgkmcnt(0)
	v_add_f32_e32 v204, v204, v205
	ds_swizzle_b32 v205, v204 offset:swizzle(SWAP,4)
	s_waitcnt lgkmcnt(0)
	v_add_f32_e32 v204, v204, v205
	ds_swizzle_b32 v205, v204 offset:swizzle(SWAP,8)
	s_waitcnt lgkmcnt(0)
	v_add_f32_e32 v204, v204, v205
	ds_swizzle_b32 v205, v204 offset:swizzle(SWAP,16)
	s_waitcnt lgkmcnt(0)
	v_add_f32_e32 v204, v204, v205
	v_mov_b32_e32 v205, v204
	s_nop 1
	v_permlane32_swap_b32_e32 v204, v205
	v_add_f32_e32 v204, v204, v205
	v_mov_b32_e32 v205, 0x358637bd
	v_fmamk_f32 v204, v204, 0x3a800000, v205
	v_rsq_f32_e32 v204, v204
	s_nop 0
	v_pk_mul_f32 v[172:173], v[172:173], v[204:205] op_sel_hi:[1,0]
	v_pk_mul_f32 v[174:175], v[174:175], v[204:205] op_sel_hi:[1,0]
	v_pk_mul_f32 v[172:173], v[188:189], v[172:173]
	v_pk_mul_f32 v[174:175], v[190:191], v[174:175]
	v_pk_fma_f32 v[172:173], v[34:35], v[172:173], v[224:225]
	v_pk_fma_f32 v[174:175], v[36:37], v[174:175], v[226:227]
	v_cvt_pk_bf16_f32 v172, v172, v173
	v_cvt_pk_bf16_f32 v173, v174, v175
	global_store_dwordx2 v146, v[172:173], s[66:67] sc0 sc1
	v_pk_mul_f32 v[176:177], v[176:177], v[204:205] op_sel_hi:[1,0]
	v_pk_mul_f32 v[178:179], v[178:179], v[204:205] op_sel_hi:[1,0]
	v_pk_mul_f32 v[176:177], v[192:193], v[176:177]
	v_pk_mul_f32 v[178:179], v[194:195], v[178:179]
	v_pk_fma_f32 v[176:177], v[38:39], v[176:177], v[228:229]
	v_pk_fma_f32 v[178:179], v[40:41], v[178:179], v[230:231]
	v_cvt_pk_bf16_f32 v176, v176, v177
	v_cvt_pk_bf16_f32 v177, v178, v179
	global_store_dwordx2 v146, v[176:177], s[66:67] offset:512 sc0 sc1
	v_pk_mul_f32 v[180:181], v[180:181], v[204:205] op_sel_hi:[1,0]
	v_pk_mul_f32 v[182:183], v[182:183], v[204:205] op_sel_hi:[1,0]
	v_pk_mul_f32 v[180:181], v[196:197], v[180:181]
	v_pk_mul_f32 v[182:183], v[198:199], v[182:183]
	v_pk_fma_f32 v[180:181], v[42:43], v[180:181], v[232:233]
	v_pk_fma_f32 v[182:183], v[44:45], v[182:183], v[234:235]
	v_cvt_pk_bf16_f32 v180, v180, v181
	v_cvt_pk_bf16_f32 v181, v182, v183
	global_store_dwordx2 v146, v[180:181], s[66:67] offset:1024 sc0 sc1
	v_pk_mul_f32 v[184:185], v[184:185], v[204:205] op_sel_hi:[1,0]
	v_pk_mul_f32 v[186:187], v[186:187], v[204:205] op_sel_hi:[1,0]
	v_pk_mul_f32 v[184:185], v[200:201], v[184:185]
	v_pk_mul_f32 v[186:187], v[202:203], v[186:187]
	v_pk_fma_f32 v[184:185], v[46:47], v[184:185], v[236:237]
	v_pk_fma_f32 v[186:187], v[48:49], v[186:187], v[238:239]
	v_cvt_pk_bf16_f32 v184, v184, v185
	v_cvt_pk_bf16_f32 v185, v186, v187
	global_store_dwordx2 v146, v[184:185], s[66:67] offset:1536 sc0 sc1
	v_add_u32_e32 v146, 0x800, v146
	global_load_dwordx4 v[172:175], v144, s[46:47] nt
	global_load_dwordx4 v[176:179], v144, s[46:47] offset:1024 nt
	global_load_dwordx4 v[180:183], v144, s[46:47] offset:2048 nt
	global_load_dwordx4 v[184:187], v144, s[46:47] offset:3072 nt
	v_add_u32_e32 v144, 0x1000, v144
	s_waitcnt vmcnt(40)
; __device__ __forceinline__ unsigned pk2(float lo, float hi) { const g_f32x2 f = {lo, hi}; return __builtin_bit_cast(unsigned, __builtin_convertvector(f, g_bf16x2)); }
; __device__ __forceinline__ void p_norm(const float* hlat, const float* hctx, const float* g, const float* modl, int sh_off, int sc_off, bf16_t* A, int M,
;                                        const float* part, const float* cgate, float* hcout) {
;     ...
;         float ss = 0.f;
; #pragma unroll
;         for (int i = 0; i < 4; ++i) {
;             if (part != nullptr && row >= NLAT) {
;                 const size_t po = (size_t)(row - NLAT) * 1024 + i * 256 + lane * 4;
;                 const float4 p0 = *(const float4*)(part + po), p1 = *(const float4*)(part + (size_t)4096 * 1024 + po), cg = *(const float4*)(cgate + i * 256 + lane * 4);
;                 v[i].x += cg.x * (p0.x + p1.x); v[i].y += cg.y * (p0.y + p1.y); v[i].z += cg.z * (p0.z + p1.z); v[i].w += cg.w * (p0.w + p1.w);
;                 *(float4*)(hcout + po) = v[i];
;             }
;             ss += v[i].x * v[i].x + v[i].y * v[i].y + v[i].z * v[i].z + v[i].w * v[i].w; }
;         ss = wave_sum(ss);
;         const float rstd = rsqrtf(ss * (1.0f / 1024.0f) + EPS);
;         const float* mr = modl + (size_t)r * 6144;
; #pragma unroll
;         for (int i = 0; i < 4; ++i) {
;             const int k = i * 256 + lane * 4;
;             const float4 gg = *(const float4*)(g + k), scv = *(const float4*)(mr + sc_off + k), shv = *(const float4*)(mr + sh_off + k);
;             const float o0 = v[i].x * rstd * gg.x * (1.0f + scv.x) + shv.x, o1 = v[i].y * rstd * gg.y * (1.0f + scv.y) + shv.y;
;             const float o2 = v[i].z * rstd * gg.z * (1.0f + scv.z) + shv.z, o3 = v[i].w * rstd * gg.w * (1.0f + scv.w) + shv.w;
;             uint2 w; w.x = pk2(o0, o1); w.y = pk2(o2, o3);
;             *(uint2*)(A + (size_t)row * 1024 + k) = w;
;         }
	v_pk_mul_f32 v[242:243], v[80:81], v[80:81]
	v_pk_mul_f32 v[244:245], v[84:85], v[84:85]
	v_pk_mul_f32 v[246:247], v[82:83], v[82:83]
	v_pk_mul_f32 v[248:249], v[86:87], v[86:87]
	v_add_f32_e32 v204, v245, v244
	v_add_f32_e32 v205, v243, v242
	v_add_f32_e32 v204, v248, v204
	v_add_f32_e32 v205, v246, v205
	v_add_f32_e32 v204, v249, v204
	v_add_f32_e32 v205, v247, v205
	v_pk_mul_f32 v[242:243], v[88:89], v[88:89]
	v_pk_mul_f32 v[244:245], v[92:93], v[92:93]
	v_pk_mul_f32 v[246:247], v[90:91], v[90:91]
	v_pk_mul_f32 v[248:249], v[94:95], v[94:95]
	v_add_f32_e32 v206, v243, v242
	v_add_f32_e32 v207, v245, v244
	v_add_f32_e32 v206, v246, v206
	v_add_f32_e32 v207, v248, v207
	v_add_f32_e32 v206, v247, v206
	v_add_f32_e32 v207, v249, v207
	v_add_f32_e32 v204, v205, v204
	v_add_f32_e32 v204, v204, v206
	v_add_f32_e32 v204, v204, v207
	ds_swizzle_b32 v205, v204 offset:swizzle(SWAP,1)
	s_waitcnt lgkmcnt(0)
	v_add_f32_e32 v204, v204, v205
	ds_swizzle_b32 v205, v204 offset:swizzle(SWAP,2)
	s_waitcnt lgkmcnt(0)
	v_add_f32_e32 v204, v204, v205
	ds_swizzle_b32 v205, v204 offset:swizzle(SWAP,4)
	s_waitcnt lgkmcnt(0)
	v_add_f32_e32 v204, v204, v205
	ds_swizzle_b32 v205, v204 offset:swizzle(SWAP,8)
	s_waitcnt lgkmcnt(0)
	v_add_f32_e32 v204, v204, v205
	ds_swizzle_b32 v205, v204 offset:swizzle(SWAP,16)
	s_waitcnt lgkmcnt(0)
	v_add_f32_e32 v204, v204, v205
	v_mov_b32_e32 v205, v204
	s_nop 1
	v_permlane32_swap_b32_e32 v204, v205
	v_add_f32_e32 v204, v204, v205
	v_mov_b32_e32 v205, 0x358637bd
	v_fmamk_f32 v204, v204, 0x3a800000, v205
	v_rsq_f32_e32 v204, v204
	s_nop 0
	v_pk_mul_f32 v[80:81], v[80:81], v[204:205] op_sel_hi:[1,0]
	v_pk_mul_f32 v[82:83], v[82:83], v[204:205] op_sel_hi:[1,0]
	v_pk_mul_f32 v[80:81], v[188:189], v[80:81]
	v_pk_mul_f32 v[82:83], v[190:191], v[82:83]
	v_pk_fma_f32 v[80:81], v[34:35], v[80:81], v[224:225]
	v_pk_fma_f32 v[82:83], v[36:37], v[82:83], v[226:227]
	v_cvt_pk_bf16_f32 v80, v80, v81
	v_cvt_pk_bf16_f32 v81, v82, v83
	global_store_dwordx2 v146, v[80:81], s[66:67] sc0 sc1
	v_pk_mul_f32 v[84:85], v[84:85], v[204:205] op_sel_hi:[1,0]
	v_pk_mul_f32 v[86:87], v[86:87], v[204:205] op_sel_hi:[1,0]
	v_pk_mul_f32 v[84:85], v[192:193], v[84:85]
	v_pk_mul_f32 v[86:87], v[194:195], v[86:87]
	v_pk_fma_f32 v[84:85], v[38:39], v[84:85], v[228:229]
	v_pk_fma_f32 v[86:87], v[40:41], v[86:87], v[230:231]
	v_cvt_pk_bf16_f32 v84, v84, v85
	v_cvt_pk_bf16_f32 v85, v86, v87
	global_store_dwordx2 v146, v[84:85], s[66:67] offset:512 sc0 sc1
	v_pk_mul_f32 v[88:89], v[88:89], v[204:205] op_sel_hi:[1,0]
	v_pk_mul_f32 v[90:91], v[90:91], v[204:205] op_sel_hi:[1,0]
	v_pk_mul_f32 v[88:89], v[196:197], v[88:89]
	v_pk_mul_f32 v[90:91], v[198:199], v[90:91]
	v_pk_fma_f32 v[88:89], v[42:43], v[88:89], v[232:233]
	v_pk_fma_f32 v[90:91], v[44:45], v[90:91], v[234:235]
	v_cvt_pk_bf16_f32 v88, v88, v89
	v_cvt_pk_bf16_f32 v89, v90, v91
	global_store_dwordx2 v146, v[88:89], s[66:67] offset:1024 sc0 sc1
	v_pk_mul_f32 v[92:93], v[92:93], v[204:205] op_sel_hi:[1,0]
	v_pk_mul_f32 v[94:95], v[94:95], v[204:205] op_sel_hi:[1,0]
	v_pk_mul_f32 v[92:93], v[200:201], v[92:93]
	v_pk_mul_f32 v[94:95], v[202:203], v[94:95]
	v_pk_fma_f32 v[92:93], v[46:47], v[92:93], v[236:237]
	v_pk_fma_f32 v[94:95], v[48:49], v[94:95], v[238:239]
	v_cvt_pk_bf16_f32 v92, v92, v93
	v_cvt_pk_bf16_f32 v93, v94, v95
	global_store_dwordx2 v146, v[92:93], s[66:67] offset:1536 sc0 sc1
	v_add_u32_e32 v146, 0x800, v146
	global_load_dwordx4 v[80:83], v144, s[46:47] nt
	global_load_dwordx4 v[84:87], v144, s[46:47] offset:1024 nt
	global_load_dwordx4 v[88:91], v144, s[46:47] offset:2048 nt
	global_load_dwordx4 v[92:95], v144, s[46:47] offset:3072 nt
	v_add_u32_e32 v144, 0x1000, v144
	s_waitcnt vmcnt(40)
	v_pk_mul_f32 v[242:243], v[96:97], v[96:97]
	v_pk_mul_f32 v[244:245], v[100:101], v[100:101]
	v_pk_mul_f32 v[246:247], v[98:99], v[98:99]
	v_pk_mul_f32 v[248:249], v[102:103], v[102:103]
	v_add_f32_e32 v204, v245, v244
	v_add_f32_e32 v205, v243, v242
	v_add_f32_e32 v204, v248, v204
	v_add_f32_e32 v205, v246, v205
	v_add_f32_e32 v204, v249, v204
	v_add_f32_e32 v205, v247, v205
	v_pk_mul_f32 v[242:243], v[104:105], v[104:105]
	v_pk_mul_f32 v[244:245], v[108:109], v[108:109]
	v_pk_mul_f32 v[246:247], v[106:107], v[106:107]
	v_pk_mul_f32 v[248:249], v[110:111], v[110:111]
	v_add_f32_e32 v206, v243, v242
	v_add_f32_e32 v207, v245, v244
	v_add_f32_e32 v206, v246, v206
	v_add_f32_e32 v207, v248, v207
	v_add_f32_e32 v206, v247, v206
	v_add_f32_e32 v207, v249, v207
	v_add_f32_e32 v204, v205, v204
	v_add_f32_e32 v204, v204, v206
	v_add_f32_e32 v204, v204, v207
	ds_swizzle_b32 v205, v204 offset:swizzle(SWAP,1)
	s_waitcnt lgkmcnt(0)
	v_add_f32_e32 v204, v204, v205
	ds_swizzle_b32 v205, v204 offset:swizzle(SWAP,2)
	s_waitcnt lgkmcnt(0)
	v_add_f32_e32 v204, v204, v205
	ds_swizzle_b32 v205, v204 offset:swizzle(SWAP,4)
	s_waitcnt lgkmcnt(0)
	v_add_f32_e32 v204, v204, v205
	ds_swizzle_b32 v205, v204 offset:swizzle(SWAP,8)
	s_waitcnt lgkmcnt(0)
	v_add_f32_e32 v204, v204, v205
	ds_swizzle_b32 v205, v204 offset:swizzle(SWAP,16)
	s_waitcnt lgkmcnt(0)
; __device__ __forceinline__ unsigned pk2(float lo, float hi) { const g_f32x2 f = {lo, hi}; return __builtin_bit_cast(unsigned, __builtin_convertvector(f, g_bf16x2)); }
; __device__ __forceinline__ void p_norm(const float* hlat, const float* hctx, const float* g, const float* modl, int sh_off, int sc_off, bf16_t* A, int M,
;                                        const float* part, const float* cgate, float* hcout) {
;     ...
;         float ss = 0.f;
; #pragma unroll
;         for (int i = 0; i < 4; ++i) {
;             if (part != nullptr && row >= NLAT) {
;                 const size_t po = (size_t)(row - NLAT) * 1024 + i * 256 + lane * 4;
;                 const float4 p0 = *(const float4*)(part + po), p1 = *(const float4*)(part + (size_t)4096 * 1024 + po), cg = *(const float4*)(cgate + i * 256 + lane * 4);
;                 v[i].x += cg.x * (p0.x + p1.x); v[i].y += cg.y * (p0.y + p1.y); v[i].z += cg.z * (p0.z + p1.z); v[i].w += cg.w * (p0.w + p1.w);
;                 *(float4*)(hcout + po) = v[i];
;             }
;             ss += v[i].x * v[i].x + v[i].y * v[i].y + v[i].z * v[i].z + v[i].w * v[i].w; }
;         ss = wave_sum(ss);
;         const float rstd = rsqrtf(ss * (1.0f / 1024.0f) + EPS);
;         const float* mr = modl + (size_t)r * 6144;
; #pragma unroll
;         for (int i = 0; i < 4; ++i) {
;             const int k = i * 256 + lane * 4;
;             const float4 gg = *(const float4*)(g + k), scv = *(const float4*)(mr + sc_off + k), shv = *(const float4*)(mr + sh_off + k);
;             const float o0 = v[i].x * rstd * gg.x * (1.0f + scv.x) + shv.x, o1 = v[i].y * rstd * gg.y * (1.0f + scv.y) + shv.y;
;             const float o2 = v[i].z * rstd * gg.z * (1.0f + scv.z) + shv.z, o3 = v[i].w * rstd * gg.w * (1.0f + scv.w) + shv.w;
;             uint2 w; w.x = pk2(o0, o1); w.y = pk2(o2, o3);
;             *(uint2*)(A + (size_t)row * 1024 + k) = w;
;         }
	v_add_f32_e32 v204, v204, v205
	v_mov_b32_e32 v205, v204
	s_nop 1
	v_permlane32_swap_b32_e32 v204, v205
	v_add_f32_e32 v204, v204, v205
	v_mov_b32_e32 v205, 0x358637bd
	v_fmamk_f32 v204, v204, 0x3a800000, v205
	v_rsq_f32_e32 v204, v204
	s_nop 0
	v_pk_mul_f32 v[96:97], v[96:97], v[204:205] op_sel_hi:[1,0]
	v_pk_mul_f32 v[98:99], v[98:99], v[204:205] op_sel_hi:[1,0]
	v_pk_mul_f32 v[96:97], v[188:189], v[96:97]
	v_pk_mul_f32 v[98:99], v[190:191], v[98:99]
	v_pk_fma_f32 v[96:97], v[34:35], v[96:97], v[224:225]
	v_pk_fma_f32 v[98:99], v[36:37], v[98:99], v[226:227]
	v_cvt_pk_bf16_f32 v96, v96, v97
	v_cvt_pk_bf16_f32 v97, v98, v99
	global_store_dwordx2 v146, v[96:97], s[66:67] sc0 sc1
	v_pk_mul_f32 v[100:101], v[100:101], v[204:205] op_sel_hi:[1,0]
	v_pk_mul_f32 v[102:103], v[102:103], v[204:205] op_sel_hi:[1,0]
	v_pk_mul_f32 v[100:101], v[192:193], v[100:101]
	v_pk_mul_f32 v[102:103], v[194:195], v[102:103]
	v_pk_fma_f32 v[100:101], v[38:39], v[100:101], v[228:229]
	v_pk_fma_f32 v[102:103], v[40:41], v[102:103], v[230:231]
	v_cvt_pk_bf16_f32 v100, v100, v101
	v_cvt_pk_bf16_f32 v101, v102, v103
	global_store_dwordx2 v146, v[100:101], s[66:67] offset:512 sc0 sc1
	v_pk_mul_f32 v[104:105], v[104:105], v[204:205] op_sel_hi:[1,0]
	v_pk_mul_f32 v[106:107], v[106:107], v[204:205] op_sel_hi:[1,0]
	v_pk_mul_f32 v[104:105], v[196:197], v[104:105]
	v_pk_mul_f32 v[106:107], v[198:199], v[106:107]
	v_pk_fma_f32 v[104:105], v[42:43], v[104:105], v[232:233]
	v_pk_fma_f32 v[106:107], v[44:45], v[106:107], v[234:235]
	v_cvt_pk_bf16_f32 v104, v104, v105
	v_cvt_pk_bf16_f32 v105, v106, v107
	global_store_dwordx2 v146, v[104:105], s[66:67] offset:1024 sc0 sc1
	v_pk_mul_f32 v[108:109], v[108:109], v[204:205] op_sel_hi:[1,0]
	v_pk_mul_f32 v[110:111], v[110:111], v[204:205] op_sel_hi:[1,0]
	v_pk_mul_f32 v[108:109], v[200:201], v[108:109]
	v_pk_mul_f32 v[110:111], v[202:203], v[110:111]
	v_pk_fma_f32 v[108:109], v[46:47], v[108:109], v[236:237]
	v_pk_fma_f32 v[110:111], v[48:49], v[110:111], v[238:239]
	v_cvt_pk_bf16_f32 v108, v108, v109
	v_cvt_pk_bf16_f32 v109, v110, v111
	global_store_dwordx2 v146, v[108:109], s[66:67] offset:1536 sc0 sc1
	v_add_u32_e32 v146, 0x800, v146
	global_load_dwordx4 v[96:99], v144, s[46:47] nt
	global_load_dwordx4 v[100:103], v144, s[46:47] offset:1024 nt
	global_load_dwordx4 v[104:107], v144, s[46:47] offset:2048 nt
	global_load_dwordx4 v[108:111], v144, s[46:47] offset:3072 nt
	v_add_u32_e32 v144, 0x1000, v144
	s_waitcnt vmcnt(40)
	v_pk_mul_f32 v[242:243], v[112:113], v[112:113]
	v_pk_mul_f32 v[244:245], v[116:117], v[116:117]
	v_pk_mul_f32 v[246:247], v[114:115], v[114:115]
	v_pk_mul_f32 v[248:249], v[118:119], v[118:119]
	v_add_f32_e32 v204, v245, v244
	v_add_f32_e32 v205, v243, v242
	v_add_f32_e32 v204, v248, v204
	v_add_f32_e32 v205, v246, v205
	v_add_f32_e32 v204, v249, v204
	v_add_f32_e32 v205, v247, v205
	v_pk_mul_f32 v[242:243], v[120:121], v[120:121]
	v_pk_mul_f32 v[244:245], v[124:125], v[124:125]
	v_pk_mul_f32 v[246:247], v[122:123], v[122:123]
	v_pk_mul_f32 v[248:249], v[126:127], v[126:127]
	v_add_f32_e32 v206, v243, v242
	v_add_f32_e32 v207, v245, v244
	v_add_f32_e32 v206, v246, v206
	v_add_f32_e32 v207, v248, v207
	v_add_f32_e32 v206, v247, v206
	v_add_f32_e32 v207, v249, v207
	v_add_f32_e32 v204, v205, v204
	v_add_f32_e32 v204, v204, v206
	v_add_f32_e32 v204, v204, v207
	ds_swizzle_b32 v205, v204 offset:swizzle(SWAP,1)
	s_waitcnt lgkmcnt(0)
	v_add_f32_e32 v204, v204, v205
	ds_swizzle_b32 v205, v204 offset:swizzle(SWAP,2)
	s_waitcnt lgkmcnt(0)
	v_add_f32_e32 v204, v204, v205
	ds_swizzle_b32 v205, v204 offset:swizzle(SWAP,4)
	s_waitcnt lgkmcnt(0)
	v_add_f32_e32 v204, v204, v205
	ds_swizzle_b32 v205, v204 offset:swizzle(SWAP,8)
	s_waitcnt lgkmcnt(0)
	v_add_f32_e32 v204, v204, v205
	ds_swizzle_b32 v205, v204 offset:swizzle(SWAP,16)
	s_waitcnt lgkmcnt(0)
	v_add_f32_e32 v204, v204, v205
	v_mov_b32_e32 v205, v204
	s_nop 1
	v_permlane32_swap_b32_e32 v204, v205
	v_add_f32_e32 v204, v204, v205
	v_mov_b32_e32 v205, 0x358637bd
	v_fmamk_f32 v204, v204, 0x3a800000, v205
	v_rsq_f32_e32 v204, v204
	s_nop 0
	v_pk_mul_f32 v[112:113], v[112:113], v[204:205] op_sel_hi:[1,0]
	v_pk_mul_f32 v[114:115], v[114:115], v[204:205] op_sel_hi:[1,0]
	v_pk_mul_f32 v[112:113], v[188:189], v[112:113]
	v_pk_mul_f32 v[114:115], v[190:191], v[114:115]
	v_pk_fma_f32 v[112:113], v[34:35], v[112:113], v[224:225]
	v_pk_fma_f32 v[114:115], v[36:37], v[114:115], v[226:227]
	v_cvt_pk_bf16_f32 v112, v112, v113
	v_cvt_pk_bf16_f32 v113, v114, v115
	global_store_dwordx2 v146, v[112:113], s[66:67] sc0 sc1
	v_pk_mul_f32 v[116:117], v[116:117], v[204:205] op_sel_hi:[1,0]
	v_pk_mul_f32 v[118:119], v[118:119], v[204:205] op_sel_hi:[1,0]
	v_pk_mul_f32 v[116:117], v[192:193], v[116:117]
	v_pk_mul_f32 v[118:119], v[194:195], v[118:119]
	v_pk_fma_f32 v[116:117], v[38:39], v[116:117], v[228:229]
	v_pk_fma_f32 v[118:119], v[40:41], v[118:119], v[230:231]
	v_cvt_pk_bf16_f32 v116, v116, v117
	v_cvt_pk_bf16_f32 v117, v118, v119
	global_store_dwordx2 v146, v[116:117], s[66:67] offset:512 sc0 sc1
	v_pk_mul_f32 v[120:121], v[120:121], v[204:205] op_sel_hi:[1,0]
	v_pk_mul_f32 v[122:123], v[122:123], v[204:205] op_sel_hi:[1,0]
	v_pk_mul_f32 v[120:121], v[196:197], v[120:121]
	v_pk_mul_f32 v[122:123], v[198:199], v[122:123]
	v_pk_fma_f32 v[120:121], v[42:43], v[120:121], v[232:233]
	v_pk_fma_f32 v[122:123], v[44:45], v[122:123], v[234:235]
	v_cvt_pk_bf16_f32 v120, v120, v121
	v_cvt_pk_bf16_f32 v121, v122, v123
	global_store_dwordx2 v146, v[120:121], s[66:67] offset:1024 sc0 sc1
	v_pk_mul_f32 v[124:125], v[124:125], v[204:205] op_sel_hi:[1,0]
	v_pk_mul_f32 v[126:127], v[126:127], v[204:205] op_sel_hi:[1,0]
	v_pk_mul_f32 v[124:125], v[200:201], v[124:125]
	v_pk_mul_f32 v[126:127], v[202:203], v[126:127]
	v_pk_fma_f32 v[124:125], v[46:47], v[124:125], v[236:237]
	v_pk_fma_f32 v[126:127], v[48:49], v[126:127], v[238:239]
	v_cvt_pk_bf16_f32 v124, v124, v125
	v_cvt_pk_bf16_f32 v125, v126, v127
	global_store_dwordx2 v146, v[124:125], s[66:67] offset:1536 sc0 sc1
	v_add_u32_e32 v146, 0x800, v146
	global_load_dwordx4 v[112:115], v144, s[46:47] nt
	global_load_dwordx4 v[116:119], v144, s[46:47] offset:1024 nt
	global_load_dwordx4 v[120:123], v144, s[46:47] offset:2048 nt
	global_load_dwordx4 v[124:127], v144, s[46:47] offset:3072 nt
	v_add_u32_e32 v144, 0x1000, v144
	s_waitcnt vmcnt(40)
; __device__ __forceinline__ unsigned pk2(float lo, float hi) { const g_f32x2 f = {lo, hi}; return __builtin_bit_cast(unsigned, __builtin_convertvector(f, g_bf16x2)); }
; __device__ __forceinline__ void p_norm(const float* hlat, const float* hctx, const float* g, const float* modl, int sh_off, int sc_off, bf16_t* A, int M,
;                                        const float* part, const float* cgate, float* hcout) {
;     ...
;         float ss = 0.f;
; #pragma unroll
;         for (int i = 0; i < 4; ++i) {
;             if (part != nullptr && row >= NLAT) {
;                 const size_t po = (size_t)(row - NLAT) * 1024 + i * 256 + lane * 4;
;                 const float4 p0 = *(const float4*)(part + po), p1 = *(const float4*)(part + (size_t)4096 * 1024 + po), cg = *(const float4*)(cgate + i * 256 + lane * 4);
;                 v[i].x += cg.x * (p0.x + p1.x); v[i].y += cg.y * (p0.y + p1.y); v[i].z += cg.z * (p0.z + p1.z); v[i].w += cg.w * (p0.w + p1.w);
;                 *(float4*)(hcout + po) = v[i];
;             }
;             ss += v[i].x * v[i].x + v[i].y * v[i].y + v[i].z * v[i].z + v[i].w * v[i].w; }
;         ss = wave_sum(ss);
;         const float rstd = rsqrtf(ss * (1.0f / 1024.0f) + EPS);
;         const float* mr = modl + (size_t)r * 6144;
; #pragma unroll
;         for (int i = 0; i < 4; ++i) {
;             const int k = i * 256 + lane * 4;
;             const float4 gg = *(const float4*)(g + k), scv = *(const float4*)(mr + sc_off + k), shv = *(const float4*)(mr + sh_off + k);
;             const float o0 = v[i].x * rstd * gg.x * (1.0f + scv.x) + shv.x, o1 = v[i].y * rstd * gg.y * (1.0f + scv.y) + shv.y;
;             const float o2 = v[i].z * rstd * gg.z * (1.0f + scv.z) + shv.z, o3 = v[i].w * rstd * gg.w * (1.0f + scv.w) + shv.w;
;             uint2 w; w.x = pk2(o0, o1); w.y = pk2(o2, o3);
;             *(uint2*)(A + (size_t)row * 1024 + k) = w;
;         }
	v_pk_mul_f32 v[242:243], v[128:129], v[128:129]
	v_pk_mul_f32 v[244:245], v[132:133], v[132:133]
	v_pk_mul_f32 v[246:247], v[130:131], v[130:131]
	v_pk_mul_f32 v[248:249], v[134:135], v[134:135]
	v_add_f32_e32 v204, v245, v244
	v_add_f32_e32 v205, v243, v242
	v_add_f32_e32 v204, v248, v204
	v_add_f32_e32 v205, v246, v205
	v_add_f32_e32 v204, v249, v204
	v_add_f32_e32 v205, v247, v205
	v_pk_mul_f32 v[242:243], v[136:137], v[136:137]
	v_pk_mul_f32 v[244:245], v[140:141], v[140:141]
	v_pk_mul_f32 v[246:247], v[138:139], v[138:139]
	v_pk_mul_f32 v[248:249], v[142:143], v[142:143]
	v_add_f32_e32 v206, v243, v242
	v_add_f32_e32 v207, v245, v244
	v_add_f32_e32 v206, v246, v206
	v_add_f32_e32 v207, v248, v207
	v_add_f32_e32 v206, v247, v206
	v_add_f32_e32 v207, v249, v207
	v_add_f32_e32 v204, v205, v204
	v_add_f32_e32 v204, v204, v206
	v_add_f32_e32 v204, v204, v207
	ds_swizzle_b32 v205, v204 offset:swizzle(SWAP,1)
	s_waitcnt lgkmcnt(0)
	v_add_f32_e32 v204, v204, v205
	ds_swizzle_b32 v205, v204 offset:swizzle(SWAP,2)
	s_waitcnt lgkmcnt(0)
	v_add_f32_e32 v204, v204, v205
	ds_swizzle_b32 v205, v204 offset:swizzle(SWAP,4)
	s_waitcnt lgkmcnt(0)
	v_add_f32_e32 v204, v204, v205
	ds_swizzle_b32 v205, v204 offset:swizzle(SWAP,8)
	s_waitcnt lgkmcnt(0)
	v_add_f32_e32 v204, v204, v205
	ds_swizzle_b32 v205, v204 offset:swizzle(SWAP,16)
	s_waitcnt lgkmcnt(0)
	v_add_f32_e32 v204, v204, v205
	v_mov_b32_e32 v205, v204
	s_nop 1
	v_permlane32_swap_b32_e32 v204, v205
	v_add_f32_e32 v204, v204, v205
	v_mov_b32_e32 v205, 0x358637bd
	v_fmamk_f32 v204, v204, 0x3a800000, v205
	v_rsq_f32_e32 v204, v204
	s_nop 0
	v_pk_mul_f32 v[128:129], v[128:129], v[204:205] op_sel_hi:[1,0]
	v_pk_mul_f32 v[130:131], v[130:131], v[204:205] op_sel_hi:[1,0]
	v_pk_mul_f32 v[128:129], v[188:189], v[128:129]
	v_pk_mul_f32 v[130:131], v[190:191], v[130:131]
	v_pk_fma_f32 v[128:129], v[34:35], v[128:129], v[224:225]
	v_pk_fma_f32 v[130:131], v[36:37], v[130:131], v[226:227]
	v_cvt_pk_bf16_f32 v128, v128, v129
	v_cvt_pk_bf16_f32 v129, v130, v131
	global_store_dwordx2 v146, v[128:129], s[66:67] sc0 sc1
	v_pk_mul_f32 v[132:133], v[132:133], v[204:205] op_sel_hi:[1,0]
	v_pk_mul_f32 v[134:135], v[134:135], v[204:205] op_sel_hi:[1,0]
	v_pk_mul_f32 v[132:133], v[192:193], v[132:133]
	v_pk_mul_f32 v[134:135], v[194:195], v[134:135]
	v_pk_fma_f32 v[132:133], v[38:39], v[132:133], v[228:229]
	v_pk_fma_f32 v[134:135], v[40:41], v[134:135], v[230:231]
	v_cvt_pk_bf16_f32 v132, v132, v133
	v_cvt_pk_bf16_f32 v133, v134, v135
	global_store_dwordx2 v146, v[132:133], s[66:67] offset:512 sc0 sc1
	v_pk_mul_f32 v[136:137], v[136:137], v[204:205] op_sel_hi:[1,0]
	v_pk_mul_f32 v[138:139], v[138:139], v[204:205] op_sel_hi:[1,0]
	v_pk_mul_f32 v[136:137], v[196:197], v[136:137]
	v_pk_mul_f32 v[138:139], v[198:199], v[138:139]
	v_pk_fma_f32 v[136:137], v[42:43], v[136:137], v[232:233]
	v_pk_fma_f32 v[138:139], v[44:45], v[138:139], v[234:235]
	v_cvt_pk_bf16_f32 v136, v136, v137
	v_cvt_pk_bf16_f32 v137, v138, v139
	global_store_dwordx2 v146, v[136:137], s[66:67] offset:1024 sc0 sc1
	v_pk_mul_f32 v[140:141], v[140:141], v[204:205] op_sel_hi:[1,0]
	v_pk_mul_f32 v[142:143], v[142:143], v[204:205] op_sel_hi:[1,0]
	v_pk_mul_f32 v[140:141], v[200:201], v[140:141]
	v_pk_mul_f32 v[142:143], v[202:203], v[142:143]
	v_pk_fma_f32 v[140:141], v[46:47], v[140:141], v[236:237]
	v_pk_fma_f32 v[142:143], v[48:49], v[142:143], v[238:239]
	v_cvt_pk_bf16_f32 v140, v140, v141
	v_cvt_pk_bf16_f32 v141, v142, v143
	global_store_dwordx2 v146, v[140:141], s[66:67] offset:1536 sc0 sc1
	v_add_u32_e32 v146, 0x800, v146
	global_load_dwordx4 v[128:131], v144, s[46:47] nt
	global_load_dwordx4 v[132:135], v144, s[46:47] offset:1024 nt
	global_load_dwordx4 v[136:139], v144, s[46:47] offset:2048 nt
	global_load_dwordx4 v[140:143], v144, s[46:47] offset:3072 nt
	v_add_u32_e32 v144, 0x1000, v144
	s_waitcnt vmcnt(40)
	v_pk_mul_f32 v[242:243], v[156:157], v[156:157]
	v_pk_mul_f32 v[244:245], v[160:161], v[160:161]
	v_pk_mul_f32 v[246:247], v[158:159], v[158:159]
	v_pk_mul_f32 v[248:249], v[162:163], v[162:163]
	v_add_f32_e32 v204, v245, v244
	v_add_f32_e32 v205, v243, v242
	v_add_f32_e32 v204, v248, v204
	v_add_f32_e32 v205, v246, v205
	v_add_f32_e32 v204, v249, v204
	v_add_f32_e32 v205, v247, v205
	v_pk_mul_f32 v[242:243], v[164:165], v[164:165]
	v_pk_mul_f32 v[244:245], v[168:169], v[168:169]
	v_pk_mul_f32 v[246:247], v[166:167], v[166:167]
	v_pk_mul_f32 v[248:249], v[170:171], v[170:171]
	v_add_f32_e32 v206, v243, v242
	v_add_f32_e32 v207, v245, v244
	v_add_f32_e32 v206, v246, v206
	v_add_f32_e32 v207, v248, v207
	v_add_f32_e32 v206, v247, v206
	v_add_f32_e32 v207, v249, v207
	v_add_f32_e32 v204, v205, v204
	v_add_f32_e32 v204, v204, v206
	v_add_f32_e32 v204, v204, v207
	ds_swizzle_b32 v205, v204 offset:swizzle(SWAP,1)
	s_waitcnt lgkmcnt(0)
	v_add_f32_e32 v204, v204, v205
	ds_swizzle_b32 v205, v204 offset:swizzle(SWAP,2)
	s_waitcnt lgkmcnt(0)
	v_add_f32_e32 v204, v204, v205
	ds_swizzle_b32 v205, v204 offset:swizzle(SWAP,4)
	s_waitcnt lgkmcnt(0)
	v_add_f32_e32 v204, v204, v205
	ds_swizzle_b32 v205, v204 offset:swizzle(SWAP,8)
	s_waitcnt lgkmcnt(0)
	v_add_f32_e32 v204, v204, v205
	ds_swizzle_b32 v205, v204 offset:swizzle(SWAP,16)
	s_waitcnt lgkmcnt(0)
; __device__ __forceinline__ unsigned pk2(float lo, float hi) { const g_f32x2 f = {lo, hi}; return __builtin_bit_cast(unsigned, __builtin_convertvector(f, g_bf16x2)); }
; #define PN_LOAD(dst, rw) do { const float* s_ = (rw) < NLAT ? hlat + (size_t)(rw) * 1024 : hctx + (size_t)((rw) - NLAT) * 1024; \
;         _Pragma("unroll") for (int i = 0; i < 4; ++i) dst[i] = *(const float4*)(s_ + i * 256 + lane * 4); } while (0)
; __device__ __forceinline__ void p_norm(const float* hlat, const float* hctx, const float* g, const float* modl, int sh_off, int sc_off, bf16_t* A, int M,
;                                        const float* part, const float* cgate, float* hcout) {
;     ...
;     if (row < M) PN_LOAD(v, row);
;     while (row < M) {
;         const int nrow = row + stride;
;         if (nrow < M) PN_LOAD(nv, nrow);
;     ...
;         float ss = 0.f;
; #pragma unroll
;         for (int i = 0; i < 4; ++i) {
;             if (part != nullptr && row >= NLAT) {
;                 const size_t po = (size_t)(row - NLAT) * 1024 + i * 256 + lane * 4;
;                 const float4 p0 = *(const float4*)(part + po), p1 = *(const float4*)(part + (size_t)4096 * 1024 + po), cg = *(const float4*)(cgate + i * 256 + lane * 4);
;                 v[i].x += cg.x * (p0.x + p1.x); v[i].y += cg.y * (p0.y + p1.y); v[i].z += cg.z * (p0.z + p1.z); v[i].w += cg.w * (p0.w + p1.w);
;                 *(float4*)(hcout + po) = v[i];
;             }
;             ss += v[i].x * v[i].x + v[i].y * v[i].y + v[i].z * v[i].z + v[i].w * v[i].w; }
;         ss = wave_sum(ss);
;         const float rstd = rsqrtf(ss * (1.0f / 1024.0f) + EPS);
;         const float* mr = modl + (size_t)r * 6144;
; #pragma unroll
;         for (int i = 0; i < 4; ++i) {
;             const int k = i * 256 + lane * 4;
;             const float4 gg = *(const float4*)(g + k), scv = *(const float4*)(mr + sc_off + k), shv = *(const float4*)(mr + sh_off + k);
;             const float o0 = v[i].x * rstd * gg.x * (1.0f + scv.x) + shv.x, o1 = v[i].y * rstd * gg.y * (1.0f + scv.y) + shv.y;
;             const float o2 = v[i].z * rstd * gg.z * (1.0f + scv.z) + shv.z, o3 = v[i].w * rstd * gg.w * (1.0f + scv.w) + shv.w;
;             uint2 w; w.x = pk2(o0, o1); w.y = pk2(o2, o3);
;             *(uint2*)(A + (size_t)row * 1024 + k) = w;
;         }
	v_add_f32_e32 v204, v204, v205
	v_mov_b32_e32 v205, v204
	s_nop 1
	v_permlane32_swap_b32_e32 v204, v205
	v_add_f32_e32 v204, v204, v205
	v_mov_b32_e32 v205, 0x358637bd
	v_fmamk_f32 v204, v204, 0x3a800000, v205
	v_rsq_f32_e32 v204, v204
	s_nop 0
	v_pk_mul_f32 v[156:157], v[156:157], v[204:205] op_sel_hi:[1,0]
	v_pk_mul_f32 v[158:159], v[158:159], v[204:205] op_sel_hi:[1,0]
	v_pk_mul_f32 v[156:157], v[188:189], v[156:157]
	v_pk_mul_f32 v[158:159], v[190:191], v[158:159]
	v_pk_fma_f32 v[156:157], v[34:35], v[156:157], v[224:225]
	v_pk_fma_f32 v[158:159], v[36:37], v[158:159], v[226:227]
	v_cvt_pk_bf16_f32 v156, v156, v157
	v_cvt_pk_bf16_f32 v157, v158, v159
	global_store_dwordx2 v146, v[156:157], s[66:67] sc0 sc1
	v_pk_mul_f32 v[160:161], v[160:161], v[204:205] op_sel_hi:[1,0]
	v_pk_mul_f32 v[162:163], v[162:163], v[204:205] op_sel_hi:[1,0]
	v_pk_mul_f32 v[160:161], v[192:193], v[160:161]
	v_pk_mul_f32 v[162:163], v[194:195], v[162:163]
	v_pk_fma_f32 v[160:161], v[38:39], v[160:161], v[228:229]
	v_pk_fma_f32 v[162:163], v[40:41], v[162:163], v[230:231]
	v_cvt_pk_bf16_f32 v160, v160, v161
	v_cvt_pk_bf16_f32 v161, v162, v163
	global_store_dwordx2 v146, v[160:161], s[66:67] offset:512 sc0 sc1
	v_pk_mul_f32 v[164:165], v[164:165], v[204:205] op_sel_hi:[1,0]
	v_pk_mul_f32 v[166:167], v[166:167], v[204:205] op_sel_hi:[1,0]
	v_pk_mul_f32 v[164:165], v[196:197], v[164:165]
	v_pk_mul_f32 v[166:167], v[198:199], v[166:167]
	v_pk_fma_f32 v[164:165], v[42:43], v[164:165], v[232:233]
	v_pk_fma_f32 v[166:167], v[44:45], v[166:167], v[234:235]
	v_cvt_pk_bf16_f32 v164, v164, v165
	v_cvt_pk_bf16_f32 v165, v166, v167
	global_store_dwordx2 v146, v[164:165], s[66:67] offset:1024 sc0 sc1
	v_pk_mul_f32 v[168:169], v[168:169], v[204:205] op_sel_hi:[1,0]
	v_pk_mul_f32 v[170:171], v[170:171], v[204:205] op_sel_hi:[1,0]
	v_pk_mul_f32 v[168:169], v[200:201], v[168:169]
	v_pk_mul_f32 v[170:171], v[202:203], v[170:171]
	v_pk_fma_f32 v[168:169], v[46:47], v[168:169], v[236:237]
	v_pk_fma_f32 v[170:171], v[48:49], v[170:171], v[238:239]
	v_cvt_pk_bf16_f32 v168, v168, v169
	v_cvt_pk_bf16_f32 v169, v170, v171
	global_store_dwordx2 v146, v[168:169], s[66:67] offset:1536 sc0 sc1
	v_add_u32_e32 v146, 0x800, v146
	v_lshl_add_u32 v144, v50, 13, v241
	v_mov_b32_e32 v152, v144
	v_add_u32_e32 v150, 0x1000000, v144
	global_load_dwordx4 v[156:159], v144, s[16:17]
	global_load_dwordx4 v[160:163], v144, s[16:17] offset:1024
	global_load_dwordx4 v[164:167], v144, s[16:17] offset:2048
	global_load_dwordx4 v[168:171], v144, s[16:17] offset:3072
	v_add_u32_e32 v144, 0x1000, v144
	s_waitcnt vmcnt(40)
	v_pk_mul_f32 v[242:243], v[172:173], v[172:173]
	v_pk_mul_f32 v[244:245], v[176:177], v[176:177]
	v_pk_mul_f32 v[246:247], v[174:175], v[174:175]
	v_pk_mul_f32 v[248:249], v[178:179], v[178:179]
	v_add_f32_e32 v204, v245, v244
	v_add_f32_e32 v205, v243, v242
	v_add_f32_e32 v204, v248, v204
	v_add_f32_e32 v205, v246, v205
	v_add_f32_e32 v204, v249, v204
	v_add_f32_e32 v205, v247, v205
	v_pk_mul_f32 v[242:243], v[180:181], v[180:181]
	v_pk_mul_f32 v[244:245], v[184:185], v[184:185]
	v_pk_mul_f32 v[246:247], v[182:183], v[182:183]
	v_pk_mul_f32 v[248:249], v[186:187], v[186:187]
	v_add_f32_e32 v206, v243, v242
	v_add_f32_e32 v207, v245, v244
	v_add_f32_e32 v206, v246, v206
	v_add_f32_e32 v207, v248, v207
	v_add_f32_e32 v206, v247, v206
	v_add_f32_e32 v207, v249, v207
	v_add_f32_e32 v204, v205, v204
	v_add_f32_e32 v204, v204, v206
	v_add_f32_e32 v204, v204, v207
	ds_swizzle_b32 v205, v204 offset:swizzle(SWAP,1)
	s_waitcnt lgkmcnt(0)
	v_add_f32_e32 v204, v204, v205
	ds_swizzle_b32 v205, v204 offset:swizzle(SWAP,2)
	s_waitcnt lgkmcnt(0)
	v_add_f32_e32 v204, v204, v205
	ds_swizzle_b32 v205, v204 offset:swizzle(SWAP,4)
	s_waitcnt lgkmcnt(0)
	v_add_f32_e32 v204, v204, v205
	ds_swizzle_b32 v205, v204 offset:swizzle(SWAP,8)
	s_waitcnt lgkmcnt(0)
	v_add_f32_e32 v204, v204, v205
	ds_swizzle_b32 v205, v204 offset:swizzle(SWAP,16)
	s_waitcnt lgkmcnt(0)
	v_add_f32_e32 v204, v204, v205
	v_mov_b32_e32 v205, v204
	s_nop 1
	v_permlane32_swap_b32_e32 v204, v205
	v_add_f32_e32 v204, v204, v205
	v_mov_b32_e32 v205, 0x358637bd
	v_fmamk_f32 v204, v204, 0x3a800000, v205
	v_rsq_f32_e32 v204, v204
	s_nop 0
	v_pk_mul_f32 v[172:173], v[172:173], v[204:205] op_sel_hi:[1,0]
	v_pk_mul_f32 v[174:175], v[174:175], v[204:205] op_sel_hi:[1,0]
	v_pk_mul_f32 v[172:173], v[188:189], v[172:173]
	v_pk_mul_f32 v[174:175], v[190:191], v[174:175]
	v_pk_fma_f32 v[172:173], v[34:35], v[172:173], v[224:225]
	v_pk_fma_f32 v[174:175], v[36:37], v[174:175], v[226:227]
	v_cvt_pk_bf16_f32 v172, v172, v173
	v_cvt_pk_bf16_f32 v173, v174, v175
	global_store_dwordx2 v146, v[172:173], s[66:67] sc0 sc1
	v_pk_mul_f32 v[176:177], v[176:177], v[204:205] op_sel_hi:[1,0]
	v_pk_mul_f32 v[178:179], v[178:179], v[204:205] op_sel_hi:[1,0]
	v_pk_mul_f32 v[176:177], v[192:193], v[176:177]
	v_pk_mul_f32 v[178:179], v[194:195], v[178:179]
	v_pk_fma_f32 v[176:177], v[38:39], v[176:177], v[228:229]
	v_pk_fma_f32 v[178:179], v[40:41], v[178:179], v[230:231]
	v_cvt_pk_bf16_f32 v176, v176, v177
	v_cvt_pk_bf16_f32 v177, v178, v179
	global_store_dwordx2 v146, v[176:177], s[66:67] offset:512 sc0 sc1
	v_pk_mul_f32 v[180:181], v[180:181], v[204:205] op_sel_hi:[1,0]
	v_pk_mul_f32 v[182:183], v[182:183], v[204:205] op_sel_hi:[1,0]
	v_pk_mul_f32 v[180:181], v[196:197], v[180:181]
	v_pk_mul_f32 v[182:183], v[198:199], v[182:183]
	v_pk_fma_f32 v[180:181], v[42:43], v[180:181], v[232:233]
	v_pk_fma_f32 v[182:183], v[44:45], v[182:183], v[234:235]
	v_cvt_pk_bf16_f32 v180, v180, v181
	v_cvt_pk_bf16_f32 v181, v182, v183
	global_store_dwordx2 v146, v[180:181], s[66:67] offset:1024 sc0 sc1
	v_pk_mul_f32 v[184:185], v[184:185], v[204:205] op_sel_hi:[1,0]
	v_pk_mul_f32 v[186:187], v[186:187], v[204:205] op_sel_hi:[1,0]
	v_pk_mul_f32 v[184:185], v[200:201], v[184:185]
	v_pk_mul_f32 v[186:187], v[202:203], v[186:187]
	v_pk_fma_f32 v[184:185], v[46:47], v[184:185], v[236:237]
	v_pk_fma_f32 v[186:187], v[48:49], v[186:187], v[238:239]
	v_cvt_pk_bf16_f32 v184, v184, v185
	v_cvt_pk_bf16_f32 v185, v186, v187
	global_store_dwordx2 v146, v[184:185], s[66:67] offset:1536 sc0 sc1
	v_add_u32_e32 v146, 0x800, v146
	global_load_dwordx4 v[172:175], v144, s[16:17]
	global_load_dwordx4 v[176:179], v144, s[16:17] offset:1024
	global_load_dwordx4 v[180:183], v144, s[16:17] offset:2048
	global_load_dwordx4 v[184:187], v144, s[16:17] offset:3072
	v_add_u32_e32 v144, 0x1000, v144
	s_waitcnt vmcnt(40)
; __device__ __forceinline__ unsigned pk2(float lo, float hi) { const g_f32x2 f = {lo, hi}; return __builtin_bit_cast(unsigned, __builtin_convertvector(f, g_bf16x2)); }
; __device__ __forceinline__ void p_norm(const float* hlat, const float* hctx, const float* g, const float* modl, int sh_off, int sc_off, bf16_t* A, int M,
;                                        const float* part, const float* cgate, float* hcout) {
;     ...
;         float ss = 0.f;
; #pragma unroll
;         for (int i = 0; i < 4; ++i) {
;             if (part != nullptr && row >= NLAT) {
;                 const size_t po = (size_t)(row - NLAT) * 1024 + i * 256 + lane * 4;
;                 const float4 p0 = *(const float4*)(part + po), p1 = *(const float4*)(part + (size_t)4096 * 1024 + po), cg = *(const float4*)(cgate + i * 256 + lane * 4);
;                 v[i].x += cg.x * (p0.x + p1.x); v[i].y += cg.y * (p0.y + p1.y); v[i].z += cg.z * (p0.z + p1.z); v[i].w += cg.w * (p0.w + p1.w);
;                 *(float4*)(hcout + po) = v[i];
;             }
;             ss += v[i].x * v[i].x + v[i].y * v[i].y + v[i].z * v[i].z + v[i].w * v[i].w; }
;         ss = wave_sum(ss);
;         const float rstd = rsqrtf(ss * (1.0f / 1024.0f) + EPS);
;         const float* mr = modl + (size_t)r * 6144;
; #pragma unroll
;         for (int i = 0; i < 4; ++i) {
;             const int k = i * 256 + lane * 4;
;             const float4 gg = *(const float4*)(g + k), scv = *(const float4*)(mr + sc_off + k), shv = *(const float4*)(mr + sh_off + k);
;             const float o0 = v[i].x * rstd * gg.x * (1.0f + scv.x) + shv.x, o1 = v[i].y * rstd * gg.y * (1.0f + scv.y) + shv.y;
;             const float o2 = v[i].z * rstd * gg.z * (1.0f + scv.z) + shv.z, o3 = v[i].w * rstd * gg.w * (1.0f + scv.w) + shv.w;
;             uint2 w; w.x = pk2(o0, o1); w.y = pk2(o2, o3);
;             *(uint2*)(A + (size_t)row * 1024 + k) = w;
;         }
	v_pk_mul_f32 v[242:243], v[80:81], v[80:81]
	v_pk_mul_f32 v[244:245], v[84:85], v[84:85]
	v_pk_mul_f32 v[246:247], v[82:83], v[82:83]
	v_pk_mul_f32 v[248:249], v[86:87], v[86:87]
	v_add_f32_e32 v204, v245, v244
	v_add_f32_e32 v205, v243, v242
	v_add_f32_e32 v204, v248, v204
	v_add_f32_e32 v205, v246, v205
	v_add_f32_e32 v204, v249, v204
	v_add_f32_e32 v205, v247, v205
	v_pk_mul_f32 v[242:243], v[88:89], v[88:89]
	v_pk_mul_f32 v[244:245], v[92:93], v[92:93]
	v_pk_mul_f32 v[246:247], v[90:91], v[90:91]
	v_pk_mul_f32 v[248:249], v[94:95], v[94:95]
	v_add_f32_e32 v206, v243, v242
	v_add_f32_e32 v207, v245, v244
	v_add_f32_e32 v206, v246, v206
	v_add_f32_e32 v207, v248, v207
	v_add_f32_e32 v206, v247, v206
	v_add_f32_e32 v207, v249, v207
	v_add_f32_e32 v204, v205, v204
	v_add_f32_e32 v204, v204, v206
	v_add_f32_e32 v204, v204, v207
	ds_swizzle_b32 v205, v204 offset:swizzle(SWAP,1)
	s_waitcnt lgkmcnt(0)
	v_add_f32_e32 v204, v204, v205
	ds_swizzle_b32 v205, v204 offset:swizzle(SWAP,2)
	s_waitcnt lgkmcnt(0)
	v_add_f32_e32 v204, v204, v205
	ds_swizzle_b32 v205, v204 offset:swizzle(SWAP,4)
	s_waitcnt lgkmcnt(0)
	v_add_f32_e32 v204, v204, v205
	ds_swizzle_b32 v205, v204 offset:swizzle(SWAP,8)
	s_waitcnt lgkmcnt(0)
	v_add_f32_e32 v204, v204, v205
	ds_swizzle_b32 v205, v204 offset:swizzle(SWAP,16)
	s_waitcnt lgkmcnt(0)
	v_add_f32_e32 v204, v204, v205
	v_mov_b32_e32 v205, v204
	s_nop 1
	v_permlane32_swap_b32_e32 v204, v205
	v_add_f32_e32 v204, v204, v205
	v_mov_b32_e32 v205, 0x358637bd
	v_fmamk_f32 v204, v204, 0x3a800000, v205
	v_rsq_f32_e32 v204, v204
	s_nop 0
	v_pk_mul_f32 v[80:81], v[80:81], v[204:205] op_sel_hi:[1,0]
	v_pk_mul_f32 v[82:83], v[82:83], v[204:205] op_sel_hi:[1,0]
	v_pk_mul_f32 v[80:81], v[188:189], v[80:81]
	v_pk_mul_f32 v[82:83], v[190:191], v[82:83]
	v_pk_fma_f32 v[80:81], v[34:35], v[80:81], v[224:225]
	v_pk_fma_f32 v[82:83], v[36:37], v[82:83], v[226:227]
	v_cvt_pk_bf16_f32 v80, v80, v81
	v_cvt_pk_bf16_f32 v81, v82, v83
	global_store_dwordx2 v146, v[80:81], s[66:67] sc0 sc1
	v_pk_mul_f32 v[84:85], v[84:85], v[204:205] op_sel_hi:[1,0]
	v_pk_mul_f32 v[86:87], v[86:87], v[204:205] op_sel_hi:[1,0]
	v_pk_mul_f32 v[84:85], v[192:193], v[84:85]
	v_pk_mul_f32 v[86:87], v[194:195], v[86:87]
	v_pk_fma_f32 v[84:85], v[38:39], v[84:85], v[228:229]
	v_pk_fma_f32 v[86:87], v[40:41], v[86:87], v[230:231]
	v_cvt_pk_bf16_f32 v84, v84, v85
	v_cvt_pk_bf16_f32 v85, v86, v87
	global_store_dwordx2 v146, v[84:85], s[66:67] offset:512 sc0 sc1
	v_pk_mul_f32 v[88:89], v[88:89], v[204:205] op_sel_hi:[1,0]
	v_pk_mul_f32 v[90:91], v[90:91], v[204:205] op_sel_hi:[1,0]
	v_pk_mul_f32 v[88:89], v[196:197], v[88:89]
	v_pk_mul_f32 v[90:91], v[198:199], v[90:91]
	v_pk_fma_f32 v[88:89], v[42:43], v[88:89], v[232:233]
	v_pk_fma_f32 v[90:91], v[44:45], v[90:91], v[234:235]
	v_cvt_pk_bf16_f32 v88, v88, v89
	v_cvt_pk_bf16_f32 v89, v90, v91
	global_store_dwordx2 v146, v[88:89], s[66:67] offset:1024 sc0 sc1
	v_pk_mul_f32 v[92:93], v[92:93], v[204:205] op_sel_hi:[1,0]
	v_pk_mul_f32 v[94:95], v[94:95], v[204:205] op_sel_hi:[1,0]
	v_pk_mul_f32 v[92:93], v[200:201], v[92:93]
	v_pk_mul_f32 v[94:95], v[202:203], v[94:95]
	v_pk_fma_f32 v[92:93], v[46:47], v[92:93], v[236:237]
	v_pk_fma_f32 v[94:95], v[48:49], v[94:95], v[238:239]
	v_cvt_pk_bf16_f32 v92, v92, v93
	v_cvt_pk_bf16_f32 v93, v94, v95
	global_store_dwordx2 v146, v[92:93], s[66:67] offset:1536 sc0 sc1
	v_add_u32_e32 v146, 0x800, v146
	s_waitcnt vmcnt(36)
	v_pk_mul_f32 v[242:243], v[96:97], v[96:97]
	v_pk_mul_f32 v[244:245], v[100:101], v[100:101]
	v_pk_mul_f32 v[246:247], v[98:99], v[98:99]
	v_pk_mul_f32 v[248:249], v[102:103], v[102:103]
	v_add_f32_e32 v204, v245, v244
	v_add_f32_e32 v205, v243, v242
	v_add_f32_e32 v204, v248, v204
	v_add_f32_e32 v205, v246, v205
	v_add_f32_e32 v204, v249, v204
	v_add_f32_e32 v205, v247, v205
	v_pk_mul_f32 v[242:243], v[104:105], v[104:105]
	v_pk_mul_f32 v[244:245], v[108:109], v[108:109]
	v_pk_mul_f32 v[246:247], v[106:107], v[106:107]
	v_pk_mul_f32 v[248:249], v[110:111], v[110:111]
	v_add_f32_e32 v206, v243, v242
	v_add_f32_e32 v207, v245, v244
	v_add_f32_e32 v206, v246, v206
	v_add_f32_e32 v207, v248, v207
	v_add_f32_e32 v206, v247, v206
	v_add_f32_e32 v207, v249, v207
	v_add_f32_e32 v204, v205, v204
	v_add_f32_e32 v204, v204, v206
	v_add_f32_e32 v204, v204, v207
	ds_swizzle_b32 v205, v204 offset:swizzle(SWAP,1)
	s_waitcnt lgkmcnt(0)
	v_add_f32_e32 v204, v204, v205
	ds_swizzle_b32 v205, v204 offset:swizzle(SWAP,2)
	s_waitcnt lgkmcnt(0)
	v_add_f32_e32 v204, v204, v205
	ds_swizzle_b32 v205, v204 offset:swizzle(SWAP,4)
	s_waitcnt lgkmcnt(0)
	v_add_f32_e32 v204, v204, v205
	ds_swizzle_b32 v205, v204 offset:swizzle(SWAP,8)
	s_waitcnt lgkmcnt(0)
	v_add_f32_e32 v204, v204, v205
	ds_swizzle_b32 v205, v204 offset:swizzle(SWAP,16)
	s_waitcnt lgkmcnt(0)
; __device__ __forceinline__ unsigned pk2(float lo, float hi) { const g_f32x2 f = {lo, hi}; return __builtin_bit_cast(unsigned, __builtin_convertvector(f, g_bf16x2)); }
; __device__ __forceinline__ void p_norm(const float* hlat, const float* hctx, const float* g, const float* modl, int sh_off, int sc_off, bf16_t* A, int M,
;                                        const float* part, const float* cgate, float* hcout) {
;     ...
;         float ss = 0.f;
; #pragma unroll
;         for (int i = 0; i < 4; ++i) {
;             if (part != nullptr && row >= NLAT) {
;                 const size_t po = (size_t)(row - NLAT) * 1024 + i * 256 + lane * 4;
;                 const float4 p0 = *(const float4*)(part + po), p1 = *(const float4*)(part + (size_t)4096 * 1024 + po), cg = *(const float4*)(cgate + i * 256 + lane * 4);
;                 v[i].x += cg.x * (p0.x + p1.x); v[i].y += cg.y * (p0.y + p1.y); v[i].z += cg.z * (p0.z + p1.z); v[i].w += cg.w * (p0.w + p1.w);
;                 *(float4*)(hcout + po) = v[i];
;             }
;             ss += v[i].x * v[i].x + v[i].y * v[i].y + v[i].z * v[i].z + v[i].w * v[i].w; }
;         ss = wave_sum(ss);
;         const float rstd = rsqrtf(ss * (1.0f / 1024.0f) + EPS);
;         const float* mr = modl + (size_t)r * 6144;
; #pragma unroll
;         for (int i = 0; i < 4; ++i) {
;             const int k = i * 256 + lane * 4;
;             const float4 gg = *(const float4*)(g + k), scv = *(const float4*)(mr + sc_off + k), shv = *(const float4*)(mr + sh_off + k);
;             const float o0 = v[i].x * rstd * gg.x * (1.0f + scv.x) + shv.x, o1 = v[i].y * rstd * gg.y * (1.0f + scv.y) + shv.y;
;             const float o2 = v[i].z * rstd * gg.z * (1.0f + scv.z) + shv.z, o3 = v[i].w * rstd * gg.w * (1.0f + scv.w) + shv.w;
;             uint2 w; w.x = pk2(o0, o1); w.y = pk2(o2, o3);
;             *(uint2*)(A + (size_t)row * 1024 + k) = w;
;         }
	v_add_f32_e32 v204, v204, v205
	v_mov_b32_e32 v205, v204
	s_nop 1
	v_permlane32_swap_b32_e32 v204, v205
	v_add_f32_e32 v204, v204, v205
	v_mov_b32_e32 v205, 0x358637bd
	v_fmamk_f32 v204, v204, 0x3a800000, v205
	v_rsq_f32_e32 v204, v204
	s_nop 0
	v_pk_mul_f32 v[96:97], v[96:97], v[204:205] op_sel_hi:[1,0]
	v_pk_mul_f32 v[98:99], v[98:99], v[204:205] op_sel_hi:[1,0]
	v_pk_mul_f32 v[96:97], v[188:189], v[96:97]
	v_pk_mul_f32 v[98:99], v[190:191], v[98:99]
	v_pk_fma_f32 v[96:97], v[34:35], v[96:97], v[224:225]
	v_pk_fma_f32 v[98:99], v[36:37], v[98:99], v[226:227]
	v_cvt_pk_bf16_f32 v96, v96, v97
	v_cvt_pk_bf16_f32 v97, v98, v99
	global_store_dwordx2 v146, v[96:97], s[66:67] sc0 sc1
	v_pk_mul_f32 v[100:101], v[100:101], v[204:205] op_sel_hi:[1,0]
	v_pk_mul_f32 v[102:103], v[102:103], v[204:205] op_sel_hi:[1,0]
	v_pk_mul_f32 v[100:101], v[192:193], v[100:101]
	v_pk_mul_f32 v[102:103], v[194:195], v[102:103]
	v_pk_fma_f32 v[100:101], v[38:39], v[100:101], v[228:229]
	v_pk_fma_f32 v[102:103], v[40:41], v[102:103], v[230:231]
	v_cvt_pk_bf16_f32 v100, v100, v101
	v_cvt_pk_bf16_f32 v101, v102, v103
	global_store_dwordx2 v146, v[100:101], s[66:67] offset:512 sc0 sc1
	v_pk_mul_f32 v[104:105], v[104:105], v[204:205] op_sel_hi:[1,0]
	v_pk_mul_f32 v[106:107], v[106:107], v[204:205] op_sel_hi:[1,0]
	v_pk_mul_f32 v[104:105], v[196:197], v[104:105]
	v_pk_mul_f32 v[106:107], v[198:199], v[106:107]
	v_pk_fma_f32 v[104:105], v[42:43], v[104:105], v[232:233]
	v_pk_fma_f32 v[106:107], v[44:45], v[106:107], v[234:235]
	v_cvt_pk_bf16_f32 v104, v104, v105
	v_cvt_pk_bf16_f32 v105, v106, v107
	global_store_dwordx2 v146, v[104:105], s[66:67] offset:1024 sc0 sc1
	v_pk_mul_f32 v[108:109], v[108:109], v[204:205] op_sel_hi:[1,0]
	v_pk_mul_f32 v[110:111], v[110:111], v[204:205] op_sel_hi:[1,0]
	v_pk_mul_f32 v[108:109], v[200:201], v[108:109]
	v_pk_mul_f32 v[110:111], v[202:203], v[110:111]
	v_pk_fma_f32 v[108:109], v[46:47], v[108:109], v[236:237]
	v_pk_fma_f32 v[110:111], v[48:49], v[110:111], v[238:239]
	v_cvt_pk_bf16_f32 v108, v108, v109
	v_cvt_pk_bf16_f32 v109, v110, v111
	global_store_dwordx2 v146, v[108:109], s[66:67] offset:1536 sc0 sc1
	v_add_u32_e32 v146, 0x800, v146
	s_waitcnt vmcnt(32)
	v_pk_mul_f32 v[242:243], v[112:113], v[112:113]
	v_pk_mul_f32 v[244:245], v[116:117], v[116:117]
	v_pk_mul_f32 v[246:247], v[114:115], v[114:115]
	v_pk_mul_f32 v[248:249], v[118:119], v[118:119]
	v_add_f32_e32 v204, v245, v244
	v_add_f32_e32 v205, v243, v242
	v_add_f32_e32 v204, v248, v204
	v_add_f32_e32 v205, v246, v205
	v_add_f32_e32 v204, v249, v204
	v_add_f32_e32 v205, v247, v205
	v_pk_mul_f32 v[242:243], v[120:121], v[120:121]
	v_pk_mul_f32 v[244:245], v[124:125], v[124:125]
	v_pk_mul_f32 v[246:247], v[122:123], v[122:123]
	v_pk_mul_f32 v[248:249], v[126:127], v[126:127]
	v_add_f32_e32 v206, v243, v242
	v_add_f32_e32 v207, v245, v244
	v_add_f32_e32 v206, v246, v206
	v_add_f32_e32 v207, v248, v207
	v_add_f32_e32 v206, v247, v206
	v_add_f32_e32 v207, v249, v207
	v_add_f32_e32 v204, v205, v204
	v_add_f32_e32 v204, v204, v206
	v_add_f32_e32 v204, v204, v207
	ds_swizzle_b32 v205, v204 offset:swizzle(SWAP,1)
	s_waitcnt lgkmcnt(0)
	v_add_f32_e32 v204, v204, v205
	ds_swizzle_b32 v205, v204 offset:swizzle(SWAP,2)
	s_waitcnt lgkmcnt(0)
	v_add_f32_e32 v204, v204, v205
	ds_swizzle_b32 v205, v204 offset:swizzle(SWAP,4)
	s_waitcnt lgkmcnt(0)
	v_add_f32_e32 v204, v204, v205
	ds_swizzle_b32 v205, v204 offset:swizzle(SWAP,8)
	s_waitcnt lgkmcnt(0)
	v_add_f32_e32 v204, v204, v205
	ds_swizzle_b32 v205, v204 offset:swizzle(SWAP,16)
	s_waitcnt lgkmcnt(0)
	v_add_f32_e32 v204, v204, v205
	v_mov_b32_e32 v205, v204
	s_nop 1
	v_permlane32_swap_b32_e32 v204, v205
	v_add_f32_e32 v204, v204, v205
	v_mov_b32_e32 v205, 0x358637bd
	v_fmamk_f32 v204, v204, 0x3a800000, v205
	v_rsq_f32_e32 v204, v204
	s_nop 0
	v_pk_mul_f32 v[112:113], v[112:113], v[204:205] op_sel_hi:[1,0]
	v_pk_mul_f32 v[114:115], v[114:115], v[204:205] op_sel_hi:[1,0]
	v_pk_mul_f32 v[112:113], v[188:189], v[112:113]
	v_pk_mul_f32 v[114:115], v[190:191], v[114:115]
	v_pk_fma_f32 v[112:113], v[34:35], v[112:113], v[224:225]
	v_pk_fma_f32 v[114:115], v[36:37], v[114:115], v[226:227]
	v_cvt_pk_bf16_f32 v112, v112, v113
	v_cvt_pk_bf16_f32 v113, v114, v115
	global_store_dwordx2 v146, v[112:113], s[66:67] sc0 sc1
	v_pk_mul_f32 v[116:117], v[116:117], v[204:205] op_sel_hi:[1,0]
	v_pk_mul_f32 v[118:119], v[118:119], v[204:205] op_sel_hi:[1,0]
	v_pk_mul_f32 v[116:117], v[192:193], v[116:117]
	v_pk_mul_f32 v[118:119], v[194:195], v[118:119]
	v_pk_fma_f32 v[116:117], v[38:39], v[116:117], v[228:229]
	v_pk_fma_f32 v[118:119], v[40:41], v[118:119], v[230:231]
	v_cvt_pk_bf16_f32 v116, v116, v117
	v_cvt_pk_bf16_f32 v117, v118, v119
	global_store_dwordx2 v146, v[116:117], s[66:67] offset:512 sc0 sc1
	v_pk_mul_f32 v[120:121], v[120:121], v[204:205] op_sel_hi:[1,0]
	v_pk_mul_f32 v[122:123], v[122:123], v[204:205] op_sel_hi:[1,0]
	v_pk_mul_f32 v[120:121], v[196:197], v[120:121]
	v_pk_mul_f32 v[122:123], v[198:199], v[122:123]
	v_pk_fma_f32 v[120:121], v[42:43], v[120:121], v[232:233]
	v_pk_fma_f32 v[122:123], v[44:45], v[122:123], v[234:235]
	v_cvt_pk_bf16_f32 v120, v120, v121
	v_cvt_pk_bf16_f32 v121, v122, v123
	global_store_dwordx2 v146, v[120:121], s[66:67] offset:1024 sc0 sc1
	v_pk_mul_f32 v[124:125], v[124:125], v[204:205] op_sel_hi:[1,0]
	v_pk_mul_f32 v[126:127], v[126:127], v[204:205] op_sel_hi:[1,0]
	v_pk_mul_f32 v[124:125], v[200:201], v[124:125]
	v_pk_mul_f32 v[126:127], v[202:203], v[126:127]
	v_pk_fma_f32 v[124:125], v[46:47], v[124:125], v[236:237]
	v_pk_fma_f32 v[126:127], v[48:49], v[126:127], v[238:239]
	v_cvt_pk_bf16_f32 v124, v124, v125
	v_cvt_pk_bf16_f32 v125, v126, v127
	global_store_dwordx2 v146, v[124:125], s[66:67] offset:1536 sc0 sc1
	v_add_u32_e32 v146, 0x800, v146
	s_waitcnt vmcnt(28)
; __device__ __forceinline__ unsigned pk2(float lo, float hi) { const g_f32x2 f = {lo, hi}; return __builtin_bit_cast(unsigned, __builtin_convertvector(f, g_bf16x2)); }
; __device__ __forceinline__ void p_norm(const float* hlat, const float* hctx, const float* g, const float* modl, int sh_off, int sc_off, bf16_t* A, int M,
;                                        const float* part, const float* cgate, float* hcout) {
;     ...
;         float ss = 0.f;
; #pragma unroll
;         for (int i = 0; i < 4; ++i) {
;             if (part != nullptr && row >= NLAT) {
;                 const size_t po = (size_t)(row - NLAT) * 1024 + i * 256 + lane * 4;
;                 const float4 p0 = *(const float4*)(part + po), p1 = *(const float4*)(part + (size_t)4096 * 1024 + po), cg = *(const float4*)(cgate + i * 256 + lane * 4);
;                 v[i].x += cg.x * (p0.x + p1.x); v[i].y += cg.y * (p0.y + p1.y); v[i].z += cg.z * (p0.z + p1.z); v[i].w += cg.w * (p0.w + p1.w);
;                 *(float4*)(hcout + po) = v[i];
;             }
;             ss += v[i].x * v[i].x + v[i].y * v[i].y + v[i].z * v[i].z + v[i].w * v[i].w; }
;         ss = wave_sum(ss);
;         const float rstd = rsqrtf(ss * (1.0f / 1024.0f) + EPS);
;         const float* mr = modl + (size_t)r * 6144;
; #pragma unroll
;         for (int i = 0; i < 4; ++i) {
;             const int k = i * 256 + lane * 4;
;             const float4 gg = *(const float4*)(g + k), scv = *(const float4*)(mr + sc_off + k), shv = *(const float4*)(mr + sh_off + k);
;             const float o0 = v[i].x * rstd * gg.x * (1.0f + scv.x) + shv.x, o1 = v[i].y * rstd * gg.y * (1.0f + scv.y) + shv.y;
;             const float o2 = v[i].z * rstd * gg.z * (1.0f + scv.z) + shv.z, o3 = v[i].w * rstd * gg.w * (1.0f + scv.w) + shv.w;
;             uint2 w; w.x = pk2(o0, o1); w.y = pk2(o2, o3);
;             *(uint2*)(A + (size_t)row * 1024 + k) = w;
;         }
	v_pk_mul_f32 v[242:243], v[128:129], v[128:129]
	v_pk_mul_f32 v[244:245], v[132:133], v[132:133]
	v_pk_mul_f32 v[246:247], v[130:131], v[130:131]
	v_pk_mul_f32 v[248:249], v[134:135], v[134:135]
	v_add_f32_e32 v204, v245, v244
	v_add_f32_e32 v205, v243, v242
	v_add_f32_e32 v204, v248, v204
	v_add_f32_e32 v205, v246, v205
	v_add_f32_e32 v204, v249, v204
	v_add_f32_e32 v205, v247, v205
	v_pk_mul_f32 v[242:243], v[136:137], v[136:137]
	v_pk_mul_f32 v[244:245], v[140:141], v[140:141]
	v_pk_mul_f32 v[246:247], v[138:139], v[138:139]
	v_pk_mul_f32 v[248:249], v[142:143], v[142:143]
	v_add_f32_e32 v206, v243, v242
	v_add_f32_e32 v207, v245, v244
	v_add_f32_e32 v206, v246, v206
	v_add_f32_e32 v207, v248, v207
	v_add_f32_e32 v206, v247, v206
	v_add_f32_e32 v207, v249, v207
	v_add_f32_e32 v204, v205, v204
	v_add_f32_e32 v204, v204, v206
	v_add_f32_e32 v204, v204, v207
	ds_swizzle_b32 v205, v204 offset:swizzle(SWAP,1)
	s_waitcnt lgkmcnt(0)
	v_add_f32_e32 v204, v204, v205
	ds_swizzle_b32 v205, v204 offset:swizzle(SWAP,2)
	s_waitcnt lgkmcnt(0)
	v_add_f32_e32 v204, v204, v205
	ds_swizzle_b32 v205, v204 offset:swizzle(SWAP,4)
	s_waitcnt lgkmcnt(0)
	v_add_f32_e32 v204, v204, v205
	ds_swizzle_b32 v205, v204 offset:swizzle(SWAP,8)
	s_waitcnt lgkmcnt(0)
	v_add_f32_e32 v204, v204, v205
	ds_swizzle_b32 v205, v204 offset:swizzle(SWAP,16)
	s_waitcnt lgkmcnt(0)
	v_add_f32_e32 v204, v204, v205
	v_mov_b32_e32 v205, v204
	s_nop 1
	v_permlane32_swap_b32_e32 v204, v205
	v_add_f32_e32 v204, v204, v205
	v_mov_b32_e32 v205, 0x358637bd
	v_fmamk_f32 v204, v204, 0x3a800000, v205
	v_rsq_f32_e32 v204, v204
	s_nop 0
	v_pk_mul_f32 v[128:129], v[128:129], v[204:205] op_sel_hi:[1,0]
	v_pk_mul_f32 v[130:131], v[130:131], v[204:205] op_sel_hi:[1,0]
	v_pk_mul_f32 v[128:129], v[188:189], v[128:129]
	v_pk_mul_f32 v[130:131], v[190:191], v[130:131]
	v_pk_fma_f32 v[128:129], v[34:35], v[128:129], v[224:225]
	v_pk_fma_f32 v[130:131], v[36:37], v[130:131], v[226:227]
	v_cvt_pk_bf16_f32 v128, v128, v129
	v_cvt_pk_bf16_f32 v129, v130, v131
	global_store_dwordx2 v146, v[128:129], s[66:67] sc0 sc1
	v_pk_mul_f32 v[132:133], v[132:133], v[204:205] op_sel_hi:[1,0]
	v_pk_mul_f32 v[134:135], v[134:135], v[204:205] op_sel_hi:[1,0]
	v_pk_mul_f32 v[132:133], v[192:193], v[132:133]
	v_pk_mul_f32 v[134:135], v[194:195], v[134:135]
	v_pk_fma_f32 v[132:133], v[38:39], v[132:133], v[228:229]
	v_pk_fma_f32 v[134:135], v[40:41], v[134:135], v[230:231]
	v_cvt_pk_bf16_f32 v132, v132, v133
	v_cvt_pk_bf16_f32 v133, v134, v135
	global_store_dwordx2 v146, v[132:133], s[66:67] offset:512 sc0 sc1
	v_pk_mul_f32 v[136:137], v[136:137], v[204:205] op_sel_hi:[1,0]
	v_pk_mul_f32 v[138:139], v[138:139], v[204:205] op_sel_hi:[1,0]
	v_pk_mul_f32 v[136:137], v[196:197], v[136:137]
	v_pk_mul_f32 v[138:139], v[198:199], v[138:139]
	v_pk_fma_f32 v[136:137], v[42:43], v[136:137], v[232:233]
	v_pk_fma_f32 v[138:139], v[44:45], v[138:139], v[234:235]
	v_cvt_pk_bf16_f32 v136, v136, v137
	v_cvt_pk_bf16_f32 v137, v138, v139
	global_store_dwordx2 v146, v[136:137], s[66:67] offset:1024 sc0 sc1
	v_pk_mul_f32 v[140:141], v[140:141], v[204:205] op_sel_hi:[1,0]
	v_pk_mul_f32 v[142:143], v[142:143], v[204:205] op_sel_hi:[1,0]
	v_pk_mul_f32 v[140:141], v[200:201], v[140:141]
	v_pk_mul_f32 v[142:143], v[202:203], v[142:143]
	v_pk_fma_f32 v[140:141], v[46:47], v[140:141], v[236:237]
	v_pk_fma_f32 v[142:143], v[48:49], v[142:143], v[238:239]
	v_cvt_pk_bf16_f32 v140, v140, v141
	v_cvt_pk_bf16_f32 v141, v142, v143
	global_store_dwordx2 v146, v[140:141], s[66:67] offset:1536 sc0 sc1
	v_add_u32_e32 v146, 0x800, v146
	v_add_u32_e32 v151, 0x60000, v241
	global_load_dwordx4 v[34:37], v151, s[98:99]
	global_load_dwordx4 v[38:41], v151, s[98:99] offset:1024
	global_load_dwordx4 v[42:45], v151, s[98:99] offset:2048
	global_load_dwordx4 v[46:49], v151, s[98:99] offset:3072
	global_load_dwordx4 v[224:227], v151, s[50:51]
	global_load_dwordx4 v[228:231], v151, s[50:51] offset:1024
	global_load_dwordx4 v[232:235], v151, s[50:51] offset:2048
	global_load_dwordx4 v[236:239], v151, s[50:51] offset:3072
	s_waitcnt vmcnt(32)
	v_pk_mul_f32 v[242:243], v[156:157], v[156:157]
	v_pk_mul_f32 v[244:245], v[160:161], v[160:161]
	v_pk_mul_f32 v[246:247], v[158:159], v[158:159]
	v_pk_mul_f32 v[248:249], v[162:163], v[162:163]
	v_add_f32_e32 v204, v245, v244
	v_add_f32_e32 v205, v243, v242
	v_add_f32_e32 v204, v248, v204
	v_add_f32_e32 v205, v246, v205
	v_add_f32_e32 v204, v249, v204
	v_add_f32_e32 v205, v247, v205
	v_pk_mul_f32 v[242:243], v[164:165], v[164:165]
	v_pk_mul_f32 v[244:245], v[168:169], v[168:169]
	v_pk_mul_f32 v[246:247], v[166:167], v[166:167]
	v_pk_mul_f32 v[248:249], v[170:171], v[170:171]
	v_add_f32_e32 v206, v243, v242
	v_add_f32_e32 v207, v245, v244
	v_add_f32_e32 v206, v246, v206
	v_add_f32_e32 v207, v248, v207
	v_add_f32_e32 v206, v247, v206
	v_add_f32_e32 v207, v249, v207
	v_add_f32_e32 v204, v205, v204
	v_add_f32_e32 v204, v204, v206
	v_add_f32_e32 v204, v204, v207
	ds_swizzle_b32 v205, v204 offset:swizzle(SWAP,1)
	s_waitcnt lgkmcnt(0)
	v_add_f32_e32 v204, v204, v205
	ds_swizzle_b32 v205, v204 offset:swizzle(SWAP,2)
	s_waitcnt lgkmcnt(0)
	v_add_f32_e32 v204, v204, v205
	ds_swizzle_b32 v205, v204 offset:swizzle(SWAP,4)
	s_waitcnt lgkmcnt(0)
	v_add_f32_e32 v204, v204, v205
	ds_swizzle_b32 v205, v204 offset:swizzle(SWAP,8)
	s_waitcnt lgkmcnt(0)
	v_add_f32_e32 v204, v204, v205
	ds_swizzle_b32 v205, v204 offset:swizzle(SWAP,16)
	s_waitcnt lgkmcnt(0)
	v_add_f32_e32 v204, v204, v205
	v_mov_b32_e32 v205, v204
	s_nop 1
	v_permlane32_swap_b32_e32 v204, v205
	v_add_f32_e32 v204, v204, v205
	v_mov_b32_e32 v205, 0x358637bd
	v_fmamk_f32 v204, v204, 0x3a800000, v205
	v_rsq_f32_e32 v204, v204
	s_nop 0
	s_waitcnt vmcnt(0)
; __device__ __forceinline__ unsigned pk2(float lo, float hi) { const g_f32x2 f = {lo, hi}; return __builtin_bit_cast(unsigned, __builtin_convertvector(f, g_bf16x2)); }
; __device__ __forceinline__ void p_norm(const float* hlat, const float* hctx, const float* g, const float* modl, int sh_off, int sc_off, bf16_t* A, int M,
;                                        const float* part, const float* cgate, float* hcout) {
;     ...
;         float ss = 0.f;
; #pragma unroll
;         for (int i = 0; i < 4; ++i) {
;             if (part != nullptr && row >= NLAT) {
;                 const size_t po = (size_t)(row - NLAT) * 1024 + i * 256 + lane * 4;
;                 const float4 p0 = *(const float4*)(part + po), p1 = *(const float4*)(part + (size_t)4096 * 1024 + po), cg = *(const float4*)(cgate + i * 256 + lane * 4);
;                 v[i].x += cg.x * (p0.x + p1.x); v[i].y += cg.y * (p0.y + p1.y); v[i].z += cg.z * (p0.z + p1.z); v[i].w += cg.w * (p0.w + p1.w);
;                 *(float4*)(hcout + po) = v[i];
;             }
;             ss += v[i].x * v[i].x + v[i].y * v[i].y + v[i].z * v[i].z + v[i].w * v[i].w; }
;         ss = wave_sum(ss);
;         const float rstd = rsqrtf(ss * (1.0f / 1024.0f) + EPS);
;         const float* mr = modl + (size_t)r * 6144;
; #pragma unroll
;         for (int i = 0; i < 4; ++i) {
;             const int k = i * 256 + lane * 4;
;             const float4 gg = *(const float4*)(g + k), scv = *(const float4*)(mr + sc_off + k), shv = *(const float4*)(mr + sh_off + k);
;             const float o0 = v[i].x * rstd * gg.x * (1.0f + scv.x) + shv.x, o1 = v[i].y * rstd * gg.y * (1.0f + scv.y) + shv.y;
;             const float o2 = v[i].z * rstd * gg.z * (1.0f + scv.z) + shv.z, o3 = v[i].w * rstd * gg.w * (1.0f + scv.w) + shv.w;
;             uint2 w; w.x = pk2(o0, o1); w.y = pk2(o2, o3);
;             *(uint2*)(A + (size_t)row * 1024 + k) = w;
;         }
	v_pk_add_f32 v[34:35], v[34:35], 1.0 op_sel_hi:[1,0]
	v_pk_add_f32 v[36:37], v[36:37], 1.0 op_sel_hi:[1,0]
	v_pk_add_f32 v[38:39], v[38:39], 1.0 op_sel_hi:[1,0]
	v_pk_add_f32 v[40:41], v[40:41], 1.0 op_sel_hi:[1,0]
	v_pk_add_f32 v[42:43], v[42:43], 1.0 op_sel_hi:[1,0]
	v_pk_add_f32 v[44:45], v[44:45], 1.0 op_sel_hi:[1,0]
	v_pk_add_f32 v[46:47], v[46:47], 1.0 op_sel_hi:[1,0]
	v_pk_add_f32 v[48:49], v[48:49], 1.0 op_sel_hi:[1,0]
	v_lshlrev_b32_e32 v146, 12, v50
	v_lshl_add_u32 v146, v240, 3, v146
	v_add_u32_e32 v146, 0x4000000, v146
	v_pk_mul_f32 v[156:157], v[156:157], v[204:205] op_sel_hi:[1,0]
	v_pk_mul_f32 v[158:159], v[158:159], v[204:205] op_sel_hi:[1,0]
	v_pk_mul_f32 v[156:157], v[188:189], v[156:157]
	v_pk_mul_f32 v[158:159], v[190:191], v[158:159]
	v_pk_fma_f32 v[156:157], v[34:35], v[156:157], v[224:225]
	v_pk_fma_f32 v[158:159], v[36:37], v[158:159], v[226:227]
	v_cvt_pk_bf16_f32 v156, v156, v157
	v_cvt_pk_bf16_f32 v157, v158, v159
	global_store_dwordx2 v146, v[156:157], s[66:67] sc0 sc1
	v_pk_mul_f32 v[160:161], v[160:161], v[204:205] op_sel_hi:[1,0]
	v_pk_mul_f32 v[162:163], v[162:163], v[204:205] op_sel_hi:[1,0]
	v_pk_mul_f32 v[160:161], v[192:193], v[160:161]
	v_pk_mul_f32 v[162:163], v[194:195], v[162:163]
	v_pk_fma_f32 v[160:161], v[38:39], v[160:161], v[228:229]
	v_pk_fma_f32 v[162:163], v[40:41], v[162:163], v[230:231]
	v_cvt_pk_bf16_f32 v160, v160, v161
	v_cvt_pk_bf16_f32 v161, v162, v163
	global_store_dwordx2 v146, v[160:161], s[66:67] offset:512 sc0 sc1
	v_pk_mul_f32 v[164:165], v[164:165], v[204:205] op_sel_hi:[1,0]
	v_pk_mul_f32 v[166:167], v[166:167], v[204:205] op_sel_hi:[1,0]
	v_pk_mul_f32 v[164:165], v[196:197], v[164:165]
	v_pk_mul_f32 v[166:167], v[198:199], v[166:167]
	v_pk_fma_f32 v[164:165], v[42:43], v[164:165], v[232:233]
	v_pk_fma_f32 v[166:167], v[44:45], v[166:167], v[234:235]
	v_cvt_pk_bf16_f32 v164, v164, v165
	v_cvt_pk_bf16_f32 v165, v166, v167
	global_store_dwordx2 v146, v[164:165], s[66:67] offset:1024 sc0 sc1
	v_pk_mul_f32 v[168:169], v[168:169], v[204:205] op_sel_hi:[1,0]
	v_pk_mul_f32 v[170:171], v[170:171], v[204:205] op_sel_hi:[1,0]
	v_pk_mul_f32 v[168:169], v[200:201], v[168:169]
	v_pk_mul_f32 v[170:171], v[202:203], v[170:171]
	v_pk_fma_f32 v[168:169], v[46:47], v[168:169], v[236:237]
	v_pk_fma_f32 v[170:171], v[48:49], v[170:171], v[238:239]
	v_cvt_pk_bf16_f32 v168, v168, v169
	v_cvt_pk_bf16_f32 v169, v170, v171
	global_store_dwordx2 v146, v[168:169], s[66:67] offset:1536 sc0 sc1
	v_add_u32_e32 v146, 0x800, v146
	v_pk_mul_f32 v[242:243], v[172:173], v[172:173]
	v_pk_mul_f32 v[244:245], v[176:177], v[176:177]
	v_pk_mul_f32 v[246:247], v[174:175], v[174:175]
	v_pk_mul_f32 v[248:249], v[178:179], v[178:179]
	v_add_f32_e32 v204, v245, v244
	v_add_f32_e32 v205, v243, v242
	v_add_f32_e32 v204, v248, v204
	v_add_f32_e32 v205, v246, v205
	v_add_f32_e32 v204, v249, v204
	v_add_f32_e32 v205, v247, v205
	v_pk_mul_f32 v[242:243], v[180:181], v[180:181]
	v_pk_mul_f32 v[244:245], v[184:185], v[184:185]
	v_pk_mul_f32 v[246:247], v[182:183], v[182:183]
	v_pk_mul_f32 v[248:249], v[186:187], v[186:187]
	v_add_f32_e32 v206, v243, v242
	v_add_f32_e32 v207, v245, v244
	v_add_f32_e32 v206, v246, v206
	v_add_f32_e32 v207, v248, v207
	v_add_f32_e32 v206, v247, v206
	v_add_f32_e32 v207, v249, v207
	v_add_f32_e32 v204, v205, v204
	v_add_f32_e32 v204, v204, v206
	v_add_f32_e32 v204, v204, v207
	ds_swizzle_b32 v205, v204 offset:swizzle(SWAP,1)
	s_waitcnt lgkmcnt(0)
	v_add_f32_e32 v204, v204, v205
	ds_swizzle_b32 v205, v204 offset:swizzle(SWAP,2)
	s_waitcnt lgkmcnt(0)
	v_add_f32_e32 v204, v204, v205
	ds_swizzle_b32 v205, v204 offset:swizzle(SWAP,4)
	s_waitcnt lgkmcnt(0)
	v_add_f32_e32 v204, v204, v205
	ds_swizzle_b32 v205, v204 offset:swizzle(SWAP,8)
	s_waitcnt lgkmcnt(0)
	v_add_f32_e32 v204, v204, v205
	ds_swizzle_b32 v205, v204 offset:swizzle(SWAP,16)
	s_waitcnt lgkmcnt(0)
	v_add_f32_e32 v204, v204, v205
	v_mov_b32_e32 v205, v204
	s_nop 1
	v_permlane32_swap_b32_e32 v204, v205
	v_add_f32_e32 v204, v204, v205
	v_mov_b32_e32 v205, 0x358637bd
	v_fmamk_f32 v204, v204, 0x3a800000, v205
	v_rsq_f32_e32 v204, v204
	s_nop 0
	v_pk_mul_f32 v[172:173], v[172:173], v[204:205] op_sel_hi:[1,0]
	v_pk_mul_f32 v[174:175], v[174:175], v[204:205] op_sel_hi:[1,0]
	v_pk_mul_f32 v[172:173], v[188:189], v[172:173]
	v_pk_mul_f32 v[174:175], v[190:191], v[174:175]
	v_pk_fma_f32 v[172:173], v[34:35], v[172:173], v[224:225]
	v_pk_fma_f32 v[174:175], v[36:37], v[174:175], v[226:227]
	v_cvt_pk_bf16_f32 v172, v172, v173
	v_cvt_pk_bf16_f32 v173, v174, v175
	global_store_dwordx2 v146, v[172:173], s[66:67] sc0 sc1
	v_pk_mul_f32 v[176:177], v[176:177], v[204:205] op_sel_hi:[1,0]
	v_pk_mul_f32 v[178:179], v[178:179], v[204:205] op_sel_hi:[1,0]
	v_pk_mul_f32 v[176:177], v[192:193], v[176:177]
	v_pk_mul_f32 v[178:179], v[194:195], v[178:179]
	v_pk_fma_f32 v[176:177], v[38:39], v[176:177], v[228:229]
	v_pk_fma_f32 v[178:179], v[40:41], v[178:179], v[230:231]
	v_cvt_pk_bf16_f32 v176, v176, v177
	v_cvt_pk_bf16_f32 v177, v178, v179
	global_store_dwordx2 v146, v[176:177], s[66:67] offset:512 sc0 sc1
	v_pk_mul_f32 v[180:181], v[180:181], v[204:205] op_sel_hi:[1,0]
	v_pk_mul_f32 v[182:183], v[182:183], v[204:205] op_sel_hi:[1,0]
	v_pk_mul_f32 v[180:181], v[196:197], v[180:181]
	v_pk_mul_f32 v[182:183], v[198:199], v[182:183]
	v_pk_fma_f32 v[180:181], v[42:43], v[180:181], v[232:233]
	v_pk_fma_f32 v[182:183], v[44:45], v[182:183], v[234:235]
	v_cvt_pk_bf16_f32 v180, v180, v181
	v_cvt_pk_bf16_f32 v181, v182, v183
	global_store_dwordx2 v146, v[180:181], s[66:67] offset:1024 sc0 sc1
	v_pk_mul_f32 v[184:185], v[184:185], v[204:205] op_sel_hi:[1,0]
	v_pk_mul_f32 v[186:187], v[186:187], v[204:205] op_sel_hi:[1,0]
	v_pk_mul_f32 v[184:185], v[200:201], v[184:185]
	v_pk_mul_f32 v[186:187], v[202:203], v[186:187]
	v_pk_fma_f32 v[184:185], v[46:47], v[184:185], v[236:237]
	v_pk_fma_f32 v[186:187], v[48:49], v[186:187], v[238:239]
	v_cvt_pk_bf16_f32 v184, v184, v185
	v_cvt_pk_bf16_f32 v185, v186, v187
	global_store_dwordx2 v146, v[184:185], s[66:67] offset:1536 sc0 sc1
	v_add_u32_e32 v146, 0x800, v146

; #define PIN(i) ((const float*)(const GASP float*)karg_q(i))
; __device__ __forceinline__ int obid() { int b = blockIdx.x; asm volatile("" : "+s"(b)); return b; }
; __device__ __forceinline__ int otid() { int t = threadIdx.x; asm volatile("" : "+v"(t)); return t; }
; #define PN_LOAD(dst, rw) do { const float* s_ = (rw) < NLAT ? hlat + (size_t)(rw) * 1024 : hctx + (size_t)((rw) - NLAT) * 1024; \
;         _Pragma("unroll") for (int i = 0; i < 4; ++i) dst[i] = *(const float4*)(s_ + i * 256 + lane * 4); } while (0)
; __device__ __forceinline__ void p_norm(const float* hlat, const float* hctx, const float* g, const float* modl, int sh_off, int sc_off, bf16_t* A, int M,
;                                        const float* part, const float* cgate, float* hcout) {
;     const int tid = otid(), lane = tid & 63, wave = tid >> 6;
;     const int stride = gridDim.x * 8;
;     int row = obid() * 8 + wave;
;     float4 v[4], nv[4];
;     ...
;     if (row < M) PN_LOAD(v, row);
;     while (row < M) {
;         const int nrow = row + stride;
;         if (nrow < M) PN_LOAD(nv, nrow);
;         const int r = row < NLAT ? (row >> 11) : 16;
;         float ss = 0.f;
; #pragma unroll
;         for (int i = 0; i < 4; ++i) {
;             if (part != nullptr && row >= NLAT) {
;                 const size_t po = (size_t)(row - NLAT) * 1024 + i * 256 + lane * 4;
;                 const float4 p0 = *(const float4*)(part + po), p1 = *(const float4*)(part + (size_t)4096 * 1024 + po), cg = *(const float4*)(cgate + i * 256 + lane * 4);
;                 v[i].x += cg.x * (p0.x + p1.x); v[i].y += cg.y * (p0.y + p1.y); v[i].z += cg.z * (p0.z + p1.z); v[i].w += cg.w * (p0.w + p1.w);
;                 *(float4*)(hcout + po) = v[i];
;             }
;             ss += v[i].x * v[i].x + v[i].y * v[i].y + v[i].z * v[i].z + v[i].w * v[i].w; }
;         ss = wave_sum(ss);
;         const float rstd = rsqrtf(ss * (1.0f / 1024.0f) + EPS);
; __global__ void __launch_bounds__(512, 2) hybrid_fwd(Params P) {
;     ...
;         p_norm(POUT, hc_in, PIN(7) + l * 1024, modl, 3 * 1024, 4 * 1024, AO, Mf, last ? nullptr : (const float*)(PWS + WS_MK), modl + 16 * 6144 + 2 * 1024, hc);
.LBB0_1037:
	s_or_b64 exec, exec, s[2:3]
	s_and_b64 s[2:3], s[18:19], exec
	s_mov_b32 s2, 0x8000
	s_cselect_b32 s7, s2, 0x9000
	v_mov_b32_e32 v6, v253
	s_mov_b32 s2, s63
	s_waitcnt lgkmcnt(0)
	s_barrier
	s_lshl_b32 s5, s2, 3
	v_ashrrev_i32_e32 v1, 6, v6
	v_add_u32_e32 v50, s5, v1
	s_waitcnt vmcnt(0) lgkmcnt(0)
	v_readlane_b32 s100, v255, 45
	s_load_dwordx2 s[48:49], s[0:1], 0x38
	s_movk_i32 s101, 0xe8
	s_load_dwordx2 s[46:47], s[0:1], s101
	s_load_dwordx2 s[16:17], s[0:1], 0x10
	s_mul_i32 s101, s100, 0x66000
	s_add_u32 s50, s56, s101
	s_addc_u32 s51, s57, 0
	s_add_u32 s20, s101, 0x62000
	s_add_u32 s20, s56, s20
	s_addc_u32 s21, s57, 0
	s_add_u32 s98, s50, 0x4000
	s_addc_u32 s99, s51, 0
	s_add_u32 s50, s50, 0x3000
	s_addc_u32 s51, s51, 0
	s_lshl_b32 s101, s100, 12
	v_and_b32_e32 v240, 63, v253
	v_lshlrev_b32_e32 v241, 4, v240
	v_lshrrev_b32_e32 v148, 7, v50
	v_lshlrev_b32_e32 v146, 4, v50
	v_lshl_add_u32 v144, v146, 12, v241
	v_lshlrev_b32_e32 v146, 11, v146
	v_lshl_add_u32 v146, v240, 3, v146
	v_mul_u32_u24_e32 v148, 0x6000, v148
	v_add_u32_e32 v148, v148, v241
	s_waitcnt lgkmcnt(0)
	s_add_u32 s48, s48, s101
	s_addc_u32 s49, s49, 0
	s_cmp_eq_u32 s100, 0
	s_cselect_b32 s16, s16, s64
	s_cselect_b32 s17, s17, s65
	s_cmp_eq_u32 s100, 3
	s_cbranch_scc1 .Lnorm_P6_alt
	global_load_dwordx4 v[80:83], v144, s[46:47] nt
	global_load_dwordx4 v[84:87], v144, s[46:47] offset:1024 nt
	global_load_dwordx4 v[88:91], v144, s[46:47] offset:2048 nt
	global_load_dwordx4 v[92:95], v144, s[46:47] offset:3072 nt
	v_add_u32_e32 v144, 0x1000, v144
	global_load_dwordx4 v[34:37], v148, s[98:99]
	global_load_dwordx4 v[38:41], v148, s[98:99] offset:1024
	global_load_dwordx4 v[42:45], v148, s[98:99] offset:2048
	global_load_dwordx4 v[46:49], v148, s[98:99] offset:3072
	global_load_dwordx4 v[224:227], v148, s[50:51]
	global_load_dwordx4 v[228:231], v148, s[50:51] offset:1024
	global_load_dwordx4 v[232:235], v148, s[50:51] offset:2048
	global_load_dwordx4 v[236:239], v148, s[50:51] offset:3072
	global_load_dwordx4 v[188:191], v241, s[48:49]
	global_load_dwordx4 v[192:195], v241, s[48:49] offset:1024
	global_load_dwordx4 v[196:199], v241, s[48:49] offset:2048
	global_load_dwordx4 v[200:203], v241, s[48:49] offset:3072
	global_load_dwordx4 v[96:99], v144, s[46:47] nt
	global_load_dwordx4 v[100:103], v144, s[46:47] offset:1024 nt
	global_load_dwordx4 v[104:107], v144, s[46:47] offset:2048 nt
	global_load_dwordx4 v[108:111], v144, s[46:47] offset:3072 nt
	v_add_u32_e32 v144, 0x1000, v144
	global_load_dwordx4 v[112:115], v144, s[46:47] nt
	global_load_dwordx4 v[116:119], v144, s[46:47] offset:1024 nt
	global_load_dwordx4 v[120:123], v144, s[46:47] offset:2048 nt
	global_load_dwordx4 v[124:127], v144, s[46:47] offset:3072 nt
	v_add_u32_e32 v144, 0x1000, v144
	global_load_dwordx4 v[128:131], v144, s[46:47] nt
	global_load_dwordx4 v[132:135], v144, s[46:47] offset:1024 nt
	global_load_dwordx4 v[136:139], v144, s[46:47] offset:2048 nt
	global_load_dwordx4 v[140:143], v144, s[46:47] offset:3072 nt
	v_add_u32_e32 v144, 0x1000, v144
	global_load_dwordx4 v[156:159], v144, s[46:47] nt
	global_load_dwordx4 v[160:163], v144, s[46:47] offset:1024 nt
	global_load_dwordx4 v[164:167], v144, s[46:47] offset:2048 nt
	global_load_dwordx4 v[168:171], v144, s[46:47] offset:3072 nt
	v_add_u32_e32 v144, 0x1000, v144
	global_load_dwordx4 v[172:175], v144, s[46:47] nt
	global_load_dwordx4 v[176:179], v144, s[46:47] offset:1024 nt
	global_load_dwordx4 v[180:183], v144, s[46:47] offset:2048 nt
	global_load_dwordx4 v[184:187], v144, s[46:47] offset:3072 nt
	v_add_u32_e32 v144, 0x1000, v144
	s_waitcnt vmcnt(32)
	v_pk_mul_f32 v[242:243], v[80:81], v[80:81]
	v_pk_mul_f32 v[244:245], v[84:85], v[84:85]
	v_pk_mul_f32 v[246:247], v[82:83], v[82:83]
	v_pk_mul_f32 v[248:249], v[86:87], v[86:87]
	v_add_f32_e32 v204, v245, v244
	v_add_f32_e32 v205, v243, v242
	v_add_f32_e32 v204, v248, v204
	v_add_f32_e32 v205, v246, v205
	v_add_f32_e32 v204, v249, v204
	v_add_f32_e32 v205, v247, v205
	v_pk_mul_f32 v[242:243], v[88:89], v[88:89]
	v_pk_mul_f32 v[244:245], v[92:93], v[92:93]
	v_pk_mul_f32 v[246:247], v[90:91], v[90:91]
	v_pk_mul_f32 v[248:249], v[94:95], v[94:95]
	v_add_f32_e32 v206, v243, v242
	v_add_f32_e32 v207, v245, v244
	v_add_f32_e32 v206, v246, v206
	v_add_f32_e32 v207, v248, v207
	v_add_f32_e32 v206, v247, v206
	v_add_f32_e32 v207, v249, v207
	v_add_f32_e32 v204, v205, v204
	v_add_f32_e32 v204, v204, v206
	v_add_f32_e32 v204, v204, v207
	ds_swizzle_b32 v205, v204 offset:swizzle(SWAP,1)
	s_waitcnt lgkmcnt(0)
	v_add_f32_e32 v204, v204, v205
	ds_swizzle_b32 v205, v204 offset:swizzle(SWAP,2)
	s_waitcnt lgkmcnt(0)
	v_add_f32_e32 v204, v204, v205
	ds_swizzle_b32 v205, v204 offset:swizzle(SWAP,4)
	s_waitcnt lgkmcnt(0)
	v_add_f32_e32 v204, v204, v205
	ds_swizzle_b32 v205, v204 offset:swizzle(SWAP,8)
	s_waitcnt lgkmcnt(0)
	v_add_f32_e32 v204, v204, v205
	ds_swizzle_b32 v205, v204 offset:swizzle(SWAP,16)
	s_waitcnt lgkmcnt(0)
	v_add_f32_e32 v204, v204, v205
	v_mov_b32_e32 v205, v204
	s_nop 1
	v_permlane32_swap_b32_e32 v204, v205
	v_add_f32_e32 v204, v204, v205
	v_mov_b32_e32 v205, 0x358637bd
	v_fmamk_f32 v204, v204, 0x3a800000, v205
	v_rsq_f32_e32 v204, v204
	s_nop 0
	s_waitcnt vmcnt(20)
; __device__ __forceinline__ unsigned pk2(float lo, float hi) { const g_f32x2 f = {lo, hi}; return __builtin_bit_cast(unsigned, __builtin_convertvector(f, g_bf16x2)); }
; __device__ __forceinline__ void p_norm(const float* hlat, const float* hctx, const float* g, const float* modl, int sh_off, int sc_off, bf16_t* A, int M,
;                                        const float* part, const float* cgate, float* hcout) {
;     ...
;         float ss = 0.f;
; #pragma unroll
;         for (int i = 0; i < 4; ++i) {
;             if (part != nullptr && row >= NLAT) {
;                 const size_t po = (size_t)(row - NLAT) * 1024 + i * 256 + lane * 4;
;                 const float4 p0 = *(const float4*)(part + po), p1 = *(const float4*)(part + (size_t)4096 * 1024 + po), cg = *(const float4*)(cgate + i * 256 + lane * 4);
;                 v[i].x += cg.x * (p0.x + p1.x); v[i].y += cg.y * (p0.y + p1.y); v[i].z += cg.z * (p0.z + p1.z); v[i].w += cg.w * (p0.w + p1.w);
;                 *(float4*)(hcout + po) = v[i];
;             }
;             ss += v[i].x * v[i].x + v[i].y * v[i].y + v[i].z * v[i].z + v[i].w * v[i].w; }
;         ss = wave_sum(ss);
;         const float rstd = rsqrtf(ss * (1.0f / 1024.0f) + EPS);
;         const float* mr = modl + (size_t)r * 6144;
; #pragma unroll
;         for (int i = 0; i < 4; ++i) {
;             const int k = i * 256 + lane * 4;
;             const float4 gg = *(const float4*)(g + k), scv = *(const float4*)(mr + sc_off + k), shv = *(const float4*)(mr + sh_off + k);
;             const float o0 = v[i].x * rstd * gg.x * (1.0f + scv.x) + shv.x, o1 = v[i].y * rstd * gg.y * (1.0f + scv.y) + shv.y;
;             const float o2 = v[i].z * rstd * gg.z * (1.0f + scv.z) + shv.z, o3 = v[i].w * rstd * gg.w * (1.0f + scv.w) + shv.w;
;             uint2 w; w.x = pk2(o0, o1); w.y = pk2(o2, o3);
;             *(uint2*)(A + (size_t)row * 1024 + k) = w;
;         }
	v_pk_add_f32 v[34:35], v[34:35], 1.0 op_sel_hi:[1,0]
	v_pk_add_f32 v[36:37], v[36:37], 1.0 op_sel_hi:[1,0]
	v_pk_add_f32 v[38:39], v[38:39], 1.0 op_sel_hi:[1,0]
	v_pk_add_f32 v[40:41], v[40:41], 1.0 op_sel_hi:[1,0]
	v_pk_add_f32 v[42:43], v[42:43], 1.0 op_sel_hi:[1,0]
	v_pk_add_f32 v[44:45], v[44:45], 1.0 op_sel_hi:[1,0]
	v_pk_add_f32 v[46:47], v[46:47], 1.0 op_sel_hi:[1,0]
	v_pk_add_f32 v[48:49], v[48:49], 1.0 op_sel_hi:[1,0]
	v_pk_mul_f32 v[80:81], v[80:81], v[204:205] op_sel_hi:[1,0]
	v_pk_mul_f32 v[82:83], v[82:83], v[204:205] op_sel_hi:[1,0]
	v_pk_mul_f32 v[80:81], v[188:189], v[80:81]
	v_pk_mul_f32 v[82:83], v[190:191], v[82:83]
	v_pk_fma_f32 v[80:81], v[34:35], v[80:81], v[224:225]
	v_pk_fma_f32 v[82:83], v[36:37], v[82:83], v[226:227]
	v_cvt_pk_bf16_f32 v80, v80, v81
	v_cvt_pk_bf16_f32 v81, v82, v83
	global_store_dwordx2 v146, v[80:81], s[66:67] sc0 sc1
	v_pk_mul_f32 v[84:85], v[84:85], v[204:205] op_sel_hi:[1,0]
	v_pk_mul_f32 v[86:87], v[86:87], v[204:205] op_sel_hi:[1,0]
	v_pk_mul_f32 v[84:85], v[192:193], v[84:85]
	v_pk_mul_f32 v[86:87], v[194:195], v[86:87]
	v_pk_fma_f32 v[84:85], v[38:39], v[84:85], v[228:229]
	v_pk_fma_f32 v[86:87], v[40:41], v[86:87], v[230:231]
	v_cvt_pk_bf16_f32 v84, v84, v85
	v_cvt_pk_bf16_f32 v85, v86, v87
	global_store_dwordx2 v146, v[84:85], s[66:67] offset:512 sc0 sc1
	v_pk_mul_f32 v[88:89], v[88:89], v[204:205] op_sel_hi:[1,0]
	v_pk_mul_f32 v[90:91], v[90:91], v[204:205] op_sel_hi:[1,0]
	v_pk_mul_f32 v[88:89], v[196:197], v[88:89]
	v_pk_mul_f32 v[90:91], v[198:199], v[90:91]
	v_pk_fma_f32 v[88:89], v[42:43], v[88:89], v[232:233]
	v_pk_fma_f32 v[90:91], v[44:45], v[90:91], v[234:235]
	v_cvt_pk_bf16_f32 v88, v88, v89
	v_cvt_pk_bf16_f32 v89, v90, v91
	global_store_dwordx2 v146, v[88:89], s[66:67] offset:1024 sc0 sc1
	v_pk_mul_f32 v[92:93], v[92:93], v[204:205] op_sel_hi:[1,0]
	v_pk_mul_f32 v[94:95], v[94:95], v[204:205] op_sel_hi:[1,0]
	v_pk_mul_f32 v[92:93], v[200:201], v[92:93]
	v_pk_mul_f32 v[94:95], v[202:203], v[94:95]
	v_pk_fma_f32 v[92:93], v[46:47], v[92:93], v[236:237]
	v_pk_fma_f32 v[94:95], v[48:49], v[94:95], v[238:239]
	v_cvt_pk_bf16_f32 v92, v92, v93
	v_cvt_pk_bf16_f32 v93, v94, v95
	global_store_dwordx2 v146, v[92:93], s[66:67] offset:1536 sc0 sc1
	v_add_u32_e32 v146, 0x800, v146
	global_load_dwordx4 v[80:83], v144, s[46:47] nt
	global_load_dwordx4 v[84:87], v144, s[46:47] offset:1024 nt
	global_load_dwordx4 v[88:91], v144, s[46:47] offset:2048 nt
	global_load_dwordx4 v[92:95], v144, s[46:47] offset:3072 nt
	v_add_u32_e32 v144, 0x1000, v144
	s_waitcnt vmcnt(24)
	v_pk_mul_f32 v[242:243], v[96:97], v[96:97]
	v_pk_mul_f32 v[244:245], v[100:101], v[100:101]
	v_pk_mul_f32 v[246:247], v[98:99], v[98:99]
	v_pk_mul_f32 v[248:249], v[102:103], v[102:103]
	v_add_f32_e32 v204, v245, v244
	v_add_f32_e32 v205, v243, v242
	v_add_f32_e32 v204, v248, v204
	v_add_f32_e32 v205, v246, v205
	v_add_f32_e32 v204, v249, v204
	v_add_f32_e32 v205, v247, v205
	v_pk_mul_f32 v[242:243], v[104:105], v[104:105]
	v_pk_mul_f32 v[244:245], v[108:109], v[108:109]
	v_pk_mul_f32 v[246:247], v[106:107], v[106:107]
	v_pk_mul_f32 v[248:249], v[110:111], v[110:111]
	v_add_f32_e32 v206, v243, v242
	v_add_f32_e32 v207, v245, v244
	v_add_f32_e32 v206, v246, v206
	v_add_f32_e32 v207, v248, v207
	v_add_f32_e32 v206, v247, v206
	v_add_f32_e32 v207, v249, v207
	v_add_f32_e32 v204, v205, v204
	v_add_f32_e32 v204, v204, v206
	v_add_f32_e32 v204, v204, v207
	ds_swizzle_b32 v205, v204 offset:swizzle(SWAP,1)
	s_waitcnt lgkmcnt(0)
	v_add_f32_e32 v204, v204, v205
	ds_swizzle_b32 v205, v204 offset:swizzle(SWAP,2)
	s_waitcnt lgkmcnt(0)
	v_add_f32_e32 v204, v204, v205
	ds_swizzle_b32 v205, v204 offset:swizzle(SWAP,4)
	s_waitcnt lgkmcnt(0)
	v_add_f32_e32 v204, v204, v205
	ds_swizzle_b32 v205, v204 offset:swizzle(SWAP,8)
	s_waitcnt lgkmcnt(0)
	v_add_f32_e32 v204, v204, v205
	ds_swizzle_b32 v205, v204 offset:swizzle(SWAP,16)
	s_waitcnt lgkmcnt(0)
	v_add_f32_e32 v204, v204, v205
	v_mov_b32_e32 v205, v204
	s_nop 1
	v_permlane32_swap_b32_e32 v204, v205
	v_add_f32_e32 v204, v204, v205
	v_mov_b32_e32 v205, 0x358637bd
	v_fmamk_f32 v204, v204, 0x3a800000, v205
	v_rsq_f32_e32 v204, v204
	s_nop 0
	v_pk_mul_f32 v[96:97], v[96:97], v[204:205] op_sel_hi:[1,0]
	v_pk_mul_f32 v[98:99], v[98:99], v[204:205] op_sel_hi:[1,0]
	v_pk_mul_f32 v[96:97], v[188:189], v[96:97]
	v_pk_mul_f32 v[98:99], v[190:191], v[98:99]
	v_pk_fma_f32 v[96:97], v[34:35], v[96:97], v[224:225]
	v_pk_fma_f32 v[98:99], v[36:37], v[98:99], v[226:227]
	v_cvt_pk_bf16_f32 v96, v96, v97
	v_cvt_pk_bf16_f32 v97, v98, v99
	global_store_dwordx2 v146, v[96:97], s[66:67] sc0 sc1
	v_pk_mul_f32 v[100:101], v[100:101], v[204:205] op_sel_hi:[1,0]
	v_pk_mul_f32 v[102:103], v[102:103], v[204:205] op_sel_hi:[1,0]
	v_pk_mul_f32 v[100:101], v[192:193], v[100:101]
	v_pk_mul_f32 v[102:103], v[194:195], v[102:103]
	v_pk_fma_f32 v[100:101], v[38:39], v[100:101], v[228:229]
	v_pk_fma_f32 v[102:103], v[40:41], v[102:103], v[230:231]
	v_cvt_pk_bf16_f32 v100, v100, v101
	v_cvt_pk_bf16_f32 v101, v102, v103
	global_store_dwordx2 v146, v[100:101], s[66:67] offset:512 sc0 sc1
	v_pk_mul_f32 v[104:105], v[104:105], v[204:205] op_sel_hi:[1,0]
	v_pk_mul_f32 v[106:107], v[106:107], v[204:205] op_sel_hi:[1,0]
	v_pk_mul_f32 v[104:105], v[196:197], v[104:105]
	v_pk_mul_f32 v[106:107], v[198:199], v[106:107]
	v_pk_fma_f32 v[104:105], v[42:43], v[104:105], v[232:233]
	v_pk_fma_f32 v[106:107], v[44:45], v[106:107], v[234:235]
	v_cvt_pk_bf16_f32 v104, v104, v105
	v_cvt_pk_bf16_f32 v105, v106, v107
	global_store_dwordx2 v146, v[104:105], s[66:67] offset:1024 sc0 sc1
	v_pk_mul_f32 v[108:109], v[108:109], v[204:205] op_sel_hi:[1,0]
	v_pk_mul_f32 v[110:111], v[110:111], v[204:205] op_sel_hi:[1,0]
	v_pk_mul_f32 v[108:109], v[200:201], v[108:109]
	v_pk_mul_f32 v[110:111], v[202:203], v[110:111]
	v_pk_fma_f32 v[108:109], v[46:47], v[108:109], v[236:237]
	v_pk_fma_f32 v[110:111], v[48:49], v[110:111], v[238:239]
	v_cvt_pk_bf16_f32 v108, v108, v109
	v_cvt_pk_bf16_f32 v109, v110, v111
	global_store_dwordx2 v146, v[108:109], s[66:67] offset:1536 sc0 sc1
	v_add_u32_e32 v146, 0x800, v146
	global_load_dwordx4 v[96:99], v144, s[46:47] nt
	global_load_dwordx4 v[100:103], v144, s[46:47] offset:1024 nt
	global_load_dwordx4 v[104:107], v144, s[46:47] offset:2048 nt
	global_load_dwordx4 v[108:111], v144, s[46:47] offset:3072 nt
	v_add_u32_e32 v144, 0x1000, v144
	s_waitcnt vmcnt(28)
; __device__ __forceinline__ unsigned pk2(float lo, float hi) { const g_f32x2 f = {lo, hi}; return __builtin_bit_cast(unsigned, __builtin_convertvector(f, g_bf16x2)); }
; __device__ __forceinline__ void p_norm(const float* hlat, const float* hctx, const float* g, const float* modl, int sh_off, int sc_off, bf16_t* A, int M,
;                                        const float* part, const float* cgate, float* hcout) {
;     ...
;         for (int i = 0; i < 4; ++i) {
;             if (part != nullptr && row >= NLAT) {
;                 const size_t po = (size_t)(row - NLAT) * 1024 + i * 256 + lane * 4;
;                 const float4 p0 = *(const float4*)(part + po), p1 = *(const float4*)(part + (size_t)4096 * 1024 + po), cg = *(const float4*)(cgate + i * 256 + lane * 4);
;                 v[i].x += cg.x * (p0.x + p1.x); v[i].y += cg.y * (p0.y + p1.y); v[i].z += cg.z * (p0.z + p1.z); v[i].w += cg.w * (p0.w + p1.w);
;                 *(float4*)(hcout + po) = v[i];
;             }
;             ss += v[i].x * v[i].x + v[i].y * v[i].y + v[i].z * v[i].z + v[i].w * v[i].w; }
;         ss = wave_sum(ss);
;         const float rstd = rsqrtf(ss * (1.0f / 1024.0f) + EPS);
;         const float* mr = modl + (size_t)r * 6144;
; #pragma unroll
;         for (int i = 0; i < 4; ++i) {
;             const int k = i * 256 + lane * 4;
;             const float4 gg = *(const float4*)(g + k), scv = *(const float4*)(mr + sc_off + k), shv = *(const float4*)(mr + sh_off + k);
;             const float o0 = v[i].x * rstd * gg.x * (1.0f + scv.x) + shv.x, o1 = v[i].y * rstd * gg.y * (1.0f + scv.y) + shv.y;
;             const float o2 = v[i].z * rstd * gg.z * (1.0f + scv.z) + shv.z, o3 = v[i].w * rstd * gg.w * (1.0f + scv.w) + shv.w;
;             uint2 w; w.x = pk2(o0, o1); w.y = pk2(o2, o3);
;             *(uint2*)(A + (size_t)row * 1024 + k) = w;
;         }
	v_pk_mul_f32 v[242:243], v[112:113], v[112:113]
	v_pk_mul_f32 v[244:245], v[116:117], v[116:117]
	v_pk_mul_f32 v[246:247], v[114:115], v[114:115]
	v_pk_mul_f32 v[248:249], v[118:119], v[118:119]
	v_add_f32_e32 v204, v245, v244
	v_add_f32_e32 v205, v243, v242
	v_add_f32_e32 v204, v248, v204
	v_add_f32_e32 v205, v246, v205
	v_add_f32_e32 v204, v249, v204
	v_add_f32_e32 v205, v247, v205
	v_pk_mul_f32 v[242:243], v[120:121], v[120:121]
	v_pk_mul_f32 v[244:245], v[124:125], v[124:125]
	v_pk_mul_f32 v[246:247], v[122:123], v[122:123]
	v_pk_mul_f32 v[248:249], v[126:127], v[126:127]
	v_add_f32_e32 v206, v243, v242
	v_add_f32_e32 v207, v245, v244
	v_add_f32_e32 v206, v246, v206
	v_add_f32_e32 v207, v248, v207
	v_add_f32_e32 v206, v247, v206
	v_add_f32_e32 v207, v249, v207
	v_add_f32_e32 v204, v205, v204
	v_add_f32_e32 v204, v204, v206
	v_add_f32_e32 v204, v204, v207
	ds_swizzle_b32 v205, v204 offset:swizzle(SWAP,1)
	s_waitcnt lgkmcnt(0)
	v_add_f32_e32 v204, v204, v205
	ds_swizzle_b32 v205, v204 offset:swizzle(SWAP,2)
	s_waitcnt lgkmcnt(0)
	v_add_f32_e32 v204, v204, v205
	ds_swizzle_b32 v205, v204 offset:swizzle(SWAP,4)
	s_waitcnt lgkmcnt(0)
	v_add_f32_e32 v204, v204, v205
	ds_swizzle_b32 v205, v204 offset:swizzle(SWAP,8)
	s_waitcnt lgkmcnt(0)
	v_add_f32_e32 v204, v204, v205
	ds_swizzle_b32 v205, v204 offset:swizzle(SWAP,16)
	s_waitcnt lgkmcnt(0)
	v_add_f32_e32 v204, v204, v205
	v_mov_b32_e32 v205, v204
	s_nop 1
	v_permlane32_swap_b32_e32 v204, v205
	v_add_f32_e32 v204, v204, v205
	v_mov_b32_e32 v205, 0x358637bd
	v_fmamk_f32 v204, v204, 0x3a800000, v205
	v_rsq_f32_e32 v204, v204
	s_nop 0
	v_pk_mul_f32 v[112:113], v[112:113], v[204:205] op_sel_hi:[1,0]
	v_pk_mul_f32 v[114:115], v[114:115], v[204:205] op_sel_hi:[1,0]
	v_pk_mul_f32 v[112:113], v[188:189], v[112:113]
	v_pk_mul_f32 v[114:115], v[190:191], v[114:115]
	v_pk_fma_f32 v[112:113], v[34:35], v[112:113], v[224:225]
	v_pk_fma_f32 v[114:115], v[36:37], v[114:115], v[226:227]
	v_cvt_pk_bf16_f32 v112, v112, v113
	v_cvt_pk_bf16_f32 v113, v114, v115
	global_store_dwordx2 v146, v[112:113], s[66:67] sc0 sc1
	v_pk_mul_f32 v[116:117], v[116:117], v[204:205] op_sel_hi:[1,0]
	v_pk_mul_f32 v[118:119], v[118:119], v[204:205] op_sel_hi:[1,0]
	v_pk_mul_f32 v[116:117], v[192:193], v[116:117]
	v_pk_mul_f32 v[118:119], v[194:195], v[118:119]
	v_pk_fma_f32 v[116:117], v[38:39], v[116:117], v[228:229]
	v_pk_fma_f32 v[118:119], v[40:41], v[118:119], v[230:231]
	v_cvt_pk_bf16_f32 v116, v116, v117
	v_cvt_pk_bf16_f32 v117, v118, v119
	global_store_dwordx2 v146, v[116:117], s[66:67] offset:512 sc0 sc1
	v_pk_mul_f32 v[120:121], v[120:121], v[204:205] op_sel_hi:[1,0]
	v_pk_mul_f32 v[122:123], v[122:123], v[204:205] op_sel_hi:[1,0]
	v_pk_mul_f32 v[120:121], v[196:197], v[120:121]
	v_pk_mul_f32 v[122:123], v[198:199], v[122:123]
	v_pk_fma_f32 v[120:121], v[42:43], v[120:121], v[232:233]
	v_pk_fma_f32 v[122:123], v[44:45], v[122:123], v[234:235]
	v_cvt_pk_bf16_f32 v120, v120, v121
	v_cvt_pk_bf16_f32 v121, v122, v123
	global_store_dwordx2 v146, v[120:121], s[66:67] offset:1024 sc0 sc1
	v_pk_mul_f32 v[124:125], v[124:125], v[204:205] op_sel_hi:[1,0]
	v_pk_mul_f32 v[126:127], v[126:127], v[204:205] op_sel_hi:[1,0]
	v_pk_mul_f32 v[124:125], v[200:201], v[124:125]
	v_pk_mul_f32 v[126:127], v[202:203], v[126:127]
	v_pk_fma_f32 v[124:125], v[46:47], v[124:125], v[236:237]
	v_pk_fma_f32 v[126:127], v[48:49], v[126:127], v[238:239]
	v_cvt_pk_bf16_f32 v124, v124, v125
	v_cvt_pk_bf16_f32 v125, v126, v127
	global_store_dwordx2 v146, v[124:125], s[66:67] offset:1536 sc0 sc1
	v_add_u32_e32 v146, 0x800, v146
	global_load_dwordx4 v[112:115], v144, s[46:47] nt
	global_load_dwordx4 v[116:119], v144, s[46:47] offset:1024 nt
	global_load_dwordx4 v[120:123], v144, s[46:47] offset:2048 nt
	global_load_dwordx4 v[124:127], v144, s[46:47] offset:3072 nt
	v_add_u32_e32 v144, 0x1000, v144
	s_waitcnt vmcnt(32)
	v_pk_mul_f32 v[242:243], v[128:129], v[128:129]
	v_pk_mul_f32 v[244:245], v[132:133], v[132:133]
	v_pk_mul_f32 v[246:247], v[130:131], v[130:131]
	v_pk_mul_f32 v[248:249], v[134:135], v[134:135]
	v_add_f32_e32 v204, v245, v244
	v_add_f32_e32 v205, v243, v242
	v_add_f32_e32 v204, v248, v204
	v_add_f32_e32 v205, v246, v205
	v_add_f32_e32 v204, v249, v204
	v_add_f32_e32 v205, v247, v205
	v_pk_mul_f32 v[242:243], v[136:137], v[136:137]
	v_pk_mul_f32 v[244:245], v[140:141], v[140:141]
	v_pk_mul_f32 v[246:247], v[138:139], v[138:139]
	v_pk_mul_f32 v[248:249], v[142:143], v[142:143]
	v_add_f32_e32 v206, v243, v242
	v_add_f32_e32 v207, v245, v244
	v_add_f32_e32 v206, v246, v206
	v_add_f32_e32 v207, v248, v207
	v_add_f32_e32 v206, v247, v206
	v_add_f32_e32 v207, v249, v207
	v_add_f32_e32 v204, v205, v204
	v_add_f32_e32 v204, v204, v206
	v_add_f32_e32 v204, v204, v207
	ds_swizzle_b32 v205, v204 offset:swizzle(SWAP,1)
	s_waitcnt lgkmcnt(0)
	v_add_f32_e32 v204, v204, v205
	ds_swizzle_b32 v205, v204 offset:swizzle(SWAP,2)
	s_waitcnt lgkmcnt(0)
	v_add_f32_e32 v204, v204, v205
	ds_swizzle_b32 v205, v204 offset:swizzle(SWAP,4)
	s_waitcnt lgkmcnt(0)
	v_add_f32_e32 v204, v204, v205
	ds_swizzle_b32 v205, v204 offset:swizzle(SWAP,8)
	s_waitcnt lgkmcnt(0)
	v_add_f32_e32 v204, v204, v205
	ds_swizzle_b32 v205, v204 offset:swizzle(SWAP,16)
	s_waitcnt lgkmcnt(0)
; __device__ __forceinline__ unsigned pk2(float lo, float hi) { const g_f32x2 f = {lo, hi}; return __builtin_bit_cast(unsigned, __builtin_convertvector(f, g_bf16x2)); }
; __device__ __forceinline__ void p_norm(const float* hlat, const float* hctx, const float* g, const float* modl, int sh_off, int sc_off, bf16_t* A, int M,
;                                        const float* part, const float* cgate, float* hcout) {
;     ...
;         for (int i = 0; i < 4; ++i) {
;             if (part != nullptr && row >= NLAT) {
;                 const size_t po = (size_t)(row - NLAT) * 1024 + i * 256 + lane * 4;
;                 const float4 p0 = *(const float4*)(part + po), p1 = *(const float4*)(part + (size_t)4096 * 1024 + po), cg = *(const float4*)(cgate + i * 256 + lane * 4);
;                 v[i].x += cg.x * (p0.x + p1.x); v[i].y += cg.y * (p0.y + p1.y); v[i].z += cg.z * (p0.z + p1.z); v[i].w += cg.w * (p0.w + p1.w);
;                 *(float4*)(hcout + po) = v[i];
;             }
;             ss += v[i].x * v[i].x + v[i].y * v[i].y + v[i].z * v[i].z + v[i].w * v[i].w; }
;         ss = wave_sum(ss);
;         const float rstd = rsqrtf(ss * (1.0f / 1024.0f) + EPS);
;         const float* mr = modl + (size_t)r * 6144;
; #pragma unroll
;         for (int i = 0; i < 4; ++i) {
;             const int k = i * 256 + lane * 4;
;             const float4 gg = *(const float4*)(g + k), scv = *(const float4*)(mr + sc_off + k), shv = *(const float4*)(mr + sh_off + k);
;             const float o0 = v[i].x * rstd * gg.x * (1.0f + scv.x) + shv.x, o1 = v[i].y * rstd * gg.y * (1.0f + scv.y) + shv.y;
;             const float o2 = v[i].z * rstd * gg.z * (1.0f + scv.z) + shv.z, o3 = v[i].w * rstd * gg.w * (1.0f + scv.w) + shv.w;
;             uint2 w; w.x = pk2(o0, o1); w.y = pk2(o2, o3);
;             *(uint2*)(A + (size_t)row * 1024 + k) = w;
;         }
	v_add_f32_e32 v204, v204, v205
	v_mov_b32_e32 v205, v204
	s_nop 1
	v_permlane32_swap_b32_e32 v204, v205
	v_add_f32_e32 v204, v204, v205
	v_mov_b32_e32 v205, 0x358637bd
	v_fmamk_f32 v204, v204, 0x3a800000, v205
	v_rsq_f32_e32 v204, v204
	s_nop 0
	v_pk_mul_f32 v[128:129], v[128:129], v[204:205] op_sel_hi:[1,0]
	v_pk_mul_f32 v[130:131], v[130:131], v[204:205] op_sel_hi:[1,0]
	v_pk_mul_f32 v[128:129], v[188:189], v[128:129]
	v_pk_mul_f32 v[130:131], v[190:191], v[130:131]
	v_pk_fma_f32 v[128:129], v[34:35], v[128:129], v[224:225]
	v_pk_fma_f32 v[130:131], v[36:37], v[130:131], v[226:227]
	v_cvt_pk_bf16_f32 v128, v128, v129
	v_cvt_pk_bf16_f32 v129, v130, v131
	global_store_dwordx2 v146, v[128:129], s[66:67] sc0 sc1
	v_pk_mul_f32 v[132:133], v[132:133], v[204:205] op_sel_hi:[1,0]
	v_pk_mul_f32 v[134:135], v[134:135], v[204:205] op_sel_hi:[1,0]
	v_pk_mul_f32 v[132:133], v[192:193], v[132:133]
	v_pk_mul_f32 v[134:135], v[194:195], v[134:135]
	v_pk_fma_f32 v[132:133], v[38:39], v[132:133], v[228:229]
	v_pk_fma_f32 v[134:135], v[40:41], v[134:135], v[230:231]
	v_cvt_pk_bf16_f32 v132, v132, v133
	v_cvt_pk_bf16_f32 v133, v134, v135
	global_store_dwordx2 v146, v[132:133], s[66:67] offset:512 sc0 sc1
	v_pk_mul_f32 v[136:137], v[136:137], v[204:205] op_sel_hi:[1,0]
	v_pk_mul_f32 v[138:139], v[138:139], v[204:205] op_sel_hi:[1,0]
	v_pk_mul_f32 v[136:137], v[196:197], v[136:137]
	v_pk_mul_f32 v[138:139], v[198:199], v[138:139]
	v_pk_fma_f32 v[136:137], v[42:43], v[136:137], v[232:233]
	v_pk_fma_f32 v[138:139], v[44:45], v[138:139], v[234:235]
	v_cvt_pk_bf16_f32 v136, v136, v137
	v_cvt_pk_bf16_f32 v137, v138, v139
	global_store_dwordx2 v146, v[136:137], s[66:67] offset:1024 sc0 sc1
	v_pk_mul_f32 v[140:141], v[140:141], v[204:205] op_sel_hi:[1,0]
	v_pk_mul_f32 v[142:143], v[142:143], v[204:205] op_sel_hi:[1,0]
	v_pk_mul_f32 v[140:141], v[200:201], v[140:141]
	v_pk_mul_f32 v[142:143], v[202:203], v[142:143]
	v_pk_fma_f32 v[140:141], v[46:47], v[140:141], v[236:237]
	v_pk_fma_f32 v[142:143], v[48:49], v[142:143], v[238:239]
	v_cvt_pk_bf16_f32 v140, v140, v141
	v_cvt_pk_bf16_f32 v141, v142, v143
	global_store_dwordx2 v146, v[140:141], s[66:67] offset:1536 sc0 sc1
	v_add_u32_e32 v146, 0x800, v146
	global_load_dwordx4 v[128:131], v144, s[46:47] nt
	global_load_dwordx4 v[132:135], v144, s[46:47] offset:1024 nt
	global_load_dwordx4 v[136:139], v144, s[46:47] offset:2048 nt
	global_load_dwordx4 v[140:143], v144, s[46:47] offset:3072 nt
	v_add_u32_e32 v144, 0x1000, v144
	s_waitcnt vmcnt(36)
	v_pk_mul_f32 v[242:243], v[156:157], v[156:157]
	v_pk_mul_f32 v[244:245], v[160:161], v[160:161]
	v_pk_mul_f32 v[246:247], v[158:159], v[158:159]
	v_pk_mul_f32 v[248:249], v[162:163], v[162:163]
	v_add_f32_e32 v204, v245, v244
	v_add_f32_e32 v205, v243, v242
	v_add_f32_e32 v204, v248, v204
	v_add_f32_e32 v205, v246, v205
	v_add_f32_e32 v204, v249, v204
	v_add_f32_e32 v205, v247, v205
	v_pk_mul_f32 v[242:243], v[164:165], v[164:165]
	v_pk_mul_f32 v[244:245], v[168:169], v[168:169]
	v_pk_mul_f32 v[246:247], v[166:167], v[166:167]
	v_pk_mul_f32 v[248:249], v[170:171], v[170:171]
	v_add_f32_e32 v206, v243, v242
	v_add_f32_e32 v207, v245, v244
	v_add_f32_e32 v206, v246, v206
	v_add_f32_e32 v207, v248, v207
	v_add_f32_e32 v206, v247, v206
	v_add_f32_e32 v207, v249, v207
	v_add_f32_e32 v204, v205, v204
	v_add_f32_e32 v204, v204, v206
	v_add_f32_e32 v204, v204, v207
	ds_swizzle_b32 v205, v204 offset:swizzle(SWAP,1)
	s_waitcnt lgkmcnt(0)
	v_add_f32_e32 v204, v204, v205
	ds_swizzle_b32 v205, v204 offset:swizzle(SWAP,2)
	s_waitcnt lgkmcnt(0)
	v_add_f32_e32 v204, v204, v205
	ds_swizzle_b32 v205, v204 offset:swizzle(SWAP,4)
	s_waitcnt lgkmcnt(0)
	v_add_f32_e32 v204, v204, v205
	ds_swizzle_b32 v205, v204 offset:swizzle(SWAP,8)
	s_waitcnt lgkmcnt(0)
	v_add_f32_e32 v204, v204, v205
	ds_swizzle_b32 v205, v204 offset:swizzle(SWAP,16)
	s_waitcnt lgkmcnt(0)
	v_add_f32_e32 v204, v204, v205
	v_mov_b32_e32 v205, v204
	s_nop 1
	v_permlane32_swap_b32_e32 v204, v205
	v_add_f32_e32 v204, v204, v205
	v_mov_b32_e32 v205, 0x358637bd
	v_fmamk_f32 v204, v204, 0x3a800000, v205
	v_rsq_f32_e32 v204, v204
	s_nop 0
	v_pk_mul_f32 v[156:157], v[156:157], v[204:205] op_sel_hi:[1,0]
	v_pk_mul_f32 v[158:159], v[158:159], v[204:205] op_sel_hi:[1,0]
	v_pk_mul_f32 v[156:157], v[188:189], v[156:157]
	v_pk_mul_f32 v[158:159], v[190:191], v[158:159]
	v_pk_fma_f32 v[156:157], v[34:35], v[156:157], v[224:225]
	v_pk_fma_f32 v[158:159], v[36:37], v[158:159], v[226:227]
	v_cvt_pk_bf16_f32 v156, v156, v157
	v_cvt_pk_bf16_f32 v157, v158, v159
	global_store_dwordx2 v146, v[156:157], s[66:67] sc0 sc1
	v_pk_mul_f32 v[160:161], v[160:161], v[204:205] op_sel_hi:[1,0]
	v_pk_mul_f32 v[162:163], v[162:163], v[204:205] op_sel_hi:[1,0]
	v_pk_mul_f32 v[160:161], v[192:193], v[160:161]
	v_pk_mul_f32 v[162:163], v[194:195], v[162:163]
	v_pk_fma_f32 v[160:161], v[38:39], v[160:161], v[228:229]
	v_pk_fma_f32 v[162:163], v[40:41], v[162:163], v[230:231]
	v_cvt_pk_bf16_f32 v160, v160, v161
	v_cvt_pk_bf16_f32 v161, v162, v163
	global_store_dwordx2 v146, v[160:161], s[66:67] offset:512 sc0 sc1
	v_pk_mul_f32 v[164:165], v[164:165], v[204:205] op_sel_hi:[1,0]
	v_pk_mul_f32 v[166:167], v[166:167], v[204:205] op_sel_hi:[1,0]
	v_pk_mul_f32 v[164:165], v[196:197], v[164:165]
	v_pk_mul_f32 v[166:167], v[198:199], v[166:167]
	v_pk_fma_f32 v[164:165], v[42:43], v[164:165], v[232:233]
	v_pk_fma_f32 v[166:167], v[44:45], v[166:167], v[234:235]
	v_cvt_pk_bf16_f32 v164, v164, v165
	v_cvt_pk_bf16_f32 v165, v166, v167
	global_store_dwordx2 v146, v[164:165], s[66:67] offset:1024 sc0 sc1
	v_pk_mul_f32 v[168:169], v[168:169], v[204:205] op_sel_hi:[1,0]
	v_pk_mul_f32 v[170:171], v[170:171], v[204:205] op_sel_hi:[1,0]
	v_pk_mul_f32 v[168:169], v[200:201], v[168:169]
	v_pk_mul_f32 v[170:171], v[202:203], v[170:171]
	v_pk_fma_f32 v[168:169], v[46:47], v[168:169], v[236:237]
	v_pk_fma_f32 v[170:171], v[48:49], v[170:171], v[238:239]
	v_cvt_pk_bf16_f32 v168, v168, v169
	v_cvt_pk_bf16_f32 v169, v170, v171
	global_store_dwordx2 v146, v[168:169], s[66:67] offset:1536 sc0 sc1
	v_add_u32_e32 v146, 0x800, v146
	global_load_dwordx4 v[156:159], v144, s[46:47] nt
	global_load_dwordx4 v[160:163], v144, s[46:47] offset:1024 nt
	global_load_dwordx4 v[164:167], v144, s[46:47] offset:2048 nt
	global_load_dwordx4 v[168:171], v144, s[46:47] offset:3072 nt
	v_add_u32_e32 v144, 0x1000, v144
	s_waitcnt vmcnt(40)
; __device__ __forceinline__ unsigned pk2(float lo, float hi) { const g_f32x2 f = {lo, hi}; return __builtin_bit_cast(unsigned, __builtin_convertvector(f, g_bf16x2)); }
; __device__ __forceinline__ void p_norm(const float* hlat, const float* hctx, const float* g, const float* modl, int sh_off, int sc_off, bf16_t* A, int M,
;                                        const float* part, const float* cgate, float* hcout) {
;     ...
;         for (int i = 0; i < 4; ++i) {
;             if (part != nullptr && row >= NLAT) {
;                 const size_t po = (size_t)(row - NLAT) * 1024 + i * 256 + lane * 4;
;                 const float4 p0 = *(const float4*)(part + po), p1 = *(const float4*)(part + (size_t)4096 * 1024 + po), cg = *(const float4*)(cgate + i * 256 + lane * 4);
;                 v[i].x += cg.x * (p0.x + p1.x); v[i].y += cg.y * (p0.y + p1.y); v[i].z += cg.z * (p0.z + p1.z); v[i].w += cg.w * (p0.w + p1.w);
;                 *(float4*)(hcout + po) = v[i];
;             }
;             ss += v[i].x * v[i].x + v[i].y * v[i].y + v[i].z * v[i].z + v[i].w * v[i].w; }
;         ss = wave_sum(ss);
;         const float rstd = rsqrtf(ss * (1.0f / 1024.0f) + EPS);
;         const float* mr = modl + (size_t)r * 6144;
; #pragma unroll
;         for (int i = 0; i < 4; ++i) {
;             const int k = i * 256 + lane * 4;
;             const float4 gg = *(const float4*)(g + k), scv = *(const float4*)(mr + sc_off + k), shv = *(const float4*)(mr + sh_off + k);
;             const float o0 = v[i].x * rstd * gg.x * (1.0f + scv.x) + shv.x, o1 = v[i].y * rstd * gg.y * (1.0f + scv.y) + shv.y;
;             const float o2 = v[i].z * rstd * gg.z * (1.0f + scv.z) + shv.z, o3 = v[i].w * rstd * gg.w * (1.0f + scv.w) + shv.w;
;             uint2 w; w.x = pk2(o0, o1); w.y = pk2(o2, o3);
;             *(uint2*)(A + (size_t)row * 1024 + k) = w;
;         }
	v_pk_mul_f32 v[242:243], v[172:173], v[172:173]
	v_pk_mul_f32 v[244:245], v[176:177], v[176:177]
	v_pk_mul_f32 v[246:247], v[174:175], v[174:175]
	v_pk_mul_f32 v[248:249], v[178:179], v[178:179]
	v_add_f32_e32 v204, v245, v244
	v_add_f32_e32 v205, v243, v242
	v_add_f32_e32 v204, v248, v204
	v_add_f32_e32 v205, v246, v205
	v_add_f32_e32 v204, v249, v204
	v_add_f32_e32 v205, v247, v205
	v_pk_mul_f32 v[242:243], v[180:181], v[180:181]
	v_pk_mul_f32 v[244:245], v[184:185], v[184:185]
	v_pk_mul_f32 v[246:247], v[182:183], v[182:183]
	v_pk_mul_f32 v[248:249], v[186:187], v[186:187]
	v_add_f32_e32 v206, v243, v242
	v_add_f32_e32 v207, v245, v244
	v_add_f32_e32 v206, v246, v206
	v_add_f32_e32 v207, v248, v207
	v_add_f32_e32 v206, v247, v206
	v_add_f32_e32 v207, v249, v207
	v_add_f32_e32 v204, v205, v204
	v_add_f32_e32 v204, v204, v206
	v_add_f32_e32 v204, v204, v207
	ds_swizzle_b32 v205, v204 offset:swizzle(SWAP,1)
	s_waitcnt lgkmcnt(0)
	v_add_f32_e32 v204, v204, v205
	ds_swizzle_b32 v205, v204 offset:swizzle(SWAP,2)
	s_waitcnt lgkmcnt(0)
	v_add_f32_e32 v204, v204, v205
	ds_swizzle_b32 v205, v204 offset:swizzle(SWAP,4)
	s_waitcnt lgkmcnt(0)
	v_add_f32_e32 v204, v204, v205
	ds_swizzle_b32 v205, v204 offset:swizzle(SWAP,8)
	s_waitcnt lgkmcnt(0)
	v_add_f32_e32 v204, v204, v205
	ds_swizzle_b32 v205, v204 offset:swizzle(SWAP,16)
	s_waitcnt lgkmcnt(0)
	v_add_f32_e32 v204, v204, v205
	v_mov_b32_e32 v205, v204
	s_nop 1
	v_permlane32_swap_b32_e32 v204, v205
	v_add_f32_e32 v204, v204, v205
	v_mov_b32_e32 v205, 0x358637bd
	v_fmamk_f32 v204, v204, 0x3a800000, v205
	v_rsq_f32_e32 v204, v204
	s_nop 0
	v_pk_mul_f32 v[172:173], v[172:173], v[204:205] op_sel_hi:[1,0]
	v_pk_mul_f32 v[174:175], v[174:175], v[204:205] op_sel_hi:[1,0]
	v_pk_mul_f32 v[172:173], v[188:189], v[172:173]
	v_pk_mul_f32 v[174:175], v[190:191], v[174:175]
	v_pk_fma_f32 v[172:173], v[34:35], v[172:173], v[224:225]
	v_pk_fma_f32 v[174:175], v[36:37], v[174:175], v[226:227]
	v_cvt_pk_bf16_f32 v172, v172, v173
	v_cvt_pk_bf16_f32 v173, v174, v175
	global_store_dwordx2 v146, v[172:173], s[66:67] sc0 sc1
	v_pk_mul_f32 v[176:177], v[176:177], v[204:205] op_sel_hi:[1,0]
	v_pk_mul_f32 v[178:179], v[178:179], v[204:205] op_sel_hi:[1,0]
	v_pk_mul_f32 v[176:177], v[192:193], v[176:177]
	v_pk_mul_f32 v[178:179], v[194:195], v[178:179]
	v_pk_fma_f32 v[176:177], v[38:39], v[176:177], v[228:229]
	v_pk_fma_f32 v[178:179], v[40:41], v[178:179], v[230:231]
	v_cvt_pk_bf16_f32 v176, v176, v177
	v_cvt_pk_bf16_f32 v177, v178, v179
	global_store_dwordx2 v146, v[176:177], s[66:67] offset:512 sc0 sc1
	v_pk_mul_f32 v[180:181], v[180:181], v[204:205] op_sel_hi:[1,0]
	v_pk_mul_f32 v[182:183], v[182:183], v[204:205] op_sel_hi:[1,0]
	v_pk_mul_f32 v[180:181], v[196:197], v[180:181]
	v_pk_mul_f32 v[182:183], v[198:199], v[182:183]
	v_pk_fma_f32 v[180:181], v[42:43], v[180:181], v[232:233]
	v_pk_fma_f32 v[182:183], v[44:45], v[182:183], v[234:235]
	v_cvt_pk_bf16_f32 v180, v180, v181
	v_cvt_pk_bf16_f32 v181, v182, v183
	global_store_dwordx2 v146, v[180:181], s[66:67] offset:1024 sc0 sc1
	v_pk_mul_f32 v[184:185], v[184:185], v[204:205] op_sel_hi:[1,0]
	v_pk_mul_f32 v[186:187], v[186:187], v[204:205] op_sel_hi:[1,0]
	v_pk_mul_f32 v[184:185], v[200:201], v[184:185]
	v_pk_mul_f32 v[186:187], v[202:203], v[186:187]
	v_pk_fma_f32 v[184:185], v[46:47], v[184:185], v[236:237]
	v_pk_fma_f32 v[186:187], v[48:49], v[186:187], v[238:239]
	v_cvt_pk_bf16_f32 v184, v184, v185
	v_cvt_pk_bf16_f32 v185, v186, v187
	global_store_dwordx2 v146, v[184:185], s[66:67] offset:1536 sc0 sc1
	v_add_u32_e32 v146, 0x800, v146
	global_load_dwordx4 v[172:175], v144, s[46:47] nt
	global_load_dwordx4 v[176:179], v144, s[46:47] offset:1024 nt
	global_load_dwordx4 v[180:183], v144, s[46:47] offset:2048 nt
	global_load_dwordx4 v[184:187], v144, s[46:47] offset:3072 nt
	v_add_u32_e32 v144, 0x1000, v144
	s_waitcnt vmcnt(40)
	v_pk_mul_f32 v[242:243], v[80:81], v[80:81]
	v_pk_mul_f32 v[244:245], v[84:85], v[84:85]
	v_pk_mul_f32 v[246:247], v[82:83], v[82:83]
	v_pk_mul_f32 v[248:249], v[86:87], v[86:87]
	v_add_f32_e32 v204, v245, v244
	v_add_f32_e32 v205, v243, v242
	v_add_f32_e32 v204, v248, v204
	v_add_f32_e32 v205, v246, v205
	v_add_f32_e32 v204, v249, v204
	v_add_f32_e32 v205, v247, v205
	v_pk_mul_f32 v[242:243], v[88:89], v[88:89]
	v_pk_mul_f32 v[244:245], v[92:93], v[92:93]
	v_pk_mul_f32 v[246:247], v[90:91], v[90:91]
	v_pk_mul_f32 v[248:249], v[94:95], v[94:95]
	v_add_f32_e32 v206, v243, v242
	v_add_f32_e32 v207, v245, v244
	v_add_f32_e32 v206, v246, v206
	v_add_f32_e32 v207, v248, v207
	v_add_f32_e32 v206, v247, v206
	v_add_f32_e32 v207, v249, v207
	v_add_f32_e32 v204, v205, v204
	v_add_f32_e32 v204, v204, v206
	v_add_f32_e32 v204, v204, v207
	ds_swizzle_b32 v205, v204 offset:swizzle(SWAP,1)
	s_waitcnt lgkmcnt(0)
	v_add_f32_e32 v204, v204, v205
	ds_swizzle_b32 v205, v204 offset:swizzle(SWAP,2)
	s_waitcnt lgkmcnt(0)
	v_add_f32_e32 v204, v204, v205
	ds_swizzle_b32 v205, v204 offset:swizzle(SWAP,4)
	s_waitcnt lgkmcnt(0)
	v_add_f32_e32 v204, v204, v205
	ds_swizzle_b32 v205, v204 offset:swizzle(SWAP,8)
	s_waitcnt lgkmcnt(0)
	v_add_f32_e32 v204, v204, v205
	ds_swizzle_b32 v205, v204 offset:swizzle(SWAP,16)
	s_waitcnt lgkmcnt(0)
; __device__ __forceinline__ unsigned pk2(float lo, float hi) { const g_f32x2 f = {lo, hi}; return __builtin_bit_cast(unsigned, __builtin_convertvector(f, g_bf16x2)); }
; __device__ __forceinline__ void p_norm(const float* hlat, const float* hctx, const float* g, const float* modl, int sh_off, int sc_off, bf16_t* A, int M,
;                                        const float* part, const float* cgate, float* hcout) {
;     ...
;         for (int i = 0; i < 4; ++i) {
;             if (part != nullptr && row >= NLAT) {
;                 const size_t po = (size_t)(row - NLAT) * 1024 + i * 256 + lane * 4;
;                 const float4 p0 = *(const float4*)(part + po), p1 = *(const float4*)(part + (size_t)4096 * 1024 + po), cg = *(const float4*)(cgate + i * 256 + lane * 4);
;                 v[i].x += cg.x * (p0.x + p1.x); v[i].y += cg.y * (p0.y + p1.y); v[i].z += cg.z * (p0.z + p1.z); v[i].w += cg.w * (p0.w + p1.w);
;                 *(float4*)(hcout + po) = v[i];
;             }
;             ss += v[i].x * v[i].x + v[i].y * v[i].y + v[i].z * v[i].z + v[i].w * v[i].w; }
;         ss = wave_sum(ss);
;         const float rstd = rsqrtf(ss * (1.0f / 1024.0f) + EPS);
;         const float* mr = modl + (size_t)r * 6144;
; #pragma unroll
;         for (int i = 0; i < 4; ++i) {
;             const int k = i * 256 + lane * 4;
;             const float4 gg = *(const float4*)(g + k), scv = *(const float4*)(mr + sc_off + k), shv = *(const float4*)(mr + sh_off + k);
;             const float o0 = v[i].x * rstd * gg.x * (1.0f + scv.x) + shv.x, o1 = v[i].y * rstd * gg.y * (1.0f + scv.y) + shv.y;
;             const float o2 = v[i].z * rstd * gg.z * (1.0f + scv.z) + shv.z, o3 = v[i].w * rstd * gg.w * (1.0f + scv.w) + shv.w;
;             uint2 w; w.x = pk2(o0, o1); w.y = pk2(o2, o3);
;             *(uint2*)(A + (size_t)row * 1024 + k) = w;
;         }
	v_add_f32_e32 v204, v204, v205
	v_mov_b32_e32 v205, v204
	s_nop 1
	v_permlane32_swap_b32_e32 v204, v205
	v_add_f32_e32 v204, v204, v205
	v_mov_b32_e32 v205, 0x358637bd
	v_fmamk_f32 v204, v204, 0x3a800000, v205
	v_rsq_f32_e32 v204, v204
	s_nop 0
	v_pk_mul_f32 v[80:81], v[80:81], v[204:205] op_sel_hi:[1,0]
	v_pk_mul_f32 v[82:83], v[82:83], v[204:205] op_sel_hi:[1,0]
	v_pk_mul_f32 v[80:81], v[188:189], v[80:81]
	v_pk_mul_f32 v[82:83], v[190:191], v[82:83]
	v_pk_fma_f32 v[80:81], v[34:35], v[80:81], v[224:225]
	v_pk_fma_f32 v[82:83], v[36:37], v[82:83], v[226:227]
	v_cvt_pk_bf16_f32 v80, v80, v81
	v_cvt_pk_bf16_f32 v81, v82, v83
	global_store_dwordx2 v146, v[80:81], s[66:67] sc0 sc1
	v_pk_mul_f32 v[84:85], v[84:85], v[204:205] op_sel_hi:[1,0]
	v_pk_mul_f32 v[86:87], v[86:87], v[204:205] op_sel_hi:[1,0]
	v_pk_mul_f32 v[84:85], v[192:193], v[84:85]
	v_pk_mul_f32 v[86:87], v[194:195], v[86:87]
	v_pk_fma_f32 v[84:85], v[38:39], v[84:85], v[228:229]
	v_pk_fma_f32 v[86:87], v[40:41], v[86:87], v[230:231]
	v_cvt_pk_bf16_f32 v84, v84, v85
	v_cvt_pk_bf16_f32 v85, v86, v87
	global_store_dwordx2 v146, v[84:85], s[66:67] offset:512 sc0 sc1
	v_pk_mul_f32 v[88:89], v[88:89], v[204:205] op_sel_hi:[1,0]
	v_pk_mul_f32 v[90:91], v[90:91], v[204:205] op_sel_hi:[1,0]
	v_pk_mul_f32 v[88:89], v[196:197], v[88:89]
	v_pk_mul_f32 v[90:91], v[198:199], v[90:91]
	v_pk_fma_f32 v[88:89], v[42:43], v[88:89], v[232:233]
	v_pk_fma_f32 v[90:91], v[44:45], v[90:91], v[234:235]
	v_cvt_pk_bf16_f32 v88, v88, v89
	v_cvt_pk_bf16_f32 v89, v90, v91
	global_store_dwordx2 v146, v[88:89], s[66:67] offset:1024 sc0 sc1
	v_pk_mul_f32 v[92:93], v[92:93], v[204:205] op_sel_hi:[1,0]
	v_pk_mul_f32 v[94:95], v[94:95], v[204:205] op_sel_hi:[1,0]
	v_pk_mul_f32 v[92:93], v[200:201], v[92:93]
	v_pk_mul_f32 v[94:95], v[202:203], v[94:95]
	v_pk_fma_f32 v[92:93], v[46:47], v[92:93], v[236:237]
	v_pk_fma_f32 v[94:95], v[48:49], v[94:95], v[238:239]
	v_cvt_pk_bf16_f32 v92, v92, v93
	v_cvt_pk_bf16_f32 v93, v94, v95
	global_store_dwordx2 v146, v[92:93], s[66:67] offset:1536 sc0 sc1
	v_add_u32_e32 v146, 0x800, v146
	global_load_dwordx4 v[80:83], v144, s[46:47] nt
	global_load_dwordx4 v[84:87], v144, s[46:47] offset:1024 nt
	global_load_dwordx4 v[88:91], v144, s[46:47] offset:2048 nt
	global_load_dwordx4 v[92:95], v144, s[46:47] offset:3072 nt
	v_add_u32_e32 v144, 0x1000, v144
	s_waitcnt vmcnt(40)
	v_pk_mul_f32 v[242:243], v[96:97], v[96:97]
	v_pk_mul_f32 v[244:245], v[100:101], v[100:101]
	v_pk_mul_f32 v[246:247], v[98:99], v[98:99]
	v_pk_mul_f32 v[248:249], v[102:103], v[102:103]
	v_add_f32_e32 v204, v245, v244
	v_add_f32_e32 v205, v243, v242
	v_add_f32_e32 v204, v248, v204
	v_add_f32_e32 v205, v246, v205
	v_add_f32_e32 v204, v249, v204
	v_add_f32_e32 v205, v247, v205
	v_pk_mul_f32 v[242:243], v[104:105], v[104:105]
	v_pk_mul_f32 v[244:245], v[108:109], v[108:109]
	v_pk_mul_f32 v[246:247], v[106:107], v[106:107]
	v_pk_mul_f32 v[248:249], v[110:111], v[110:111]
	v_add_f32_e32 v206, v243, v242
	v_add_f32_e32 v207, v245, v244
	v_add_f32_e32 v206, v246, v206
	v_add_f32_e32 v207, v248, v207
	v_add_f32_e32 v206, v247, v206
	v_add_f32_e32 v207, v249, v207
	v_add_f32_e32 v204, v205, v204
	v_add_f32_e32 v204, v204, v206
	v_add_f32_e32 v204, v204, v207
	ds_swizzle_b32 v205, v204 offset:swizzle(SWAP,1)
	s_waitcnt lgkmcnt(0)
	v_add_f32_e32 v204, v204, v205
	ds_swizzle_b32 v205, v204 offset:swizzle(SWAP,2)
	s_waitcnt lgkmcnt(0)
	v_add_f32_e32 v204, v204, v205
	ds_swizzle_b32 v205, v204 offset:swizzle(SWAP,4)
	s_waitcnt lgkmcnt(0)
	v_add_f32_e32 v204, v204, v205
	ds_swizzle_b32 v205, v204 offset:swizzle(SWAP,8)
	s_waitcnt lgkmcnt(0)
	v_add_f32_e32 v204, v204, v205
	ds_swizzle_b32 v205, v204 offset:swizzle(SWAP,16)
	s_waitcnt lgkmcnt(0)
	v_add_f32_e32 v204, v204, v205
	v_mov_b32_e32 v205, v204
	s_nop 1
	v_permlane32_swap_b32_e32 v204, v205
	v_add_f32_e32 v204, v204, v205
	v_mov_b32_e32 v205, 0x358637bd
	v_fmamk_f32 v204, v204, 0x3a800000, v205
	v_rsq_f32_e32 v204, v204
	s_nop 0
	v_pk_mul_f32 v[96:97], v[96:97], v[204:205] op_sel_hi:[1,0]
	v_pk_mul_f32 v[98:99], v[98:99], v[204:205] op_sel_hi:[1,0]
	v_pk_mul_f32 v[96:97], v[188:189], v[96:97]
	v_pk_mul_f32 v[98:99], v[190:191], v[98:99]
	v_pk_fma_f32 v[96:97], v[34:35], v[96:97], v[224:225]
	v_pk_fma_f32 v[98:99], v[36:37], v[98:99], v[226:227]
	v_cvt_pk_bf16_f32 v96, v96, v97
	v_cvt_pk_bf16_f32 v97, v98, v99
	global_store_dwordx2 v146, v[96:97], s[66:67] sc0 sc1
	v_pk_mul_f32 v[100:101], v[100:101], v[204:205] op_sel_hi:[1,0]
	v_pk_mul_f32 v[102:103], v[102:103], v[204:205] op_sel_hi:[1,0]
	v_pk_mul_f32 v[100:101], v[192:193], v[100:101]
	v_pk_mul_f32 v[102:103], v[194:195], v[102:103]
	v_pk_fma_f32 v[100:101], v[38:39], v[100:101], v[228:229]
	v_pk_fma_f32 v[102:103], v[40:41], v[102:103], v[230:231]
	v_cvt_pk_bf16_f32 v100, v100, v101
	v_cvt_pk_bf16_f32 v101, v102, v103
	global_store_dwordx2 v146, v[100:101], s[66:67] offset:512 sc0 sc1
	v_pk_mul_f32 v[104:105], v[104:105], v[204:205] op_sel_hi:[1,0]
	v_pk_mul_f32 v[106:107], v[106:107], v[204:205] op_sel_hi:[1,0]
	v_pk_mul_f32 v[104:105], v[196:197], v[104:105]
	v_pk_mul_f32 v[106:107], v[198:199], v[106:107]
	v_pk_fma_f32 v[104:105], v[42:43], v[104:105], v[232:233]
	v_pk_fma_f32 v[106:107], v[44:45], v[106:107], v[234:235]
	v_cvt_pk_bf16_f32 v104, v104, v105
	v_cvt_pk_bf16_f32 v105, v106, v107
	global_store_dwordx2 v146, v[104:105], s[66:67] offset:1024 sc0 sc1
	v_pk_mul_f32 v[108:109], v[108:109], v[204:205] op_sel_hi:[1,0]
	v_pk_mul_f32 v[110:111], v[110:111], v[204:205] op_sel_hi:[1,0]
	v_pk_mul_f32 v[108:109], v[200:201], v[108:109]
	v_pk_mul_f32 v[110:111], v[202:203], v[110:111]
	v_pk_fma_f32 v[108:109], v[46:47], v[108:109], v[236:237]
	v_pk_fma_f32 v[110:111], v[48:49], v[110:111], v[238:239]
	v_cvt_pk_bf16_f32 v108, v108, v109
	v_cvt_pk_bf16_f32 v109, v110, v111
	global_store_dwordx2 v146, v[108:109], s[66:67] offset:1536 sc0 sc1
	v_add_u32_e32 v146, 0x800, v146
	global_load_dwordx4 v[96:99], v144, s[46:47] nt
	global_load_dwordx4 v[100:103], v144, s[46:47] offset:1024 nt
	global_load_dwordx4 v[104:107], v144, s[46:47] offset:2048 nt
	global_load_dwordx4 v[108:111], v144, s[46:47] offset:3072 nt
	v_add_u32_e32 v144, 0x1000, v144
	s_waitcnt vmcnt(40)
; __device__ __forceinline__ unsigned pk2(float lo, float hi) { const g_f32x2 f = {lo, hi}; return __builtin_bit_cast(unsigned, __builtin_convertvector(f, g_bf16x2)); }
; __device__ __forceinline__ void p_norm(const float* hlat, const float* hctx, const float* g, const float* modl, int sh_off, int sc_off, bf16_t* A, int M,
;                                        const float* part, const float* cgate, float* hcout) {
;     ...
;         for (int i = 0; i < 4; ++i) {
;             if (part != nullptr && row >= NLAT) {
;                 const size_t po = (size_t)(row - NLAT) * 1024 + i * 256 + lane * 4;
;                 const float4 p0 = *(const float4*)(part + po), p1 = *(const float4*)(part + (size_t)4096 * 1024 + po), cg = *(const float4*)(cgate + i * 256 + lane * 4);
;                 v[i].x += cg.x * (p0.x + p1.x); v[i].y += cg.y * (p0.y + p1.y); v[i].z += cg.z * (p0.z + p1.z); v[i].w += cg.w * (p0.w + p1.w);
;                 *(float4*)(hcout + po) = v[i];
;             }
;             ss += v[i].x * v[i].x + v[i].y * v[i].y + v[i].z * v[i].z + v[i].w * v[i].w; }
;         ss = wave_sum(ss);
;         const float rstd = rsqrtf(ss * (1.0f / 1024.0f) + EPS);
;         const float* mr = modl + (size_t)r * 6144;
; #pragma unroll
;         for (int i = 0; i < 4; ++i) {
;             const int k = i * 256 + lane * 4;
;             const float4 gg = *(const float4*)(g + k), scv = *(const float4*)(mr + sc_off + k), shv = *(const float4*)(mr + sh_off + k);
;             const float o0 = v[i].x * rstd * gg.x * (1.0f + scv.x) + shv.x, o1 = v[i].y * rstd * gg.y * (1.0f + scv.y) + shv.y;
;             const float o2 = v[i].z * rstd * gg.z * (1.0f + scv.z) + shv.z, o3 = v[i].w * rstd * gg.w * (1.0f + scv.w) + shv.w;
;             uint2 w; w.x = pk2(o0, o1); w.y = pk2(o2, o3);
;             *(uint2*)(A + (size_t)row * 1024 + k) = w;
;         }
	v_pk_mul_f32 v[242:243], v[112:113], v[112:113]
	v_pk_mul_f32 v[244:245], v[116:117], v[116:117]
	v_pk_mul_f32 v[246:247], v[114:115], v[114:115]
	v_pk_mul_f32 v[248:249], v[118:119], v[118:119]
	v_add_f32_e32 v204, v245, v244
	v_add_f32_e32 v205, v243, v242
	v_add_f32_e32 v204, v248, v204
	v_add_f32_e32 v205, v246, v205
	v_add_f32_e32 v204, v249, v204
	v_add_f32_e32 v205, v247, v205
	v_pk_mul_f32 v[242:243], v[120:121], v[120:121]
	v_pk_mul_f32 v[244:245], v[124:125], v[124:125]
	v_pk_mul_f32 v[246:247], v[122:123], v[122:123]
	v_pk_mul_f32 v[248:249], v[126:127], v[126:127]
	v_add_f32_e32 v206, v243, v242
	v_add_f32_e32 v207, v245, v244
	v_add_f32_e32 v206, v246, v206
	v_add_f32_e32 v207, v248, v207
	v_add_f32_e32 v206, v247, v206
	v_add_f32_e32 v207, v249, v207
	v_add_f32_e32 v204, v205, v204
	v_add_f32_e32 v204, v204, v206
	v_add_f32_e32 v204, v204, v207
	ds_swizzle_b32 v205, v204 offset:swizzle(SWAP,1)
	s_waitcnt lgkmcnt(0)
	v_add_f32_e32 v204, v204, v205
	ds_swizzle_b32 v205, v204 offset:swizzle(SWAP,2)
	s_waitcnt lgkmcnt(0)
	v_add_f32_e32 v204, v204, v205
	ds_swizzle_b32 v205, v204 offset:swizzle(SWAP,4)
	s_waitcnt lgkmcnt(0)
	v_add_f32_e32 v204, v204, v205
	ds_swizzle_b32 v205, v204 offset:swizzle(SWAP,8)
	s_waitcnt lgkmcnt(0)
	v_add_f32_e32 v204, v204, v205
	ds_swizzle_b32 v205, v204 offset:swizzle(SWAP,16)
	s_waitcnt lgkmcnt(0)
	v_add_f32_e32 v204, v204, v205
	v_mov_b32_e32 v205, v204
	s_nop 1
	v_permlane32_swap_b32_e32 v204, v205
	v_add_f32_e32 v204, v204, v205
	v_mov_b32_e32 v205, 0x358637bd
	v_fmamk_f32 v204, v204, 0x3a800000, v205
	v_rsq_f32_e32 v204, v204
	s_nop 0
	v_pk_mul_f32 v[112:113], v[112:113], v[204:205] op_sel_hi:[1,0]
	v_pk_mul_f32 v[114:115], v[114:115], v[204:205] op_sel_hi:[1,0]
	v_pk_mul_f32 v[112:113], v[188:189], v[112:113]
	v_pk_mul_f32 v[114:115], v[190:191], v[114:115]
	v_pk_fma_f32 v[112:113], v[34:35], v[112:113], v[224:225]
	v_pk_fma_f32 v[114:115], v[36:37], v[114:115], v[226:227]
	v_cvt_pk_bf16_f32 v112, v112, v113
	v_cvt_pk_bf16_f32 v113, v114, v115
	global_store_dwordx2 v146, v[112:113], s[66:67] sc0 sc1
	v_pk_mul_f32 v[116:117], v[116:117], v[204:205] op_sel_hi:[1,0]
	v_pk_mul_f32 v[118:119], v[118:119], v[204:205] op_sel_hi:[1,0]
	v_pk_mul_f32 v[116:117], v[192:193], v[116:117]
	v_pk_mul_f32 v[118:119], v[194:195], v[118:119]
	v_pk_fma_f32 v[116:117], v[38:39], v[116:117], v[228:229]
	v_pk_fma_f32 v[118:119], v[40:41], v[118:119], v[230:231]
	v_cvt_pk_bf16_f32 v116, v116, v117
	v_cvt_pk_bf16_f32 v117, v118, v119
	global_store_dwordx2 v146, v[116:117], s[66:67] offset:512 sc0 sc1
	v_pk_mul_f32 v[120:121], v[120:121], v[204:205] op_sel_hi:[1,0]
	v_pk_mul_f32 v[122:123], v[122:123], v[204:205] op_sel_hi:[1,0]
	v_pk_mul_f32 v[120:121], v[196:197], v[120:121]
	v_pk_mul_f32 v[122:123], v[198:199], v[122:123]
	v_pk_fma_f32 v[120:121], v[42:43], v[120:121], v[232:233]
	v_pk_fma_f32 v[122:123], v[44:45], v[122:123], v[234:235]
	v_cvt_pk_bf16_f32 v120, v120, v121
	v_cvt_pk_bf16_f32 v121, v122, v123
	global_store_dwordx2 v146, v[120:121], s[66:67] offset:1024 sc0 sc1
	v_pk_mul_f32 v[124:125], v[124:125], v[204:205] op_sel_hi:[1,0]
	v_pk_mul_f32 v[126:127], v[126:127], v[204:205] op_sel_hi:[1,0]
	v_pk_mul_f32 v[124:125], v[200:201], v[124:125]
	v_pk_mul_f32 v[126:127], v[202:203], v[126:127]
	v_pk_fma_f32 v[124:125], v[46:47], v[124:125], v[236:237]
	v_pk_fma_f32 v[126:127], v[48:49], v[126:127], v[238:239]
	v_cvt_pk_bf16_f32 v124, v124, v125
	v_cvt_pk_bf16_f32 v125, v126, v127
	global_store_dwordx2 v146, v[124:125], s[66:67] offset:1536 sc0 sc1
	v_add_u32_e32 v146, 0x800, v146
	global_load_dwordx4 v[112:115], v144, s[46:47] nt
	global_load_dwordx4 v[116:119], v144, s[46:47] offset:1024 nt
	global_load_dwordx4 v[120:123], v144, s[46:47] offset:2048 nt
	global_load_dwordx4 v[124:127], v144, s[46:47] offset:3072 nt
	v_add_u32_e32 v144, 0x1000, v144
	s_waitcnt vmcnt(40)
	v_pk_mul_f32 v[242:243], v[128:129], v[128:129]
	v_pk_mul_f32 v[244:245], v[132:133], v[132:133]
	v_pk_mul_f32 v[246:247], v[130:131], v[130:131]
	v_pk_mul_f32 v[248:249], v[134:135], v[134:135]
	v_add_f32_e32 v204, v245, v244
	v_add_f32_e32 v205, v243, v242
	v_add_f32_e32 v204, v248, v204
	v_add_f32_e32 v205, v246, v205
	v_add_f32_e32 v204, v249, v204
	v_add_f32_e32 v205, v247, v205
	v_pk_mul_f32 v[242:243], v[136:137], v[136:137]
	v_pk_mul_f32 v[244:245], v[140:141], v[140:141]
	v_pk_mul_f32 v[246:247], v[138:139], v[138:139]
	v_pk_mul_f32 v[248:249], v[142:143], v[142:143]
	v_add_f32_e32 v206, v243, v242
	v_add_f32_e32 v207, v245, v244
	v_add_f32_e32 v206, v246, v206
	v_add_f32_e32 v207, v248, v207
	v_add_f32_e32 v206, v247, v206
	v_add_f32_e32 v207, v249, v207
	v_add_f32_e32 v204, v205, v204
	v_add_f32_e32 v204, v204, v206
	v_add_f32_e32 v204, v204, v207
	ds_swizzle_b32 v205, v204 offset:swizzle(SWAP,1)
	s_waitcnt lgkmcnt(0)
	v_add_f32_e32 v204, v204, v205
	ds_swizzle_b32 v205, v204 offset:swizzle(SWAP,2)
	s_waitcnt lgkmcnt(0)
	v_add_f32_e32 v204, v204, v205
	ds_swizzle_b32 v205, v204 offset:swizzle(SWAP,4)
	s_waitcnt lgkmcnt(0)
	v_add_f32_e32 v204, v204, v205
	ds_swizzle_b32 v205, v204 offset:swizzle(SWAP,8)
	s_waitcnt lgkmcnt(0)
	v_add_f32_e32 v204, v204, v205
	ds_swizzle_b32 v205, v204 offset:swizzle(SWAP,16)
	s_waitcnt lgkmcnt(0)
; __device__ __forceinline__ unsigned pk2(float lo, float hi) { const g_f32x2 f = {lo, hi}; return __builtin_bit_cast(unsigned, __builtin_convertvector(f, g_bf16x2)); }
; #define PN_LOAD(dst, rw) do { const float* s_ = (rw) < NLAT ? hlat + (size_t)(rw) * 1024 : hctx + (size_t)((rw) - NLAT) * 1024; \
;         _Pragma("unroll") for (int i = 0; i < 4; ++i) dst[i] = *(const float4*)(s_ + i * 256 + lane * 4); } while (0)
; __device__ __forceinline__ void p_norm(const float* hlat, const float* hctx, const float* g, const float* modl, int sh_off, int sc_off, bf16_t* A, int M,
;                                        const float* part, const float* cgate, float* hcout) {
;     ...
;     if (row < M) PN_LOAD(v, row);
;     while (row < M) {
;         const int nrow = row + stride;
;         if (nrow < M) PN_LOAD(nv, nrow);
;         const int r = row < NLAT ? (row >> 11) : 16;
;         float ss = 0.f;
; #pragma unroll
;         for (int i = 0; i < 4; ++i) {
;             if (part != nullptr && row >= NLAT) {
;                 const size_t po = (size_t)(row - NLAT) * 1024 + i * 256 + lane * 4;
;                 const float4 p0 = *(const float4*)(part + po), p1 = *(const float4*)(part + (size_t)4096 * 1024 + po), cg = *(const float4*)(cgate + i * 256 + lane * 4);
;                 v[i].x += cg.x * (p0.x + p1.x); v[i].y += cg.y * (p0.y + p1.y); v[i].z += cg.z * (p0.z + p1.z); v[i].w += cg.w * (p0.w + p1.w);
;                 *(float4*)(hcout + po) = v[i];
;             }
;             ss += v[i].x * v[i].x + v[i].y * v[i].y + v[i].z * v[i].z + v[i].w * v[i].w; }
;         ss = wave_sum(ss);
;         const float rstd = rsqrtf(ss * (1.0f / 1024.0f) + EPS);
;         const float* mr = modl + (size_t)r * 6144;
; #pragma unroll
;         for (int i = 0; i < 4; ++i) {
;             const int k = i * 256 + lane * 4;
;             const float4 gg = *(const float4*)(g + k), scv = *(const float4*)(mr + sc_off + k), shv = *(const float4*)(mr + sh_off + k);
;             const float o0 = v[i].x * rstd * gg.x * (1.0f + scv.x) + shv.x, o1 = v[i].y * rstd * gg.y * (1.0f + scv.y) + shv.y;
;             const float o2 = v[i].z * rstd * gg.z * (1.0f + scv.z) + shv.z, o3 = v[i].w * rstd * gg.w * (1.0f + scv.w) + shv.w;
;             uint2 w; w.x = pk2(o0, o1); w.y = pk2(o2, o3);
;             *(uint2*)(A + (size_t)row * 1024 + k) = w;
;         }
	v_add_f32_e32 v204, v204, v205
	v_mov_b32_e32 v205, v204
	s_nop 1
	v_permlane32_swap_b32_e32 v204, v205
	v_add_f32_e32 v204, v204, v205
	v_mov_b32_e32 v205, 0x358637bd
	v_fmamk_f32 v204, v204, 0x3a800000, v205
	v_rsq_f32_e32 v204, v204
	s_nop 0
	v_pk_mul_f32 v[128:129], v[128:129], v[204:205] op_sel_hi:[1,0]
	v_pk_mul_f32 v[130:131], v[130:131], v[204:205] op_sel_hi:[1,0]
	v_pk_mul_f32 v[128:129], v[188:189], v[128:129]
	v_pk_mul_f32 v[130:131], v[190:191], v[130:131]
	v_pk_fma_f32 v[128:129], v[34:35], v[128:129], v[224:225]
	v_pk_fma_f32 v[130:131], v[36:37], v[130:131], v[226:227]
	v_cvt_pk_bf16_f32 v128, v128, v129
	v_cvt_pk_bf16_f32 v129, v130, v131
	global_store_dwordx2 v146, v[128:129], s[66:67] sc0 sc1
	v_pk_mul_f32 v[132:133], v[132:133], v[204:205] op_sel_hi:[1,0]
	v_pk_mul_f32 v[134:135], v[134:135], v[204:205] op_sel_hi:[1,0]
	v_pk_mul_f32 v[132:133], v[192:193], v[132:133]
	v_pk_mul_f32 v[134:135], v[194:195], v[134:135]
	v_pk_fma_f32 v[132:133], v[38:39], v[132:133], v[228:229]
	v_pk_fma_f32 v[134:135], v[40:41], v[134:135], v[230:231]
	v_cvt_pk_bf16_f32 v132, v132, v133
	v_cvt_pk_bf16_f32 v133, v134, v135
	global_store_dwordx2 v146, v[132:133], s[66:67] offset:512 sc0 sc1
	v_pk_mul_f32 v[136:137], v[136:137], v[204:205] op_sel_hi:[1,0]
	v_pk_mul_f32 v[138:139], v[138:139], v[204:205] op_sel_hi:[1,0]
	v_pk_mul_f32 v[136:137], v[196:197], v[136:137]
	v_pk_mul_f32 v[138:139], v[198:199], v[138:139]
	v_pk_fma_f32 v[136:137], v[42:43], v[136:137], v[232:233]
	v_pk_fma_f32 v[138:139], v[44:45], v[138:139], v[234:235]
	v_cvt_pk_bf16_f32 v136, v136, v137
	v_cvt_pk_bf16_f32 v137, v138, v139
	global_store_dwordx2 v146, v[136:137], s[66:67] offset:1024 sc0 sc1
	v_pk_mul_f32 v[140:141], v[140:141], v[204:205] op_sel_hi:[1,0]
	v_pk_mul_f32 v[142:143], v[142:143], v[204:205] op_sel_hi:[1,0]
	v_pk_mul_f32 v[140:141], v[200:201], v[140:141]
	v_pk_mul_f32 v[142:143], v[202:203], v[142:143]
	v_pk_fma_f32 v[140:141], v[46:47], v[140:141], v[236:237]
	v_pk_fma_f32 v[142:143], v[48:49], v[142:143], v[238:239]
	v_cvt_pk_bf16_f32 v140, v140, v141
	v_cvt_pk_bf16_f32 v141, v142, v143
	global_store_dwordx2 v146, v[140:141], s[66:67] offset:1536 sc0 sc1
	v_add_u32_e32 v146, 0x800, v146
	global_load_dwordx4 v[128:131], v144, s[46:47] nt
	global_load_dwordx4 v[132:135], v144, s[46:47] offset:1024 nt
	global_load_dwordx4 v[136:139], v144, s[46:47] offset:2048 nt
	global_load_dwordx4 v[140:143], v144, s[46:47] offset:3072 nt
	v_add_u32_e32 v144, 0x1000, v144
	s_waitcnt vmcnt(40)
	v_pk_mul_f32 v[242:243], v[156:157], v[156:157]
	v_pk_mul_f32 v[244:245], v[160:161], v[160:161]
	v_pk_mul_f32 v[246:247], v[158:159], v[158:159]
	v_pk_mul_f32 v[248:249], v[162:163], v[162:163]
	v_add_f32_e32 v204, v245, v244
	v_add_f32_e32 v205, v243, v242
	v_add_f32_e32 v204, v248, v204
	v_add_f32_e32 v205, v246, v205
	v_add_f32_e32 v204, v249, v204
	v_add_f32_e32 v205, v247, v205
	v_pk_mul_f32 v[242:243], v[164:165], v[164:165]
	v_pk_mul_f32 v[244:245], v[168:169], v[168:169]
	v_pk_mul_f32 v[246:247], v[166:167], v[166:167]
	v_pk_mul_f32 v[248:249], v[170:171], v[170:171]
	v_add_f32_e32 v206, v243, v242
	v_add_f32_e32 v207, v245, v244
	v_add_f32_e32 v206, v246, v206
	v_add_f32_e32 v207, v248, v207
	v_add_f32_e32 v206, v247, v206
	v_add_f32_e32 v207, v249, v207
	v_add_f32_e32 v204, v205, v204
	v_add_f32_e32 v204, v204, v206
	v_add_f32_e32 v204, v204, v207
	ds_swizzle_b32 v205, v204 offset:swizzle(SWAP,1)
	s_waitcnt lgkmcnt(0)
	v_add_f32_e32 v204, v204, v205
	ds_swizzle_b32 v205, v204 offset:swizzle(SWAP,2)
	s_waitcnt lgkmcnt(0)
	v_add_f32_e32 v204, v204, v205
	ds_swizzle_b32 v205, v204 offset:swizzle(SWAP,4)
	s_waitcnt lgkmcnt(0)
	v_add_f32_e32 v204, v204, v205
	ds_swizzle_b32 v205, v204 offset:swizzle(SWAP,8)
	s_waitcnt lgkmcnt(0)
	v_add_f32_e32 v204, v204, v205
	ds_swizzle_b32 v205, v204 offset:swizzle(SWAP,16)
	s_waitcnt lgkmcnt(0)
	v_add_f32_e32 v204, v204, v205
	v_mov_b32_e32 v205, v204
	s_nop 1
	v_permlane32_swap_b32_e32 v204, v205
	v_add_f32_e32 v204, v204, v205
	v_mov_b32_e32 v205, 0x358637bd
	v_fmamk_f32 v204, v204, 0x3a800000, v205
	v_rsq_f32_e32 v204, v204
	s_nop 0
	v_pk_mul_f32 v[156:157], v[156:157], v[204:205] op_sel_hi:[1,0]
	v_pk_mul_f32 v[158:159], v[158:159], v[204:205] op_sel_hi:[1,0]
	v_pk_mul_f32 v[156:157], v[188:189], v[156:157]
	v_pk_mul_f32 v[158:159], v[190:191], v[158:159]
	v_pk_fma_f32 v[156:157], v[34:35], v[156:157], v[224:225]
	v_pk_fma_f32 v[158:159], v[36:37], v[158:159], v[226:227]
	v_cvt_pk_bf16_f32 v156, v156, v157
	v_cvt_pk_bf16_f32 v157, v158, v159
	global_store_dwordx2 v146, v[156:157], s[66:67] sc0 sc1
	v_pk_mul_f32 v[160:161], v[160:161], v[204:205] op_sel_hi:[1,0]
	v_pk_mul_f32 v[162:163], v[162:163], v[204:205] op_sel_hi:[1,0]
	v_pk_mul_f32 v[160:161], v[192:193], v[160:161]
	v_pk_mul_f32 v[162:163], v[194:195], v[162:163]
	v_pk_fma_f32 v[160:161], v[38:39], v[160:161], v[228:229]
	v_pk_fma_f32 v[162:163], v[40:41], v[162:163], v[230:231]
	v_cvt_pk_bf16_f32 v160, v160, v161
	v_cvt_pk_bf16_f32 v161, v162, v163
	global_store_dwordx2 v146, v[160:161], s[66:67] offset:512 sc0 sc1
	v_pk_mul_f32 v[164:165], v[164:165], v[204:205] op_sel_hi:[1,0]
	v_pk_mul_f32 v[166:167], v[166:167], v[204:205] op_sel_hi:[1,0]
	v_pk_mul_f32 v[164:165], v[196:197], v[164:165]
	v_pk_mul_f32 v[166:167], v[198:199], v[166:167]
	v_pk_fma_f32 v[164:165], v[42:43], v[164:165], v[232:233]
	v_pk_fma_f32 v[166:167], v[44:45], v[166:167], v[234:235]
	v_cvt_pk_bf16_f32 v164, v164, v165
	v_cvt_pk_bf16_f32 v165, v166, v167
	global_store_dwordx2 v146, v[164:165], s[66:67] offset:1024 sc0 sc1
	v_pk_mul_f32 v[168:169], v[168:169], v[204:205] op_sel_hi:[1,0]
	v_pk_mul_f32 v[170:171], v[170:171], v[204:205] op_sel_hi:[1,0]
	v_pk_mul_f32 v[168:169], v[200:201], v[168:169]
	v_pk_mul_f32 v[170:171], v[202:203], v[170:171]
	v_pk_fma_f32 v[168:169], v[46:47], v[168:169], v[236:237]
	v_pk_fma_f32 v[170:171], v[48:49], v[170:171], v[238:239]
	v_cvt_pk_bf16_f32 v168, v168, v169
	v_cvt_pk_bf16_f32 v169, v170, v171
	global_store_dwordx2 v146, v[168:169], s[66:67] offset:1536 sc0 sc1
	v_add_u32_e32 v146, 0x800, v146
	v_lshl_add_u32 v144, v50, 13, v241
	v_mov_b32_e32 v152, v144
	v_add_u32_e32 v150, 0x1000000, v144
	global_load_dwordx4 v[156:159], v144, s[16:17]
	global_load_dwordx4 v[160:163], v144, s[16:17] offset:1024
	global_load_dwordx4 v[164:167], v144, s[16:17] offset:2048
	global_load_dwordx4 v[168:171], v144, s[16:17] offset:3072
	v_add_u32_e32 v144, 0x1000, v144
	s_waitcnt vmcnt(40)
; __device__ __forceinline__ unsigned pk2(float lo, float hi) { const g_f32x2 f = {lo, hi}; return __builtin_bit_cast(unsigned, __builtin_convertvector(f, g_bf16x2)); }
; #define PN_LOAD(dst, rw) do { const float* s_ = (rw) < NLAT ? hlat + (size_t)(rw) * 1024 : hctx + (size_t)((rw) - NLAT) * 1024; \
;         _Pragma("unroll") for (int i = 0; i < 4; ++i) dst[i] = *(const float4*)(s_ + i * 256 + lane * 4); } while (0)
; __device__ __forceinline__ void p_norm(const float* hlat, const float* hctx, const float* g, const float* modl, int sh_off, int sc_off, bf16_t* A, int M,
;                                        const float* part, const float* cgate, float* hcout) {
;     ...
;     if (row < M) PN_LOAD(v, row);
;     while (row < M) {
;         const int nrow = row + stride;
;         if (nrow < M) PN_LOAD(nv, nrow);
;         const int r = row < NLAT ? (row >> 11) : 16;
;         float ss = 0.f;
; #pragma unroll
;         for (int i = 0; i < 4; ++i) {
;             if (part != nullptr && row >= NLAT) {
;                 const size_t po = (size_t)(row - NLAT) * 1024 + i * 256 + lane * 4;
;                 const float4 p0 = *(const float4*)(part + po), p1 = *(const float4*)(part + (size_t)4096 * 1024 + po), cg = *(const float4*)(cgate + i * 256 + lane * 4);
;                 v[i].x += cg.x * (p0.x + p1.x); v[i].y += cg.y * (p0.y + p1.y); v[i].z += cg.z * (p0.z + p1.z); v[i].w += cg.w * (p0.w + p1.w);
;                 *(float4*)(hcout + po) = v[i];
;             }
;             ss += v[i].x * v[i].x + v[i].y * v[i].y + v[i].z * v[i].z + v[i].w * v[i].w; }
;         ss = wave_sum(ss);
;         const float rstd = rsqrtf(ss * (1.0f / 1024.0f) + EPS);
;         const float* mr = modl + (size_t)r * 6144;
; #pragma unroll
;         for (int i = 0; i < 4; ++i) {
;             const int k = i * 256 + lane * 4;
;             const float4 gg = *(const float4*)(g + k), scv = *(const float4*)(mr + sc_off + k), shv = *(const float4*)(mr + sh_off + k);
;             const float o0 = v[i].x * rstd * gg.x * (1.0f + scv.x) + shv.x, o1 = v[i].y * rstd * gg.y * (1.0f + scv.y) + shv.y;
;             const float o2 = v[i].z * rstd * gg.z * (1.0f + scv.z) + shv.z, o3 = v[i].w * rstd * gg.w * (1.0f + scv.w) + shv.w;
;             uint2 w; w.x = pk2(o0, o1); w.y = pk2(o2, o3);
;             *(uint2*)(A + (size_t)row * 1024 + k) = w;
;         }
	v_pk_mul_f32 v[242:243], v[172:173], v[172:173]
	v_pk_mul_f32 v[244:245], v[176:177], v[176:177]
	v_pk_mul_f32 v[246:247], v[174:175], v[174:175]
	v_pk_mul_f32 v[248:249], v[178:179], v[178:179]
	v_add_f32_e32 v204, v245, v244
	v_add_f32_e32 v205, v243, v242
	v_add_f32_e32 v204, v248, v204
	v_add_f32_e32 v205, v246, v205
	v_add_f32_e32 v204, v249, v204
	v_add_f32_e32 v205, v247, v205
	v_pk_mul_f32 v[242:243], v[180:181], v[180:181]
	v_pk_mul_f32 v[244:245], v[184:185], v[184:185]
	v_pk_mul_f32 v[246:247], v[182:183], v[182:183]
	v_pk_mul_f32 v[248:249], v[186:187], v[186:187]
	v_add_f32_e32 v206, v243, v242
	v_add_f32_e32 v207, v245, v244
	v_add_f32_e32 v206, v246, v206
	v_add_f32_e32 v207, v248, v207
	v_add_f32_e32 v206, v247, v206
	v_add_f32_e32 v207, v249, v207
	v_add_f32_e32 v204, v205, v204
	v_add_f32_e32 v204, v204, v206
	v_add_f32_e32 v204, v204, v207
	ds_swizzle_b32 v205, v204 offset:swizzle(SWAP,1)
	s_waitcnt lgkmcnt(0)
	v_add_f32_e32 v204, v204, v205
	ds_swizzle_b32 v205, v204 offset:swizzle(SWAP,2)
	s_waitcnt lgkmcnt(0)
	v_add_f32_e32 v204, v204, v205
	ds_swizzle_b32 v205, v204 offset:swizzle(SWAP,4)
	s_waitcnt lgkmcnt(0)
	v_add_f32_e32 v204, v204, v205
	ds_swizzle_b32 v205, v204 offset:swizzle(SWAP,8)
	s_waitcnt lgkmcnt(0)
	v_add_f32_e32 v204, v204, v205
	ds_swizzle_b32 v205, v204 offset:swizzle(SWAP,16)
	s_waitcnt lgkmcnt(0)
	v_add_f32_e32 v204, v204, v205
	v_mov_b32_e32 v205, v204
	s_nop 1
	v_permlane32_swap_b32_e32 v204, v205
	v_add_f32_e32 v204, v204, v205
	v_mov_b32_e32 v205, 0x358637bd
	v_fmamk_f32 v204, v204, 0x3a800000, v205
	v_rsq_f32_e32 v204, v204
	s_nop 0
	v_pk_mul_f32 v[172:173], v[172:173], v[204:205] op_sel_hi:[1,0]
	v_pk_mul_f32 v[174:175], v[174:175], v[204:205] op_sel_hi:[1,0]
	v_pk_mul_f32 v[172:173], v[188:189], v[172:173]
	v_pk_mul_f32 v[174:175], v[190:191], v[174:175]
	v_pk_fma_f32 v[172:173], v[34:35], v[172:173], v[224:225]
	v_pk_fma_f32 v[174:175], v[36:37], v[174:175], v[226:227]
	v_cvt_pk_bf16_f32 v172, v172, v173
	v_cvt_pk_bf16_f32 v173, v174, v175
	global_store_dwordx2 v146, v[172:173], s[66:67] sc0 sc1
	v_pk_mul_f32 v[176:177], v[176:177], v[204:205] op_sel_hi:[1,0]
	v_pk_mul_f32 v[178:179], v[178:179], v[204:205] op_sel_hi:[1,0]
	v_pk_mul_f32 v[176:177], v[192:193], v[176:177]
	v_pk_mul_f32 v[178:179], v[194:195], v[178:179]
	v_pk_fma_f32 v[176:177], v[38:39], v[176:177], v[228:229]
	v_pk_fma_f32 v[178:179], v[40:41], v[178:179], v[230:231]
	v_cvt_pk_bf16_f32 v176, v176, v177
	v_cvt_pk_bf16_f32 v177, v178, v179
	global_store_dwordx2 v146, v[176:177], s[66:67] offset:512 sc0 sc1
	v_pk_mul_f32 v[180:181], v[180:181], v[204:205] op_sel_hi:[1,0]
	v_pk_mul_f32 v[182:183], v[182:183], v[204:205] op_sel_hi:[1,0]
	v_pk_mul_f32 v[180:181], v[196:197], v[180:181]
	v_pk_mul_f32 v[182:183], v[198:199], v[182:183]
	v_pk_fma_f32 v[180:181], v[42:43], v[180:181], v[232:233]
	v_pk_fma_f32 v[182:183], v[44:45], v[182:183], v[234:235]
	v_cvt_pk_bf16_f32 v180, v180, v181
	v_cvt_pk_bf16_f32 v181, v182, v183
	global_store_dwordx2 v146, v[180:181], s[66:67] offset:1024 sc0 sc1
	v_pk_mul_f32 v[184:185], v[184:185], v[204:205] op_sel_hi:[1,0]
	v_pk_mul_f32 v[186:187], v[186:187], v[204:205] op_sel_hi:[1,0]
	v_pk_mul_f32 v[184:185], v[200:201], v[184:185]
	v_pk_mul_f32 v[186:187], v[202:203], v[186:187]
	v_pk_fma_f32 v[184:185], v[46:47], v[184:185], v[236:237]
	v_pk_fma_f32 v[186:187], v[48:49], v[186:187], v[238:239]
	v_cvt_pk_bf16_f32 v184, v184, v185
	v_cvt_pk_bf16_f32 v185, v186, v187
	global_store_dwordx2 v146, v[184:185], s[66:67] offset:1536 sc0 sc1
	v_add_u32_e32 v146, 0x800, v146
	global_load_dwordx4 v[172:175], v144, s[16:17]
	global_load_dwordx4 v[176:179], v144, s[16:17] offset:1024
	global_load_dwordx4 v[180:183], v144, s[16:17] offset:2048
	global_load_dwordx4 v[184:187], v144, s[16:17] offset:3072
	v_add_u32_e32 v144, 0x1000, v144
	s_waitcnt vmcnt(40)
	v_pk_mul_f32 v[242:243], v[80:81], v[80:81]
	v_pk_mul_f32 v[244:245], v[84:85], v[84:85]
	v_pk_mul_f32 v[246:247], v[82:83], v[82:83]
	v_pk_mul_f32 v[248:249], v[86:87], v[86:87]
	v_add_f32_e32 v204, v245, v244
	v_add_f32_e32 v205, v243, v242
	v_add_f32_e32 v204, v248, v204
	v_add_f32_e32 v205, v246, v205
	v_add_f32_e32 v204, v249, v204
	v_add_f32_e32 v205, v247, v205
	v_pk_mul_f32 v[242:243], v[88:89], v[88:89]
	v_pk_mul_f32 v[244:245], v[92:93], v[92:93]
	v_pk_mul_f32 v[246:247], v[90:91], v[90:91]
	v_pk_mul_f32 v[248:249], v[94:95], v[94:95]
	v_add_f32_e32 v206, v243, v242
	v_add_f32_e32 v207, v245, v244
	v_add_f32_e32 v206, v246, v206
	v_add_f32_e32 v207, v248, v207
	v_add_f32_e32 v206, v247, v206
	v_add_f32_e32 v207, v249, v207
	v_add_f32_e32 v204, v205, v204
	v_add_f32_e32 v204, v204, v206
	v_add_f32_e32 v204, v204, v207
	ds_swizzle_b32 v205, v204 offset:swizzle(SWAP,1)
	s_waitcnt lgkmcnt(0)
	v_add_f32_e32 v204, v204, v205
	ds_swizzle_b32 v205, v204 offset:swizzle(SWAP,2)
	s_waitcnt lgkmcnt(0)
	v_add_f32_e32 v204, v204, v205
	ds_swizzle_b32 v205, v204 offset:swizzle(SWAP,4)
	s_waitcnt lgkmcnt(0)
	v_add_f32_e32 v204, v204, v205
	ds_swizzle_b32 v205, v204 offset:swizzle(SWAP,8)
	s_waitcnt lgkmcnt(0)
	v_add_f32_e32 v204, v204, v205
	ds_swizzle_b32 v205, v204 offset:swizzle(SWAP,16)
	s_waitcnt lgkmcnt(0)
; __device__ __forceinline__ unsigned pk2(float lo, float hi) { const g_f32x2 f = {lo, hi}; return __builtin_bit_cast(unsigned, __builtin_convertvector(f, g_bf16x2)); }
; __device__ __forceinline__ void p_norm(const float* hlat, const float* hctx, const float* g, const float* modl, int sh_off, int sc_off, bf16_t* A, int M,
;                                        const float* part, const float* cgate, float* hcout) {
;     ...
;             if (part != nullptr && row >= NLAT) {
;                 const size_t po = (size_t)(row - NLAT) * 1024 + i * 256 + lane * 4;
;                 const float4 p0 = *(const float4*)(part + po), p1 = *(const float4*)(part + (size_t)4096 * 1024 + po), cg = *(const float4*)(cgate + i * 256 + lane * 4);
;                 v[i].x += cg.x * (p0.x + p1.x); v[i].y += cg.y * (p0.y + p1.y); v[i].z += cg.z * (p0.z + p1.z); v[i].w += cg.w * (p0.w + p1.w);
;                 *(float4*)(hcout + po) = v[i];
;             }
;             ss += v[i].x * v[i].x + v[i].y * v[i].y + v[i].z * v[i].z + v[i].w * v[i].w; }
;         ss = wave_sum(ss);
;         const float rstd = rsqrtf(ss * (1.0f / 1024.0f) + EPS);
;         const float* mr = modl + (size_t)r * 6144;
; #pragma unroll
;         for (int i = 0; i < 4; ++i) {
;             const int k = i * 256 + lane * 4;
;             const float4 gg = *(const float4*)(g + k), scv = *(const float4*)(mr + sc_off + k), shv = *(const float4*)(mr + sh_off + k);
;             const float o0 = v[i].x * rstd * gg.x * (1.0f + scv.x) + shv.x, o1 = v[i].y * rstd * gg.y * (1.0f + scv.y) + shv.y;
;             const float o2 = v[i].z * rstd * gg.z * (1.0f + scv.z) + shv.z, o3 = v[i].w * rstd * gg.w * (1.0f + scv.w) + shv.w;
;             uint2 w; w.x = pk2(o0, o1); w.y = pk2(o2, o3);
;             *(uint2*)(A + (size_t)row * 1024 + k) = w;
;         }
	v_add_f32_e32 v204, v204, v205
	v_mov_b32_e32 v205, v204
	s_nop 1
	v_permlane32_swap_b32_e32 v204, v205
	v_add_f32_e32 v204, v204, v205
	v_mov_b32_e32 v205, 0x358637bd
	v_fmamk_f32 v204, v204, 0x3a800000, v205
	v_rsq_f32_e32 v204, v204
	s_nop 0
	v_pk_mul_f32 v[80:81], v[80:81], v[204:205] op_sel_hi:[1,0]
	v_pk_mul_f32 v[82:83], v[82:83], v[204:205] op_sel_hi:[1,0]
	v_pk_mul_f32 v[80:81], v[188:189], v[80:81]
	v_pk_mul_f32 v[82:83], v[190:191], v[82:83]
	v_pk_fma_f32 v[80:81], v[34:35], v[80:81], v[224:225]
	v_pk_fma_f32 v[82:83], v[36:37], v[82:83], v[226:227]
	v_cvt_pk_bf16_f32 v80, v80, v81
	v_cvt_pk_bf16_f32 v81, v82, v83
	global_store_dwordx2 v146, v[80:81], s[66:67] sc0 sc1
	v_pk_mul_f32 v[84:85], v[84:85], v[204:205] op_sel_hi:[1,0]
	v_pk_mul_f32 v[86:87], v[86:87], v[204:205] op_sel_hi:[1,0]
	v_pk_mul_f32 v[84:85], v[192:193], v[84:85]
	v_pk_mul_f32 v[86:87], v[194:195], v[86:87]
	v_pk_fma_f32 v[84:85], v[38:39], v[84:85], v[228:229]
	v_pk_fma_f32 v[86:87], v[40:41], v[86:87], v[230:231]
	v_cvt_pk_bf16_f32 v84, v84, v85
	v_cvt_pk_bf16_f32 v85, v86, v87
	global_store_dwordx2 v146, v[84:85], s[66:67] offset:512 sc0 sc1
	v_pk_mul_f32 v[88:89], v[88:89], v[204:205] op_sel_hi:[1,0]
	v_pk_mul_f32 v[90:91], v[90:91], v[204:205] op_sel_hi:[1,0]
	v_pk_mul_f32 v[88:89], v[196:197], v[88:89]
	v_pk_mul_f32 v[90:91], v[198:199], v[90:91]
	v_pk_fma_f32 v[88:89], v[42:43], v[88:89], v[232:233]
	v_pk_fma_f32 v[90:91], v[44:45], v[90:91], v[234:235]
	v_cvt_pk_bf16_f32 v88, v88, v89
	v_cvt_pk_bf16_f32 v89, v90, v91
	global_store_dwordx2 v146, v[88:89], s[66:67] offset:1024 sc0 sc1
	v_pk_mul_f32 v[92:93], v[92:93], v[204:205] op_sel_hi:[1,0]
	v_pk_mul_f32 v[94:95], v[94:95], v[204:205] op_sel_hi:[1,0]
	v_pk_mul_f32 v[92:93], v[200:201], v[92:93]
	v_pk_mul_f32 v[94:95], v[202:203], v[94:95]
	v_pk_fma_f32 v[92:93], v[46:47], v[92:93], v[236:237]
	v_pk_fma_f32 v[94:95], v[48:49], v[94:95], v[238:239]
	v_cvt_pk_bf16_f32 v92, v92, v93
	v_cvt_pk_bf16_f32 v93, v94, v95
	global_store_dwordx2 v146, v[92:93], s[66:67] offset:1536 sc0 sc1
	v_add_u32_e32 v146, 0x800, v146
	global_load_dwordx4 v[8:11], v241, s[20:21]
	global_load_dwordx4 v[52:55], v241, s[20:21] offset:1024
	global_load_dwordx4 v[60:63], v241, s[20:21] offset:2048
	global_load_dwordx4 v[64:67], v241, s[20:21] offset:3072
	s_waitcnt vmcnt(40)
	v_pk_mul_f32 v[242:243], v[96:97], v[96:97]
	v_pk_mul_f32 v[244:245], v[100:101], v[100:101]
	v_pk_mul_f32 v[246:247], v[98:99], v[98:99]
	v_pk_mul_f32 v[248:249], v[102:103], v[102:103]
	v_add_f32_e32 v204, v245, v244
	v_add_f32_e32 v205, v243, v242
	v_add_f32_e32 v204, v248, v204
	v_add_f32_e32 v205, v246, v205
	v_add_f32_e32 v204, v249, v204
	v_add_f32_e32 v205, v247, v205
	v_pk_mul_f32 v[242:243], v[104:105], v[104:105]
	v_pk_mul_f32 v[244:245], v[108:109], v[108:109]
	v_pk_mul_f32 v[246:247], v[106:107], v[106:107]
	v_pk_mul_f32 v[248:249], v[110:111], v[110:111]
	v_add_f32_e32 v206, v243, v242
	v_add_f32_e32 v207, v245, v244
	v_add_f32_e32 v206, v246, v206
	v_add_f32_e32 v207, v248, v207
	v_add_f32_e32 v206, v247, v206
	v_add_f32_e32 v207, v249, v207
	v_add_f32_e32 v204, v205, v204
	v_add_f32_e32 v204, v204, v206
	v_add_f32_e32 v204, v204, v207
	ds_swizzle_b32 v205, v204 offset:swizzle(SWAP,1)
	s_waitcnt lgkmcnt(0)
	v_add_f32_e32 v204, v204, v205
	ds_swizzle_b32 v205, v204 offset:swizzle(SWAP,2)
	s_waitcnt lgkmcnt(0)
	v_add_f32_e32 v204, v204, v205
	ds_swizzle_b32 v205, v204 offset:swizzle(SWAP,4)
	s_waitcnt lgkmcnt(0)
	v_add_f32_e32 v204, v204, v205
	ds_swizzle_b32 v205, v204 offset:swizzle(SWAP,8)
	s_waitcnt lgkmcnt(0)
	v_add_f32_e32 v204, v204, v205
	ds_swizzle_b32 v205, v204 offset:swizzle(SWAP,16)
	s_waitcnt lgkmcnt(0)
	v_add_f32_e32 v204, v204, v205
	v_mov_b32_e32 v205, v204
	s_nop 1
	v_permlane32_swap_b32_e32 v204, v205
	v_add_f32_e32 v204, v204, v205
	v_mov_b32_e32 v205, 0x358637bd
	v_fmamk_f32 v204, v204, 0x3a800000, v205
	v_rsq_f32_e32 v204, v204
	s_nop 0
	v_pk_mul_f32 v[96:97], v[96:97], v[204:205] op_sel_hi:[1,0]
	v_pk_mul_f32 v[98:99], v[98:99], v[204:205] op_sel_hi:[1,0]
	v_pk_mul_f32 v[96:97], v[188:189], v[96:97]
	v_pk_mul_f32 v[98:99], v[190:191], v[98:99]
	v_pk_fma_f32 v[96:97], v[34:35], v[96:97], v[224:225]
	v_pk_fma_f32 v[98:99], v[36:37], v[98:99], v[226:227]
	v_cvt_pk_bf16_f32 v96, v96, v97
	v_cvt_pk_bf16_f32 v97, v98, v99
	global_store_dwordx2 v146, v[96:97], s[66:67] sc0 sc1
	v_pk_mul_f32 v[100:101], v[100:101], v[204:205] op_sel_hi:[1,0]
	v_pk_mul_f32 v[102:103], v[102:103], v[204:205] op_sel_hi:[1,0]
	v_pk_mul_f32 v[100:101], v[192:193], v[100:101]
	v_pk_mul_f32 v[102:103], v[194:195], v[102:103]
	v_pk_fma_f32 v[100:101], v[38:39], v[100:101], v[228:229]
	v_pk_fma_f32 v[102:103], v[40:41], v[102:103], v[230:231]
	v_cvt_pk_bf16_f32 v100, v100, v101
	v_cvt_pk_bf16_f32 v101, v102, v103
	global_store_dwordx2 v146, v[100:101], s[66:67] offset:512 sc0 sc1
	v_pk_mul_f32 v[104:105], v[104:105], v[204:205] op_sel_hi:[1,0]
	v_pk_mul_f32 v[106:107], v[106:107], v[204:205] op_sel_hi:[1,0]
	v_pk_mul_f32 v[104:105], v[196:197], v[104:105]
	v_pk_mul_f32 v[106:107], v[198:199], v[106:107]
	v_pk_fma_f32 v[104:105], v[42:43], v[104:105], v[232:233]
	v_pk_fma_f32 v[106:107], v[44:45], v[106:107], v[234:235]
	v_cvt_pk_bf16_f32 v104, v104, v105
	v_cvt_pk_bf16_f32 v105, v106, v107
	global_store_dwordx2 v146, v[104:105], s[66:67] offset:1024 sc0 sc1
	v_pk_mul_f32 v[108:109], v[108:109], v[204:205] op_sel_hi:[1,0]
	v_pk_mul_f32 v[110:111], v[110:111], v[204:205] op_sel_hi:[1,0]
	v_pk_mul_f32 v[108:109], v[200:201], v[108:109]
	v_pk_mul_f32 v[110:111], v[202:203], v[110:111]
	v_pk_fma_f32 v[108:109], v[46:47], v[108:109], v[236:237]
	v_pk_fma_f32 v[110:111], v[48:49], v[110:111], v[238:239]
	v_cvt_pk_bf16_f32 v108, v108, v109
	v_cvt_pk_bf16_f32 v109, v110, v111
	global_store_dwordx2 v146, v[108:109], s[66:67] offset:1536 sc0 sc1
	v_add_u32_e32 v146, 0x800, v146
	global_load_dwordx4 v[80:83], v152, s[70:71]
	global_load_dwordx4 v[84:87], v152, s[70:71] offset:1024
	global_load_dwordx4 v[88:91], v152, s[70:71] offset:2048
	global_load_dwordx4 v[92:95], v152, s[70:71] offset:3072
	global_load_dwordx4 v[96:99], v150, s[70:71]
	global_load_dwordx4 v[100:103], v150, s[70:71] offset:1024
	global_load_dwordx4 v[104:107], v150, s[70:71] offset:2048
	global_load_dwordx4 v[108:111], v150, s[70:71] offset:3072
	s_waitcnt vmcnt(44)
; __device__ __forceinline__ unsigned pk2(float lo, float hi) { const g_f32x2 f = {lo, hi}; return __builtin_bit_cast(unsigned, __builtin_convertvector(f, g_bf16x2)); }
; __device__ __forceinline__ void p_norm(const float* hlat, const float* hctx, const float* g, const float* modl, int sh_off, int sc_off, bf16_t* A, int M,
;                                        const float* part, const float* cgate, float* hcout) {
;     ...
;             if (part != nullptr && row >= NLAT) {
;                 const size_t po = (size_t)(row - NLAT) * 1024 + i * 256 + lane * 4;
;                 const float4 p0 = *(const float4*)(part + po), p1 = *(const float4*)(part + (size_t)4096 * 1024 + po), cg = *(const float4*)(cgate + i * 256 + lane * 4);
;                 v[i].x += cg.x * (p0.x + p1.x); v[i].y += cg.y * (p0.y + p1.y); v[i].z += cg.z * (p0.z + p1.z); v[i].w += cg.w * (p0.w + p1.w);
;                 *(float4*)(hcout + po) = v[i];
;             }
;             ss += v[i].x * v[i].x + v[i].y * v[i].y + v[i].z * v[i].z + v[i].w * v[i].w; }
;         ss = wave_sum(ss);
;         const float rstd = rsqrtf(ss * (1.0f / 1024.0f) + EPS);
;         const float* mr = modl + (size_t)r * 6144;
; #pragma unroll
;         for (int i = 0; i < 4; ++i) {
;             const int k = i * 256 + lane * 4;
;             const float4 gg = *(const float4*)(g + k), scv = *(const float4*)(mr + sc_off + k), shv = *(const float4*)(mr + sh_off + k);
;             const float o0 = v[i].x * rstd * gg.x * (1.0f + scv.x) + shv.x, o1 = v[i].y * rstd * gg.y * (1.0f + scv.y) + shv.y;
;             const float o2 = v[i].z * rstd * gg.z * (1.0f + scv.z) + shv.z, o3 = v[i].w * rstd * gg.w * (1.0f + scv.w) + shv.w;
;             uint2 w; w.x = pk2(o0, o1); w.y = pk2(o2, o3);
;             *(uint2*)(A + (size_t)row * 1024 + k) = w;
;         }
	v_pk_mul_f32 v[242:243], v[112:113], v[112:113]
	v_pk_mul_f32 v[244:245], v[116:117], v[116:117]
	v_pk_mul_f32 v[246:247], v[114:115], v[114:115]
	v_pk_mul_f32 v[248:249], v[118:119], v[118:119]
	v_add_f32_e32 v204, v245, v244
	v_add_f32_e32 v205, v243, v242
	v_add_f32_e32 v204, v248, v204
	v_add_f32_e32 v205, v246, v205
	v_add_f32_e32 v204, v249, v204
	v_add_f32_e32 v205, v247, v205
	v_pk_mul_f32 v[242:243], v[120:121], v[120:121]
	v_pk_mul_f32 v[244:245], v[124:125], v[124:125]
	v_pk_mul_f32 v[246:247], v[122:123], v[122:123]
	v_pk_mul_f32 v[248:249], v[126:127], v[126:127]
	v_add_f32_e32 v206, v243, v242
	v_add_f32_e32 v207, v245, v244
	v_add_f32_e32 v206, v246, v206
	v_add_f32_e32 v207, v248, v207
	v_add_f32_e32 v206, v247, v206
	v_add_f32_e32 v207, v249, v207
	v_add_f32_e32 v204, v205, v204
	v_add_f32_e32 v204, v204, v206
	v_add_f32_e32 v204, v204, v207
	ds_swizzle_b32 v205, v204 offset:swizzle(SWAP,1)
	s_waitcnt lgkmcnt(0)
	v_add_f32_e32 v204, v204, v205
	ds_swizzle_b32 v205, v204 offset:swizzle(SWAP,2)
	s_waitcnt lgkmcnt(0)
	v_add_f32_e32 v204, v204, v205
	ds_swizzle_b32 v205, v204 offset:swizzle(SWAP,4)
	s_waitcnt lgkmcnt(0)
	v_add_f32_e32 v204, v204, v205
	ds_swizzle_b32 v205, v204 offset:swizzle(SWAP,8)
	s_waitcnt lgkmcnt(0)
	v_add_f32_e32 v204, v204, v205
	ds_swizzle_b32 v205, v204 offset:swizzle(SWAP,16)
	s_waitcnt lgkmcnt(0)
	v_add_f32_e32 v204, v204, v205
	v_mov_b32_e32 v205, v204
	s_nop 1
	v_permlane32_swap_b32_e32 v204, v205
	v_add_f32_e32 v204, v204, v205
	v_mov_b32_e32 v205, 0x358637bd
	v_fmamk_f32 v204, v204, 0x3a800000, v205
	v_rsq_f32_e32 v204, v204
	s_nop 0
	v_pk_mul_f32 v[112:113], v[112:113], v[204:205] op_sel_hi:[1,0]
	v_pk_mul_f32 v[114:115], v[114:115], v[204:205] op_sel_hi:[1,0]
	v_pk_mul_f32 v[112:113], v[188:189], v[112:113]
	v_pk_mul_f32 v[114:115], v[190:191], v[114:115]
	v_pk_fma_f32 v[112:113], v[34:35], v[112:113], v[224:225]
	v_pk_fma_f32 v[114:115], v[36:37], v[114:115], v[226:227]
	v_cvt_pk_bf16_f32 v112, v112, v113
	v_cvt_pk_bf16_f32 v113, v114, v115
	global_store_dwordx2 v146, v[112:113], s[66:67] sc0 sc1
	v_pk_mul_f32 v[116:117], v[116:117], v[204:205] op_sel_hi:[1,0]
	v_pk_mul_f32 v[118:119], v[118:119], v[204:205] op_sel_hi:[1,0]
	v_pk_mul_f32 v[116:117], v[192:193], v[116:117]
	v_pk_mul_f32 v[118:119], v[194:195], v[118:119]
	v_pk_fma_f32 v[116:117], v[38:39], v[116:117], v[228:229]
	v_pk_fma_f32 v[118:119], v[40:41], v[118:119], v[230:231]
	v_cvt_pk_bf16_f32 v116, v116, v117
	v_cvt_pk_bf16_f32 v117, v118, v119
	global_store_dwordx2 v146, v[116:117], s[66:67] offset:512 sc0 sc1
	v_pk_mul_f32 v[120:121], v[120:121], v[204:205] op_sel_hi:[1,0]
	v_pk_mul_f32 v[122:123], v[122:123], v[204:205] op_sel_hi:[1,0]
	v_pk_mul_f32 v[120:121], v[196:197], v[120:121]
	v_pk_mul_f32 v[122:123], v[198:199], v[122:123]
	v_pk_fma_f32 v[120:121], v[42:43], v[120:121], v[232:233]
	v_pk_fma_f32 v[122:123], v[44:45], v[122:123], v[234:235]
	v_cvt_pk_bf16_f32 v120, v120, v121
	v_cvt_pk_bf16_f32 v121, v122, v123
	global_store_dwordx2 v146, v[120:121], s[66:67] offset:1024 sc0 sc1
	v_pk_mul_f32 v[124:125], v[124:125], v[204:205] op_sel_hi:[1,0]
	v_pk_mul_f32 v[126:127], v[126:127], v[204:205] op_sel_hi:[1,0]
	v_pk_mul_f32 v[124:125], v[200:201], v[124:125]
	v_pk_mul_f32 v[126:127], v[202:203], v[126:127]
	v_pk_fma_f32 v[124:125], v[46:47], v[124:125], v[236:237]
	v_pk_fma_f32 v[126:127], v[48:49], v[126:127], v[238:239]
	v_cvt_pk_bf16_f32 v124, v124, v125
	v_cvt_pk_bf16_f32 v125, v126, v127
	global_store_dwordx2 v146, v[124:125], s[66:67] offset:1536 sc0 sc1
	v_add_u32_e32 v146, 0x800, v146
	v_add_u32_e32 v207, 0x1000, v152
	global_load_dwordx4 v[112:115], v207, s[70:71]
	global_load_dwordx4 v[116:119], v207, s[70:71] offset:1024
	global_load_dwordx4 v[120:123], v207, s[70:71] offset:2048
	global_load_dwordx4 v[124:127], v207, s[70:71] offset:3072
	s_waitcnt vmcnt(44)
	v_pk_mul_f32 v[242:243], v[128:129], v[128:129]
	v_pk_mul_f32 v[244:245], v[132:133], v[132:133]
	v_pk_mul_f32 v[246:247], v[130:131], v[130:131]
	v_pk_mul_f32 v[248:249], v[134:135], v[134:135]
	v_add_f32_e32 v204, v245, v244
	v_add_f32_e32 v205, v243, v242
	v_add_f32_e32 v204, v248, v204
	v_add_f32_e32 v205, v246, v205
	v_add_f32_e32 v204, v249, v204
	v_add_f32_e32 v205, v247, v205
	v_pk_mul_f32 v[242:243], v[136:137], v[136:137]
	v_pk_mul_f32 v[244:245], v[140:141], v[140:141]
	v_pk_mul_f32 v[246:247], v[138:139], v[138:139]
	v_pk_mul_f32 v[248:249], v[142:143], v[142:143]
	v_add_f32_e32 v206, v243, v242
	v_add_f32_e32 v207, v245, v244
	v_add_f32_e32 v206, v246, v206
	v_add_f32_e32 v207, v248, v207
	v_add_f32_e32 v206, v247, v206
	v_add_f32_e32 v207, v249, v207
	v_add_f32_e32 v204, v205, v204
	v_add_f32_e32 v204, v204, v206
	v_add_f32_e32 v204, v204, v207
	ds_swizzle_b32 v205, v204 offset:swizzle(SWAP,1)
	s_waitcnt lgkmcnt(0)
	v_add_f32_e32 v204, v204, v205
	ds_swizzle_b32 v205, v204 offset:swizzle(SWAP,2)
	s_waitcnt lgkmcnt(0)
	v_add_f32_e32 v204, v204, v205
	ds_swizzle_b32 v205, v204 offset:swizzle(SWAP,4)
	s_waitcnt lgkmcnt(0)
	v_add_f32_e32 v204, v204, v205
	ds_swizzle_b32 v205, v204 offset:swizzle(SWAP,8)
	s_waitcnt lgkmcnt(0)
	v_add_f32_e32 v204, v204, v205
	ds_swizzle_b32 v205, v204 offset:swizzle(SWAP,16)
	s_waitcnt lgkmcnt(0)
; __device__ __forceinline__ unsigned pk2(float lo, float hi) { const g_f32x2 f = {lo, hi}; return __builtin_bit_cast(unsigned, __builtin_convertvector(f, g_bf16x2)); }
; __device__ __forceinline__ void p_norm(const float* hlat, const float* hctx, const float* g, const float* modl, int sh_off, int sc_off, bf16_t* A, int M,
;                                        const float* part, const float* cgate, float* hcout) {
;     ...
;             if (part != nullptr && row >= NLAT) {
;                 const size_t po = (size_t)(row - NLAT) * 1024 + i * 256 + lane * 4;
;                 const float4 p0 = *(const float4*)(part + po), p1 = *(const float4*)(part + (size_t)4096 * 1024 + po), cg = *(const float4*)(cgate + i * 256 + lane * 4);
;                 v[i].x += cg.x * (p0.x + p1.x); v[i].y += cg.y * (p0.y + p1.y); v[i].z += cg.z * (p0.z + p1.z); v[i].w += cg.w * (p0.w + p1.w);
;                 *(float4*)(hcout + po) = v[i];
;             }
;             ss += v[i].x * v[i].x + v[i].y * v[i].y + v[i].z * v[i].z + v[i].w * v[i].w; }
;         ss = wave_sum(ss);
;         const float rstd = rsqrtf(ss * (1.0f / 1024.0f) + EPS);
;         const float* mr = modl + (size_t)r * 6144;
; #pragma unroll
;         for (int i = 0; i < 4; ++i) {
;             const int k = i * 256 + lane * 4;
;             const float4 gg = *(const float4*)(g + k), scv = *(const float4*)(mr + sc_off + k), shv = *(const float4*)(mr + sh_off + k);
;             const float o0 = v[i].x * rstd * gg.x * (1.0f + scv.x) + shv.x, o1 = v[i].y * rstd * gg.y * (1.0f + scv.y) + shv.y;
;             const float o2 = v[i].z * rstd * gg.z * (1.0f + scv.z) + shv.z, o3 = v[i].w * rstd * gg.w * (1.0f + scv.w) + shv.w;
;             uint2 w; w.x = pk2(o0, o1); w.y = pk2(o2, o3);
;             *(uint2*)(A + (size_t)row * 1024 + k) = w;
;         }
	v_add_f32_e32 v204, v204, v205
	v_mov_b32_e32 v205, v204
	s_nop 1
	v_permlane32_swap_b32_e32 v204, v205
	v_add_f32_e32 v204, v204, v205
	v_mov_b32_e32 v205, 0x358637bd
	v_fmamk_f32 v204, v204, 0x3a800000, v205
	v_rsq_f32_e32 v204, v204
	s_nop 0
	v_pk_mul_f32 v[128:129], v[128:129], v[204:205] op_sel_hi:[1,0]
	v_pk_mul_f32 v[130:131], v[130:131], v[204:205] op_sel_hi:[1,0]
	v_pk_mul_f32 v[128:129], v[188:189], v[128:129]
	v_pk_mul_f32 v[130:131], v[190:191], v[130:131]
	v_pk_fma_f32 v[128:129], v[34:35], v[128:129], v[224:225]
	v_pk_fma_f32 v[130:131], v[36:37], v[130:131], v[226:227]
	v_cvt_pk_bf16_f32 v128, v128, v129
	v_cvt_pk_bf16_f32 v129, v130, v131
	global_store_dwordx2 v146, v[128:129], s[66:67] sc0 sc1
	v_pk_mul_f32 v[132:133], v[132:133], v[204:205] op_sel_hi:[1,0]
	v_pk_mul_f32 v[134:135], v[134:135], v[204:205] op_sel_hi:[1,0]
	v_pk_mul_f32 v[132:133], v[192:193], v[132:133]
	v_pk_mul_f32 v[134:135], v[194:195], v[134:135]
	v_pk_fma_f32 v[132:133], v[38:39], v[132:133], v[228:229]
	v_pk_fma_f32 v[134:135], v[40:41], v[134:135], v[230:231]
	v_cvt_pk_bf16_f32 v132, v132, v133
	v_cvt_pk_bf16_f32 v133, v134, v135
	global_store_dwordx2 v146, v[132:133], s[66:67] offset:512 sc0 sc1
	v_pk_mul_f32 v[136:137], v[136:137], v[204:205] op_sel_hi:[1,0]
	v_pk_mul_f32 v[138:139], v[138:139], v[204:205] op_sel_hi:[1,0]
	v_pk_mul_f32 v[136:137], v[196:197], v[136:137]
	v_pk_mul_f32 v[138:139], v[198:199], v[138:139]
	v_pk_fma_f32 v[136:137], v[42:43], v[136:137], v[232:233]
	v_pk_fma_f32 v[138:139], v[44:45], v[138:139], v[234:235]
	v_cvt_pk_bf16_f32 v136, v136, v137
	v_cvt_pk_bf16_f32 v137, v138, v139
	global_store_dwordx2 v146, v[136:137], s[66:67] offset:1024 sc0 sc1
	v_pk_mul_f32 v[140:141], v[140:141], v[204:205] op_sel_hi:[1,0]
	v_pk_mul_f32 v[142:143], v[142:143], v[204:205] op_sel_hi:[1,0]
	v_pk_mul_f32 v[140:141], v[200:201], v[140:141]
	v_pk_mul_f32 v[142:143], v[202:203], v[142:143]
	v_pk_fma_f32 v[140:141], v[46:47], v[140:141], v[236:237]
	v_pk_fma_f32 v[142:143], v[48:49], v[142:143], v[238:239]
	v_cvt_pk_bf16_f32 v140, v140, v141
	v_cvt_pk_bf16_f32 v141, v142, v143
	global_store_dwordx2 v146, v[140:141], s[66:67] offset:1536 sc0 sc1
	v_add_u32_e32 v146, 0x800, v146
	v_add_u32_e32 v151, 0x60000, v241
	global_load_dwordx4 v[34:37], v151, s[98:99]
	global_load_dwordx4 v[38:41], v151, s[98:99] offset:1024
	global_load_dwordx4 v[42:45], v151, s[98:99] offset:2048
	global_load_dwordx4 v[46:49], v151, s[98:99] offset:3072
	global_load_dwordx4 v[224:227], v151, s[50:51]
	global_load_dwordx4 v[228:231], v151, s[50:51] offset:1024
	global_load_dwordx4 v[232:235], v151, s[50:51] offset:2048
	global_load_dwordx4 v[236:239], v151, s[50:51] offset:3072
	v_add_u32_e32 v207, 0x1000, v150
	global_load_dwordx4 v[128:131], v207, s[70:71]
	global_load_dwordx4 v[132:135], v207, s[70:71] offset:1024
	global_load_dwordx4 v[136:139], v207, s[70:71] offset:2048
	global_load_dwordx4 v[140:143], v207, s[70:71] offset:3072
	s_waitcnt vmcnt(24)
	v_pk_add_f32 v[80:81], v[80:81], v[96:97]
	v_pk_add_f32 v[82:83], v[82:83], v[98:99]
	v_pk_fma_f32 v[156:157], v[80:81], v[8:9], v[156:157]
	v_pk_fma_f32 v[158:159], v[82:83], v[10:11], v[158:159]
	global_store_dwordx4 v152, v[156:159], s[64:65]
	v_pk_add_f32 v[84:85], v[84:85], v[100:101]
	v_pk_add_f32 v[86:87], v[86:87], v[102:103]
	v_pk_fma_f32 v[160:161], v[84:85], v[52:53], v[160:161]
	v_pk_fma_f32 v[162:163], v[86:87], v[54:55], v[162:163]
	global_store_dwordx4 v152, v[160:163], s[64:65] offset:1024
	v_pk_add_f32 v[88:89], v[88:89], v[104:105]
	v_pk_add_f32 v[90:91], v[90:91], v[106:107]
	v_pk_fma_f32 v[164:165], v[88:89], v[60:61], v[164:165]
	v_pk_fma_f32 v[166:167], v[90:91], v[62:63], v[166:167]
	global_store_dwordx4 v152, v[164:167], s[64:65] offset:2048
	v_pk_add_f32 v[92:93], v[92:93], v[108:109]
	v_pk_add_f32 v[94:95], v[94:95], v[110:111]
	v_pk_fma_f32 v[168:169], v[92:93], v[64:65], v[168:169]
	v_pk_fma_f32 v[170:171], v[94:95], v[66:67], v[170:171]
	global_store_dwordx4 v152, v[168:171], s[64:65] offset:3072
	v_add_u32_e32 v152, 0x1000, v152
	v_pk_mul_f32 v[242:243], v[156:157], v[156:157]
	v_pk_mul_f32 v[244:245], v[160:161], v[160:161]
	v_pk_mul_f32 v[246:247], v[158:159], v[158:159]
	v_pk_mul_f32 v[248:249], v[162:163], v[162:163]
	v_add_f32_e32 v204, v245, v244
	v_add_f32_e32 v205, v243, v242
	v_add_f32_e32 v204, v248, v204
	v_add_f32_e32 v205, v246, v205
	v_add_f32_e32 v204, v249, v204
	v_add_f32_e32 v205, v247, v205
	v_pk_mul_f32 v[242:243], v[164:165], v[164:165]
	v_pk_mul_f32 v[244:245], v[168:169], v[168:169]
	v_pk_mul_f32 v[246:247], v[166:167], v[166:167]
	v_pk_mul_f32 v[248:249], v[170:171], v[170:171]
	v_add_f32_e32 v206, v243, v242
	v_add_f32_e32 v207, v245, v244
	v_add_f32_e32 v206, v246, v206
	v_add_f32_e32 v207, v248, v207
	v_add_f32_e32 v206, v247, v206
	v_add_f32_e32 v207, v249, v207
	v_add_f32_e32 v204, v205, v204
	v_add_f32_e32 v204, v204, v206
	v_add_f32_e32 v204, v204, v207
	ds_swizzle_b32 v205, v204 offset:swizzle(SWAP,1)
	s_waitcnt lgkmcnt(0)
	v_add_f32_e32 v204, v204, v205
	ds_swizzle_b32 v205, v204 offset:swizzle(SWAP,2)
	s_waitcnt lgkmcnt(0)
	v_add_f32_e32 v204, v204, v205
	ds_swizzle_b32 v205, v204 offset:swizzle(SWAP,4)
	s_waitcnt lgkmcnt(0)
	v_add_f32_e32 v204, v204, v205
	ds_swizzle_b32 v205, v204 offset:swizzle(SWAP,8)
	s_waitcnt lgkmcnt(0)
	v_add_f32_e32 v204, v204, v205
	ds_swizzle_b32 v205, v204 offset:swizzle(SWAP,16)
	s_waitcnt lgkmcnt(0)
	v_add_f32_e32 v204, v204, v205
	v_mov_b32_e32 v205, v204
	s_nop 1
	v_permlane32_swap_b32_e32 v204, v205
	v_add_f32_e32 v204, v204, v205
	v_mov_b32_e32 v205, 0x358637bd
	v_fmamk_f32 v204, v204, 0x3a800000, v205
	v_rsq_f32_e32 v204, v204
	s_nop 0
	s_waitcnt vmcnt(8)
; __device__ __forceinline__ unsigned pk2(float lo, float hi) { const g_f32x2 f = {lo, hi}; return __builtin_bit_cast(unsigned, __builtin_convertvector(f, g_bf16x2)); }
; __device__ __forceinline__ void p_norm(const float* hlat, const float* hctx, const float* g, const float* modl, int sh_off, int sc_off, bf16_t* A, int M,
;                                        const float* part, const float* cgate, float* hcout) {
;     ...
;             if (part != nullptr && row >= NLAT) {
;                 const size_t po = (size_t)(row - NLAT) * 1024 + i * 256 + lane * 4;
;                 const float4 p0 = *(const float4*)(part + po), p1 = *(const float4*)(part + (size_t)4096 * 1024 + po), cg = *(const float4*)(cgate + i * 256 + lane * 4);
;                 v[i].x += cg.x * (p0.x + p1.x); v[i].y += cg.y * (p0.y + p1.y); v[i].z += cg.z * (p0.z + p1.z); v[i].w += cg.w * (p0.w + p1.w);
;                 *(float4*)(hcout + po) = v[i];
;             }
;             ss += v[i].x * v[i].x + v[i].y * v[i].y + v[i].z * v[i].z + v[i].w * v[i].w; }
;         ss = wave_sum(ss);
;         const float rstd = rsqrtf(ss * (1.0f / 1024.0f) + EPS);
;         const float* mr = modl + (size_t)r * 6144;
; #pragma unroll
;         for (int i = 0; i < 4; ++i) {
;             const int k = i * 256 + lane * 4;
;             const float4 gg = *(const float4*)(g + k), scv = *(const float4*)(mr + sc_off + k), shv = *(const float4*)(mr + sh_off + k);
;             const float o0 = v[i].x * rstd * gg.x * (1.0f + scv.x) + shv.x, o1 = v[i].y * rstd * gg.y * (1.0f + scv.y) + shv.y;
;             const float o2 = v[i].z * rstd * gg.z * (1.0f + scv.z) + shv.z, o3 = v[i].w * rstd * gg.w * (1.0f + scv.w) + shv.w;
;             uint2 w; w.x = pk2(o0, o1); w.y = pk2(o2, o3);
;             *(uint2*)(A + (size_t)row * 1024 + k) = w;
;         }
	v_pk_add_f32 v[34:35], v[34:35], 1.0 op_sel_hi:[1,0]
	v_pk_add_f32 v[36:37], v[36:37], 1.0 op_sel_hi:[1,0]
	v_pk_add_f32 v[38:39], v[38:39], 1.0 op_sel_hi:[1,0]
	v_pk_add_f32 v[40:41], v[40:41], 1.0 op_sel_hi:[1,0]
	v_pk_add_f32 v[42:43], v[42:43], 1.0 op_sel_hi:[1,0]
	v_pk_add_f32 v[44:45], v[44:45], 1.0 op_sel_hi:[1,0]
	v_pk_add_f32 v[46:47], v[46:47], 1.0 op_sel_hi:[1,0]
	v_pk_add_f32 v[48:49], v[48:49], 1.0 op_sel_hi:[1,0]
	v_lshlrev_b32_e32 v146, 12, v50
	v_lshl_add_u32 v146, v240, 3, v146
	v_add_u32_e32 v146, 0x4000000, v146
	v_pk_mul_f32 v[156:157], v[156:157], v[204:205] op_sel_hi:[1,0]
	v_pk_mul_f32 v[158:159], v[158:159], v[204:205] op_sel_hi:[1,0]
	v_pk_mul_f32 v[156:157], v[188:189], v[156:157]
	v_pk_mul_f32 v[158:159], v[190:191], v[158:159]
	v_pk_fma_f32 v[156:157], v[34:35], v[156:157], v[224:225]
	v_pk_fma_f32 v[158:159], v[36:37], v[158:159], v[226:227]
	v_cvt_pk_bf16_f32 v156, v156, v157
	v_cvt_pk_bf16_f32 v157, v158, v159
	global_store_dwordx2 v146, v[156:157], s[66:67] sc0 sc1
	v_pk_mul_f32 v[160:161], v[160:161], v[204:205] op_sel_hi:[1,0]
	v_pk_mul_f32 v[162:163], v[162:163], v[204:205] op_sel_hi:[1,0]
	v_pk_mul_f32 v[160:161], v[192:193], v[160:161]
	v_pk_mul_f32 v[162:163], v[194:195], v[162:163]
	v_pk_fma_f32 v[160:161], v[38:39], v[160:161], v[228:229]
	v_pk_fma_f32 v[162:163], v[40:41], v[162:163], v[230:231]
	v_cvt_pk_bf16_f32 v160, v160, v161
	v_cvt_pk_bf16_f32 v161, v162, v163
	global_store_dwordx2 v146, v[160:161], s[66:67] offset:512 sc0 sc1
	v_pk_mul_f32 v[164:165], v[164:165], v[204:205] op_sel_hi:[1,0]
	v_pk_mul_f32 v[166:167], v[166:167], v[204:205] op_sel_hi:[1,0]
	v_pk_mul_f32 v[164:165], v[196:197], v[164:165]
	v_pk_mul_f32 v[166:167], v[198:199], v[166:167]
	v_pk_fma_f32 v[164:165], v[42:43], v[164:165], v[232:233]
	v_pk_fma_f32 v[166:167], v[44:45], v[166:167], v[234:235]
	v_cvt_pk_bf16_f32 v164, v164, v165
	v_cvt_pk_bf16_f32 v165, v166, v167
	global_store_dwordx2 v146, v[164:165], s[66:67] offset:1024 sc0 sc1
	v_pk_mul_f32 v[168:169], v[168:169], v[204:205] op_sel_hi:[1,0]
	v_pk_mul_f32 v[170:171], v[170:171], v[204:205] op_sel_hi:[1,0]
	v_pk_mul_f32 v[168:169], v[200:201], v[168:169]
	v_pk_mul_f32 v[170:171], v[202:203], v[170:171]
	v_pk_fma_f32 v[168:169], v[46:47], v[168:169], v[236:237]
	v_pk_fma_f32 v[170:171], v[48:49], v[170:171], v[238:239]
	v_cvt_pk_bf16_f32 v168, v168, v169
	v_cvt_pk_bf16_f32 v169, v170, v171
	global_store_dwordx2 v146, v[168:169], s[66:67] offset:1536 sc0 sc1
	v_add_u32_e32 v146, 0x800, v146
	s_waitcnt vmcnt(8)
	v_pk_add_f32 v[112:113], v[112:113], v[128:129]
	v_pk_add_f32 v[114:115], v[114:115], v[130:131]
	v_pk_fma_f32 v[172:173], v[112:113], v[8:9], v[172:173]
	v_pk_fma_f32 v[174:175], v[114:115], v[10:11], v[174:175]
	global_store_dwordx4 v152, v[172:175], s[64:65]
	v_pk_add_f32 v[116:117], v[116:117], v[132:133]
	v_pk_add_f32 v[118:119], v[118:119], v[134:135]
	v_pk_fma_f32 v[176:177], v[116:117], v[52:53], v[176:177]
	v_pk_fma_f32 v[178:179], v[118:119], v[54:55], v[178:179]
	global_store_dwordx4 v152, v[176:179], s[64:65] offset:1024
	v_pk_add_f32 v[120:121], v[120:121], v[136:137]
	v_pk_add_f32 v[122:123], v[122:123], v[138:139]
	v_pk_fma_f32 v[180:181], v[120:121], v[60:61], v[180:181]
	v_pk_fma_f32 v[182:183], v[122:123], v[62:63], v[182:183]
	global_store_dwordx4 v152, v[180:183], s[64:65] offset:2048
	v_pk_add_f32 v[124:125], v[124:125], v[140:141]
	v_pk_add_f32 v[126:127], v[126:127], v[142:143]
	v_pk_fma_f32 v[184:185], v[124:125], v[64:65], v[184:185]
	v_pk_fma_f32 v[186:187], v[126:127], v[66:67], v[186:187]
	global_store_dwordx4 v152, v[184:187], s[64:65] offset:3072
	v_add_u32_e32 v152, 0x1000, v152
	v_pk_mul_f32 v[242:243], v[172:173], v[172:173]
	v_pk_mul_f32 v[244:245], v[176:177], v[176:177]
	v_pk_mul_f32 v[246:247], v[174:175], v[174:175]
	v_pk_mul_f32 v[248:249], v[178:179], v[178:179]
	v_add_f32_e32 v204, v245, v244
	v_add_f32_e32 v205, v243, v242
	v_add_f32_e32 v204, v248, v204
	v_add_f32_e32 v205, v246, v205
	v_add_f32_e32 v204, v249, v204
	v_add_f32_e32 v205, v247, v205
	v_pk_mul_f32 v[242:243], v[180:181], v[180:181]
	v_pk_mul_f32 v[244:245], v[184:185], v[184:185]
	v_pk_mul_f32 v[246:247], v[182:183], v[182:183]
	v_pk_mul_f32 v[248:249], v[186:187], v[186:187]
	v_add_f32_e32 v206, v243, v242
	v_add_f32_e32 v207, v245, v244
	v_add_f32_e32 v206, v246, v206
	v_add_f32_e32 v207, v248, v207
	v_add_f32_e32 v206, v247, v206
	v_add_f32_e32 v207, v249, v207
	v_add_f32_e32 v204, v205, v204
	v_add_f32_e32 v204, v204, v206
	v_add_f32_e32 v204, v204, v207
	ds_swizzle_b32 v205, v204 offset:swizzle(SWAP,1)
	s_waitcnt lgkmcnt(0)
	v_add_f32_e32 v204, v204, v205
	ds_swizzle_b32 v205, v204 offset:swizzle(SWAP,2)
	s_waitcnt lgkmcnt(0)
	v_add_f32_e32 v204, v204, v205
	ds_swizzle_b32 v205, v204 offset:swizzle(SWAP,4)
	s_waitcnt lgkmcnt(0)
	v_add_f32_e32 v204, v204, v205
	ds_swizzle_b32 v205, v204 offset:swizzle(SWAP,8)
	s_waitcnt lgkmcnt(0)
	v_add_f32_e32 v204, v204, v205
	ds_swizzle_b32 v205, v204 offset:swizzle(SWAP,16)
	s_waitcnt lgkmcnt(0)
; __device__ __forceinline__ unsigned pk2(float lo, float hi) { const g_f32x2 f = {lo, hi}; return __builtin_bit_cast(unsigned, __builtin_convertvector(f, g_bf16x2)); }
; #define PN_LOAD(dst, rw) do { const float* s_ = (rw) < NLAT ? hlat + (size_t)(rw) * 1024 : hctx + (size_t)((rw) - NLAT) * 1024; \
;         _Pragma("unroll") for (int i = 0; i < 4; ++i) dst[i] = *(const float4*)(s_ + i * 256 + lane * 4); } while (0)
; __device__ __forceinline__ void p_norm(const float* hlat, const float* hctx, const float* g, const float* modl, int sh_off, int sc_off, bf16_t* A, int M,
;                                        const float* part, const float* cgate, float* hcout) {
;     ...
;     if (row < M) PN_LOAD(v, row);
;     while (row < M) {
;         const int nrow = row + stride;
;         if (nrow < M) PN_LOAD(nv, nrow);
;         const int r = row < NLAT ? (row >> 11) : 16;
;         float ss = 0.f;
; #pragma unroll
;         for (int i = 0; i < 4; ++i) {
;             if (part != nullptr && row >= NLAT) {
;                 const size_t po = (size_t)(row - NLAT) * 1024 + i * 256 + lane * 4;
;                 const float4 p0 = *(const float4*)(part + po), p1 = *(const float4*)(part + (size_t)4096 * 1024 + po), cg = *(const float4*)(cgate + i * 256 + lane * 4);
;                 v[i].x += cg.x * (p0.x + p1.x); v[i].y += cg.y * (p0.y + p1.y); v[i].z += cg.z * (p0.z + p1.z); v[i].w += cg.w * (p0.w + p1.w);
;                 *(float4*)(hcout + po) = v[i];
;             }
;             ss += v[i].x * v[i].x + v[i].y * v[i].y + v[i].z * v[i].z + v[i].w * v[i].w; }
;         ss = wave_sum(ss);
;         const float rstd = rsqrtf(ss * (1.0f / 1024.0f) + EPS);
;         const float* mr = modl + (size_t)r * 6144;
; #pragma unroll
;         for (int i = 0; i < 4; ++i) {
;             const int k = i * 256 + lane * 4;
;             const float4 gg = *(const float4*)(g + k), scv = *(const float4*)(mr + sc_off + k), shv = *(const float4*)(mr + sh_off + k);
;             const float o0 = v[i].x * rstd * gg.x * (1.0f + scv.x) + shv.x, o1 = v[i].y * rstd * gg.y * (1.0f + scv.y) + shv.y;
;             const float o2 = v[i].z * rstd * gg.z * (1.0f + scv.z) + shv.z, o3 = v[i].w * rstd * gg.w * (1.0f + scv.w) + shv.w;
;             uint2 w; w.x = pk2(o0, o1); w.y = pk2(o2, o3);
;             *(uint2*)(A + (size_t)row * 1024 + k) = w;
;         }
	v_add_f32_e32 v204, v204, v205
	v_mov_b32_e32 v205, v204
	s_nop 1
	v_permlane32_swap_b32_e32 v204, v205
	v_add_f32_e32 v204, v204, v205
	v_mov_b32_e32 v205, 0x358637bd
	v_fmamk_f32 v204, v204, 0x3a800000, v205
	v_rsq_f32_e32 v204, v204
	s_nop 0
	v_pk_mul_f32 v[172:173], v[172:173], v[204:205] op_sel_hi:[1,0]
	v_pk_mul_f32 v[174:175], v[174:175], v[204:205] op_sel_hi:[1,0]
	v_pk_mul_f32 v[172:173], v[188:189], v[172:173]
	v_pk_mul_f32 v[174:175], v[190:191], v[174:175]
	v_pk_fma_f32 v[172:173], v[34:35], v[172:173], v[224:225]
	v_pk_fma_f32 v[174:175], v[36:37], v[174:175], v[226:227]
	v_cvt_pk_bf16_f32 v172, v172, v173
	v_cvt_pk_bf16_f32 v173, v174, v175
	global_store_dwordx2 v146, v[172:173], s[66:67] sc0 sc1
	v_pk_mul_f32 v[176:177], v[176:177], v[204:205] op_sel_hi:[1,0]
	v_pk_mul_f32 v[178:179], v[178:179], v[204:205] op_sel_hi:[1,0]
	v_pk_mul_f32 v[176:177], v[192:193], v[176:177]
	v_pk_mul_f32 v[178:179], v[194:195], v[178:179]
	v_pk_fma_f32 v[176:177], v[38:39], v[176:177], v[228:229]
	v_pk_fma_f32 v[178:179], v[40:41], v[178:179], v[230:231]
	v_cvt_pk_bf16_f32 v176, v176, v177
	v_cvt_pk_bf16_f32 v177, v178, v179
	global_store_dwordx2 v146, v[176:177], s[66:67] offset:512 sc0 sc1
	v_pk_mul_f32 v[180:181], v[180:181], v[204:205] op_sel_hi:[1,0]
	v_pk_mul_f32 v[182:183], v[182:183], v[204:205] op_sel_hi:[1,0]
	v_pk_mul_f32 v[180:181], v[196:197], v[180:181]
	v_pk_mul_f32 v[182:183], v[198:199], v[182:183]
	v_pk_fma_f32 v[180:181], v[42:43], v[180:181], v[232:233]
	v_pk_fma_f32 v[182:183], v[44:45], v[182:183], v[234:235]
	v_cvt_pk_bf16_f32 v180, v180, v181
	v_cvt_pk_bf16_f32 v181, v182, v183
	global_store_dwordx2 v146, v[180:181], s[66:67] offset:1024 sc0 sc1
	v_pk_mul_f32 v[184:185], v[184:185], v[204:205] op_sel_hi:[1,0]
	v_pk_mul_f32 v[186:187], v[186:187], v[204:205] op_sel_hi:[1,0]
	v_pk_mul_f32 v[184:185], v[200:201], v[184:185]
	v_pk_mul_f32 v[186:187], v[202:203], v[186:187]
	v_pk_fma_f32 v[184:185], v[46:47], v[184:185], v[236:237]
	v_pk_fma_f32 v[186:187], v[48:49], v[186:187], v[238:239]
	v_cvt_pk_bf16_f32 v184, v184, v185
	v_cvt_pk_bf16_f32 v185, v186, v187
	global_store_dwordx2 v146, v[184:185], s[66:67] offset:1536 sc0 sc1
	v_add_u32_e32 v146, 0x800, v146
	s_branch .Lnorm_P6_end
.Lnorm_P6_alt:
	global_load_dwordx4 v[80:83], v144, s[46:47] nt
	global_load_dwordx4 v[84:87], v144, s[46:47] offset:1024 nt
	global_load_dwordx4 v[88:91], v144, s[46:47] offset:2048 nt
	global_load_dwordx4 v[92:95], v144, s[46:47] offset:3072 nt
	v_add_u32_e32 v144, 0x1000, v144
	global_load_dwordx4 v[34:37], v148, s[98:99]
	global_load_dwordx4 v[38:41], v148, s[98:99] offset:1024
	global_load_dwordx4 v[42:45], v148, s[98:99] offset:2048
	global_load_dwordx4 v[46:49], v148, s[98:99] offset:3072
	global_load_dwordx4 v[224:227], v148, s[50:51]
	global_load_dwordx4 v[228:231], v148, s[50:51] offset:1024
	global_load_dwordx4 v[232:235], v148, s[50:51] offset:2048
	global_load_dwordx4 v[236:239], v148, s[50:51] offset:3072
	global_load_dwordx4 v[188:191], v241, s[48:49]
	global_load_dwordx4 v[192:195], v241, s[48:49] offset:1024
	global_load_dwordx4 v[196:199], v241, s[48:49] offset:2048
	global_load_dwordx4 v[200:203], v241, s[48:49] offset:3072
	global_load_dwordx4 v[96:99], v144, s[46:47] nt
	global_load_dwordx4 v[100:103], v144, s[46:47] offset:1024 nt
	global_load_dwordx4 v[104:107], v144, s[46:47] offset:2048 nt
	global_load_dwordx4 v[108:111], v144, s[46:47] offset:3072 nt
	v_add_u32_e32 v144, 0x1000, v144
	global_load_dwordx4 v[112:115], v144, s[46:47] nt
	global_load_dwordx4 v[116:119], v144, s[46:47] offset:1024 nt
	global_load_dwordx4 v[120:123], v144, s[46:47] offset:2048 nt
	global_load_dwordx4 v[124:127], v144, s[46:47] offset:3072 nt
	v_add_u32_e32 v144, 0x1000, v144
	global_load_dwordx4 v[128:131], v144, s[46:47] nt
	global_load_dwordx4 v[132:135], v144, s[46:47] offset:1024 nt
	global_load_dwordx4 v[136:139], v144, s[46:47] offset:2048 nt
	global_load_dwordx4 v[140:143], v144, s[46:47] offset:3072 nt
	v_add_u32_e32 v144, 0x1000, v144
	global_load_dwordx4 v[156:159], v144, s[46:47] nt
	global_load_dwordx4 v[160:163], v144, s[46:47] offset:1024 nt
	global_load_dwordx4 v[164:167], v144, s[46:47] offset:2048 nt
	global_load_dwordx4 v[168:171], v144, s[46:47] offset:3072 nt
	v_add_u32_e32 v144, 0x1000, v144
	global_load_dwordx4 v[172:175], v144, s[46:47] nt
	global_load_dwordx4 v[176:179], v144, s[46:47] offset:1024 nt
	global_load_dwordx4 v[180:183], v144, s[46:47] offset:2048 nt
	global_load_dwordx4 v[184:187], v144, s[46:47] offset:3072 nt
	v_add_u32_e32 v144, 0x1000, v144
	s_waitcnt vmcnt(32)
	v_pk_mul_f32 v[242:243], v[80:81], v[80:81]
	v_pk_mul_f32 v[244:245], v[84:85], v[84:85]
	v_pk_mul_f32 v[246:247], v[82:83], v[82:83]
	v_pk_mul_f32 v[248:249], v[86:87], v[86:87]
	v_add_f32_e32 v204, v245, v244
	v_add_f32_e32 v205, v243, v242
	v_add_f32_e32 v204, v248, v204
	v_add_f32_e32 v205, v246, v205
	v_add_f32_e32 v204, v249, v204
	v_add_f32_e32 v205, v247, v205
	v_pk_mul_f32 v[242:243], v[88:89], v[88:89]
	v_pk_mul_f32 v[244:245], v[92:93], v[92:93]
	v_pk_mul_f32 v[246:247], v[90:91], v[90:91]
	v_pk_mul_f32 v[248:249], v[94:95], v[94:95]
	v_add_f32_e32 v206, v243, v242
	v_add_f32_e32 v207, v245, v244
	v_add_f32_e32 v206, v246, v206
	v_add_f32_e32 v207, v248, v207
	v_add_f32_e32 v206, v247, v206
	v_add_f32_e32 v207, v249, v207
	v_add_f32_e32 v204, v205, v204
	v_add_f32_e32 v204, v204, v206
	v_add_f32_e32 v204, v204, v207
	ds_swizzle_b32 v205, v204 offset:swizzle(SWAP,1)
	s_waitcnt lgkmcnt(0)
	v_add_f32_e32 v204, v204, v205
	ds_swizzle_b32 v205, v204 offset:swizzle(SWAP,2)
	s_waitcnt lgkmcnt(0)
; __device__ __forceinline__ unsigned pk2(float lo, float hi) { const g_f32x2 f = {lo, hi}; return __builtin_bit_cast(unsigned, __builtin_convertvector(f, g_bf16x2)); }
; __device__ __forceinline__ void p_norm(const float* hlat, const float* hctx, const float* g, const float* modl, int sh_off, int sc_off, bf16_t* A, int M,
;                                        const float* part, const float* cgate, float* hcout) {
;     ...
;         ss = wave_sum(ss);
;         const float rstd = rsqrtf(ss * (1.0f / 1024.0f) + EPS);
;         const float* mr = modl + (size_t)r * 6144;
; #pragma unroll
;         for (int i = 0; i < 4; ++i) {
;             const int k = i * 256 + lane * 4;
;             const float4 gg = *(const float4*)(g + k), scv = *(const float4*)(mr + sc_off + k), shv = *(const float4*)(mr + sh_off + k);
;             const float o0 = v[i].x * rstd * gg.x * (1.0f + scv.x) + shv.x, o1 = v[i].y * rstd * gg.y * (1.0f + scv.y) + shv.y;
;             const float o2 = v[i].z * rstd * gg.z * (1.0f + scv.z) + shv.z, o3 = v[i].w * rstd * gg.w * (1.0f + scv.w) + shv.w;
;             uint2 w; w.x = pk2(o0, o1); w.y = pk2(o2, o3);
;             *(uint2*)(A + (size_t)row * 1024 + k) = w;
;         }
	v_add_f32_e32 v204, v204, v205
	ds_swizzle_b32 v205, v204 offset:swizzle(SWAP,4)
	s_waitcnt lgkmcnt(0)
	v_add_f32_e32 v204, v204, v205
	ds_swizzle_b32 v205, v204 offset:swizzle(SWAP,8)
	s_waitcnt lgkmcnt(0)
	v_add_f32_e32 v204, v204, v205
	ds_swizzle_b32 v205, v204 offset:swizzle(SWAP,16)
	s_waitcnt lgkmcnt(0)
	v_add_f32_e32 v204, v204, v205
	v_mov_b32_e32 v205, v204
	s_nop 1
	v_permlane32_swap_b32_e32 v204, v205
	v_add_f32_e32 v204, v204, v205
	v_mov_b32_e32 v205, 0x358637bd
	v_fmamk_f32 v204, v204, 0x3a800000, v205
	v_rsq_f32_e32 v204, v204
	s_nop 0
	s_waitcnt vmcnt(20)
	v_pk_add_f32 v[34:35], v[34:35], 1.0 op_sel_hi:[1,0]
	v_pk_add_f32 v[36:37], v[36:37], 1.0 op_sel_hi:[1,0]
	v_pk_add_f32 v[38:39], v[38:39], 1.0 op_sel_hi:[1,0]
	v_pk_add_f32 v[40:41], v[40:41], 1.0 op_sel_hi:[1,0]
	v_pk_add_f32 v[42:43], v[42:43], 1.0 op_sel_hi:[1,0]
	v_pk_add_f32 v[44:45], v[44:45], 1.0 op_sel_hi:[1,0]
	v_pk_add_f32 v[46:47], v[46:47], 1.0 op_sel_hi:[1,0]
	v_pk_add_f32 v[48:49], v[48:49], 1.0 op_sel_hi:[1,0]
	v_pk_mul_f32 v[80:81], v[80:81], v[204:205] op_sel_hi:[1,0]
	v_pk_mul_f32 v[82:83], v[82:83], v[204:205] op_sel_hi:[1,0]
	v_pk_mul_f32 v[80:81], v[188:189], v[80:81]
	v_pk_mul_f32 v[82:83], v[190:191], v[82:83]
	v_pk_fma_f32 v[80:81], v[34:35], v[80:81], v[224:225]
	v_pk_fma_f32 v[82:83], v[36:37], v[82:83], v[226:227]
	v_cvt_pk_bf16_f32 v80, v80, v81
	v_cvt_pk_bf16_f32 v81, v82, v83
	global_store_dwordx2 v146, v[80:81], s[66:67] sc0 sc1
	v_pk_mul_f32 v[84:85], v[84:85], v[204:205] op_sel_hi:[1,0]
	v_pk_mul_f32 v[86:87], v[86:87], v[204:205] op_sel_hi:[1,0]
	v_pk_mul_f32 v[84:85], v[192:193], v[84:85]
	v_pk_mul_f32 v[86:87], v[194:195], v[86:87]
	v_pk_fma_f32 v[84:85], v[38:39], v[84:85], v[228:229]
	v_pk_fma_f32 v[86:87], v[40:41], v[86:87], v[230:231]
	v_cvt_pk_bf16_f32 v84, v84, v85
	v_cvt_pk_bf16_f32 v85, v86, v87
	global_store_dwordx2 v146, v[84:85], s[66:67] offset:512 sc0 sc1
	v_pk_mul_f32 v[88:89], v[88:89], v[204:205] op_sel_hi:[1,0]
	v_pk_mul_f32 v[90:91], v[90:91], v[204:205] op_sel_hi:[1,0]
	v_pk_mul_f32 v[88:89], v[196:197], v[88:89]
	v_pk_mul_f32 v[90:91], v[198:199], v[90:91]
	v_pk_fma_f32 v[88:89], v[42:43], v[88:89], v[232:233]
	v_pk_fma_f32 v[90:91], v[44:45], v[90:91], v[234:235]
	v_cvt_pk_bf16_f32 v88, v88, v89
	v_cvt_pk_bf16_f32 v89, v90, v91
	global_store_dwordx2 v146, v[88:89], s[66:67] offset:1024 sc0 sc1
	v_pk_mul_f32 v[92:93], v[92:93], v[204:205] op_sel_hi:[1,0]
	v_pk_mul_f32 v[94:95], v[94:95], v[204:205] op_sel_hi:[1,0]
	v_pk_mul_f32 v[92:93], v[200:201], v[92:93]
	v_pk_mul_f32 v[94:95], v[202:203], v[94:95]
	v_pk_fma_f32 v[92:93], v[46:47], v[92:93], v[236:237]
	v_pk_fma_f32 v[94:95], v[48:49], v[94:95], v[238:239]
	v_cvt_pk_bf16_f32 v92, v92, v93
	v_cvt_pk_bf16_f32 v93, v94, v95
	global_store_dwordx2 v146, v[92:93], s[66:67] offset:1536 sc0 sc1
	v_add_u32_e32 v146, 0x800, v146
	global_load_dwordx4 v[80:83], v144, s[46:47] nt
	global_load_dwordx4 v[84:87], v144, s[46:47] offset:1024 nt
	global_load_dwordx4 v[88:91], v144, s[46:47] offset:2048 nt
	global_load_dwordx4 v[92:95], v144, s[46:47] offset:3072 nt
	v_add_u32_e32 v144, 0x1000, v144
	s_waitcnt vmcnt(24)
	v_pk_mul_f32 v[242:243], v[96:97], v[96:97]
	v_pk_mul_f32 v[244:245], v[100:101], v[100:101]
	v_pk_mul_f32 v[246:247], v[98:99], v[98:99]
	v_pk_mul_f32 v[248:249], v[102:103], v[102:103]
	v_add_f32_e32 v204, v245, v244
	v_add_f32_e32 v205, v243, v242
	v_add_f32_e32 v204, v248, v204
	v_add_f32_e32 v205, v246, v205
	v_add_f32_e32 v204, v249, v204
	v_add_f32_e32 v205, v247, v205
	v_pk_mul_f32 v[242:243], v[104:105], v[104:105]
	v_pk_mul_f32 v[244:245], v[108:109], v[108:109]
	v_pk_mul_f32 v[246:247], v[106:107], v[106:107]
	v_pk_mul_f32 v[248:249], v[110:111], v[110:111]
	v_add_f32_e32 v206, v243, v242
	v_add_f32_e32 v207, v245, v244
	v_add_f32_e32 v206, v246, v206
	v_add_f32_e32 v207, v248, v207
	v_add_f32_e32 v206, v247, v206
	v_add_f32_e32 v207, v249, v207
	v_add_f32_e32 v204, v205, v204
	v_add_f32_e32 v204, v204, v206
	v_add_f32_e32 v204, v204, v207
	ds_swizzle_b32 v205, v204 offset:swizzle(SWAP,1)
	s_waitcnt lgkmcnt(0)
	v_add_f32_e32 v204, v204, v205
	ds_swizzle_b32 v205, v204 offset:swizzle(SWAP,2)
	s_waitcnt lgkmcnt(0)
	v_add_f32_e32 v204, v204, v205
	ds_swizzle_b32 v205, v204 offset:swizzle(SWAP,4)
	s_waitcnt lgkmcnt(0)
	v_add_f32_e32 v204, v204, v205
	ds_swizzle_b32 v205, v204 offset:swizzle(SWAP,8)
	s_waitcnt lgkmcnt(0)
	v_add_f32_e32 v204, v204, v205
	ds_swizzle_b32 v205, v204 offset:swizzle(SWAP,16)
	s_waitcnt lgkmcnt(0)
; __device__ __forceinline__ unsigned pk2(float lo, float hi) { const g_f32x2 f = {lo, hi}; return __builtin_bit_cast(unsigned, __builtin_convertvector(f, g_bf16x2)); }
; __device__ __forceinline__ void p_norm(const float* hlat, const float* hctx, const float* g, const float* modl, int sh_off, int sc_off, bf16_t* A, int M,
;                                        const float* part, const float* cgate, float* hcout) {
;     ...
;         for (int i = 0; i < 4; ++i) {
;             if (part != nullptr && row >= NLAT) {
;                 const size_t po = (size_t)(row - NLAT) * 1024 + i * 256 + lane * 4;
;                 const float4 p0 = *(const float4*)(part + po), p1 = *(const float4*)(part + (size_t)4096 * 1024 + po), cg = *(const float4*)(cgate + i * 256 + lane * 4);
;                 v[i].x += cg.x * (p0.x + p1.x); v[i].y += cg.y * (p0.y + p1.y); v[i].z += cg.z * (p0.z + p1.z); v[i].w += cg.w * (p0.w + p1.w);
;                 *(float4*)(hcout + po) = v[i];
;             }
;             ss += v[i].x * v[i].x + v[i].y * v[i].y + v[i].z * v[i].z + v[i].w * v[i].w; }
;         ss = wave_sum(ss);
;         const float rstd = rsqrtf(ss * (1.0f / 1024.0f) + EPS);
;         const float* mr = modl + (size_t)r * 6144;
; #pragma unroll
;         for (int i = 0; i < 4; ++i) {
;             const int k = i * 256 + lane * 4;
;             const float4 gg = *(const float4*)(g + k), scv = *(const float4*)(mr + sc_off + k), shv = *(const float4*)(mr + sh_off + k);
;             const float o0 = v[i].x * rstd * gg.x * (1.0f + scv.x) + shv.x, o1 = v[i].y * rstd * gg.y * (1.0f + scv.y) + shv.y;
;             const float o2 = v[i].z * rstd * gg.z * (1.0f + scv.z) + shv.z, o3 = v[i].w * rstd * gg.w * (1.0f + scv.w) + shv.w;
;             uint2 w; w.x = pk2(o0, o1); w.y = pk2(o2, o3);
;             *(uint2*)(A + (size_t)row * 1024 + k) = w;
;         }
	v_add_f32_e32 v204, v204, v205
	v_mov_b32_e32 v205, v204
	s_nop 1
	v_permlane32_swap_b32_e32 v204, v205
	v_add_f32_e32 v204, v204, v205
	v_mov_b32_e32 v205, 0x358637bd
	v_fmamk_f32 v204, v204, 0x3a800000, v205
	v_rsq_f32_e32 v204, v204
	s_nop 0
	v_pk_mul_f32 v[96:97], v[96:97], v[204:205] op_sel_hi:[1,0]
	v_pk_mul_f32 v[98:99], v[98:99], v[204:205] op_sel_hi:[1,0]
	v_pk_mul_f32 v[96:97], v[188:189], v[96:97]
	v_pk_mul_f32 v[98:99], v[190:191], v[98:99]
	v_pk_fma_f32 v[96:97], v[34:35], v[96:97], v[224:225]
	v_pk_fma_f32 v[98:99], v[36:37], v[98:99], v[226:227]
	v_cvt_pk_bf16_f32 v96, v96, v97
	v_cvt_pk_bf16_f32 v97, v98, v99
	global_store_dwordx2 v146, v[96:97], s[66:67] sc0 sc1
	v_pk_mul_f32 v[100:101], v[100:101], v[204:205] op_sel_hi:[1,0]
	v_pk_mul_f32 v[102:103], v[102:103], v[204:205] op_sel_hi:[1,0]
	v_pk_mul_f32 v[100:101], v[192:193], v[100:101]
	v_pk_mul_f32 v[102:103], v[194:195], v[102:103]
	v_pk_fma_f32 v[100:101], v[38:39], v[100:101], v[228:229]
	v_pk_fma_f32 v[102:103], v[40:41], v[102:103], v[230:231]
	v_cvt_pk_bf16_f32 v100, v100, v101
	v_cvt_pk_bf16_f32 v101, v102, v103
	global_store_dwordx2 v146, v[100:101], s[66:67] offset:512 sc0 sc1
	v_pk_mul_f32 v[104:105], v[104:105], v[204:205] op_sel_hi:[1,0]
	v_pk_mul_f32 v[106:107], v[106:107], v[204:205] op_sel_hi:[1,0]
	v_pk_mul_f32 v[104:105], v[196:197], v[104:105]
	v_pk_mul_f32 v[106:107], v[198:199], v[106:107]
	v_pk_fma_f32 v[104:105], v[42:43], v[104:105], v[232:233]
	v_pk_fma_f32 v[106:107], v[44:45], v[106:107], v[234:235]
	v_cvt_pk_bf16_f32 v104, v104, v105
	v_cvt_pk_bf16_f32 v105, v106, v107
	global_store_dwordx2 v146, v[104:105], s[66:67] offset:1024 sc0 sc1
	v_pk_mul_f32 v[108:109], v[108:109], v[204:205] op_sel_hi:[1,0]
	v_pk_mul_f32 v[110:111], v[110:111], v[204:205] op_sel_hi:[1,0]
	v_pk_mul_f32 v[108:109], v[200:201], v[108:109]
	v_pk_mul_f32 v[110:111], v[202:203], v[110:111]
	v_pk_fma_f32 v[108:109], v[46:47], v[108:109], v[236:237]
	v_pk_fma_f32 v[110:111], v[48:49], v[110:111], v[238:239]
	v_cvt_pk_bf16_f32 v108, v108, v109
	v_cvt_pk_bf16_f32 v109, v110, v111
	global_store_dwordx2 v146, v[108:109], s[66:67] offset:1536 sc0 sc1
	v_add_u32_e32 v146, 0x800, v146
	global_load_dwordx4 v[96:99], v144, s[46:47] nt
	global_load_dwordx4 v[100:103], v144, s[46:47] offset:1024 nt
	global_load_dwordx4 v[104:107], v144, s[46:47] offset:2048 nt
	global_load_dwordx4 v[108:111], v144, s[46:47] offset:3072 nt
	v_add_u32_e32 v144, 0x1000, v144
	s_waitcnt vmcnt(28)
	v_pk_mul_f32 v[242:243], v[112:113], v[112:113]
	v_pk_mul_f32 v[244:245], v[116:117], v[116:117]
	v_pk_mul_f32 v[246:247], v[114:115], v[114:115]
	v_pk_mul_f32 v[248:249], v[118:119], v[118:119]
	v_add_f32_e32 v204, v245, v244
	v_add_f32_e32 v205, v243, v242
	v_add_f32_e32 v204, v248, v204
	v_add_f32_e32 v205, v246, v205
	v_add_f32_e32 v204, v249, v204
	v_add_f32_e32 v205, v247, v205
	v_pk_mul_f32 v[242:243], v[120:121], v[120:121]
	v_pk_mul_f32 v[244:245], v[124:125], v[124:125]
	v_pk_mul_f32 v[246:247], v[122:123], v[122:123]
	v_pk_mul_f32 v[248:249], v[126:127], v[126:127]
	v_add_f32_e32 v206, v243, v242
	v_add_f32_e32 v207, v245, v244
	v_add_f32_e32 v206, v246, v206
	v_add_f32_e32 v207, v248, v207
	v_add_f32_e32 v206, v247, v206
	v_add_f32_e32 v207, v249, v207
	v_add_f32_e32 v204, v205, v204
	v_add_f32_e32 v204, v204, v206
	v_add_f32_e32 v204, v204, v207
	ds_swizzle_b32 v205, v204 offset:swizzle(SWAP,1)
	s_waitcnt lgkmcnt(0)
	v_add_f32_e32 v204, v204, v205
	ds_swizzle_b32 v205, v204 offset:swizzle(SWAP,2)
	s_waitcnt lgkmcnt(0)
	v_add_f32_e32 v204, v204, v205
	ds_swizzle_b32 v205, v204 offset:swizzle(SWAP,4)
	s_waitcnt lgkmcnt(0)
	v_add_f32_e32 v204, v204, v205
	ds_swizzle_b32 v205, v204 offset:swizzle(SWAP,8)
	s_waitcnt lgkmcnt(0)
	v_add_f32_e32 v204, v204, v205
	ds_swizzle_b32 v205, v204 offset:swizzle(SWAP,16)
	s_waitcnt lgkmcnt(0)
	v_add_f32_e32 v204, v204, v205
	v_mov_b32_e32 v205, v204
	s_nop 1
	v_permlane32_swap_b32_e32 v204, v205
	v_add_f32_e32 v204, v204, v205
	v_mov_b32_e32 v205, 0x358637bd
	v_fmamk_f32 v204, v204, 0x3a800000, v205
	v_rsq_f32_e32 v204, v204
	s_nop 0
	v_pk_mul_f32 v[112:113], v[112:113], v[204:205] op_sel_hi:[1,0]
	v_pk_mul_f32 v[114:115], v[114:115], v[204:205] op_sel_hi:[1,0]
	v_pk_mul_f32 v[112:113], v[188:189], v[112:113]
	v_pk_mul_f32 v[114:115], v[190:191], v[114:115]
	v_pk_fma_f32 v[112:113], v[34:35], v[112:113], v[224:225]
	v_pk_fma_f32 v[114:115], v[36:37], v[114:115], v[226:227]
	v_cvt_pk_bf16_f32 v112, v112, v113
	v_cvt_pk_bf16_f32 v113, v114, v115
	global_store_dwordx2 v146, v[112:113], s[66:67] sc0 sc1
	v_pk_mul_f32 v[116:117], v[116:117], v[204:205] op_sel_hi:[1,0]
	v_pk_mul_f32 v[118:119], v[118:119], v[204:205] op_sel_hi:[1,0]
	v_pk_mul_f32 v[116:117], v[192:193], v[116:117]
	v_pk_mul_f32 v[118:119], v[194:195], v[118:119]
	v_pk_fma_f32 v[116:117], v[38:39], v[116:117], v[228:229]
	v_pk_fma_f32 v[118:119], v[40:41], v[118:119], v[230:231]
	v_cvt_pk_bf16_f32 v116, v116, v117
	v_cvt_pk_bf16_f32 v117, v118, v119
	global_store_dwordx2 v146, v[116:117], s[66:67] offset:512 sc0 sc1
	v_pk_mul_f32 v[120:121], v[120:121], v[204:205] op_sel_hi:[1,0]
	v_pk_mul_f32 v[122:123], v[122:123], v[204:205] op_sel_hi:[1,0]
	v_pk_mul_f32 v[120:121], v[196:197], v[120:121]
	v_pk_mul_f32 v[122:123], v[198:199], v[122:123]
	v_pk_fma_f32 v[120:121], v[42:43], v[120:121], v[232:233]
	v_pk_fma_f32 v[122:123], v[44:45], v[122:123], v[234:235]
	v_cvt_pk_bf16_f32 v120, v120, v121
	v_cvt_pk_bf16_f32 v121, v122, v123
	global_store_dwordx2 v146, v[120:121], s[66:67] offset:1024 sc0 sc1
	v_pk_mul_f32 v[124:125], v[124:125], v[204:205] op_sel_hi:[1,0]
	v_pk_mul_f32 v[126:127], v[126:127], v[204:205] op_sel_hi:[1,0]
	v_pk_mul_f32 v[124:125], v[200:201], v[124:125]
	v_pk_mul_f32 v[126:127], v[202:203], v[126:127]
	v_pk_fma_f32 v[124:125], v[46:47], v[124:125], v[236:237]
	v_pk_fma_f32 v[126:127], v[48:49], v[126:127], v[238:239]
	v_cvt_pk_bf16_f32 v124, v124, v125
	v_cvt_pk_bf16_f32 v125, v126, v127
	global_store_dwordx2 v146, v[124:125], s[66:67] offset:1536 sc0 sc1
	v_add_u32_e32 v146, 0x800, v146
	global_load_dwordx4 v[112:115], v144, s[46:47] nt
	global_load_dwordx4 v[116:119], v144, s[46:47] offset:1024 nt
	global_load_dwordx4 v[120:123], v144, s[46:47] offset:2048 nt
	global_load_dwordx4 v[124:127], v144, s[46:47] offset:3072 nt
	v_add_u32_e32 v144, 0x1000, v144
	s_waitcnt vmcnt(32)
; __device__ __forceinline__ unsigned pk2(float lo, float hi) { const g_f32x2 f = {lo, hi}; return __builtin_bit_cast(unsigned, __builtin_convertvector(f, g_bf16x2)); }
; __device__ __forceinline__ void p_norm(const float* hlat, const float* hctx, const float* g, const float* modl, int sh_off, int sc_off, bf16_t* A, int M,
;                                        const float* part, const float* cgate, float* hcout) {
;     ...
;         for (int i = 0; i < 4; ++i) {
;             if (part != nullptr && row >= NLAT) {
;                 const size_t po = (size_t)(row - NLAT) * 1024 + i * 256 + lane * 4;
;                 const float4 p0 = *(const float4*)(part + po), p1 = *(const float4*)(part + (size_t)4096 * 1024 + po), cg = *(const float4*)(cgate + i * 256 + lane * 4);
;                 v[i].x += cg.x * (p0.x + p1.x); v[i].y += cg.y * (p0.y + p1.y); v[i].z += cg.z * (p0.z + p1.z); v[i].w += cg.w * (p0.w + p1.w);
;                 *(float4*)(hcout + po) = v[i];
;             }
;             ss += v[i].x * v[i].x + v[i].y * v[i].y + v[i].z * v[i].z + v[i].w * v[i].w; }
;         ss = wave_sum(ss);
;         const float rstd = rsqrtf(ss * (1.0f / 1024.0f) + EPS);
;         const float* mr = modl + (size_t)r * 6144;
; #pragma unroll
;         for (int i = 0; i < 4; ++i) {
;             const int k = i * 256 + lane * 4;
;             const float4 gg = *(const float4*)(g + k), scv = *(const float4*)(mr + sc_off + k), shv = *(const float4*)(mr + sh_off + k);
;             const float o0 = v[i].x * rstd * gg.x * (1.0f + scv.x) + shv.x, o1 = v[i].y * rstd * gg.y * (1.0f + scv.y) + shv.y;
;             const float o2 = v[i].z * rstd * gg.z * (1.0f + scv.z) + shv.z, o3 = v[i].w * rstd * gg.w * (1.0f + scv.w) + shv.w;
;             uint2 w; w.x = pk2(o0, o1); w.y = pk2(o2, o3);
;             *(uint2*)(A + (size_t)row * 1024 + k) = w;
;         }
	v_pk_mul_f32 v[242:243], v[128:129], v[128:129]
	v_pk_mul_f32 v[244:245], v[132:133], v[132:133]
	v_pk_mul_f32 v[246:247], v[130:131], v[130:131]
	v_pk_mul_f32 v[248:249], v[134:135], v[134:135]
	v_add_f32_e32 v204, v245, v244
	v_add_f32_e32 v205, v243, v242
	v_add_f32_e32 v204, v248, v204
	v_add_f32_e32 v205, v246, v205
	v_add_f32_e32 v204, v249, v204
	v_add_f32_e32 v205, v247, v205
	v_pk_mul_f32 v[242:243], v[136:137], v[136:137]
	v_pk_mul_f32 v[244:245], v[140:141], v[140:141]
	v_pk_mul_f32 v[246:247], v[138:139], v[138:139]
	v_pk_mul_f32 v[248:249], v[142:143], v[142:143]
	v_add_f32_e32 v206, v243, v242
	v_add_f32_e32 v207, v245, v244
	v_add_f32_e32 v206, v246, v206
	v_add_f32_e32 v207, v248, v207
	v_add_f32_e32 v206, v247, v206
	v_add_f32_e32 v207, v249, v207
	v_add_f32_e32 v204, v205, v204
	v_add_f32_e32 v204, v204, v206
	v_add_f32_e32 v204, v204, v207
	ds_swizzle_b32 v205, v204 offset:swizzle(SWAP,1)
	s_waitcnt lgkmcnt(0)
	v_add_f32_e32 v204, v204, v205
	ds_swizzle_b32 v205, v204 offset:swizzle(SWAP,2)
	s_waitcnt lgkmcnt(0)
	v_add_f32_e32 v204, v204, v205
	ds_swizzle_b32 v205, v204 offset:swizzle(SWAP,4)
	s_waitcnt lgkmcnt(0)
	v_add_f32_e32 v204, v204, v205
	ds_swizzle_b32 v205, v204 offset:swizzle(SWAP,8)
	s_waitcnt lgkmcnt(0)
	v_add_f32_e32 v204, v204, v205
	ds_swizzle_b32 v205, v204 offset:swizzle(SWAP,16)
	s_waitcnt lgkmcnt(0)
	v_add_f32_e32 v204, v204, v205
	v_mov_b32_e32 v205, v204
	s_nop 1
	v_permlane32_swap_b32_e32 v204, v205
	v_add_f32_e32 v204, v204, v205
	v_mov_b32_e32 v205, 0x358637bd
	v_fmamk_f32 v204, v204, 0x3a800000, v205
	v_rsq_f32_e32 v204, v204
	s_nop 0
	v_pk_mul_f32 v[128:129], v[128:129], v[204:205] op_sel_hi:[1,0]
	v_pk_mul_f32 v[130:131], v[130:131], v[204:205] op_sel_hi:[1,0]
	v_pk_mul_f32 v[128:129], v[188:189], v[128:129]
	v_pk_mul_f32 v[130:131], v[190:191], v[130:131]
	v_pk_fma_f32 v[128:129], v[34:35], v[128:129], v[224:225]
	v_pk_fma_f32 v[130:131], v[36:37], v[130:131], v[226:227]
	v_cvt_pk_bf16_f32 v128, v128, v129
	v_cvt_pk_bf16_f32 v129, v130, v131
	global_store_dwordx2 v146, v[128:129], s[66:67] sc0 sc1
	v_pk_mul_f32 v[132:133], v[132:133], v[204:205] op_sel_hi:[1,0]
	v_pk_mul_f32 v[134:135], v[134:135], v[204:205] op_sel_hi:[1,0]
	v_pk_mul_f32 v[132:133], v[192:193], v[132:133]
	v_pk_mul_f32 v[134:135], v[194:195], v[134:135]
	v_pk_fma_f32 v[132:133], v[38:39], v[132:133], v[228:229]
	v_pk_fma_f32 v[134:135], v[40:41], v[134:135], v[230:231]
	v_cvt_pk_bf16_f32 v132, v132, v133
	v_cvt_pk_bf16_f32 v133, v134, v135
	global_store_dwordx2 v146, v[132:133], s[66:67] offset:512 sc0 sc1
	v_pk_mul_f32 v[136:137], v[136:137], v[204:205] op_sel_hi:[1,0]
	v_pk_mul_f32 v[138:139], v[138:139], v[204:205] op_sel_hi:[1,0]
	v_pk_mul_f32 v[136:137], v[196:197], v[136:137]
	v_pk_mul_f32 v[138:139], v[198:199], v[138:139]
	v_pk_fma_f32 v[136:137], v[42:43], v[136:137], v[232:233]
	v_pk_fma_f32 v[138:139], v[44:45], v[138:139], v[234:235]
	v_cvt_pk_bf16_f32 v136, v136, v137
	v_cvt_pk_bf16_f32 v137, v138, v139
	global_store_dwordx2 v146, v[136:137], s[66:67] offset:1024 sc0 sc1
	v_pk_mul_f32 v[140:141], v[140:141], v[204:205] op_sel_hi:[1,0]
	v_pk_mul_f32 v[142:143], v[142:143], v[204:205] op_sel_hi:[1,0]
	v_pk_mul_f32 v[140:141], v[200:201], v[140:141]
	v_pk_mul_f32 v[142:143], v[202:203], v[142:143]
	v_pk_fma_f32 v[140:141], v[46:47], v[140:141], v[236:237]
	v_pk_fma_f32 v[142:143], v[48:49], v[142:143], v[238:239]
	v_cvt_pk_bf16_f32 v140, v140, v141
	v_cvt_pk_bf16_f32 v141, v142, v143
	global_store_dwordx2 v146, v[140:141], s[66:67] offset:1536 sc0 sc1
	v_add_u32_e32 v146, 0x800, v146
	global_load_dwordx4 v[128:131], v144, s[46:47] nt
	global_load_dwordx4 v[132:135], v144, s[46:47] offset:1024 nt
	global_load_dwordx4 v[136:139], v144, s[46:47] offset:2048 nt
	global_load_dwordx4 v[140:143], v144, s[46:47] offset:3072 nt
	v_add_u32_e32 v144, 0x1000, v144
	s_waitcnt vmcnt(36)
	v_pk_mul_f32 v[242:243], v[156:157], v[156:157]
	v_pk_mul_f32 v[244:245], v[160:161], v[160:161]
	v_pk_mul_f32 v[246:247], v[158:159], v[158:159]
	v_pk_mul_f32 v[248:249], v[162:163], v[162:163]
	v_add_f32_e32 v204, v245, v244
	v_add_f32_e32 v205, v243, v242
	v_add_f32_e32 v204, v248, v204
	v_add_f32_e32 v205, v246, v205
	v_add_f32_e32 v204, v249, v204
	v_add_f32_e32 v205, v247, v205
	v_pk_mul_f32 v[242:243], v[164:165], v[164:165]
	v_pk_mul_f32 v[244:245], v[168:169], v[168:169]
	v_pk_mul_f32 v[246:247], v[166:167], v[166:167]
	v_pk_mul_f32 v[248:249], v[170:171], v[170:171]
	v_add_f32_e32 v206, v243, v242
	v_add_f32_e32 v207, v245, v244
	v_add_f32_e32 v206, v246, v206
	v_add_f32_e32 v207, v248, v207
	v_add_f32_e32 v206, v247, v206
	v_add_f32_e32 v207, v249, v207
	v_add_f32_e32 v204, v205, v204
	v_add_f32_e32 v204, v204, v206
	v_add_f32_e32 v204, v204, v207
	ds_swizzle_b32 v205, v204 offset:swizzle(SWAP,1)
	s_waitcnt lgkmcnt(0)
	v_add_f32_e32 v204, v204, v205
	ds_swizzle_b32 v205, v204 offset:swizzle(SWAP,2)
	s_waitcnt lgkmcnt(0)
	v_add_f32_e32 v204, v204, v205
	ds_swizzle_b32 v205, v204 offset:swizzle(SWAP,4)
	s_waitcnt lgkmcnt(0)
	v_add_f32_e32 v204, v204, v205
	ds_swizzle_b32 v205, v204 offset:swizzle(SWAP,8)
	s_waitcnt lgkmcnt(0)
	v_add_f32_e32 v204, v204, v205
	ds_swizzle_b32 v205, v204 offset:swizzle(SWAP,16)
	s_waitcnt lgkmcnt(0)
; __device__ __forceinline__ unsigned pk2(float lo, float hi) { const g_f32x2 f = {lo, hi}; return __builtin_bit_cast(unsigned, __builtin_convertvector(f, g_bf16x2)); }
; __device__ __forceinline__ void p_norm(const float* hlat, const float* hctx, const float* g, const float* modl, int sh_off, int sc_off, bf16_t* A, int M,
;                                        const float* part, const float* cgate, float* hcout) {
;     ...
;         for (int i = 0; i < 4; ++i) {
;             if (part != nullptr && row >= NLAT) {
;                 const size_t po = (size_t)(row - NLAT) * 1024 + i * 256 + lane * 4;
;                 const float4 p0 = *(const float4*)(part + po), p1 = *(const float4*)(part + (size_t)4096 * 1024 + po), cg = *(const float4*)(cgate + i * 256 + lane * 4);
;                 v[i].x += cg.x * (p0.x + p1.x); v[i].y += cg.y * (p0.y + p1.y); v[i].z += cg.z * (p0.z + p1.z); v[i].w += cg.w * (p0.w + p1.w);
;                 *(float4*)(hcout + po) = v[i];
;             }
;             ss += v[i].x * v[i].x + v[i].y * v[i].y + v[i].z * v[i].z + v[i].w * v[i].w; }
;         ss = wave_sum(ss);
;         const float rstd = rsqrtf(ss * (1.0f / 1024.0f) + EPS);
;         const float* mr = modl + (size_t)r * 6144;
; #pragma unroll
;         for (int i = 0; i < 4; ++i) {
;             const int k = i * 256 + lane * 4;
;             const float4 gg = *(const float4*)(g + k), scv = *(const float4*)(mr + sc_off + k), shv = *(const float4*)(mr + sh_off + k);
;             const float o0 = v[i].x * rstd * gg.x * (1.0f + scv.x) + shv.x, o1 = v[i].y * rstd * gg.y * (1.0f + scv.y) + shv.y;
;             const float o2 = v[i].z * rstd * gg.z * (1.0f + scv.z) + shv.z, o3 = v[i].w * rstd * gg.w * (1.0f + scv.w) + shv.w;
;             uint2 w; w.x = pk2(o0, o1); w.y = pk2(o2, o3);
;             *(uint2*)(A + (size_t)row * 1024 + k) = w;
;         }
	v_add_f32_e32 v204, v204, v205
	v_mov_b32_e32 v205, v204
	s_nop 1
	v_permlane32_swap_b32_e32 v204, v205
	v_add_f32_e32 v204, v204, v205
	v_mov_b32_e32 v205, 0x358637bd
	v_fmamk_f32 v204, v204, 0x3a800000, v205
	v_rsq_f32_e32 v204, v204
	s_nop 0
	v_pk_mul_f32 v[156:157], v[156:157], v[204:205] op_sel_hi:[1,0]
	v_pk_mul_f32 v[158:159], v[158:159], v[204:205] op_sel_hi:[1,0]
	v_pk_mul_f32 v[156:157], v[188:189], v[156:157]
	v_pk_mul_f32 v[158:159], v[190:191], v[158:159]
	v_pk_fma_f32 v[156:157], v[34:35], v[156:157], v[224:225]
	v_pk_fma_f32 v[158:159], v[36:37], v[158:159], v[226:227]
	v_cvt_pk_bf16_f32 v156, v156, v157
	v_cvt_pk_bf16_f32 v157, v158, v159
	global_store_dwordx2 v146, v[156:157], s[66:67] sc0 sc1
	v_pk_mul_f32 v[160:161], v[160:161], v[204:205] op_sel_hi:[1,0]
	v_pk_mul_f32 v[162:163], v[162:163], v[204:205] op_sel_hi:[1,0]
	v_pk_mul_f32 v[160:161], v[192:193], v[160:161]
	v_pk_mul_f32 v[162:163], v[194:195], v[162:163]
	v_pk_fma_f32 v[160:161], v[38:39], v[160:161], v[228:229]
	v_pk_fma_f32 v[162:163], v[40:41], v[162:163], v[230:231]
	v_cvt_pk_bf16_f32 v160, v160, v161
	v_cvt_pk_bf16_f32 v161, v162, v163
	global_store_dwordx2 v146, v[160:161], s[66:67] offset:512 sc0 sc1
	v_pk_mul_f32 v[164:165], v[164:165], v[204:205] op_sel_hi:[1,0]
	v_pk_mul_f32 v[166:167], v[166:167], v[204:205] op_sel_hi:[1,0]
	v_pk_mul_f32 v[164:165], v[196:197], v[164:165]
	v_pk_mul_f32 v[166:167], v[198:199], v[166:167]
	v_pk_fma_f32 v[164:165], v[42:43], v[164:165], v[232:233]
	v_pk_fma_f32 v[166:167], v[44:45], v[166:167], v[234:235]
	v_cvt_pk_bf16_f32 v164, v164, v165
	v_cvt_pk_bf16_f32 v165, v166, v167
	global_store_dwordx2 v146, v[164:165], s[66:67] offset:1024 sc0 sc1
	v_pk_mul_f32 v[168:169], v[168:169], v[204:205] op_sel_hi:[1,0]
	v_pk_mul_f32 v[170:171], v[170:171], v[204:205] op_sel_hi:[1,0]
	v_pk_mul_f32 v[168:169], v[200:201], v[168:169]
	v_pk_mul_f32 v[170:171], v[202:203], v[170:171]
	v_pk_fma_f32 v[168:169], v[46:47], v[168:169], v[236:237]
	v_pk_fma_f32 v[170:171], v[48:49], v[170:171], v[238:239]
	v_cvt_pk_bf16_f32 v168, v168, v169
	v_cvt_pk_bf16_f32 v169, v170, v171
	global_store_dwordx2 v146, v[168:169], s[66:67] offset:1536 sc0 sc1
	v_add_u32_e32 v146, 0x800, v146
	global_load_dwordx4 v[156:159], v144, s[46:47] nt
	global_load_dwordx4 v[160:163], v144, s[46:47] offset:1024 nt
	global_load_dwordx4 v[164:167], v144, s[46:47] offset:2048 nt
	global_load_dwordx4 v[168:171], v144, s[46:47] offset:3072 nt
	v_add_u32_e32 v144, 0x1000, v144
	s_waitcnt vmcnt(40)
	v_pk_mul_f32 v[242:243], v[172:173], v[172:173]
	v_pk_mul_f32 v[244:245], v[176:177], v[176:177]
	v_pk_mul_f32 v[246:247], v[174:175], v[174:175]
	v_pk_mul_f32 v[248:249], v[178:179], v[178:179]
	v_add_f32_e32 v204, v245, v244
	v_add_f32_e32 v205, v243, v242
	v_add_f32_e32 v204, v248, v204
	v_add_f32_e32 v205, v246, v205
	v_add_f32_e32 v204, v249, v204
	v_add_f32_e32 v205, v247, v205
	v_pk_mul_f32 v[242:243], v[180:181], v[180:181]
	v_pk_mul_f32 v[244:245], v[184:185], v[184:185]
	v_pk_mul_f32 v[246:247], v[182:183], v[182:183]
	v_pk_mul_f32 v[248:249], v[186:187], v[186:187]
	v_add_f32_e32 v206, v243, v242
	v_add_f32_e32 v207, v245, v244
	v_add_f32_e32 v206, v246, v206
	v_add_f32_e32 v207, v248, v207
	v_add_f32_e32 v206, v247, v206
	v_add_f32_e32 v207, v249, v207
	v_add_f32_e32 v204, v205, v204
	v_add_f32_e32 v204, v204, v206
	v_add_f32_e32 v204, v204, v207
	ds_swizzle_b32 v205, v204 offset:swizzle(SWAP,1)
	s_waitcnt lgkmcnt(0)
	v_add_f32_e32 v204, v204, v205
	ds_swizzle_b32 v205, v204 offset:swizzle(SWAP,2)
	s_waitcnt lgkmcnt(0)
	v_add_f32_e32 v204, v204, v205
	ds_swizzle_b32 v205, v204 offset:swizzle(SWAP,4)
	s_waitcnt lgkmcnt(0)
	v_add_f32_e32 v204, v204, v205
	ds_swizzle_b32 v205, v204 offset:swizzle(SWAP,8)
	s_waitcnt lgkmcnt(0)
	v_add_f32_e32 v204, v204, v205
	ds_swizzle_b32 v205, v204 offset:swizzle(SWAP,16)
	s_waitcnt lgkmcnt(0)
	v_add_f32_e32 v204, v204, v205
	v_mov_b32_e32 v205, v204
	s_nop 1
	v_permlane32_swap_b32_e32 v204, v205
	v_add_f32_e32 v204, v204, v205
	v_mov_b32_e32 v205, 0x358637bd
	v_fmamk_f32 v204, v204, 0x3a800000, v205
	v_rsq_f32_e32 v204, v204
	s_nop 0
	v_pk_mul_f32 v[172:173], v[172:173], v[204:205] op_sel_hi:[1,0]
	v_pk_mul_f32 v[174:175], v[174:175], v[204:205] op_sel_hi:[1,0]
	v_pk_mul_f32 v[172:173], v[188:189], v[172:173]
	v_pk_mul_f32 v[174:175], v[190:191], v[174:175]
	v_pk_fma_f32 v[172:173], v[34:35], v[172:173], v[224:225]
	v_pk_fma_f32 v[174:175], v[36:37], v[174:175], v[226:227]
	v_cvt_pk_bf16_f32 v172, v172, v173
	v_cvt_pk_bf16_f32 v173, v174, v175
	global_store_dwordx2 v146, v[172:173], s[66:67] sc0 sc1
	v_pk_mul_f32 v[176:177], v[176:177], v[204:205] op_sel_hi:[1,0]
	v_pk_mul_f32 v[178:179], v[178:179], v[204:205] op_sel_hi:[1,0]
	v_pk_mul_f32 v[176:177], v[192:193], v[176:177]
	v_pk_mul_f32 v[178:179], v[194:195], v[178:179]
	v_pk_fma_f32 v[176:177], v[38:39], v[176:177], v[228:229]
	v_pk_fma_f32 v[178:179], v[40:41], v[178:179], v[230:231]
	v_cvt_pk_bf16_f32 v176, v176, v177
	v_cvt_pk_bf16_f32 v177, v178, v179
	global_store_dwordx2 v146, v[176:177], s[66:67] offset:512 sc0 sc1
	v_pk_mul_f32 v[180:181], v[180:181], v[204:205] op_sel_hi:[1,0]
	v_pk_mul_f32 v[182:183], v[182:183], v[204:205] op_sel_hi:[1,0]
	v_pk_mul_f32 v[180:181], v[196:197], v[180:181]
	v_pk_mul_f32 v[182:183], v[198:199], v[182:183]
	v_pk_fma_f32 v[180:181], v[42:43], v[180:181], v[232:233]
	v_pk_fma_f32 v[182:183], v[44:45], v[182:183], v[234:235]
	v_cvt_pk_bf16_f32 v180, v180, v181
	v_cvt_pk_bf16_f32 v181, v182, v183
	global_store_dwordx2 v146, v[180:181], s[66:67] offset:1024 sc0 sc1
	v_pk_mul_f32 v[184:185], v[184:185], v[204:205] op_sel_hi:[1,0]
	v_pk_mul_f32 v[186:187], v[186:187], v[204:205] op_sel_hi:[1,0]
	v_pk_mul_f32 v[184:185], v[200:201], v[184:185]
	v_pk_mul_f32 v[186:187], v[202:203], v[186:187]
	v_pk_fma_f32 v[184:185], v[46:47], v[184:185], v[236:237]
	v_pk_fma_f32 v[186:187], v[48:49], v[186:187], v[238:239]
	v_cvt_pk_bf16_f32 v184, v184, v185
	v_cvt_pk_bf16_f32 v185, v186, v187
	global_store_dwordx2 v146, v[184:185], s[66:67] offset:1536 sc0 sc1
	v_add_u32_e32 v146, 0x800, v146
	global_load_dwordx4 v[172:175], v144, s[46:47] nt
	global_load_dwordx4 v[176:179], v144, s[46:47] offset:1024 nt
	global_load_dwordx4 v[180:183], v144, s[46:47] offset:2048 nt
	global_load_dwordx4 v[184:187], v144, s[46:47] offset:3072 nt
	v_add_u32_e32 v144, 0x1000, v144
	s_waitcnt vmcnt(40)
; __device__ __forceinline__ unsigned pk2(float lo, float hi) { const g_f32x2 f = {lo, hi}; return __builtin_bit_cast(unsigned, __builtin_convertvector(f, g_bf16x2)); }
; __device__ __forceinline__ void p_norm(const float* hlat, const float* hctx, const float* g, const float* modl, int sh_off, int sc_off, bf16_t* A, int M,
;                                        const float* part, const float* cgate, float* hcout) {
;     ...
;         for (int i = 0; i < 4; ++i) {
;             if (part != nullptr && row >= NLAT) {
;                 const size_t po = (size_t)(row - NLAT) * 1024 + i * 256 + lane * 4;
;                 const float4 p0 = *(const float4*)(part + po), p1 = *(const float4*)(part + (size_t)4096 * 1024 + po), cg = *(const float4*)(cgate + i * 256 + lane * 4);
;                 v[i].x += cg.x * (p0.x + p1.x); v[i].y += cg.y * (p0.y + p1.y); v[i].z += cg.z * (p0.z + p1.z); v[i].w += cg.w * (p0.w + p1.w);
;                 *(float4*)(hcout + po) = v[i];
;             }
;             ss += v[i].x * v[i].x + v[i].y * v[i].y + v[i].z * v[i].z + v[i].w * v[i].w; }
;         ss = wave_sum(ss);
;         const float rstd = rsqrtf(ss * (1.0f / 1024.0f) + EPS);
;         const float* mr = modl + (size_t)r * 6144;
; #pragma unroll
;         for (int i = 0; i < 4; ++i) {
;             const int k = i * 256 + lane * 4;
;             const float4 gg = *(const float4*)(g + k), scv = *(const float4*)(mr + sc_off + k), shv = *(const float4*)(mr + sh_off + k);
;             const float o0 = v[i].x * rstd * gg.x * (1.0f + scv.x) + shv.x, o1 = v[i].y * rstd * gg.y * (1.0f + scv.y) + shv.y;
;             const float o2 = v[i].z * rstd * gg.z * (1.0f + scv.z) + shv.z, o3 = v[i].w * rstd * gg.w * (1.0f + scv.w) + shv.w;
;             uint2 w; w.x = pk2(o0, o1); w.y = pk2(o2, o3);
;             *(uint2*)(A + (size_t)row * 1024 + k) = w;
;         }
	v_pk_mul_f32 v[242:243], v[80:81], v[80:81]
	v_pk_mul_f32 v[244:245], v[84:85], v[84:85]
	v_pk_mul_f32 v[246:247], v[82:83], v[82:83]
	v_pk_mul_f32 v[248:249], v[86:87], v[86:87]
	v_add_f32_e32 v204, v245, v244
	v_add_f32_e32 v205, v243, v242
	v_add_f32_e32 v204, v248, v204
	v_add_f32_e32 v205, v246, v205
	v_add_f32_e32 v204, v249, v204
	v_add_f32_e32 v205, v247, v205
	v_pk_mul_f32 v[242:243], v[88:89], v[88:89]
	v_pk_mul_f32 v[244:245], v[92:93], v[92:93]
	v_pk_mul_f32 v[246:247], v[90:91], v[90:91]
	v_pk_mul_f32 v[248:249], v[94:95], v[94:95]
	v_add_f32_e32 v206, v243, v242
	v_add_f32_e32 v207, v245, v244
	v_add_f32_e32 v206, v246, v206
	v_add_f32_e32 v207, v248, v207
	v_add_f32_e32 v206, v247, v206
	v_add_f32_e32 v207, v249, v207
	v_add_f32_e32 v204, v205, v204
	v_add_f32_e32 v204, v204, v206
	v_add_f32_e32 v204, v204, v207
	ds_swizzle_b32 v205, v204 offset:swizzle(SWAP,1)
	s_waitcnt lgkmcnt(0)
	v_add_f32_e32 v204, v204, v205
	ds_swizzle_b32 v205, v204 offset:swizzle(SWAP,2)
	s_waitcnt lgkmcnt(0)
	v_add_f32_e32 v204, v204, v205
	ds_swizzle_b32 v205, v204 offset:swizzle(SWAP,4)
	s_waitcnt lgkmcnt(0)
	v_add_f32_e32 v204, v204, v205
	ds_swizzle_b32 v205, v204 offset:swizzle(SWAP,8)
	s_waitcnt lgkmcnt(0)
	v_add_f32_e32 v204, v204, v205
	ds_swizzle_b32 v205, v204 offset:swizzle(SWAP,16)
	s_waitcnt lgkmcnt(0)
	v_add_f32_e32 v204, v204, v205
	v_mov_b32_e32 v205, v204
	s_nop 1
	v_permlane32_swap_b32_e32 v204, v205
	v_add_f32_e32 v204, v204, v205
	v_mov_b32_e32 v205, 0x358637bd
	v_fmamk_f32 v204, v204, 0x3a800000, v205
	v_rsq_f32_e32 v204, v204
	s_nop 0
	v_pk_mul_f32 v[80:81], v[80:81], v[204:205] op_sel_hi:[1,0]
	v_pk_mul_f32 v[82:83], v[82:83], v[204:205] op_sel_hi:[1,0]
	v_pk_mul_f32 v[80:81], v[188:189], v[80:81]
	v_pk_mul_f32 v[82:83], v[190:191], v[82:83]
	v_pk_fma_f32 v[80:81], v[34:35], v[80:81], v[224:225]
	v_pk_fma_f32 v[82:83], v[36:37], v[82:83], v[226:227]
	v_cvt_pk_bf16_f32 v80, v80, v81
	v_cvt_pk_bf16_f32 v81, v82, v83
	global_store_dwordx2 v146, v[80:81], s[66:67] sc0 sc1
	v_pk_mul_f32 v[84:85], v[84:85], v[204:205] op_sel_hi:[1,0]
	v_pk_mul_f32 v[86:87], v[86:87], v[204:205] op_sel_hi:[1,0]
	v_pk_mul_f32 v[84:85], v[192:193], v[84:85]
	v_pk_mul_f32 v[86:87], v[194:195], v[86:87]
	v_pk_fma_f32 v[84:85], v[38:39], v[84:85], v[228:229]
	v_pk_fma_f32 v[86:87], v[40:41], v[86:87], v[230:231]
	v_cvt_pk_bf16_f32 v84, v84, v85
	v_cvt_pk_bf16_f32 v85, v86, v87
	global_store_dwordx2 v146, v[84:85], s[66:67] offset:512 sc0 sc1
	v_pk_mul_f32 v[88:89], v[88:89], v[204:205] op_sel_hi:[1,0]
	v_pk_mul_f32 v[90:91], v[90:91], v[204:205] op_sel_hi:[1,0]
	v_pk_mul_f32 v[88:89], v[196:197], v[88:89]
	v_pk_mul_f32 v[90:91], v[198:199], v[90:91]
	v_pk_fma_f32 v[88:89], v[42:43], v[88:89], v[232:233]
	v_pk_fma_f32 v[90:91], v[44:45], v[90:91], v[234:235]
	v_cvt_pk_bf16_f32 v88, v88, v89
	v_cvt_pk_bf16_f32 v89, v90, v91
	global_store_dwordx2 v146, v[88:89], s[66:67] offset:1024 sc0 sc1
	v_pk_mul_f32 v[92:93], v[92:93], v[204:205] op_sel_hi:[1,0]
	v_pk_mul_f32 v[94:95], v[94:95], v[204:205] op_sel_hi:[1,0]
	v_pk_mul_f32 v[92:93], v[200:201], v[92:93]
	v_pk_mul_f32 v[94:95], v[202:203], v[94:95]
	v_pk_fma_f32 v[92:93], v[46:47], v[92:93], v[236:237]
	v_pk_fma_f32 v[94:95], v[48:49], v[94:95], v[238:239]
	v_cvt_pk_bf16_f32 v92, v92, v93
	v_cvt_pk_bf16_f32 v93, v94, v95
	global_store_dwordx2 v146, v[92:93], s[66:67] offset:1536 sc0 sc1
	v_add_u32_e32 v146, 0x800, v146
	global_load_dwordx4 v[80:83], v144, s[46:47] nt
	global_load_dwordx4 v[84:87], v144, s[46:47] offset:1024 nt
	global_load_dwordx4 v[88:91], v144, s[46:47] offset:2048 nt
	global_load_dwordx4 v[92:95], v144, s[46:47] offset:3072 nt
	v_add_u32_e32 v144, 0x1000, v144
	s_waitcnt vmcnt(40)
	v_pk_mul_f32 v[242:243], v[96:97], v[96:97]
	v_pk_mul_f32 v[244:245], v[100:101], v[100:101]
	v_pk_mul_f32 v[246:247], v[98:99], v[98:99]
	v_pk_mul_f32 v[248:249], v[102:103], v[102:103]
	v_add_f32_e32 v204, v245, v244
	v_add_f32_e32 v205, v243, v242
	v_add_f32_e32 v204, v248, v204
	v_add_f32_e32 v205, v246, v205
	v_add_f32_e32 v204, v249, v204
	v_add_f32_e32 v205, v247, v205
	v_pk_mul_f32 v[242:243], v[104:105], v[104:105]
	v_pk_mul_f32 v[244:245], v[108:109], v[108:109]
	v_pk_mul_f32 v[246:247], v[106:107], v[106:107]
	v_pk_mul_f32 v[248:249], v[110:111], v[110:111]
	v_add_f32_e32 v206, v243, v242
	v_add_f32_e32 v207, v245, v244
	v_add_f32_e32 v206, v246, v206
	v_add_f32_e32 v207, v248, v207
	v_add_f32_e32 v206, v247, v206
	v_add_f32_e32 v207, v249, v207
	v_add_f32_e32 v204, v205, v204
	v_add_f32_e32 v204, v204, v206
	v_add_f32_e32 v204, v204, v207
	ds_swizzle_b32 v205, v204 offset:swizzle(SWAP,1)
	s_waitcnt lgkmcnt(0)
	v_add_f32_e32 v204, v204, v205
	ds_swizzle_b32 v205, v204 offset:swizzle(SWAP,2)
	s_waitcnt lgkmcnt(0)
	v_add_f32_e32 v204, v204, v205
	ds_swizzle_b32 v205, v204 offset:swizzle(SWAP,4)
	s_waitcnt lgkmcnt(0)
	v_add_f32_e32 v204, v204, v205
	ds_swizzle_b32 v205, v204 offset:swizzle(SWAP,8)
	s_waitcnt lgkmcnt(0)
	v_add_f32_e32 v204, v204, v205
	ds_swizzle_b32 v205, v204 offset:swizzle(SWAP,16)
	s_waitcnt lgkmcnt(0)
; __device__ __forceinline__ unsigned pk2(float lo, float hi) { const g_f32x2 f = {lo, hi}; return __builtin_bit_cast(unsigned, __builtin_convertvector(f, g_bf16x2)); }
; __device__ __forceinline__ void p_norm(const float* hlat, const float* hctx, const float* g, const float* modl, int sh_off, int sc_off, bf16_t* A, int M,
;                                        const float* part, const float* cgate, float* hcout) {
;     ...
;         for (int i = 0; i < 4; ++i) {
;             if (part != nullptr && row >= NLAT) {
;                 const size_t po = (size_t)(row - NLAT) * 1024 + i * 256 + lane * 4;
;                 const float4 p0 = *(const float4*)(part + po), p1 = *(const float4*)(part + (size_t)4096 * 1024 + po), cg = *(const float4*)(cgate + i * 256 + lane * 4);
;                 v[i].x += cg.x * (p0.x + p1.x); v[i].y += cg.y * (p0.y + p1.y); v[i].z += cg.z * (p0.z + p1.z); v[i].w += cg.w * (p0.w + p1.w);
;                 *(float4*)(hcout + po) = v[i];
;             }
;             ss += v[i].x * v[i].x + v[i].y * v[i].y + v[i].z * v[i].z + v[i].w * v[i].w; }
;         ss = wave_sum(ss);
;         const float rstd = rsqrtf(ss * (1.0f / 1024.0f) + EPS);
;         const float* mr = modl + (size_t)r * 6144;
; #pragma unroll
;         for (int i = 0; i < 4; ++i) {
;             const int k = i * 256 + lane * 4;
;             const float4 gg = *(const float4*)(g + k), scv = *(const float4*)(mr + sc_off + k), shv = *(const float4*)(mr + sh_off + k);
;             const float o0 = v[i].x * rstd * gg.x * (1.0f + scv.x) + shv.x, o1 = v[i].y * rstd * gg.y * (1.0f + scv.y) + shv.y;
;             const float o2 = v[i].z * rstd * gg.z * (1.0f + scv.z) + shv.z, o3 = v[i].w * rstd * gg.w * (1.0f + scv.w) + shv.w;
;             uint2 w; w.x = pk2(o0, o1); w.y = pk2(o2, o3);
;             *(uint2*)(A + (size_t)row * 1024 + k) = w;
;         }
	v_add_f32_e32 v204, v204, v205
	v_mov_b32_e32 v205, v204
	s_nop 1
	v_permlane32_swap_b32_e32 v204, v205
	v_add_f32_e32 v204, v204, v205
	v_mov_b32_e32 v205, 0x358637bd
	v_fmamk_f32 v204, v204, 0x3a800000, v205
	v_rsq_f32_e32 v204, v204
	s_nop 0
	v_pk_mul_f32 v[96:97], v[96:97], v[204:205] op_sel_hi:[1,0]
	v_pk_mul_f32 v[98:99], v[98:99], v[204:205] op_sel_hi:[1,0]
	v_pk_mul_f32 v[96:97], v[188:189], v[96:97]
	v_pk_mul_f32 v[98:99], v[190:191], v[98:99]
	v_pk_fma_f32 v[96:97], v[34:35], v[96:97], v[224:225]
	v_pk_fma_f32 v[98:99], v[36:37], v[98:99], v[226:227]
	v_cvt_pk_bf16_f32 v96, v96, v97
	v_cvt_pk_bf16_f32 v97, v98, v99
	global_store_dwordx2 v146, v[96:97], s[66:67] sc0 sc1
	v_pk_mul_f32 v[100:101], v[100:101], v[204:205] op_sel_hi:[1,0]
	v_pk_mul_f32 v[102:103], v[102:103], v[204:205] op_sel_hi:[1,0]
	v_pk_mul_f32 v[100:101], v[192:193], v[100:101]
	v_pk_mul_f32 v[102:103], v[194:195], v[102:103]
	v_pk_fma_f32 v[100:101], v[38:39], v[100:101], v[228:229]
	v_pk_fma_f32 v[102:103], v[40:41], v[102:103], v[230:231]
	v_cvt_pk_bf16_f32 v100, v100, v101
	v_cvt_pk_bf16_f32 v101, v102, v103
	global_store_dwordx2 v146, v[100:101], s[66:67] offset:512 sc0 sc1
	v_pk_mul_f32 v[104:105], v[104:105], v[204:205] op_sel_hi:[1,0]
	v_pk_mul_f32 v[106:107], v[106:107], v[204:205] op_sel_hi:[1,0]
	v_pk_mul_f32 v[104:105], v[196:197], v[104:105]
	v_pk_mul_f32 v[106:107], v[198:199], v[106:107]
	v_pk_fma_f32 v[104:105], v[42:43], v[104:105], v[232:233]
	v_pk_fma_f32 v[106:107], v[44:45], v[106:107], v[234:235]
	v_cvt_pk_bf16_f32 v104, v104, v105
	v_cvt_pk_bf16_f32 v105, v106, v107
	global_store_dwordx2 v146, v[104:105], s[66:67] offset:1024 sc0 sc1
	v_pk_mul_f32 v[108:109], v[108:109], v[204:205] op_sel_hi:[1,0]
	v_pk_mul_f32 v[110:111], v[110:111], v[204:205] op_sel_hi:[1,0]
	v_pk_mul_f32 v[108:109], v[200:201], v[108:109]
	v_pk_mul_f32 v[110:111], v[202:203], v[110:111]
	v_pk_fma_f32 v[108:109], v[46:47], v[108:109], v[236:237]
	v_pk_fma_f32 v[110:111], v[48:49], v[110:111], v[238:239]
	v_cvt_pk_bf16_f32 v108, v108, v109
	v_cvt_pk_bf16_f32 v109, v110, v111
	global_store_dwordx2 v146, v[108:109], s[66:67] offset:1536 sc0 sc1
	v_add_u32_e32 v146, 0x800, v146
	global_load_dwordx4 v[96:99], v144, s[46:47] nt
	global_load_dwordx4 v[100:103], v144, s[46:47] offset:1024 nt
	global_load_dwordx4 v[104:107], v144, s[46:47] offset:2048 nt
	global_load_dwordx4 v[108:111], v144, s[46:47] offset:3072 nt
	v_add_u32_e32 v144, 0x1000, v144
	s_waitcnt vmcnt(40)
	v_pk_mul_f32 v[242:243], v[112:113], v[112:113]
	v_pk_mul_f32 v[244:245], v[116:117], v[116:117]
	v_pk_mul_f32 v[246:247], v[114:115], v[114:115]
	v_pk_mul_f32 v[248:249], v[118:119], v[118:119]
	v_add_f32_e32 v204, v245, v244
	v_add_f32_e32 v205, v243, v242
	v_add_f32_e32 v204, v248, v204
	v_add_f32_e32 v205, v246, v205
	v_add_f32_e32 v204, v249, v204
	v_add_f32_e32 v205, v247, v205
	v_pk_mul_f32 v[242:243], v[120:121], v[120:121]
	v_pk_mul_f32 v[244:245], v[124:125], v[124:125]
	v_pk_mul_f32 v[246:247], v[122:123], v[122:123]
	v_pk_mul_f32 v[248:249], v[126:127], v[126:127]
	v_add_f32_e32 v206, v243, v242
	v_add_f32_e32 v207, v245, v244
	v_add_f32_e32 v206, v246, v206
	v_add_f32_e32 v207, v248, v207
	v_add_f32_e32 v206, v247, v206
	v_add_f32_e32 v207, v249, v207
	v_add_f32_e32 v204, v205, v204
	v_add_f32_e32 v204, v204, v206
	v_add_f32_e32 v204, v204, v207
	ds_swizzle_b32 v205, v204 offset:swizzle(SWAP,1)
	s_waitcnt lgkmcnt(0)
	v_add_f32_e32 v204, v204, v205
	ds_swizzle_b32 v205, v204 offset:swizzle(SWAP,2)
	s_waitcnt lgkmcnt(0)
	v_add_f32_e32 v204, v204, v205
	ds_swizzle_b32 v205, v204 offset:swizzle(SWAP,4)
	s_waitcnt lgkmcnt(0)
	v_add_f32_e32 v204, v204, v205
	ds_swizzle_b32 v205, v204 offset:swizzle(SWAP,8)
	s_waitcnt lgkmcnt(0)
	v_add_f32_e32 v204, v204, v205
	ds_swizzle_b32 v205, v204 offset:swizzle(SWAP,16)
	s_waitcnt lgkmcnt(0)
	v_add_f32_e32 v204, v204, v205
	v_mov_b32_e32 v205, v204
	s_nop 1
	v_permlane32_swap_b32_e32 v204, v205
	v_add_f32_e32 v204, v204, v205
	v_mov_b32_e32 v205, 0x358637bd
	v_fmamk_f32 v204, v204, 0x3a800000, v205
	v_rsq_f32_e32 v204, v204
	s_nop 0
	v_pk_mul_f32 v[112:113], v[112:113], v[204:205] op_sel_hi:[1,0]
	v_pk_mul_f32 v[114:115], v[114:115], v[204:205] op_sel_hi:[1,0]
	v_pk_mul_f32 v[112:113], v[188:189], v[112:113]
	v_pk_mul_f32 v[114:115], v[190:191], v[114:115]
	v_pk_fma_f32 v[112:113], v[34:35], v[112:113], v[224:225]
	v_pk_fma_f32 v[114:115], v[36:37], v[114:115], v[226:227]
	v_cvt_pk_bf16_f32 v112, v112, v113
	v_cvt_pk_bf16_f32 v113, v114, v115
	global_store_dwordx2 v146, v[112:113], s[66:67] sc0 sc1
	v_pk_mul_f32 v[116:117], v[116:117], v[204:205] op_sel_hi:[1,0]
	v_pk_mul_f32 v[118:119], v[118:119], v[204:205] op_sel_hi:[1,0]
	v_pk_mul_f32 v[116:117], v[192:193], v[116:117]
	v_pk_mul_f32 v[118:119], v[194:195], v[118:119]
	v_pk_fma_f32 v[116:117], v[38:39], v[116:117], v[228:229]
	v_pk_fma_f32 v[118:119], v[40:41], v[118:119], v[230:231]
	v_cvt_pk_bf16_f32 v116, v116, v117
	v_cvt_pk_bf16_f32 v117, v118, v119
	global_store_dwordx2 v146, v[116:117], s[66:67] offset:512 sc0 sc1
	v_pk_mul_f32 v[120:121], v[120:121], v[204:205] op_sel_hi:[1,0]
	v_pk_mul_f32 v[122:123], v[122:123], v[204:205] op_sel_hi:[1,0]
	v_pk_mul_f32 v[120:121], v[196:197], v[120:121]
	v_pk_mul_f32 v[122:123], v[198:199], v[122:123]
	v_pk_fma_f32 v[120:121], v[42:43], v[120:121], v[232:233]
	v_pk_fma_f32 v[122:123], v[44:45], v[122:123], v[234:235]
	v_cvt_pk_bf16_f32 v120, v120, v121
	v_cvt_pk_bf16_f32 v121, v122, v123
	global_store_dwordx2 v146, v[120:121], s[66:67] offset:1024 sc0 sc1
	v_pk_mul_f32 v[124:125], v[124:125], v[204:205] op_sel_hi:[1,0]
	v_pk_mul_f32 v[126:127], v[126:127], v[204:205] op_sel_hi:[1,0]
	v_pk_mul_f32 v[124:125], v[200:201], v[124:125]
	v_pk_mul_f32 v[126:127], v[202:203], v[126:127]
	v_pk_fma_f32 v[124:125], v[46:47], v[124:125], v[236:237]
	v_pk_fma_f32 v[126:127], v[48:49], v[126:127], v[238:239]
	v_cvt_pk_bf16_f32 v124, v124, v125
	v_cvt_pk_bf16_f32 v125, v126, v127
	global_store_dwordx2 v146, v[124:125], s[66:67] offset:1536 sc0 sc1
	v_add_u32_e32 v146, 0x800, v146
	global_load_dwordx4 v[112:115], v144, s[46:47] nt
	global_load_dwordx4 v[116:119], v144, s[46:47] offset:1024 nt
	global_load_dwordx4 v[120:123], v144, s[46:47] offset:2048 nt
	global_load_dwordx4 v[124:127], v144, s[46:47] offset:3072 nt
	v_add_u32_e32 v144, 0x1000, v144
	s_waitcnt vmcnt(40)
; __device__ __forceinline__ unsigned pk2(float lo, float hi) { const g_f32x2 f = {lo, hi}; return __builtin_bit_cast(unsigned, __builtin_convertvector(f, g_bf16x2)); }
; __device__ __forceinline__ void p_norm(const float* hlat, const float* hctx, const float* g, const float* modl, int sh_off, int sc_off, bf16_t* A, int M,
;                                        const float* part, const float* cgate, float* hcout) {
;     ...
;         for (int i = 0; i < 4; ++i) {
;             if (part != nullptr && row >= NLAT) {
;                 const size_t po = (size_t)(row - NLAT) * 1024 + i * 256 + lane * 4;
;                 const float4 p0 = *(const float4*)(part + po), p1 = *(const float4*)(part + (size_t)4096 * 1024 + po), cg = *(const float4*)(cgate + i * 256 + lane * 4);
;                 v[i].x += cg.x * (p0.x + p1.x); v[i].y += cg.y * (p0.y + p1.y); v[i].z += cg.z * (p0.z + p1.z); v[i].w += cg.w * (p0.w + p1.w);
;                 *(float4*)(hcout + po) = v[i];
;             }
;             ss += v[i].x * v[i].x + v[i].y * v[i].y + v[i].z * v[i].z + v[i].w * v[i].w; }
;         ss = wave_sum(ss);
;         const float rstd = rsqrtf(ss * (1.0f / 1024.0f) + EPS);
;         const float* mr = modl + (size_t)r * 6144;
; #pragma unroll
;         for (int i = 0; i < 4; ++i) {
;             const int k = i * 256 + lane * 4;
;             const float4 gg = *(const float4*)(g + k), scv = *(const float4*)(mr + sc_off + k), shv = *(const float4*)(mr + sh_off + k);
;             const float o0 = v[i].x * rstd * gg.x * (1.0f + scv.x) + shv.x, o1 = v[i].y * rstd * gg.y * (1.0f + scv.y) + shv.y;
;             const float o2 = v[i].z * rstd * gg.z * (1.0f + scv.z) + shv.z, o3 = v[i].w * rstd * gg.w * (1.0f + scv.w) + shv.w;
;             uint2 w; w.x = pk2(o0, o1); w.y = pk2(o2, o3);
;             *(uint2*)(A + (size_t)row * 1024 + k) = w;
;         }
	v_pk_mul_f32 v[242:243], v[128:129], v[128:129]
	v_pk_mul_f32 v[244:245], v[132:133], v[132:133]
	v_pk_mul_f32 v[246:247], v[130:131], v[130:131]
	v_pk_mul_f32 v[248:249], v[134:135], v[134:135]
	v_add_f32_e32 v204, v245, v244
	v_add_f32_e32 v205, v243, v242
	v_add_f32_e32 v204, v248, v204
	v_add_f32_e32 v205, v246, v205
	v_add_f32_e32 v204, v249, v204
	v_add_f32_e32 v205, v247, v205
	v_pk_mul_f32 v[242:243], v[136:137], v[136:137]
	v_pk_mul_f32 v[244:245], v[140:141], v[140:141]
	v_pk_mul_f32 v[246:247], v[138:139], v[138:139]
	v_pk_mul_f32 v[248:249], v[142:143], v[142:143]
	v_add_f32_e32 v206, v243, v242
	v_add_f32_e32 v207, v245, v244
	v_add_f32_e32 v206, v246, v206
	v_add_f32_e32 v207, v248, v207
	v_add_f32_e32 v206, v247, v206
	v_add_f32_e32 v207, v249, v207
	v_add_f32_e32 v204, v205, v204
	v_add_f32_e32 v204, v204, v206
	v_add_f32_e32 v204, v204, v207
	ds_swizzle_b32 v205, v204 offset:swizzle(SWAP,1)
	s_waitcnt lgkmcnt(0)
	v_add_f32_e32 v204, v204, v205
	ds_swizzle_b32 v205, v204 offset:swizzle(SWAP,2)
	s_waitcnt lgkmcnt(0)
	v_add_f32_e32 v204, v204, v205
	ds_swizzle_b32 v205, v204 offset:swizzle(SWAP,4)
	s_waitcnt lgkmcnt(0)
	v_add_f32_e32 v204, v204, v205
	ds_swizzle_b32 v205, v204 offset:swizzle(SWAP,8)
	s_waitcnt lgkmcnt(0)
	v_add_f32_e32 v204, v204, v205
	ds_swizzle_b32 v205, v204 offset:swizzle(SWAP,16)
	s_waitcnt lgkmcnt(0)
	v_add_f32_e32 v204, v204, v205
	v_mov_b32_e32 v205, v204
	s_nop 1
	v_permlane32_swap_b32_e32 v204, v205
	v_add_f32_e32 v204, v204, v205
	v_mov_b32_e32 v205, 0x358637bd
	v_fmamk_f32 v204, v204, 0x3a800000, v205
	v_rsq_f32_e32 v204, v204
	s_nop 0
	v_pk_mul_f32 v[128:129], v[128:129], v[204:205] op_sel_hi:[1,0]
	v_pk_mul_f32 v[130:131], v[130:131], v[204:205] op_sel_hi:[1,0]
	v_pk_mul_f32 v[128:129], v[188:189], v[128:129]
	v_pk_mul_f32 v[130:131], v[190:191], v[130:131]
	v_pk_fma_f32 v[128:129], v[34:35], v[128:129], v[224:225]
	v_pk_fma_f32 v[130:131], v[36:37], v[130:131], v[226:227]
	v_cvt_pk_bf16_f32 v128, v128, v129
	v_cvt_pk_bf16_f32 v129, v130, v131
	global_store_dwordx2 v146, v[128:129], s[66:67] sc0 sc1
	v_pk_mul_f32 v[132:133], v[132:133], v[204:205] op_sel_hi:[1,0]
	v_pk_mul_f32 v[134:135], v[134:135], v[204:205] op_sel_hi:[1,0]
	v_pk_mul_f32 v[132:133], v[192:193], v[132:133]
	v_pk_mul_f32 v[134:135], v[194:195], v[134:135]
	v_pk_fma_f32 v[132:133], v[38:39], v[132:133], v[228:229]
	v_pk_fma_f32 v[134:135], v[40:41], v[134:135], v[230:231]
	v_cvt_pk_bf16_f32 v132, v132, v133
	v_cvt_pk_bf16_f32 v133, v134, v135
	global_store_dwordx2 v146, v[132:133], s[66:67] offset:512 sc0 sc1
	v_pk_mul_f32 v[136:137], v[136:137], v[204:205] op_sel_hi:[1,0]
	v_pk_mul_f32 v[138:139], v[138:139], v[204:205] op_sel_hi:[1,0]
	v_pk_mul_f32 v[136:137], v[196:197], v[136:137]
	v_pk_mul_f32 v[138:139], v[198:199], v[138:139]
	v_pk_fma_f32 v[136:137], v[42:43], v[136:137], v[232:233]
	v_pk_fma_f32 v[138:139], v[44:45], v[138:139], v[234:235]
	v_cvt_pk_bf16_f32 v136, v136, v137
	v_cvt_pk_bf16_f32 v137, v138, v139
	global_store_dwordx2 v146, v[136:137], s[66:67] offset:1024 sc0 sc1
	v_pk_mul_f32 v[140:141], v[140:141], v[204:205] op_sel_hi:[1,0]
	v_pk_mul_f32 v[142:143], v[142:143], v[204:205] op_sel_hi:[1,0]
	v_pk_mul_f32 v[140:141], v[200:201], v[140:141]
	v_pk_mul_f32 v[142:143], v[202:203], v[142:143]
	v_pk_fma_f32 v[140:141], v[46:47], v[140:141], v[236:237]
	v_pk_fma_f32 v[142:143], v[48:49], v[142:143], v[238:239]
	v_cvt_pk_bf16_f32 v140, v140, v141
	v_cvt_pk_bf16_f32 v141, v142, v143
	global_store_dwordx2 v146, v[140:141], s[66:67] offset:1536 sc0 sc1
	v_add_u32_e32 v146, 0x800, v146
	global_load_dwordx4 v[128:131], v144, s[46:47] nt
	global_load_dwordx4 v[132:135], v144, s[46:47] offset:1024 nt
	global_load_dwordx4 v[136:139], v144, s[46:47] offset:2048 nt
	global_load_dwordx4 v[140:143], v144, s[46:47] offset:3072 nt
	v_add_u32_e32 v144, 0x1000, v144
	s_waitcnt vmcnt(40)
	v_pk_mul_f32 v[242:243], v[156:157], v[156:157]
	v_pk_mul_f32 v[244:245], v[160:161], v[160:161]
	v_pk_mul_f32 v[246:247], v[158:159], v[158:159]
	v_pk_mul_f32 v[248:249], v[162:163], v[162:163]
	v_add_f32_e32 v204, v245, v244
	v_add_f32_e32 v205, v243, v242
	v_add_f32_e32 v204, v248, v204
	v_add_f32_e32 v205, v246, v205
	v_add_f32_e32 v204, v249, v204
	v_add_f32_e32 v205, v247, v205
	v_pk_mul_f32 v[242:243], v[164:165], v[164:165]
	v_pk_mul_f32 v[244:245], v[168:169], v[168:169]
	v_pk_mul_f32 v[246:247], v[166:167], v[166:167]
	v_pk_mul_f32 v[248:249], v[170:171], v[170:171]
	v_add_f32_e32 v206, v243, v242
	v_add_f32_e32 v207, v245, v244
	v_add_f32_e32 v206, v246, v206
	v_add_f32_e32 v207, v248, v207
	v_add_f32_e32 v206, v247, v206
	v_add_f32_e32 v207, v249, v207
	v_add_f32_e32 v204, v205, v204
	v_add_f32_e32 v204, v204, v206
	v_add_f32_e32 v204, v204, v207
	ds_swizzle_b32 v205, v204 offset:swizzle(SWAP,1)
	s_waitcnt lgkmcnt(0)
	v_add_f32_e32 v204, v204, v205
	ds_swizzle_b32 v205, v204 offset:swizzle(SWAP,2)
	s_waitcnt lgkmcnt(0)
	v_add_f32_e32 v204, v204, v205
	ds_swizzle_b32 v205, v204 offset:swizzle(SWAP,4)
	s_waitcnt lgkmcnt(0)
	v_add_f32_e32 v204, v204, v205
	ds_swizzle_b32 v205, v204 offset:swizzle(SWAP,8)
	s_waitcnt lgkmcnt(0)
	v_add_f32_e32 v204, v204, v205
	ds_swizzle_b32 v205, v204 offset:swizzle(SWAP,16)
	s_waitcnt lgkmcnt(0)
; __device__ __forceinline__ unsigned pk2(float lo, float hi) { const g_f32x2 f = {lo, hi}; return __builtin_bit_cast(unsigned, __builtin_convertvector(f, g_bf16x2)); }
; __device__ __forceinline__ void p_norm(const float* hlat, const float* hctx, const float* g, const float* modl, int sh_off, int sc_off, bf16_t* A, int M,
;                                        const float* part, const float* cgate, float* hcout) {
;     ...
;         for (int i = 0; i < 4; ++i) {
;             if (part != nullptr && row >= NLAT) {
;                 const size_t po = (size_t)(row - NLAT) * 1024 + i * 256 + lane * 4;
;                 const float4 p0 = *(const float4*)(part + po), p1 = *(const float4*)(part + (size_t)4096 * 1024 + po), cg = *(const float4*)(cgate + i * 256 + lane * 4);
;                 v[i].x += cg.x * (p0.x + p1.x); v[i].y += cg.y * (p0.y + p1.y); v[i].z += cg.z * (p0.z + p1.z); v[i].w += cg.w * (p0.w + p1.w);
;                 *(float4*)(hcout + po) = v[i];
;             }
;             ss += v[i].x * v[i].x + v[i].y * v[i].y + v[i].z * v[i].z + v[i].w * v[i].w; }
;         ss = wave_sum(ss);
;         const float rstd = rsqrtf(ss * (1.0f / 1024.0f) + EPS);
;         const float* mr = modl + (size_t)r * 6144;
; #pragma unroll
;         for (int i = 0; i < 4; ++i) {
;             const int k = i * 256 + lane * 4;
;             const float4 gg = *(const float4*)(g + k), scv = *(const float4*)(mr + sc_off + k), shv = *(const float4*)(mr + sh_off + k);
;             const float o0 = v[i].x * rstd * gg.x * (1.0f + scv.x) + shv.x, o1 = v[i].y * rstd * gg.y * (1.0f + scv.y) + shv.y;
;             const float o2 = v[i].z * rstd * gg.z * (1.0f + scv.z) + shv.z, o3 = v[i].w * rstd * gg.w * (1.0f + scv.w) + shv.w;
;             uint2 w; w.x = pk2(o0, o1); w.y = pk2(o2, o3);
;             *(uint2*)(A + (size_t)row * 1024 + k) = w;
;         }
	v_add_f32_e32 v204, v204, v205
	v_mov_b32_e32 v205, v204
	s_nop 1
	v_permlane32_swap_b32_e32 v204, v205
	v_add_f32_e32 v204, v204, v205
	v_mov_b32_e32 v205, 0x358637bd
	v_fmamk_f32 v204, v204, 0x3a800000, v205
	v_rsq_f32_e32 v204, v204
	s_nop 0
	v_pk_mul_f32 v[156:157], v[156:157], v[204:205] op_sel_hi:[1,0]
	v_pk_mul_f32 v[158:159], v[158:159], v[204:205] op_sel_hi:[1,0]
	v_pk_mul_f32 v[156:157], v[188:189], v[156:157]
	v_pk_mul_f32 v[158:159], v[190:191], v[158:159]
	v_pk_fma_f32 v[156:157], v[34:35], v[156:157], v[224:225]
	v_pk_fma_f32 v[158:159], v[36:37], v[158:159], v[226:227]
	v_cvt_pk_bf16_f32 v156, v156, v157
	v_cvt_pk_bf16_f32 v157, v158, v159
	global_store_dwordx2 v146, v[156:157], s[66:67] sc0 sc1
	v_pk_mul_f32 v[160:161], v[160:161], v[204:205] op_sel_hi:[1,0]
	v_pk_mul_f32 v[162:163], v[162:163], v[204:205] op_sel_hi:[1,0]
	v_pk_mul_f32 v[160:161], v[192:193], v[160:161]
	v_pk_mul_f32 v[162:163], v[194:195], v[162:163]
	v_pk_fma_f32 v[160:161], v[38:39], v[160:161], v[228:229]
	v_pk_fma_f32 v[162:163], v[40:41], v[162:163], v[230:231]
	v_cvt_pk_bf16_f32 v160, v160, v161
	v_cvt_pk_bf16_f32 v161, v162, v163
	global_store_dwordx2 v146, v[160:161], s[66:67] offset:512 sc0 sc1
	v_pk_mul_f32 v[164:165], v[164:165], v[204:205] op_sel_hi:[1,0]
	v_pk_mul_f32 v[166:167], v[166:167], v[204:205] op_sel_hi:[1,0]
	v_pk_mul_f32 v[164:165], v[196:197], v[164:165]
	v_pk_mul_f32 v[166:167], v[198:199], v[166:167]
	v_pk_fma_f32 v[164:165], v[42:43], v[164:165], v[232:233]
	v_pk_fma_f32 v[166:167], v[44:45], v[166:167], v[234:235]
	v_cvt_pk_bf16_f32 v164, v164, v165
	v_cvt_pk_bf16_f32 v165, v166, v167
	global_store_dwordx2 v146, v[164:165], s[66:67] offset:1024 sc0 sc1
	v_pk_mul_f32 v[168:169], v[168:169], v[204:205] op_sel_hi:[1,0]
	v_pk_mul_f32 v[170:171], v[170:171], v[204:205] op_sel_hi:[1,0]
	v_pk_mul_f32 v[168:169], v[200:201], v[168:169]
	v_pk_mul_f32 v[170:171], v[202:203], v[170:171]
	v_pk_fma_f32 v[168:169], v[46:47], v[168:169], v[236:237]
	v_pk_fma_f32 v[170:171], v[48:49], v[170:171], v[238:239]
	v_cvt_pk_bf16_f32 v168, v168, v169
	v_cvt_pk_bf16_f32 v169, v170, v171
	global_store_dwordx2 v146, v[168:169], s[66:67] offset:1536 sc0 sc1
	v_add_u32_e32 v146, 0x800, v146
	s_waitcnt vmcnt(36)
	v_pk_mul_f32 v[242:243], v[172:173], v[172:173]
	v_pk_mul_f32 v[244:245], v[176:177], v[176:177]
	v_pk_mul_f32 v[246:247], v[174:175], v[174:175]
	v_pk_mul_f32 v[248:249], v[178:179], v[178:179]
	v_add_f32_e32 v204, v245, v244
	v_add_f32_e32 v205, v243, v242
	v_add_f32_e32 v204, v248, v204
	v_add_f32_e32 v205, v246, v205
	v_add_f32_e32 v204, v249, v204
	v_add_f32_e32 v205, v247, v205
	v_pk_mul_f32 v[242:243], v[180:181], v[180:181]
	v_pk_mul_f32 v[244:245], v[184:185], v[184:185]
	v_pk_mul_f32 v[246:247], v[182:183], v[182:183]
	v_pk_mul_f32 v[248:249], v[186:187], v[186:187]
	v_add_f32_e32 v206, v243, v242
	v_add_f32_e32 v207, v245, v244
	v_add_f32_e32 v206, v246, v206
	v_add_f32_e32 v207, v248, v207
	v_add_f32_e32 v206, v247, v206
	v_add_f32_e32 v207, v249, v207
	v_add_f32_e32 v204, v205, v204
	v_add_f32_e32 v204, v204, v206
	v_add_f32_e32 v204, v204, v207
	ds_swizzle_b32 v205, v204 offset:swizzle(SWAP,1)
	s_waitcnt lgkmcnt(0)
	v_add_f32_e32 v204, v204, v205
	ds_swizzle_b32 v205, v204 offset:swizzle(SWAP,2)
	s_waitcnt lgkmcnt(0)
	v_add_f32_e32 v204, v204, v205
	ds_swizzle_b32 v205, v204 offset:swizzle(SWAP,4)
	s_waitcnt lgkmcnt(0)
	v_add_f32_e32 v204, v204, v205
	ds_swizzle_b32 v205, v204 offset:swizzle(SWAP,8)
	s_waitcnt lgkmcnt(0)
	v_add_f32_e32 v204, v204, v205
	ds_swizzle_b32 v205, v204 offset:swizzle(SWAP,16)
	s_waitcnt lgkmcnt(0)
	v_add_f32_e32 v204, v204, v205
	v_mov_b32_e32 v205, v204
	s_nop 1
	v_permlane32_swap_b32_e32 v204, v205
	v_add_f32_e32 v204, v204, v205
	v_mov_b32_e32 v205, 0x358637bd
	v_fmamk_f32 v204, v204, 0x3a800000, v205
	v_rsq_f32_e32 v204, v204
	s_nop 0
	v_pk_mul_f32 v[172:173], v[172:173], v[204:205] op_sel_hi:[1,0]
	v_pk_mul_f32 v[174:175], v[174:175], v[204:205] op_sel_hi:[1,0]
	v_pk_mul_f32 v[172:173], v[188:189], v[172:173]
	v_pk_mul_f32 v[174:175], v[190:191], v[174:175]
	v_pk_fma_f32 v[172:173], v[34:35], v[172:173], v[224:225]
	v_pk_fma_f32 v[174:175], v[36:37], v[174:175], v[226:227]
	v_cvt_pk_bf16_f32 v172, v172, v173
	v_cvt_pk_bf16_f32 v173, v174, v175
	global_store_dwordx2 v146, v[172:173], s[66:67] sc0 sc1
	v_pk_mul_f32 v[176:177], v[176:177], v[204:205] op_sel_hi:[1,0]
	v_pk_mul_f32 v[178:179], v[178:179], v[204:205] op_sel_hi:[1,0]
	v_pk_mul_f32 v[176:177], v[192:193], v[176:177]
	v_pk_mul_f32 v[178:179], v[194:195], v[178:179]
	v_pk_fma_f32 v[176:177], v[38:39], v[176:177], v[228:229]
	v_pk_fma_f32 v[178:179], v[40:41], v[178:179], v[230:231]
	v_cvt_pk_bf16_f32 v176, v176, v177
	v_cvt_pk_bf16_f32 v177, v178, v179
	global_store_dwordx2 v146, v[176:177], s[66:67] offset:512 sc0 sc1
	v_pk_mul_f32 v[180:181], v[180:181], v[204:205] op_sel_hi:[1,0]
	v_pk_mul_f32 v[182:183], v[182:183], v[204:205] op_sel_hi:[1,0]
	v_pk_mul_f32 v[180:181], v[196:197], v[180:181]
	v_pk_mul_f32 v[182:183], v[198:199], v[182:183]
	v_pk_fma_f32 v[180:181], v[42:43], v[180:181], v[232:233]
	v_pk_fma_f32 v[182:183], v[44:45], v[182:183], v[234:235]
	v_cvt_pk_bf16_f32 v180, v180, v181
	v_cvt_pk_bf16_f32 v181, v182, v183
	global_store_dwordx2 v146, v[180:181], s[66:67] offset:1024 sc0 sc1
	v_pk_mul_f32 v[184:185], v[184:185], v[204:205] op_sel_hi:[1,0]
	v_pk_mul_f32 v[186:187], v[186:187], v[204:205] op_sel_hi:[1,0]
	v_pk_mul_f32 v[184:185], v[200:201], v[184:185]
	v_pk_mul_f32 v[186:187], v[202:203], v[186:187]
	v_pk_fma_f32 v[184:185], v[46:47], v[184:185], v[236:237]
	v_pk_fma_f32 v[186:187], v[48:49], v[186:187], v[238:239]
	v_cvt_pk_bf16_f32 v184, v184, v185
	v_cvt_pk_bf16_f32 v185, v186, v187
	global_store_dwordx2 v146, v[184:185], s[66:67] offset:1536 sc0 sc1
	v_add_u32_e32 v146, 0x800, v146
	s_waitcnt vmcnt(32)
; __device__ __forceinline__ unsigned pk2(float lo, float hi) { const g_f32x2 f = {lo, hi}; return __builtin_bit_cast(unsigned, __builtin_convertvector(f, g_bf16x2)); }
; template <int K> __device__ __forceinline__ float swz(float v) { return __int_as_float(__builtin_amdgcn_ds_swizzle(__float_as_int(v), (K << 10) | 0x1f)); }
; __device__ __forceinline__ float x32_sum(float v) { auto r = __builtin_amdgcn_permlane32_swap(__float_as_uint(v), __float_as_uint(v), false, false); return __uint_as_float(r[0]) + __uint_as_float(r[1]); }
; __device__ __forceinline__ float wave_sum(float v) {
;     v += swz<1>(v); v += swz<2>(v); v += swz<4>(v); v += swz<8>(v); v += swz<16>(v);
;     return x32_sum(v);
; __device__ __forceinline__ void p_norm(const float* hlat, const float* hctx, const float* g, const float* modl, int sh_off, int sc_off, bf16_t* A, int M,
;                                        const float* part, const float* cgate, float* hcout) {
;     ...
;             ss += v[i].x * v[i].x + v[i].y * v[i].y + v[i].z * v[i].z + v[i].w * v[i].w; }
;         ss = wave_sum(ss);
;         const float rstd = rsqrtf(ss * (1.0f / 1024.0f) + EPS);
;         const float* mr = modl + (size_t)r * 6144;
; #pragma unroll
;         for (int i = 0; i < 4; ++i) {
;             const int k = i * 256 + lane * 4;
;             const float4 gg = *(const float4*)(g + k), scv = *(const float4*)(mr + sc_off + k), shv = *(const float4*)(mr + sh_off + k);
;             const float o0 = v[i].x * rstd * gg.x * (1.0f + scv.x) + shv.x, o1 = v[i].y * rstd * gg.y * (1.0f + scv.y) + shv.y;
;             const float o2 = v[i].z * rstd * gg.z * (1.0f + scv.z) + shv.z, o3 = v[i].w * rstd * gg.w * (1.0f + scv.w) + shv.w;
;             uint2 w; w.x = pk2(o0, o1); w.y = pk2(o2, o3);
;             *(uint2*)(A + (size_t)row * 1024 + k) = w;
;         }
	v_pk_mul_f32 v[242:243], v[80:81], v[80:81]
	v_pk_mul_f32 v[244:245], v[84:85], v[84:85]
	v_pk_mul_f32 v[246:247], v[82:83], v[82:83]
	v_pk_mul_f32 v[248:249], v[86:87], v[86:87]
	v_add_f32_e32 v204, v245, v244
	v_add_f32_e32 v205, v243, v242
	v_add_f32_e32 v204, v248, v204
	v_add_f32_e32 v205, v246, v205
	v_add_f32_e32 v204, v249, v204
	v_add_f32_e32 v205, v247, v205
	v_pk_mul_f32 v[242:243], v[88:89], v[88:89]
	v_pk_mul_f32 v[244:245], v[92:93], v[92:93]
	v_pk_mul_f32 v[246:247], v[90:91], v[90:91]
	v_pk_mul_f32 v[248:249], v[94:95], v[94:95]
	v_add_f32_e32 v206, v243, v242
	v_add_f32_e32 v207, v245, v244
	v_add_f32_e32 v206, v246, v206
	v_add_f32_e32 v207, v248, v207
	v_add_f32_e32 v206, v247, v206
	v_add_f32_e32 v207, v249, v207
	v_add_f32_e32 v204, v205, v204
	v_add_f32_e32 v204, v204, v206
	v_add_f32_e32 v204, v204, v207
	ds_swizzle_b32 v205, v204 offset:swizzle(SWAP,1)
	s_waitcnt lgkmcnt(0)
	v_add_f32_e32 v204, v204, v205
	ds_swizzle_b32 v205, v204 offset:swizzle(SWAP,2)
	s_waitcnt lgkmcnt(0)
	v_add_f32_e32 v204, v204, v205
	ds_swizzle_b32 v205, v204 offset:swizzle(SWAP,4)
	s_waitcnt lgkmcnt(0)
	v_add_f32_e32 v204, v204, v205
	ds_swizzle_b32 v205, v204 offset:swizzle(SWAP,8)
	s_waitcnt lgkmcnt(0)
	v_add_f32_e32 v204, v204, v205
	ds_swizzle_b32 v205, v204 offset:swizzle(SWAP,16)
	s_waitcnt lgkmcnt(0)
	v_add_f32_e32 v204, v204, v205
	v_mov_b32_e32 v205, v204
	s_nop 1
	v_permlane32_swap_b32_e32 v204, v205
	v_add_f32_e32 v204, v204, v205
	v_mov_b32_e32 v205, 0x358637bd
	v_fmamk_f32 v204, v204, 0x3a800000, v205
	v_rsq_f32_e32 v204, v204
	s_nop 0
	v_pk_mul_f32 v[80:81], v[80:81], v[204:205] op_sel_hi:[1,0]
	v_pk_mul_f32 v[82:83], v[82:83], v[204:205] op_sel_hi:[1,0]
	v_pk_mul_f32 v[80:81], v[188:189], v[80:81]
	v_pk_mul_f32 v[82:83], v[190:191], v[82:83]
	v_pk_fma_f32 v[80:81], v[34:35], v[80:81], v[224:225]
	v_pk_fma_f32 v[82:83], v[36:37], v[82:83], v[226:227]
	v_cvt_pk_bf16_f32 v80, v80, v81
	v_cvt_pk_bf16_f32 v81, v82, v83
	global_store_dwordx2 v146, v[80:81], s[66:67] sc0 sc1
	v_pk_mul_f32 v[84:85], v[84:85], v[204:205] op_sel_hi:[1,0]
	v_pk_mul_f32 v[86:87], v[86:87], v[204:205] op_sel_hi:[1,0]
	v_pk_mul_f32 v[84:85], v[192:193], v[84:85]
	v_pk_mul_f32 v[86:87], v[194:195], v[86:87]
	v_pk_fma_f32 v[84:85], v[38:39], v[84:85], v[228:229]
	v_pk_fma_f32 v[86:87], v[40:41], v[86:87], v[230:231]
	v_cvt_pk_bf16_f32 v84, v84, v85
	v_cvt_pk_bf16_f32 v85, v86, v87
	global_store_dwordx2 v146, v[84:85], s[66:67] offset:512 sc0 sc1
	v_pk_mul_f32 v[88:89], v[88:89], v[204:205] op_sel_hi:[1,0]
	v_pk_mul_f32 v[90:91], v[90:91], v[204:205] op_sel_hi:[1,0]
	v_pk_mul_f32 v[88:89], v[196:197], v[88:89]
	v_pk_mul_f32 v[90:91], v[198:199], v[90:91]
	v_pk_fma_f32 v[88:89], v[42:43], v[88:89], v[232:233]
	v_pk_fma_f32 v[90:91], v[44:45], v[90:91], v[234:235]
	v_cvt_pk_bf16_f32 v88, v88, v89
	v_cvt_pk_bf16_f32 v89, v90, v91
	global_store_dwordx2 v146, v[88:89], s[66:67] offset:1024 sc0 sc1
	v_pk_mul_f32 v[92:93], v[92:93], v[204:205] op_sel_hi:[1,0]
	v_pk_mul_f32 v[94:95], v[94:95], v[204:205] op_sel_hi:[1,0]
	v_pk_mul_f32 v[92:93], v[200:201], v[92:93]
	v_pk_mul_f32 v[94:95], v[202:203], v[94:95]
	v_pk_fma_f32 v[92:93], v[46:47], v[92:93], v[236:237]
	v_pk_fma_f32 v[94:95], v[48:49], v[94:95], v[238:239]
	v_cvt_pk_bf16_f32 v92, v92, v93
	v_cvt_pk_bf16_f32 v93, v94, v95
	global_store_dwordx2 v146, v[92:93], s[66:67] offset:1536 sc0 sc1
	v_add_u32_e32 v146, 0x800, v146
	s_waitcnt vmcnt(28)
	v_pk_mul_f32 v[242:243], v[96:97], v[96:97]
	v_pk_mul_f32 v[244:245], v[100:101], v[100:101]
	v_pk_mul_f32 v[246:247], v[98:99], v[98:99]
	v_pk_mul_f32 v[248:249], v[102:103], v[102:103]
	v_add_f32_e32 v204, v245, v244
	v_add_f32_e32 v205, v243, v242
	v_add_f32_e32 v204, v248, v204
	v_add_f32_e32 v205, v246, v205
	v_add_f32_e32 v204, v249, v204
	v_add_f32_e32 v205, v247, v205
	v_pk_mul_f32 v[242:243], v[104:105], v[104:105]
	v_pk_mul_f32 v[244:245], v[108:109], v[108:109]
	v_pk_mul_f32 v[246:247], v[106:107], v[106:107]
	v_pk_mul_f32 v[248:249], v[110:111], v[110:111]
	v_add_f32_e32 v206, v243, v242
	v_add_f32_e32 v207, v245, v244
	v_add_f32_e32 v206, v246, v206
	v_add_f32_e32 v207, v248, v207
	v_add_f32_e32 v206, v247, v206
	v_add_f32_e32 v207, v249, v207
	v_add_f32_e32 v204, v205, v204
	v_add_f32_e32 v204, v204, v206
	v_add_f32_e32 v204, v204, v207
	ds_swizzle_b32 v205, v204 offset:swizzle(SWAP,1)
	s_waitcnt lgkmcnt(0)
	v_add_f32_e32 v204, v204, v205
	ds_swizzle_b32 v205, v204 offset:swizzle(SWAP,2)
	s_waitcnt lgkmcnt(0)
	v_add_f32_e32 v204, v204, v205
	ds_swizzle_b32 v205, v204 offset:swizzle(SWAP,4)
	s_waitcnt lgkmcnt(0)
	v_add_f32_e32 v204, v204, v205
	ds_swizzle_b32 v205, v204 offset:swizzle(SWAP,8)
	s_waitcnt lgkmcnt(0)
	v_add_f32_e32 v204, v204, v205
	ds_swizzle_b32 v205, v204 offset:swizzle(SWAP,16)
	s_waitcnt lgkmcnt(0)
; __device__ __forceinline__ unsigned pk2(float lo, float hi) { const g_f32x2 f = {lo, hi}; return __builtin_bit_cast(unsigned, __builtin_convertvector(f, g_bf16x2)); }
; template <int K> __device__ __forceinline__ float swz(float v) { return __int_as_float(__builtin_amdgcn_ds_swizzle(__float_as_int(v), (K << 10) | 0x1f)); }
; __device__ __forceinline__ float x32_sum(float v) { auto r = __builtin_amdgcn_permlane32_swap(__float_as_uint(v), __float_as_uint(v), false, false); return __uint_as_float(r[0]) + __uint_as_float(r[1]); }
; __device__ __forceinline__ float wave_sum(float v) {
;     v += swz<1>(v); v += swz<2>(v); v += swz<4>(v); v += swz<8>(v); v += swz<16>(v);
;     return x32_sum(v);
; __device__ __forceinline__ void p_norm(const float* hlat, const float* hctx, const float* g, const float* modl, int sh_off, int sc_off, bf16_t* A, int M,
;                                        const float* part, const float* cgate, float* hcout) {
;     ...
;             ss += v[i].x * v[i].x + v[i].y * v[i].y + v[i].z * v[i].z + v[i].w * v[i].w; }
;         ss = wave_sum(ss);
;         const float rstd = rsqrtf(ss * (1.0f / 1024.0f) + EPS);
;         const float* mr = modl + (size_t)r * 6144;
; #pragma unroll
;         for (int i = 0; i < 4; ++i) {
;             const int k = i * 256 + lane * 4;
;             const float4 gg = *(const float4*)(g + k), scv = *(const float4*)(mr + sc_off + k), shv = *(const float4*)(mr + sh_off + k);
;             const float o0 = v[i].x * rstd * gg.x * (1.0f + scv.x) + shv.x, o1 = v[i].y * rstd * gg.y * (1.0f + scv.y) + shv.y;
;             const float o2 = v[i].z * rstd * gg.z * (1.0f + scv.z) + shv.z, o3 = v[i].w * rstd * gg.w * (1.0f + scv.w) + shv.w;
;             uint2 w; w.x = pk2(o0, o1); w.y = pk2(o2, o3);
;             *(uint2*)(A + (size_t)row * 1024 + k) = w;
;         }
	v_add_f32_e32 v204, v204, v205
	v_mov_b32_e32 v205, v204
	s_nop 1
	v_permlane32_swap_b32_e32 v204, v205
	v_add_f32_e32 v204, v204, v205
	v_mov_b32_e32 v205, 0x358637bd
	v_fmamk_f32 v204, v204, 0x3a800000, v205
	v_rsq_f32_e32 v204, v204
	s_nop 0
	v_pk_mul_f32 v[96:97], v[96:97], v[204:205] op_sel_hi:[1,0]
	v_pk_mul_f32 v[98:99], v[98:99], v[204:205] op_sel_hi:[1,0]
	v_pk_mul_f32 v[96:97], v[188:189], v[96:97]
	v_pk_mul_f32 v[98:99], v[190:191], v[98:99]
	v_pk_fma_f32 v[96:97], v[34:35], v[96:97], v[224:225]
	v_pk_fma_f32 v[98:99], v[36:37], v[98:99], v[226:227]
	v_cvt_pk_bf16_f32 v96, v96, v97
	v_cvt_pk_bf16_f32 v97, v98, v99
	global_store_dwordx2 v146, v[96:97], s[66:67] sc0 sc1
	v_pk_mul_f32 v[100:101], v[100:101], v[204:205] op_sel_hi:[1,0]
	v_pk_mul_f32 v[102:103], v[102:103], v[204:205] op_sel_hi:[1,0]
	v_pk_mul_f32 v[100:101], v[192:193], v[100:101]
	v_pk_mul_f32 v[102:103], v[194:195], v[102:103]
	v_pk_fma_f32 v[100:101], v[38:39], v[100:101], v[228:229]
	v_pk_fma_f32 v[102:103], v[40:41], v[102:103], v[230:231]
	v_cvt_pk_bf16_f32 v100, v100, v101
	v_cvt_pk_bf16_f32 v101, v102, v103
	global_store_dwordx2 v146, v[100:101], s[66:67] offset:512 sc0 sc1
	v_pk_mul_f32 v[104:105], v[104:105], v[204:205] op_sel_hi:[1,0]
	v_pk_mul_f32 v[106:107], v[106:107], v[204:205] op_sel_hi:[1,0]
	v_pk_mul_f32 v[104:105], v[196:197], v[104:105]
	v_pk_mul_f32 v[106:107], v[198:199], v[106:107]
	v_pk_fma_f32 v[104:105], v[42:43], v[104:105], v[232:233]
	v_pk_fma_f32 v[106:107], v[44:45], v[106:107], v[234:235]
	v_cvt_pk_bf16_f32 v104, v104, v105
	v_cvt_pk_bf16_f32 v105, v106, v107
	global_store_dwordx2 v146, v[104:105], s[66:67] offset:1024 sc0 sc1
	v_pk_mul_f32 v[108:109], v[108:109], v[204:205] op_sel_hi:[1,0]
	v_pk_mul_f32 v[110:111], v[110:111], v[204:205] op_sel_hi:[1,0]
	v_pk_mul_f32 v[108:109], v[200:201], v[108:109]
	v_pk_mul_f32 v[110:111], v[202:203], v[110:111]
	v_pk_fma_f32 v[108:109], v[46:47], v[108:109], v[236:237]
	v_pk_fma_f32 v[110:111], v[48:49], v[110:111], v[238:239]
	v_cvt_pk_bf16_f32 v108, v108, v109
	v_cvt_pk_bf16_f32 v109, v110, v111
	global_store_dwordx2 v146, v[108:109], s[66:67] offset:1536 sc0 sc1
	v_add_u32_e32 v146, 0x800, v146
	s_waitcnt vmcnt(24)
	v_pk_mul_f32 v[242:243], v[112:113], v[112:113]
	v_pk_mul_f32 v[244:245], v[116:117], v[116:117]
	v_pk_mul_f32 v[246:247], v[114:115], v[114:115]
	v_pk_mul_f32 v[248:249], v[118:119], v[118:119]
	v_add_f32_e32 v204, v245, v244
	v_add_f32_e32 v205, v243, v242
	v_add_f32_e32 v204, v248, v204
	v_add_f32_e32 v205, v246, v205
	v_add_f32_e32 v204, v249, v204
	v_add_f32_e32 v205, v247, v205
	v_pk_mul_f32 v[242:243], v[120:121], v[120:121]
	v_pk_mul_f32 v[244:245], v[124:125], v[124:125]
	v_pk_mul_f32 v[246:247], v[122:123], v[122:123]
	v_pk_mul_f32 v[248:249], v[126:127], v[126:127]
	v_add_f32_e32 v206, v243, v242
	v_add_f32_e32 v207, v245, v244
	v_add_f32_e32 v206, v246, v206
	v_add_f32_e32 v207, v248, v207
	v_add_f32_e32 v206, v247, v206
	v_add_f32_e32 v207, v249, v207
	v_add_f32_e32 v204, v205, v204
	v_add_f32_e32 v204, v204, v206
	v_add_f32_e32 v204, v204, v207
	ds_swizzle_b32 v205, v204 offset:swizzle(SWAP,1)
	s_waitcnt lgkmcnt(0)
	v_add_f32_e32 v204, v204, v205
	ds_swizzle_b32 v205, v204 offset:swizzle(SWAP,2)
	s_waitcnt lgkmcnt(0)
	v_add_f32_e32 v204, v204, v205
	ds_swizzle_b32 v205, v204 offset:swizzle(SWAP,4)
	s_waitcnt lgkmcnt(0)
	v_add_f32_e32 v204, v204, v205
	ds_swizzle_b32 v205, v204 offset:swizzle(SWAP,8)
	s_waitcnt lgkmcnt(0)
	v_add_f32_e32 v204, v204, v205
	ds_swizzle_b32 v205, v204 offset:swizzle(SWAP,16)
	s_waitcnt lgkmcnt(0)
	v_add_f32_e32 v204, v204, v205
	v_mov_b32_e32 v205, v204
	s_nop 1
	v_permlane32_swap_b32_e32 v204, v205
	v_add_f32_e32 v204, v204, v205
	v_mov_b32_e32 v205, 0x358637bd
	v_fmamk_f32 v204, v204, 0x3a800000, v205
	v_rsq_f32_e32 v204, v204
	s_nop 0
	v_pk_mul_f32 v[112:113], v[112:113], v[204:205] op_sel_hi:[1,0]
	v_pk_mul_f32 v[114:115], v[114:115], v[204:205] op_sel_hi:[1,0]
	v_pk_mul_f32 v[112:113], v[188:189], v[112:113]
	v_pk_mul_f32 v[114:115], v[190:191], v[114:115]
	v_pk_fma_f32 v[112:113], v[34:35], v[112:113], v[224:225]
	v_pk_fma_f32 v[114:115], v[36:37], v[114:115], v[226:227]
	v_cvt_pk_bf16_f32 v112, v112, v113
	v_cvt_pk_bf16_f32 v113, v114, v115
	global_store_dwordx2 v146, v[112:113], s[66:67] sc0 sc1
	v_pk_mul_f32 v[116:117], v[116:117], v[204:205] op_sel_hi:[1,0]
	v_pk_mul_f32 v[118:119], v[118:119], v[204:205] op_sel_hi:[1,0]
	v_pk_mul_f32 v[116:117], v[192:193], v[116:117]
	v_pk_mul_f32 v[118:119], v[194:195], v[118:119]
	v_pk_fma_f32 v[116:117], v[38:39], v[116:117], v[228:229]
	v_pk_fma_f32 v[118:119], v[40:41], v[118:119], v[230:231]
	v_cvt_pk_bf16_f32 v116, v116, v117
	v_cvt_pk_bf16_f32 v117, v118, v119
	global_store_dwordx2 v146, v[116:117], s[66:67] offset:512 sc0 sc1
	v_pk_mul_f32 v[120:121], v[120:121], v[204:205] op_sel_hi:[1,0]
	v_pk_mul_f32 v[122:123], v[122:123], v[204:205] op_sel_hi:[1,0]
	v_pk_mul_f32 v[120:121], v[196:197], v[120:121]
	v_pk_mul_f32 v[122:123], v[198:199], v[122:123]
	v_pk_fma_f32 v[120:121], v[42:43], v[120:121], v[232:233]
	v_pk_fma_f32 v[122:123], v[44:45], v[122:123], v[234:235]
	v_cvt_pk_bf16_f32 v120, v120, v121
	v_cvt_pk_bf16_f32 v121, v122, v123
	global_store_dwordx2 v146, v[120:121], s[66:67] offset:1024 sc0 sc1
	v_pk_mul_f32 v[124:125], v[124:125], v[204:205] op_sel_hi:[1,0]
	v_pk_mul_f32 v[126:127], v[126:127], v[204:205] op_sel_hi:[1,0]
	v_pk_mul_f32 v[124:125], v[200:201], v[124:125]
	v_pk_mul_f32 v[126:127], v[202:203], v[126:127]
	v_pk_fma_f32 v[124:125], v[46:47], v[124:125], v[236:237]
	v_pk_fma_f32 v[126:127], v[48:49], v[126:127], v[238:239]
	v_cvt_pk_bf16_f32 v124, v124, v125
	v_cvt_pk_bf16_f32 v125, v126, v127
	global_store_dwordx2 v146, v[124:125], s[66:67] offset:1536 sc0 sc1
	v_add_u32_e32 v146, 0x800, v146
	s_waitcnt vmcnt(20)
; __device__ __forceinline__ unsigned pk2(float lo, float hi) { const g_f32x2 f = {lo, hi}; return __builtin_bit_cast(unsigned, __builtin_convertvector(f, g_bf16x2)); }
; template <int K> __device__ __forceinline__ float swz(float v) { return __int_as_float(__builtin_amdgcn_ds_swizzle(__float_as_int(v), (K << 10) | 0x1f)); }
; __device__ __forceinline__ float x32_sum(float v) { auto r = __builtin_amdgcn_permlane32_swap(__float_as_uint(v), __float_as_uint(v), false, false); return __uint_as_float(r[0]) + __uint_as_float(r[1]); }
; __device__ __forceinline__ float wave_sum(float v) {
;     v += swz<1>(v); v += swz<2>(v); v += swz<4>(v); v += swz<8>(v); v += swz<16>(v);
;     return x32_sum(v);
; __device__ __forceinline__ void p_norm(const float* hlat, const float* hctx, const float* g, const float* modl, int sh_off, int sc_off, bf16_t* A, int M,
;                                        const float* part, const float* cgate, float* hcout) {
;     ...
;             ss += v[i].x * v[i].x + v[i].y * v[i].y + v[i].z * v[i].z + v[i].w * v[i].w; }
;         ss = wave_sum(ss);
;         const float rstd = rsqrtf(ss * (1.0f / 1024.0f) + EPS);
;         const float* mr = modl + (size_t)r * 6144;
; #pragma unroll
;         for (int i = 0; i < 4; ++i) {
;             const int k = i * 256 + lane * 4;
;             const float4 gg = *(const float4*)(g + k), scv = *(const float4*)(mr + sc_off + k), shv = *(const float4*)(mr + sh_off + k);
;             const float o0 = v[i].x * rstd * gg.x * (1.0f + scv.x) + shv.x, o1 = v[i].y * rstd * gg.y * (1.0f + scv.y) + shv.y;
;             const float o2 = v[i].z * rstd * gg.z * (1.0f + scv.z) + shv.z, o3 = v[i].w * rstd * gg.w * (1.0f + scv.w) + shv.w;
;             uint2 w; w.x = pk2(o0, o1); w.y = pk2(o2, o3);
;             *(uint2*)(A + (size_t)row * 1024 + k) = w;
;         }
	v_pk_mul_f32 v[242:243], v[128:129], v[128:129]
	v_pk_mul_f32 v[244:245], v[132:133], v[132:133]
	v_pk_mul_f32 v[246:247], v[130:131], v[130:131]
	v_pk_mul_f32 v[248:249], v[134:135], v[134:135]
	v_add_f32_e32 v204, v245, v244
	v_add_f32_e32 v205, v243, v242
	v_add_f32_e32 v204, v248, v204
	v_add_f32_e32 v205, v246, v205
	v_add_f32_e32 v204, v249, v204
	v_add_f32_e32 v205, v247, v205
	v_pk_mul_f32 v[242:243], v[136:137], v[136:137]
	v_pk_mul_f32 v[244:245], v[140:141], v[140:141]
	v_pk_mul_f32 v[246:247], v[138:139], v[138:139]
	v_pk_mul_f32 v[248:249], v[142:143], v[142:143]
	v_add_f32_e32 v206, v243, v242
	v_add_f32_e32 v207, v245, v244
	v_add_f32_e32 v206, v246, v206
	v_add_f32_e32 v207, v248, v207
	v_add_f32_e32 v206, v247, v206
	v_add_f32_e32 v207, v249, v207
	v_add_f32_e32 v204, v205, v204
	v_add_f32_e32 v204, v204, v206
	v_add_f32_e32 v204, v204, v207
	ds_swizzle_b32 v205, v204 offset:swizzle(SWAP,1)
	s_waitcnt lgkmcnt(0)
	v_add_f32_e32 v204, v204, v205
	ds_swizzle_b32 v205, v204 offset:swizzle(SWAP,2)
	s_waitcnt lgkmcnt(0)
	v_add_f32_e32 v204, v204, v205
	ds_swizzle_b32 v205, v204 offset:swizzle(SWAP,4)
	s_waitcnt lgkmcnt(0)
	v_add_f32_e32 v204, v204, v205
	ds_swizzle_b32 v205, v204 offset:swizzle(SWAP,8)
	s_waitcnt lgkmcnt(0)
	v_add_f32_e32 v204, v204, v205
	ds_swizzle_b32 v205, v204 offset:swizzle(SWAP,16)
	s_waitcnt lgkmcnt(0)
	v_add_f32_e32 v204, v204, v205
	v_mov_b32_e32 v205, v204
	s_nop 1
	v_permlane32_swap_b32_e32 v204, v205
	v_add_f32_e32 v204, v204, v205
	v_mov_b32_e32 v205, 0x358637bd
	v_fmamk_f32 v204, v204, 0x3a800000, v205
	v_rsq_f32_e32 v204, v204
	s_nop 0
	v_pk_mul_f32 v[128:129], v[128:129], v[204:205] op_sel_hi:[1,0]
	v_pk_mul_f32 v[130:131], v[130:131], v[204:205] op_sel_hi:[1,0]
	v_pk_mul_f32 v[128:129], v[188:189], v[128:129]
	v_pk_mul_f32 v[130:131], v[190:191], v[130:131]
	v_pk_fma_f32 v[128:129], v[34:35], v[128:129], v[224:225]
	v_pk_fma_f32 v[130:131], v[36:37], v[130:131], v[226:227]
	v_cvt_pk_bf16_f32 v128, v128, v129
	v_cvt_pk_bf16_f32 v129, v130, v131
	global_store_dwordx2 v146, v[128:129], s[66:67] sc0 sc1
	v_pk_mul_f32 v[132:133], v[132:133], v[204:205] op_sel_hi:[1,0]
	v_pk_mul_f32 v[134:135], v[134:135], v[204:205] op_sel_hi:[1,0]
	v_pk_mul_f32 v[132:133], v[192:193], v[132:133]
	v_pk_mul_f32 v[134:135], v[194:195], v[134:135]
	v_pk_fma_f32 v[132:133], v[38:39], v[132:133], v[228:229]
	v_pk_fma_f32 v[134:135], v[40:41], v[134:135], v[230:231]
	v_cvt_pk_bf16_f32 v132, v132, v133
	v_cvt_pk_bf16_f32 v133, v134, v135
	global_store_dwordx2 v146, v[132:133], s[66:67] offset:512 sc0 sc1
	v_pk_mul_f32 v[136:137], v[136:137], v[204:205] op_sel_hi:[1,0]
	v_pk_mul_f32 v[138:139], v[138:139], v[204:205] op_sel_hi:[1,0]
	v_pk_mul_f32 v[136:137], v[196:197], v[136:137]
	v_pk_mul_f32 v[138:139], v[198:199], v[138:139]
	v_pk_fma_f32 v[136:137], v[42:43], v[136:137], v[232:233]
	v_pk_fma_f32 v[138:139], v[44:45], v[138:139], v[234:235]
	v_cvt_pk_bf16_f32 v136, v136, v137
	v_cvt_pk_bf16_f32 v137, v138, v139
	global_store_dwordx2 v146, v[136:137], s[66:67] offset:1024 sc0 sc1
	v_pk_mul_f32 v[140:141], v[140:141], v[204:205] op_sel_hi:[1,0]
	v_pk_mul_f32 v[142:143], v[142:143], v[204:205] op_sel_hi:[1,0]
	v_pk_mul_f32 v[140:141], v[200:201], v[140:141]
	v_pk_mul_f32 v[142:143], v[202:203], v[142:143]
	v_pk_fma_f32 v[140:141], v[46:47], v[140:141], v[236:237]
	v_pk_fma_f32 v[142:143], v[48:49], v[142:143], v[238:239]
	v_cvt_pk_bf16_f32 v140, v140, v141
	v_cvt_pk_bf16_f32 v141, v142, v143
	global_store_dwordx2 v146, v[140:141], s[66:67] offset:1536 sc0 sc1
	v_add_u32_e32 v146, 0x800, v146
